# GEMM K-loop priorities inverted: load/stage segments prio 1, MMA blocks prio 0 (DA fast-path priorities kept)
# baseline (speedup 1.0000x reference)
; #define STAGE(P, BASE, br, kt) do { int _so = ((br) * K + (kt) * BK) * 2; \
;     __builtin_amdgcn_raw_ptr_buffer_load_lds(rs_##BASE, (__attribute__((address_space(3))) void*)((char*)(P) + tx * 16), 16, voff0, _so, 0, 0); \
;     __builtin_amdgcn_raw_ptr_buffer_load_lds(rs_##BASE, (__attribute__((address_space(3))) void*)((char*)(P) + tx * 16 + 8192), 16, voff1, _so, 0, 0); } while (0)
; #define LDA(dst, b, h) _Pragma("unroll") for (int m = 0; m < 4; ++m) _Pragma("unroll") for (int k = 0; k < 2; ++k) \
;     dst[m][k] = *reinterpret_cast<const bf16x8*>((char*)SA(b, h) + lds_byte(wr * 64 + m * 16 + fr, k * 32 + fq * 8))
; #define LDB(dst, b, h) _Pragma("unroll") for (int n = 0; n < 2; ++n) _Pragma("unroll") for (int k = 0; k < 2; ++k) \
;     dst[n][k] = *reinterpret_cast<const bf16x8*>((char*)SB(b, h) + lds_byte(wc * 32 + n * 16 + fr, k * 32 + fq * 8))
; #define MMA(ai, bj, At, Bt_) do { __builtin_amdgcn_s_setprio(1); \
;     _Pragma("unroll") for (int m = 0; m < 4; ++m) _Pragma("unroll") for (int n = 0; n < 2; ++n) _Pragma("unroll") for (int k = 0; k < 2; ++k) \
;       acc[ai][bj][m][n] = __builtin_amdgcn_mfma_f32_16x16x32_bf16(At[m][k], Bt_[n][k], acc[ai][bj][m][n], 0, 0, 0); \
;     __builtin_amdgcn_s_setprio(0); } while (0)
; #define WAIT_V(n) asm volatile("s_waitcnt vmcnt(" #n ")" ::: "memory")
; #define WAIT_L(n) asm volatile("s_waitcnt lgkmcnt(" #n ")" ::: "memory")
; #define BAR __builtin_amdgcn_s_barrier()
; #define SCHED __builtin_amdgcn_sched_barrier(0)
; template <class Epi> ...
;     ...
;     LDB(B0, 0, 0); SCHED; LDA(At, 0, 0); STAGE(SA(1, 1), A, brow + HALF, t + 1);
;     WAIT_L(8); BAR; WAIT_L(0); MMA(0, 0, At, B0); BAR; SCHED;
;     LDB(B1, 0, 1); STAGE(SB(0, 0), Bt, bcol, t + 2);
;     BAR; WAIT_L(0); MMA(0, 1, At, B1); BAR;
;     LDA(At, 0, 1); STAGE(SA(0, 0), A, brow, t + 2);
;     BAR; WAIT_L(0); MMA(1, 0, At, B0); BAR; SCHED;
;     STAGE(SB(0, 1), Bt, bcol + HALF, t + 2);
;     WAIT_V(6); BAR; MMA(1, 1, At, B1); BAR;
.Lpk0:
	ds_read_b128 v[156:159], v155
	ds_read_b128 v[166:169], v155 offset:1024
	ds_read_b128 v[170:173], v155 offset:2048
	ds_read_b128 v[186:189], v155 offset:3072
	s_add_i32 s35, s21, s34
	v_readfirstlane_b32 s37, v152
	s_add_i32 s36, s35, 0x40080
	s_mov_b32 m0, s37
	v_readfirstlane_b32 s37, v151
	ds_read_b128 v[190:193], v143
	ds_read_b128 v[194:197], v143 offset:1024
	ds_read_b128 v[198:201], v142
	ds_read_b128 v[202:205], v142 offset:1024
	ds_read_b128 v[206:209], v141
	ds_read_b128 v[210:213], v141 offset:1024
	ds_read_b128 v[214:217], v140
	ds_read_b128 v[218:221], v140 offset:1024
	buffer_load_dwordx4 v32, s[4:7], s36 offen lds
	s_mov_b32 m0, s37
	s_nop 0
	buffer_load_dwordx4 v130, s[4:7], s36 offen lds
	s_waitcnt lgkmcnt(8)
	s_barrier
	s_waitcnt lgkmcnt(0)
	s_setprio 0
	s_waitcnt lgkmcnt(7)
	v_mfma_f32_16x16x32_bf16 v[126:129], v[190:193], v[156:159], 0
	v_mfma_f32_16x16x32_bf16 v[122:125], v[190:193], v[170:173], 0
	s_waitcnt lgkmcnt(5)
	v_mfma_f32_16x16x32_bf16 v[118:121], v[198:201], v[156:159], 0
	v_mfma_f32_16x16x32_bf16 v[114:117], v[198:201], v[170:173], 0
	s_waitcnt lgkmcnt(3)
	v_mfma_f32_16x16x32_bf16 v[110:113], v[206:209], v[156:159], 0
	v_mfma_f32_16x16x32_bf16 v[106:109], v[206:209], v[170:173], 0
	s_waitcnt lgkmcnt(1)
	v_mfma_f32_16x16x32_bf16 v[102:105], v[214:217], v[156:159], 0
	v_mfma_f32_16x16x32_bf16 v[98:101], v[214:217], v[170:173], 0
	v_mfma_f32_16x16x32_bf16 v[126:129], v[194:197], v[166:169], v[126:129]
	v_mfma_f32_16x16x32_bf16 v[122:125], v[194:197], v[186:189], v[122:125]
	v_mfma_f32_16x16x32_bf16 v[118:121], v[202:205], v[166:169], v[118:121]
	v_mfma_f32_16x16x32_bf16 v[114:117], v[202:205], v[186:189], v[114:117]
	v_mfma_f32_16x16x32_bf16 v[110:113], v[210:213], v[166:169], v[110:113]
	v_mfma_f32_16x16x32_bf16 v[106:109], v[210:213], v[186:189], v[106:109]
	s_waitcnt lgkmcnt(0)
	v_mfma_f32_16x16x32_bf16 v[102:105], v[218:221], v[166:169], v[102:105]
	v_mfma_f32_16x16x32_bf16 v[98:101], v[218:221], v[186:189], v[98:101]
	s_setprio 1
	s_barrier
	s_add_i32 s36, s20, s34
	v_readfirstlane_b32 s38, v137
	s_add_i32 s37, s36, 0x100
	s_mov_b32 m0, s38
	v_readfirstlane_b32 s38, v139
	ds_read_b128 v[222:225], v149
	ds_read_b128 v[226:229], v149 offset:1024
	ds_read_b128 v[230:233], v149 offset:2048
	ds_read_b128 v[234:237], v149 offset:3072
	buffer_load_dwordx4 v32, s[76:79], s37 offen lds
	s_mov_b32 m0, s38
	s_nop 0
	buffer_load_dwordx4 v130, s[76:79], s37 offen lds
	s_barrier
	s_waitcnt lgkmcnt(0)
	s_setprio 0
	s_waitcnt lgkmcnt(3)
	v_mfma_f32_16x16x32_bf16 v[94:97], v[190:193], v[222:225], 0
	s_waitcnt lgkmcnt(1)
	v_mfma_f32_16x16x32_bf16 v[90:93], v[190:193], v[230:233], 0
	v_mfma_f32_16x16x32_bf16 v[86:89], v[198:201], v[222:225], 0
	v_mfma_f32_16x16x32_bf16 v[82:85], v[198:201], v[230:233], 0
	v_mfma_f32_16x16x32_bf16 v[78:81], v[206:209], v[222:225], 0
	v_mfma_f32_16x16x32_bf16 v[74:77], v[206:209], v[230:233], 0
	v_mfma_f32_16x16x32_bf16 v[70:73], v[214:217], v[222:225], 0
	v_mfma_f32_16x16x32_bf16 v[66:69], v[214:217], v[230:233], 0
	v_mfma_f32_16x16x32_bf16 v[94:97], v[194:197], v[226:229], v[94:97]
	s_waitcnt lgkmcnt(0)
	v_mfma_f32_16x16x32_bf16 v[90:93], v[194:197], v[234:237], v[90:93]
	v_mfma_f32_16x16x32_bf16 v[86:89], v[202:205], v[226:229], v[86:89]
	v_mfma_f32_16x16x32_bf16 v[82:85], v[202:205], v[234:237], v[82:85]
	v_mfma_f32_16x16x32_bf16 v[78:81], v[210:213], v[226:229], v[78:81]
	v_mfma_f32_16x16x32_bf16 v[74:77], v[210:213], v[234:237], v[74:77]
	v_mfma_f32_16x16x32_bf16 v[70:73], v[218:221], v[226:229], v[70:73]
	v_mfma_f32_16x16x32_bf16 v[66:69], v[218:221], v[234:237], v[66:69]
	s_setprio 1
	v_readfirstlane_b32 s38, v136
	s_add_i32 s37, s35, 0x100
	s_mov_b32 m0, s38
	v_readfirstlane_b32 s38, v135
	s_barrier
	ds_read_b128 v[190:193], v143 offset:16384
	ds_read_b128 v[194:197], v143 offset:17408
	ds_read_b128 v[198:201], v142 offset:16384
	ds_read_b128 v[202:205], v142 offset:17408
	ds_read_b128 v[206:209], v141 offset:16384
	ds_read_b128 v[210:213], v141 offset:17408
	ds_read_b128 v[214:217], v140 offset:16384
	ds_read_b128 v[218:221], v140 offset:17408
	buffer_load_dwordx4 v32, s[4:7], s37 offen lds
	s_mov_b32 m0, s38
	s_nop 0
	buffer_load_dwordx4 v130, s[4:7], s37 offen lds
	s_barrier
	s_waitcnt lgkmcnt(0)
	s_setprio 0
	s_waitcnt lgkmcnt(7)
	v_mfma_f32_16x16x32_bf16 v[62:65], v[190:193], v[156:159], 0
	v_mfma_f32_16x16x32_bf16 v[58:61], v[190:193], v[170:173], 0
	s_waitcnt lgkmcnt(5)
	v_mfma_f32_16x16x32_bf16 v[54:57], v[198:201], v[156:159], 0
	v_mfma_f32_16x16x32_bf16 v[50:53], v[198:201], v[170:173], 0
	s_waitcnt lgkmcnt(3)
	v_mfma_f32_16x16x32_bf16 v[46:49], v[206:209], v[156:159], 0
	v_mfma_f32_16x16x32_bf16 v[42:45], v[206:209], v[170:173], 0
	s_waitcnt lgkmcnt(1)
	v_mfma_f32_16x16x32_bf16 v[38:41], v[214:217], v[156:159], 0
	v_mfma_f32_16x16x32_bf16 v[34:37], v[214:217], v[170:173], 0
	v_mfma_f32_16x16x32_bf16 v[62:65], v[194:197], v[166:169], v[62:65]
	v_mfma_f32_16x16x32_bf16 v[58:61], v[194:197], v[186:189], v[58:61]
	v_mfma_f32_16x16x32_bf16 v[54:57], v[202:205], v[166:169], v[54:57]
	v_mfma_f32_16x16x32_bf16 v[50:53], v[202:205], v[186:189], v[50:53]
	v_mfma_f32_16x16x32_bf16 v[46:49], v[210:213], v[166:169], v[46:49]
	v_mfma_f32_16x16x32_bf16 v[42:45], v[210:213], v[186:189], v[42:45]
	s_waitcnt lgkmcnt(0)
	v_mfma_f32_16x16x32_bf16 v[38:41], v[218:221], v[166:169], v[38:41]
	v_mfma_f32_16x16x32_bf16 v[34:37], v[218:221], v[186:189], v[34:37]
	s_setprio 1
	s_barrier
	v_readfirstlane_b32 s38, v134
	s_add_i32 s37, s36, 0x40100
	s_mov_b32 m0, s38
	v_readfirstlane_b32 s38, v138
	buffer_load_dwordx4 v32, s[76:79], s37 offen lds
	s_mov_b32 m0, s38
	s_nop 0
	buffer_load_dwordx4 v130, s[76:79], s37 offen lds
	s_waitcnt vmcnt(6)
	s_barrier
; #define STAGE(P, BASE, br, kt) do { int _so = ((br) * K + (kt) * BK) * 2; \
;     __builtin_amdgcn_raw_ptr_buffer_load_lds(rs_##BASE, (__attribute__((address_space(3))) void*)((char*)(P) + tx * 16), 16, voff0, _so, 0, 0); \
;     __builtin_amdgcn_raw_ptr_buffer_load_lds(rs_##BASE, (__attribute__((address_space(3))) void*)((char*)(P) + tx * 16 + 8192), 16, voff1, _so, 0, 0); } while (0)
; #define LDA(dst, b, h) _Pragma("unroll") for (int m = 0; m < 4; ++m) _Pragma("unroll") for (int k = 0; k < 2; ++k) \
;     dst[m][k] = *reinterpret_cast<const bf16x8*>((char*)SA(b, h) + lds_byte(wr * 64 + m * 16 + fr, k * 32 + fq * 8))
; #define LDB(dst, b, h) _Pragma("unroll") for (int n = 0; n < 2; ++n) _Pragma("unroll") for (int k = 0; k < 2; ++k) \
;     dst[n][k] = *reinterpret_cast<const bf16x8*>((char*)SB(b, h) + lds_byte(wc * 32 + n * 16 + fr, k * 32 + fq * 8))
; #define MMA(ai, bj, At, Bt_) do { __builtin_amdgcn_s_setprio(1); \
;     _Pragma("unroll") for (int m = 0; m < 4; ++m) _Pragma("unroll") for (int n = 0; n < 2; ++n) _Pragma("unroll") for (int k = 0; k < 2; ++k) \
;       acc[ai][bj][m][n] = __builtin_amdgcn_mfma_f32_16x16x32_bf16(At[m][k], Bt_[n][k], acc[ai][bj][m][n], 0, 0, 0); \
;     __builtin_amdgcn_s_setprio(0); } while (0)
; #define WAIT_V(n) asm volatile("s_waitcnt vmcnt(" #n ")" ::: "memory")
; #define WAIT_L(n) asm volatile("s_waitcnt lgkmcnt(" #n ")" ::: "memory")
; #define BAR __builtin_amdgcn_s_barrier()
; #define SCHED __builtin_amdgcn_sched_barrier(0)
; template <class Epi> ...
;     ...
;     WAIT_V(6); BAR; MMA(1, 1, At, B1); BAR;
;     LDB(B0, 1, 0); SCHED; LDA(At, 1, 0); STAGE(SA(0, 1), A, brow + HALF, t + 2);
;     WAIT_L(8); BAR; WAIT_L(0); MMA(0, 0, At, B0); BAR; SCHED;
;     LDB(B1, 1, 1); STAGE(SB(1, 0), Bt, bcol, t + 3);
;     BAR; WAIT_L(0); MMA(0, 1, At, B1); BAR;
;     LDA(At, 1, 1); STAGE(SA(1, 0), A, brow, t + 3);
;     BAR; WAIT_L(0); MMA(1, 0, At, B0); BAR; SCHED;
;     STAGE(SB(1, 1), Bt, bcol + HALF, t + 3);
;     WAIT_V(6); BAR; MMA(1, 1, At, B1); BAR;
	s_setprio 0
	v_mfma_f32_16x16x32_bf16 v[28:31], v[190:193], v[222:225], 0
	v_mfma_f32_16x16x32_bf16 v[24:27], v[190:193], v[230:233], 0
	v_mfma_f32_16x16x32_bf16 v[20:23], v[198:201], v[222:225], 0
	v_mfma_f32_16x16x32_bf16 v[16:19], v[198:201], v[230:233], 0
	v_mfma_f32_16x16x32_bf16 v[12:15], v[206:209], v[222:225], 0
	v_mfma_f32_16x16x32_bf16 v[8:11], v[206:209], v[230:233], 0
	v_mfma_f32_16x16x32_bf16 v[4:7], v[214:217], v[222:225], 0
	v_mfma_f32_16x16x32_bf16 v[0:3], v[214:217], v[230:233], 0
	v_mfma_f32_16x16x32_bf16 v[28:31], v[194:197], v[226:229], v[28:31]
	v_mfma_f32_16x16x32_bf16 v[24:27], v[194:197], v[234:237], v[24:27]
	v_mfma_f32_16x16x32_bf16 v[20:23], v[202:205], v[226:229], v[20:23]
	v_mfma_f32_16x16x32_bf16 v[16:19], v[202:205], v[234:237], v[16:19]
	v_mfma_f32_16x16x32_bf16 v[12:15], v[210:213], v[226:229], v[12:15]
	v_mfma_f32_16x16x32_bf16 v[8:11], v[210:213], v[234:237], v[8:11]
	v_mfma_f32_16x16x32_bf16 v[4:7], v[218:221], v[226:229], v[4:7]
	v_mfma_f32_16x16x32_bf16 v[0:3], v[218:221], v[234:237], v[0:3]
	s_setprio 1
	s_barrier
	ds_read_b128 v[156:159], v145
	ds_read_b128 v[166:169], v145 offset:1024
	ds_read_b128 v[170:173], v145 offset:2048
	ds_read_b128 v[186:189], v145 offset:3072
	v_readfirstlane_b32 s38, v132
	s_add_i32 s37, s35, 0x40100
	s_mov_b32 m0, s38
	v_readfirstlane_b32 s38, v131
	ds_read_b128 v[190:193], v143 offset:32768
	ds_read_b128 v[194:197], v143 offset:33792
	ds_read_b128 v[198:201], v142 offset:32768
	ds_read_b128 v[202:205], v142 offset:33792
	ds_read_b128 v[206:209], v141 offset:32768
	ds_read_b128 v[210:213], v141 offset:33792
	ds_read_b128 v[214:217], v140 offset:32768
	ds_read_b128 v[218:221], v140 offset:33792
	buffer_load_dwordx4 v32, s[4:7], s37 offen lds
	s_mov_b32 m0, s38
	s_nop 0
	buffer_load_dwordx4 v130, s[4:7], s37 offen lds
	s_waitcnt lgkmcnt(8)
	s_barrier
	s_waitcnt lgkmcnt(0)
	s_setprio 0
	s_waitcnt lgkmcnt(7)
	v_mfma_f32_16x16x32_bf16 v[126:129], v[190:193], v[156:159], v[126:129]
	v_mfma_f32_16x16x32_bf16 v[122:125], v[190:193], v[170:173], v[122:125]
	s_waitcnt lgkmcnt(5)
	v_mfma_f32_16x16x32_bf16 v[118:121], v[198:201], v[156:159], v[118:121]
	v_mfma_f32_16x16x32_bf16 v[114:117], v[198:201], v[170:173], v[114:117]
	s_waitcnt lgkmcnt(3)
	v_mfma_f32_16x16x32_bf16 v[110:113], v[206:209], v[156:159], v[110:113]
	v_mfma_f32_16x16x32_bf16 v[106:109], v[206:209], v[170:173], v[106:109]
	s_waitcnt lgkmcnt(1)
	v_mfma_f32_16x16x32_bf16 v[102:105], v[214:217], v[156:159], v[102:105]
	v_mfma_f32_16x16x32_bf16 v[98:101], v[214:217], v[170:173], v[98:101]
	v_mfma_f32_16x16x32_bf16 v[126:129], v[194:197], v[166:169], v[126:129]
	v_mfma_f32_16x16x32_bf16 v[122:125], v[194:197], v[186:189], v[122:125]
	v_mfma_f32_16x16x32_bf16 v[118:121], v[202:205], v[166:169], v[118:121]
	v_mfma_f32_16x16x32_bf16 v[114:117], v[202:205], v[186:189], v[114:117]
	v_mfma_f32_16x16x32_bf16 v[110:113], v[210:213], v[166:169], v[110:113]
	v_mfma_f32_16x16x32_bf16 v[106:109], v[210:213], v[186:189], v[106:109]
	s_waitcnt lgkmcnt(0)
	v_mfma_f32_16x16x32_bf16 v[102:105], v[218:221], v[166:169], v[102:105]
	v_mfma_f32_16x16x32_bf16 v[98:101], v[218:221], v[186:189], v[98:101]
	s_setprio 1
	s_barrier
	v_readfirstlane_b32 s38, v146
	s_add_i32 s37, s36, 0x180
	s_mov_b32 m0, s38
	v_readfirstlane_b32 s38, v147
	ds_read_b128 v[222:225], v144
	ds_read_b128 v[226:229], v144 offset:1024
	ds_read_b128 v[230:233], v144 offset:2048
	ds_read_b128 v[234:237], v144 offset:3072
	buffer_load_dwordx4 v32, s[76:79], s37 offen lds
	s_mov_b32 m0, s38
	s_nop 0
	buffer_load_dwordx4 v130, s[76:79], s37 offen lds
	s_barrier
	s_waitcnt lgkmcnt(0)
	s_setprio 0
	s_waitcnt lgkmcnt(3)
	v_mfma_f32_16x16x32_bf16 v[94:97], v[190:193], v[222:225], v[94:97]
	s_waitcnt lgkmcnt(1)
	v_mfma_f32_16x16x32_bf16 v[90:93], v[190:193], v[230:233], v[90:93]
	v_mfma_f32_16x16x32_bf16 v[86:89], v[198:201], v[222:225], v[86:89]
	v_mfma_f32_16x16x32_bf16 v[82:85], v[198:201], v[230:233], v[82:85]
	v_mfma_f32_16x16x32_bf16 v[78:81], v[206:209], v[222:225], v[78:81]
	v_mfma_f32_16x16x32_bf16 v[74:77], v[206:209], v[230:233], v[74:77]
	v_mfma_f32_16x16x32_bf16 v[70:73], v[214:217], v[222:225], v[70:73]
	v_mfma_f32_16x16x32_bf16 v[66:69], v[214:217], v[230:233], v[66:69]
	v_mfma_f32_16x16x32_bf16 v[94:97], v[194:197], v[226:229], v[94:97]
	s_waitcnt lgkmcnt(0)
	v_mfma_f32_16x16x32_bf16 v[90:93], v[194:197], v[234:237], v[90:93]
	v_mfma_f32_16x16x32_bf16 v[86:89], v[202:205], v[226:229], v[86:89]
	v_mfma_f32_16x16x32_bf16 v[82:85], v[202:205], v[234:237], v[82:85]
	v_mfma_f32_16x16x32_bf16 v[78:81], v[210:213], v[226:229], v[78:81]
	v_mfma_f32_16x16x32_bf16 v[74:77], v[210:213], v[234:237], v[74:77]
	v_mfma_f32_16x16x32_bf16 v[70:73], v[218:221], v[226:229], v[70:73]
	v_mfma_f32_16x16x32_bf16 v[66:69], v[218:221], v[234:237], v[66:69]
	s_setprio 1
	v_readfirstlane_b32 s37, v148
	s_addk_i32 s35, 0x180
	s_mov_b32 m0, s37
	v_readfirstlane_b32 s37, v150
	s_barrier
	ds_read_b128 v[190:193], v143 offset:49152
	ds_read_b128 v[194:197], v143 offset:50176
	ds_read_b128 v[198:201], v142 offset:49152
	ds_read_b128 v[202:205], v142 offset:50176
	ds_read_b128 v[206:209], v141 offset:49152
	ds_read_b128 v[210:213], v141 offset:50176
	ds_read_b128 v[214:217], v140 offset:49152
	ds_read_b128 v[218:221], v140 offset:50176
	buffer_load_dwordx4 v32, s[4:7], s35 offen lds
	s_mov_b32 m0, s37
	s_nop 0
	buffer_load_dwordx4 v130, s[4:7], s35 offen lds
	s_barrier
; #define STAGE(P, BASE, br, kt) do { int _so = ((br) * K + (kt) * BK) * 2; \
;     __builtin_amdgcn_raw_ptr_buffer_load_lds(rs_##BASE, (__attribute__((address_space(3))) void*)((char*)(P) + tx * 16), 16, voff0, _so, 0, 0); \
;     __builtin_amdgcn_raw_ptr_buffer_load_lds(rs_##BASE, (__attribute__((address_space(3))) void*)((char*)(P) + tx * 16 + 8192), 16, voff1, _so, 0, 0); } while (0)
; #define LDA(dst, b, h) _Pragma("unroll") for (int m = 0; m < 4; ++m) _Pragma("unroll") for (int k = 0; k < 2; ++k) \
;     dst[m][k] = *reinterpret_cast<const bf16x8*>((char*)SA(b, h) + lds_byte(wr * 64 + m * 16 + fr, k * 32 + fq * 8))
; #define LDB(dst, b, h) _Pragma("unroll") for (int n = 0; n < 2; ++n) _Pragma("unroll") for (int k = 0; k < 2; ++k) \
;     dst[n][k] = *reinterpret_cast<const bf16x8*>((char*)SB(b, h) + lds_byte(wc * 32 + n * 16 + fr, k * 32 + fq * 8))
; #define MMA(ai, bj, At, Bt_) do { __builtin_amdgcn_s_setprio(1); \
;     _Pragma("unroll") for (int m = 0; m < 4; ++m) _Pragma("unroll") for (int n = 0; n < 2; ++n) _Pragma("unroll") for (int k = 0; k < 2; ++k) \
;       acc[ai][bj][m][n] = __builtin_amdgcn_mfma_f32_16x16x32_bf16(At[m][k], Bt_[n][k], acc[ai][bj][m][n], 0, 0, 0); \
;     __builtin_amdgcn_s_setprio(0); } while (0)
; #define WAIT_V(n) asm volatile("s_waitcnt vmcnt(" #n ")" ::: "memory")
; #define WAIT_L(n) asm volatile("s_waitcnt lgkmcnt(" #n ")" ::: "memory")
; #define BAR __builtin_amdgcn_s_barrier()
; #define SCHED __builtin_amdgcn_sched_barrier(0)
; template <class Epi> ...
;     ...
;     LDB(B0, 0, 0); SCHED; LDA(At, 0, 0); STAGE(SA(1, 1), A, brow + HALF, t + 1);
;     WAIT_L(8); BAR; WAIT_L(0); MMA(0, 0, At, B0); BAR; SCHED;
;     LDB(B1, 0, 1); STAGE(SB(0, 0), Bt, bcol, t + 2);
;     ...
;     BAR; WAIT_L(0); MMA(1, 0, At, B0); BAR; SCHED;
;     STAGE(SB(1, 1), Bt, bcol + HALF, t + 3);
;     WAIT_V(6); BAR; MMA(1, 1, At, B1); BAR;
;   }
	s_waitcnt lgkmcnt(0)
	s_setprio 0
	s_waitcnt lgkmcnt(7)
	v_mfma_f32_16x16x32_bf16 v[62:65], v[190:193], v[156:159], v[62:65]
	v_mfma_f32_16x16x32_bf16 v[58:61], v[190:193], v[170:173], v[58:61]
	s_waitcnt lgkmcnt(5)
	v_mfma_f32_16x16x32_bf16 v[54:57], v[198:201], v[156:159], v[54:57]
	v_mfma_f32_16x16x32_bf16 v[50:53], v[198:201], v[170:173], v[50:53]
	s_waitcnt lgkmcnt(3)
	v_mfma_f32_16x16x32_bf16 v[46:49], v[206:209], v[156:159], v[46:49]
	v_mfma_f32_16x16x32_bf16 v[42:45], v[206:209], v[170:173], v[42:45]
	s_waitcnt lgkmcnt(1)
	v_mfma_f32_16x16x32_bf16 v[38:41], v[214:217], v[156:159], v[38:41]
	v_mfma_f32_16x16x32_bf16 v[34:37], v[214:217], v[170:173], v[34:37]
	v_mfma_f32_16x16x32_bf16 v[62:65], v[194:197], v[166:169], v[62:65]
	v_mfma_f32_16x16x32_bf16 v[58:61], v[194:197], v[186:189], v[58:61]
	v_mfma_f32_16x16x32_bf16 v[54:57], v[202:205], v[166:169], v[54:57]
	v_mfma_f32_16x16x32_bf16 v[50:53], v[202:205], v[186:189], v[50:53]
	v_mfma_f32_16x16x32_bf16 v[46:49], v[210:213], v[166:169], v[46:49]
	v_mfma_f32_16x16x32_bf16 v[42:45], v[210:213], v[186:189], v[42:45]
	s_waitcnt lgkmcnt(0)
	v_mfma_f32_16x16x32_bf16 v[38:41], v[218:221], v[166:169], v[38:41]
	v_mfma_f32_16x16x32_bf16 v[34:37], v[218:221], v[186:189], v[34:37]
	s_setprio 1
	s_barrier
	v_readfirstlane_b32 s35, v153
	s_add_i32 s36, s36, 0x40180
	s_mov_b32 m0, s35
	v_readfirstlane_b32 s35, v154
	buffer_load_dwordx4 v32, s[76:79], s36 offen lds
	s_mov_b32 m0, s35
	s_nop 0
	buffer_load_dwordx4 v130, s[76:79], s36 offen lds
	s_waitcnt vmcnt(6)
	s_barrier
	s_setprio 0
	v_mfma_f32_16x16x32_bf16 v[28:31], v[190:193], v[222:225], v[28:31]
	v_mfma_f32_16x16x32_bf16 v[24:27], v[190:193], v[230:233], v[24:27]
	v_mfma_f32_16x16x32_bf16 v[20:23], v[198:201], v[222:225], v[20:23]
	v_mfma_f32_16x16x32_bf16 v[16:19], v[198:201], v[230:233], v[16:19]
	v_mfma_f32_16x16x32_bf16 v[12:15], v[206:209], v[222:225], v[12:15]
	v_mfma_f32_16x16x32_bf16 v[8:11], v[206:209], v[230:233], v[8:11]
	v_mfma_f32_16x16x32_bf16 v[4:7], v[214:217], v[222:225], v[4:7]
	v_mfma_f32_16x16x32_bf16 v[0:3], v[214:217], v[230:233], v[0:3]
	v_mfma_f32_16x16x32_bf16 v[28:31], v[194:197], v[226:229], v[28:31]
	v_mfma_f32_16x16x32_bf16 v[24:27], v[194:197], v[234:237], v[24:27]
	v_mfma_f32_16x16x32_bf16 v[20:23], v[202:205], v[226:229], v[20:23]
	v_mfma_f32_16x16x32_bf16 v[16:19], v[202:205], v[234:237], v[16:19]
	v_mfma_f32_16x16x32_bf16 v[12:15], v[210:213], v[226:229], v[12:15]
	v_mfma_f32_16x16x32_bf16 v[8:11], v[210:213], v[234:237], v[8:11]
	v_mfma_f32_16x16x32_bf16 v[4:7], v[218:221], v[226:229], v[4:7]
	v_mfma_f32_16x16x32_bf16 v[0:3], v[218:221], v[234:237], v[0:3]
	s_setprio 1
	s_add_i32 s31, s31, 2
	s_addk_i32 s34, 0x100
	s_cmp_lt_u32 s31, 12
	s_barrier
	s_cbranch_scc1 .LBB0_74
	s_branch .Lpx0
.LBB0_74:
	ds_read_b128 v[156:159], v155
	ds_read_b128 v[166:169], v155 offset:1024
	ds_read_b128 v[170:173], v155 offset:2048
	ds_read_b128 v[186:189], v155 offset:3072
	s_add_i32 s35, s21, s34
	v_readfirstlane_b32 s37, v152
	s_add_i32 s36, s35, 0x40080
	s_mov_b32 m0, s37
	v_readfirstlane_b32 s37, v151
	ds_read_b128 v[190:193], v143
	ds_read_b128 v[194:197], v143 offset:1024
	ds_read_b128 v[198:201], v142
	ds_read_b128 v[202:205], v142 offset:1024
	ds_read_b128 v[206:209], v141
	ds_read_b128 v[210:213], v141 offset:1024
	ds_read_b128 v[214:217], v140
	ds_read_b128 v[218:221], v140 offset:1024
	buffer_load_dwordx4 v32, s[4:7], s36 offen lds
	s_mov_b32 m0, s37
	s_nop 0
	buffer_load_dwordx4 v130, s[4:7], s36 offen lds
	s_waitcnt lgkmcnt(8)
	s_barrier
	s_waitcnt lgkmcnt(0)
	s_setprio 0
	s_waitcnt lgkmcnt(7)
	v_mfma_f32_16x16x32_bf16 v[126:129], v[190:193], v[156:159], v[126:129]
	v_mfma_f32_16x16x32_bf16 v[122:125], v[190:193], v[170:173], v[122:125]
	s_waitcnt lgkmcnt(5)
	v_mfma_f32_16x16x32_bf16 v[118:121], v[198:201], v[156:159], v[118:121]
	v_mfma_f32_16x16x32_bf16 v[114:117], v[198:201], v[170:173], v[114:117]
	s_waitcnt lgkmcnt(3)
	v_mfma_f32_16x16x32_bf16 v[110:113], v[206:209], v[156:159], v[110:113]
	v_mfma_f32_16x16x32_bf16 v[106:109], v[206:209], v[170:173], v[106:109]
	s_waitcnt lgkmcnt(1)
	v_mfma_f32_16x16x32_bf16 v[102:105], v[214:217], v[156:159], v[102:105]
	v_mfma_f32_16x16x32_bf16 v[98:101], v[214:217], v[170:173], v[98:101]
	v_mfma_f32_16x16x32_bf16 v[126:129], v[194:197], v[166:169], v[126:129]
	v_mfma_f32_16x16x32_bf16 v[122:125], v[194:197], v[186:189], v[122:125]
	v_mfma_f32_16x16x32_bf16 v[118:121], v[202:205], v[166:169], v[118:121]
	v_mfma_f32_16x16x32_bf16 v[114:117], v[202:205], v[186:189], v[114:117]
	v_mfma_f32_16x16x32_bf16 v[110:113], v[210:213], v[166:169], v[110:113]
	v_mfma_f32_16x16x32_bf16 v[106:109], v[210:213], v[186:189], v[106:109]
	s_waitcnt lgkmcnt(0)
	v_mfma_f32_16x16x32_bf16 v[102:105], v[218:221], v[166:169], v[102:105]
	v_mfma_f32_16x16x32_bf16 v[98:101], v[218:221], v[186:189], v[98:101]
	s_setprio 1
	s_barrier
	s_add_i32 s36, s20, s34
	v_readfirstlane_b32 s38, v137
	s_add_i32 s37, s36, 0x100
	s_mov_b32 m0, s38
	v_readfirstlane_b32 s38, v139
	ds_read_b128 v[222:225], v149
	ds_read_b128 v[226:229], v149 offset:1024
	ds_read_b128 v[230:233], v149 offset:2048
	ds_read_b128 v[234:237], v149 offset:3072
	buffer_load_dwordx4 v32, s[76:79], s37 offen lds
	s_mov_b32 m0, s38
	s_nop 0
	buffer_load_dwordx4 v130, s[76:79], s37 offen lds
	s_barrier
; #define STAGE(P, BASE, br, kt) do { int _so = ((br) * K + (kt) * BK) * 2; \
;     __builtin_amdgcn_raw_ptr_buffer_load_lds(rs_##BASE, (__attribute__((address_space(3))) void*)((char*)(P) + tx * 16), 16, voff0, _so, 0, 0); \
;     __builtin_amdgcn_raw_ptr_buffer_load_lds(rs_##BASE, (__attribute__((address_space(3))) void*)((char*)(P) + tx * 16 + 8192), 16, voff1, _so, 0, 0); } while (0)
; #define LDA(dst, b, h) _Pragma("unroll") for (int m = 0; m < 4; ++m) _Pragma("unroll") for (int k = 0; k < 2; ++k) \
;     dst[m][k] = *reinterpret_cast<const bf16x8*>((char*)SA(b, h) + lds_byte(wr * 64 + m * 16 + fr, k * 32 + fq * 8))
; #define LDB(dst, b, h) _Pragma("unroll") for (int n = 0; n < 2; ++n) _Pragma("unroll") for (int k = 0; k < 2; ++k) \
;     dst[n][k] = *reinterpret_cast<const bf16x8*>((char*)SB(b, h) + lds_byte(wc * 32 + n * 16 + fr, k * 32 + fq * 8))
; #define MMA(ai, bj, At, Bt_) do { __builtin_amdgcn_s_setprio(1); \
;     _Pragma("unroll") for (int m = 0; m < 4; ++m) _Pragma("unroll") for (int n = 0; n < 2; ++n) _Pragma("unroll") for (int k = 0; k < 2; ++k) \
;       acc[ai][bj][m][n] = __builtin_amdgcn_mfma_f32_16x16x32_bf16(At[m][k], Bt_[n][k], acc[ai][bj][m][n], 0, 0, 0); \
;     __builtin_amdgcn_s_setprio(0); } while (0)
; #define WAIT_V(n) asm volatile("s_waitcnt vmcnt(" #n ")" ::: "memory")
; #define WAIT_L(n) asm volatile("s_waitcnt lgkmcnt(" #n ")" ::: "memory")
; #define BAR __builtin_amdgcn_s_barrier()
; #define SCHED __builtin_amdgcn_sched_barrier(0)
; template <class Epi> ...
;     ...
;     BAR; WAIT_L(0); MMA(0, 1, At, B1); BAR;
;     LDA(At, 0, 1); STAGE(SA(0, 0), A, brow, t + 2);
;     BAR; WAIT_L(0); MMA(1, 0, At, B0); BAR; SCHED;
;     STAGE(SB(0, 1), Bt, bcol + HALF, t + 2);
;     WAIT_V(6); BAR; MMA(1, 1, At, B1); BAR;
;     LDB(B0, 1, 0); SCHED; LDA(At, 1, 0); STAGE(SA(0, 1), A, brow + HALF, t + 2);
	s_waitcnt lgkmcnt(0)
	s_setprio 0
	s_waitcnt lgkmcnt(3)
	v_mfma_f32_16x16x32_bf16 v[94:97], v[190:193], v[222:225], v[94:97]
	s_waitcnt lgkmcnt(1)
	v_mfma_f32_16x16x32_bf16 v[90:93], v[190:193], v[230:233], v[90:93]
	v_mfma_f32_16x16x32_bf16 v[86:89], v[198:201], v[222:225], v[86:89]
	v_mfma_f32_16x16x32_bf16 v[82:85], v[198:201], v[230:233], v[82:85]
	v_mfma_f32_16x16x32_bf16 v[78:81], v[206:209], v[222:225], v[78:81]
	v_mfma_f32_16x16x32_bf16 v[74:77], v[206:209], v[230:233], v[74:77]
	v_mfma_f32_16x16x32_bf16 v[70:73], v[214:217], v[222:225], v[70:73]
	v_mfma_f32_16x16x32_bf16 v[66:69], v[214:217], v[230:233], v[66:69]
	v_mfma_f32_16x16x32_bf16 v[94:97], v[194:197], v[226:229], v[94:97]
	s_waitcnt lgkmcnt(0)
	v_mfma_f32_16x16x32_bf16 v[90:93], v[194:197], v[234:237], v[90:93]
	v_mfma_f32_16x16x32_bf16 v[86:89], v[202:205], v[226:229], v[86:89]
	v_mfma_f32_16x16x32_bf16 v[82:85], v[202:205], v[234:237], v[82:85]
	v_mfma_f32_16x16x32_bf16 v[78:81], v[210:213], v[226:229], v[78:81]
	v_mfma_f32_16x16x32_bf16 v[74:77], v[210:213], v[234:237], v[74:77]
	v_mfma_f32_16x16x32_bf16 v[70:73], v[218:221], v[226:229], v[70:73]
	v_mfma_f32_16x16x32_bf16 v[66:69], v[218:221], v[234:237], v[66:69]
	s_setprio 1
	v_readfirstlane_b32 s38, v136
	s_add_i32 s37, s35, 0x100
	s_mov_b32 m0, s38
	v_readfirstlane_b32 s38, v135
	s_barrier
	ds_read_b128 v[190:193], v143 offset:16384
	ds_read_b128 v[194:197], v143 offset:17408
	ds_read_b128 v[198:201], v142 offset:16384
	ds_read_b128 v[202:205], v142 offset:17408
	ds_read_b128 v[206:209], v141 offset:16384
	ds_read_b128 v[210:213], v141 offset:17408
	ds_read_b128 v[214:217], v140 offset:16384
	ds_read_b128 v[218:221], v140 offset:17408
	buffer_load_dwordx4 v32, s[4:7], s37 offen lds
	s_mov_b32 m0, s38
	s_nop 0
	buffer_load_dwordx4 v130, s[4:7], s37 offen lds
	s_barrier
	s_waitcnt lgkmcnt(0)
	s_setprio 0
	s_waitcnt lgkmcnt(7)
	v_mfma_f32_16x16x32_bf16 v[62:65], v[190:193], v[156:159], v[62:65]
	v_mfma_f32_16x16x32_bf16 v[58:61], v[190:193], v[170:173], v[58:61]
	s_waitcnt lgkmcnt(5)
	v_mfma_f32_16x16x32_bf16 v[54:57], v[198:201], v[156:159], v[54:57]
	v_mfma_f32_16x16x32_bf16 v[50:53], v[198:201], v[170:173], v[50:53]
	s_waitcnt lgkmcnt(3)
	v_mfma_f32_16x16x32_bf16 v[46:49], v[206:209], v[156:159], v[46:49]
	v_mfma_f32_16x16x32_bf16 v[42:45], v[206:209], v[170:173], v[42:45]
	s_waitcnt lgkmcnt(1)
	v_mfma_f32_16x16x32_bf16 v[38:41], v[214:217], v[156:159], v[38:41]
	v_mfma_f32_16x16x32_bf16 v[34:37], v[214:217], v[170:173], v[34:37]
	v_mfma_f32_16x16x32_bf16 v[62:65], v[194:197], v[166:169], v[62:65]
	v_mfma_f32_16x16x32_bf16 v[58:61], v[194:197], v[186:189], v[58:61]
	v_mfma_f32_16x16x32_bf16 v[54:57], v[202:205], v[166:169], v[54:57]
	v_mfma_f32_16x16x32_bf16 v[50:53], v[202:205], v[186:189], v[50:53]
	v_mfma_f32_16x16x32_bf16 v[46:49], v[210:213], v[166:169], v[46:49]
	v_mfma_f32_16x16x32_bf16 v[42:45], v[210:213], v[186:189], v[42:45]
	s_waitcnt lgkmcnt(0)
	v_mfma_f32_16x16x32_bf16 v[38:41], v[218:221], v[166:169], v[38:41]
	v_mfma_f32_16x16x32_bf16 v[34:37], v[218:221], v[186:189], v[34:37]
	s_setprio 1
	s_barrier
	v_readfirstlane_b32 s38, v134
	s_add_i32 s37, s36, 0x40100
	s_mov_b32 m0, s38
	v_readfirstlane_b32 s38, v138
	buffer_load_dwordx4 v32, s[76:79], s37 offen lds
	s_mov_b32 m0, s38
	s_nop 0
	buffer_load_dwordx4 v130, s[76:79], s37 offen lds
	s_waitcnt vmcnt(6)
	s_barrier
	s_setprio 0
	v_mfma_f32_16x16x32_bf16 v[28:31], v[190:193], v[222:225], v[28:31]
	v_mfma_f32_16x16x32_bf16 v[24:27], v[190:193], v[230:233], v[24:27]
	v_mfma_f32_16x16x32_bf16 v[20:23], v[198:201], v[222:225], v[20:23]
	v_mfma_f32_16x16x32_bf16 v[16:19], v[198:201], v[230:233], v[16:19]
	v_mfma_f32_16x16x32_bf16 v[12:15], v[206:209], v[222:225], v[12:15]
	v_mfma_f32_16x16x32_bf16 v[8:11], v[206:209], v[230:233], v[8:11]
	v_mfma_f32_16x16x32_bf16 v[4:7], v[214:217], v[222:225], v[4:7]
	v_mfma_f32_16x16x32_bf16 v[0:3], v[214:217], v[230:233], v[0:3]
	v_mfma_f32_16x16x32_bf16 v[28:31], v[194:197], v[226:229], v[28:31]
	v_mfma_f32_16x16x32_bf16 v[24:27], v[194:197], v[234:237], v[24:27]
	v_mfma_f32_16x16x32_bf16 v[20:23], v[202:205], v[226:229], v[20:23]
	v_mfma_f32_16x16x32_bf16 v[16:19], v[202:205], v[234:237], v[16:19]
	v_mfma_f32_16x16x32_bf16 v[12:15], v[210:213], v[226:229], v[12:15]
	v_mfma_f32_16x16x32_bf16 v[8:11], v[210:213], v[234:237], v[8:11]
	v_mfma_f32_16x16x32_bf16 v[4:7], v[218:221], v[226:229], v[4:7]
	v_mfma_f32_16x16x32_bf16 v[0:3], v[218:221], v[234:237], v[0:3]
	s_setprio 1
	s_barrier
	ds_read_b128 v[156:159], v145
	ds_read_b128 v[166:169], v145 offset:1024
	ds_read_b128 v[170:173], v145 offset:2048
	ds_read_b128 v[186:189], v145 offset:3072
	v_readfirstlane_b32 s38, v132
	s_add_i32 s37, s35, 0x40100
	s_mov_b32 m0, s38
	v_readfirstlane_b32 s38, v131
	ds_read_b128 v[190:193], v143 offset:32768
	ds_read_b128 v[194:197], v143 offset:33792
	ds_read_b128 v[198:201], v142 offset:32768
	ds_read_b128 v[202:205], v142 offset:33792
	ds_read_b128 v[206:209], v141 offset:32768
	ds_read_b128 v[210:213], v141 offset:33792
	ds_read_b128 v[214:217], v140 offset:32768
	ds_read_b128 v[218:221], v140 offset:33792
	buffer_load_dwordx4 v32, s[4:7], s37 offen lds
	s_mov_b32 m0, s38
	s_nop 0
	buffer_load_dwordx4 v130, s[4:7], s37 offen lds
	s_waitcnt lgkmcnt(8)
	s_barrier
; #define STAGE(P, BASE, br, kt) do { int _so = ((br) * K + (kt) * BK) * 2; \
;     __builtin_amdgcn_raw_ptr_buffer_load_lds(rs_##BASE, (__attribute__((address_space(3))) void*)((char*)(P) + tx * 16), 16, voff0, _so, 0, 0); \
;     __builtin_amdgcn_raw_ptr_buffer_load_lds(rs_##BASE, (__attribute__((address_space(3))) void*)((char*)(P) + tx * 16 + 8192), 16, voff1, _so, 0, 0); } while (0)
; #define LDA(dst, b, h) _Pragma("unroll") for (int m = 0; m < 4; ++m) _Pragma("unroll") for (int k = 0; k < 2; ++k) \
;     dst[m][k] = *reinterpret_cast<const bf16x8*>((char*)SA(b, h) + lds_byte(wr * 64 + m * 16 + fr, k * 32 + fq * 8))
; #define LDB(dst, b, h) _Pragma("unroll") for (int n = 0; n < 2; ++n) _Pragma("unroll") for (int k = 0; k < 2; ++k) \
;     dst[n][k] = *reinterpret_cast<const bf16x8*>((char*)SB(b, h) + lds_byte(wc * 32 + n * 16 + fr, k * 32 + fq * 8))
; #define MMA(ai, bj, At, Bt_) do { __builtin_amdgcn_s_setprio(1); \
;     _Pragma("unroll") for (int m = 0; m < 4; ++m) _Pragma("unroll") for (int n = 0; n < 2; ++n) _Pragma("unroll") for (int k = 0; k < 2; ++k) \
;       acc[ai][bj][m][n] = __builtin_amdgcn_mfma_f32_16x16x32_bf16(At[m][k], Bt_[n][k], acc[ai][bj][m][n], 0, 0, 0); \
;     __builtin_amdgcn_s_setprio(0); } while (0)
; #define WAIT_V(n) asm volatile("s_waitcnt vmcnt(" #n ")" ::: "memory")
; #define WAIT_L(n) asm volatile("s_waitcnt lgkmcnt(" #n ")" ::: "memory")
; #define BAR __builtin_amdgcn_s_barrier()
; #define SCHED __builtin_amdgcn_sched_barrier(0)
; template <class Epi> ...
;     ...
;     WAIT_L(8); BAR; WAIT_L(0); MMA(0, 0, At, B0); BAR; SCHED;
;     LDB(B1, 1, 1); STAGE(SB(1, 0), Bt, bcol, t + 3);
;     BAR; WAIT_L(0); MMA(0, 1, At, B1); BAR;
;     LDA(At, 1, 1); STAGE(SA(1, 0), A, brow, t + 3);
;     BAR; WAIT_L(0); MMA(1, 0, At, B0); BAR; SCHED;
;     STAGE(SB(1, 1), Bt, bcol + HALF, t + 3);
;     WAIT_V(6); BAR; MMA(1, 1, At, B1); BAR;
;   }
	s_waitcnt lgkmcnt(0)
	s_setprio 0
	s_waitcnt lgkmcnt(7)
	v_mfma_f32_16x16x32_bf16 v[126:129], v[190:193], v[156:159], v[126:129]
	v_mfma_f32_16x16x32_bf16 v[122:125], v[190:193], v[170:173], v[122:125]
	s_waitcnt lgkmcnt(5)
	v_mfma_f32_16x16x32_bf16 v[118:121], v[198:201], v[156:159], v[118:121]
	v_mfma_f32_16x16x32_bf16 v[114:117], v[198:201], v[170:173], v[114:117]
	s_waitcnt lgkmcnt(3)
	v_mfma_f32_16x16x32_bf16 v[110:113], v[206:209], v[156:159], v[110:113]
	v_mfma_f32_16x16x32_bf16 v[106:109], v[206:209], v[170:173], v[106:109]
	s_waitcnt lgkmcnt(1)
	v_mfma_f32_16x16x32_bf16 v[102:105], v[214:217], v[156:159], v[102:105]
	v_mfma_f32_16x16x32_bf16 v[98:101], v[214:217], v[170:173], v[98:101]
	v_mfma_f32_16x16x32_bf16 v[126:129], v[194:197], v[166:169], v[126:129]
	v_mfma_f32_16x16x32_bf16 v[122:125], v[194:197], v[186:189], v[122:125]
	v_mfma_f32_16x16x32_bf16 v[118:121], v[202:205], v[166:169], v[118:121]
	v_mfma_f32_16x16x32_bf16 v[114:117], v[202:205], v[186:189], v[114:117]
	v_mfma_f32_16x16x32_bf16 v[110:113], v[210:213], v[166:169], v[110:113]
	v_mfma_f32_16x16x32_bf16 v[106:109], v[210:213], v[186:189], v[106:109]
	s_waitcnt lgkmcnt(0)
	v_mfma_f32_16x16x32_bf16 v[102:105], v[218:221], v[166:169], v[102:105]
	v_mfma_f32_16x16x32_bf16 v[98:101], v[218:221], v[186:189], v[98:101]
	s_setprio 1
	s_barrier
	v_readfirstlane_b32 s38, v146
	s_add_i32 s37, s36, 0x180
	s_mov_b32 m0, s38
	v_readfirstlane_b32 s38, v147
	ds_read_b128 v[222:225], v144
	ds_read_b128 v[226:229], v144 offset:1024
	ds_read_b128 v[230:233], v144 offset:2048
	ds_read_b128 v[234:237], v144 offset:3072
	buffer_load_dwordx4 v32, s[76:79], s37 offen lds
	s_mov_b32 m0, s38
	s_nop 0
	buffer_load_dwordx4 v130, s[76:79], s37 offen lds
	s_barrier
	s_waitcnt lgkmcnt(0)
	s_setprio 0
	s_waitcnt lgkmcnt(3)
	v_mfma_f32_16x16x32_bf16 v[94:97], v[190:193], v[222:225], v[94:97]
	s_waitcnt lgkmcnt(1)
	v_mfma_f32_16x16x32_bf16 v[90:93], v[190:193], v[230:233], v[90:93]
	v_mfma_f32_16x16x32_bf16 v[86:89], v[198:201], v[222:225], v[86:89]
	v_mfma_f32_16x16x32_bf16 v[82:85], v[198:201], v[230:233], v[82:85]
	v_mfma_f32_16x16x32_bf16 v[78:81], v[206:209], v[222:225], v[78:81]
	v_mfma_f32_16x16x32_bf16 v[74:77], v[206:209], v[230:233], v[74:77]
	v_mfma_f32_16x16x32_bf16 v[70:73], v[214:217], v[222:225], v[70:73]
	v_mfma_f32_16x16x32_bf16 v[66:69], v[214:217], v[230:233], v[66:69]
	v_mfma_f32_16x16x32_bf16 v[94:97], v[194:197], v[226:229], v[94:97]
	s_waitcnt lgkmcnt(0)
	v_mfma_f32_16x16x32_bf16 v[90:93], v[194:197], v[234:237], v[90:93]
	v_mfma_f32_16x16x32_bf16 v[86:89], v[202:205], v[226:229], v[86:89]
	v_mfma_f32_16x16x32_bf16 v[82:85], v[202:205], v[234:237], v[82:85]
	v_mfma_f32_16x16x32_bf16 v[78:81], v[210:213], v[226:229], v[78:81]
	v_mfma_f32_16x16x32_bf16 v[74:77], v[210:213], v[234:237], v[74:77]
	v_mfma_f32_16x16x32_bf16 v[70:73], v[218:221], v[226:229], v[70:73]
	v_mfma_f32_16x16x32_bf16 v[66:69], v[218:221], v[234:237], v[66:69]
	s_setprio 1
	v_readfirstlane_b32 s37, v148
	s_addk_i32 s35, 0x180
	s_mov_b32 m0, s37
	v_readfirstlane_b32 s37, v150
	s_barrier
	ds_read_b128 v[190:193], v143 offset:49152
	ds_read_b128 v[194:197], v143 offset:50176
	ds_read_b128 v[198:201], v142 offset:49152
	ds_read_b128 v[202:205], v142 offset:50176
	ds_read_b128 v[206:209], v141 offset:49152
	ds_read_b128 v[210:213], v141 offset:50176
	ds_read_b128 v[214:217], v140 offset:49152
	ds_read_b128 v[218:221], v140 offset:50176
	buffer_load_dwordx4 v32, s[4:7], s35 offen lds
	s_mov_b32 m0, s37
	s_nop 0
	buffer_load_dwordx4 v130, s[4:7], s35 offen lds
	s_barrier
	s_waitcnt lgkmcnt(0)
	s_setprio 0
	s_waitcnt lgkmcnt(7)
	v_mfma_f32_16x16x32_bf16 v[62:65], v[190:193], v[156:159], v[62:65]
	v_mfma_f32_16x16x32_bf16 v[58:61], v[190:193], v[170:173], v[58:61]
	s_waitcnt lgkmcnt(5)
	v_mfma_f32_16x16x32_bf16 v[54:57], v[198:201], v[156:159], v[54:57]
	v_mfma_f32_16x16x32_bf16 v[50:53], v[198:201], v[170:173], v[50:53]
	s_waitcnt lgkmcnt(3)
	v_mfma_f32_16x16x32_bf16 v[46:49], v[206:209], v[156:159], v[46:49]
	v_mfma_f32_16x16x32_bf16 v[42:45], v[206:209], v[170:173], v[42:45]
	s_waitcnt lgkmcnt(1)
	v_mfma_f32_16x16x32_bf16 v[38:41], v[214:217], v[156:159], v[38:41]
	v_mfma_f32_16x16x32_bf16 v[34:37], v[214:217], v[170:173], v[34:37]
	v_mfma_f32_16x16x32_bf16 v[62:65], v[194:197], v[166:169], v[62:65]
	v_mfma_f32_16x16x32_bf16 v[58:61], v[194:197], v[186:189], v[58:61]
	v_mfma_f32_16x16x32_bf16 v[54:57], v[202:205], v[166:169], v[54:57]
	v_mfma_f32_16x16x32_bf16 v[50:53], v[202:205], v[186:189], v[50:53]
	v_mfma_f32_16x16x32_bf16 v[46:49], v[210:213], v[166:169], v[46:49]
	v_mfma_f32_16x16x32_bf16 v[42:45], v[210:213], v[186:189], v[42:45]
	s_waitcnt lgkmcnt(0)
	v_mfma_f32_16x16x32_bf16 v[38:41], v[218:221], v[166:169], v[38:41]
	v_mfma_f32_16x16x32_bf16 v[34:37], v[218:221], v[186:189], v[34:37]
	s_setprio 1
	s_barrier
	v_readfirstlane_b32 s35, v153
	s_add_i32 s36, s36, 0x40180
	s_mov_b32 m0, s35
	v_readfirstlane_b32 s35, v154
	buffer_load_dwordx4 v32, s[76:79], s36 offen lds
	s_mov_b32 m0, s35
	s_nop 0
	buffer_load_dwordx4 v130, s[76:79], s36 offen lds
	s_waitcnt vmcnt(6)
	s_barrier
	s_setprio 0
	v_mfma_f32_16x16x32_bf16 v[28:31], v[190:193], v[222:225], v[28:31]
	v_mfma_f32_16x16x32_bf16 v[24:27], v[190:193], v[230:233], v[24:27]
	v_mfma_f32_16x16x32_bf16 v[20:23], v[198:201], v[222:225], v[20:23]
	v_mfma_f32_16x16x32_bf16 v[16:19], v[198:201], v[230:233], v[16:19]
	v_mfma_f32_16x16x32_bf16 v[12:15], v[206:209], v[222:225], v[12:15]
	v_mfma_f32_16x16x32_bf16 v[8:11], v[206:209], v[230:233], v[8:11]
	v_mfma_f32_16x16x32_bf16 v[4:7], v[214:217], v[222:225], v[4:7]
	v_mfma_f32_16x16x32_bf16 v[0:3], v[214:217], v[230:233], v[0:3]
	v_mfma_f32_16x16x32_bf16 v[28:31], v[194:197], v[226:229], v[28:31]
	v_mfma_f32_16x16x32_bf16 v[24:27], v[194:197], v[234:237], v[24:27]
	v_mfma_f32_16x16x32_bf16 v[20:23], v[202:205], v[226:229], v[20:23]
	v_mfma_f32_16x16x32_bf16 v[16:19], v[202:205], v[234:237], v[16:19]
	v_mfma_f32_16x16x32_bf16 v[12:15], v[210:213], v[226:229], v[12:15]
	v_mfma_f32_16x16x32_bf16 v[8:11], v[210:213], v[234:237], v[8:11]
	v_mfma_f32_16x16x32_bf16 v[4:7], v[218:221], v[226:229], v[4:7]
	v_mfma_f32_16x16x32_bf16 v[0:3], v[218:221], v[234:237], v[0:3]
	s_setprio 1
	s_add_i32 s31, s31, 2
	s_addk_i32 s34, 0x100
	s_cmp_lt_u32 s31, 12
	s_barrier
	s_cbranch_scc1 .LBB0_74
; #define STAGE(P, BASE, br, kt) do { int _so = ((br) * K + (kt) * BK) * 2; \
;     __builtin_amdgcn_raw_ptr_buffer_load_lds(rs_##BASE, (__attribute__((address_space(3))) void*)((char*)(P) + tx * 16), 16, voff0, _so, 0, 0); \
;     __builtin_amdgcn_raw_ptr_buffer_load_lds(rs_##BASE, (__attribute__((address_space(3))) void*)((char*)(P) + tx * 16 + 8192), 16, voff1, _so, 0, 0); } while (0)
; #define LDA(dst, b, h) _Pragma("unroll") for (int m = 0; m < 4; ++m) _Pragma("unroll") for (int k = 0; k < 2; ++k) \
;     dst[m][k] = *reinterpret_cast<const bf16x8*>((char*)SA(b, h) + lds_byte(wr * 64 + m * 16 + fr, k * 32 + fq * 8))
; #define LDB(dst, b, h) _Pragma("unroll") for (int n = 0; n < 2; ++n) _Pragma("unroll") for (int k = 0; k < 2; ++k) \
;     dst[n][k] = *reinterpret_cast<const bf16x8*>((char*)SB(b, h) + lds_byte(wc * 32 + n * 16 + fr, k * 32 + fq * 8))
; #define MMA(ai, bj, At, Bt_) do { __builtin_amdgcn_s_setprio(1); \
;     _Pragma("unroll") for (int m = 0; m < 4; ++m) _Pragma("unroll") for (int n = 0; n < 2; ++n) _Pragma("unroll") for (int k = 0; k < 2; ++k) \
;       acc[ai][bj][m][n] = __builtin_amdgcn_mfma_f32_16x16x32_bf16(At[m][k], Bt_[n][k], acc[ai][bj][m][n], 0, 0, 0); \
;     __builtin_amdgcn_s_setprio(0); } while (0)
; #define WAIT_V(n) asm volatile("s_waitcnt vmcnt(" #n ")" ::: "memory")
; #define WAIT_L(n) asm volatile("s_waitcnt lgkmcnt(" #n ")" ::: "memory")
; #define BAR __builtin_amdgcn_s_barrier()
; template <class Epi> ...
;     ...
;   { LDB(B0, 0, 0); LDA(At, 0, 0); STAGE(SA(1, 1), A, brow + HALF, nt - 1);
;     BAR; WAIT_L(0); MMA(0, 0, At, B0); BAR;
;     LDB(B1, 0, 1); BAR; WAIT_L(0); MMA(0, 1, At, B1); BAR;
;     LDA(At, 0, 1); WAIT_V(4); BAR; WAIT_L(0); MMA(1, 0, At, B0); MMA(1, 1, At, B1); BAR; }
.Lpx0:
	v_readfirstlane_b32 s20, v152
	s_add_i32 s21, s21, 0x40780
	s_mov_b32 s6, s78
	s_mov_b32 s7, s79
	s_mov_b32 m0, s20
	v_readfirstlane_b32 s20, v151
	ds_read_b128 v[156:159], v155
	ds_read_b128 v[166:169], v155 offset:1024
	ds_read_b128 v[170:173], v155 offset:2048
	ds_read_b128 v[186:189], v155 offset:3072
	ds_read_b128 v[190:193], v143
	ds_read_b128 v[194:197], v143 offset:1024
	ds_read_b128 v[198:201], v142
	ds_read_b128 v[202:205], v142 offset:1024
	ds_read_b128 v[206:209], v141
	ds_read_b128 v[210:213], v141 offset:1024
	ds_read_b128 v[214:217], v140
	ds_read_b128 v[218:221], v140 offset:1024
	buffer_load_dwordx4 v32, s[4:7], s21 offen lds
	s_mov_b32 m0, s20
	s_nop 0
	buffer_load_dwordx4 v130, s[4:7], s21 offen lds
	s_barrier
	s_waitcnt lgkmcnt(0)
	s_setprio 0
	s_waitcnt lgkmcnt(7)
	v_mfma_f32_16x16x32_bf16 v[126:129], v[190:193], v[156:159], v[126:129]
	v_mfma_f32_16x16x32_bf16 v[122:125], v[190:193], v[170:173], v[122:125]
	s_waitcnt lgkmcnt(5)
	v_mfma_f32_16x16x32_bf16 v[118:121], v[198:201], v[156:159], v[118:121]
	v_mfma_f32_16x16x32_bf16 v[114:117], v[198:201], v[170:173], v[114:117]
	s_waitcnt lgkmcnt(3)
	v_mfma_f32_16x16x32_bf16 v[110:113], v[206:209], v[156:159], v[110:113]
	v_mfma_f32_16x16x32_bf16 v[106:109], v[206:209], v[170:173], v[106:109]
	s_waitcnt lgkmcnt(1)
	v_mfma_f32_16x16x32_bf16 v[102:105], v[214:217], v[156:159], v[102:105]
	v_mfma_f32_16x16x32_bf16 v[98:101], v[214:217], v[170:173], v[98:101]
	v_mfma_f32_16x16x32_bf16 v[126:129], v[194:197], v[166:169], v[126:129]
	v_mfma_f32_16x16x32_bf16 v[122:125], v[194:197], v[186:189], v[122:125]
	v_mfma_f32_16x16x32_bf16 v[118:121], v[202:205], v[166:169], v[118:121]
	v_mfma_f32_16x16x32_bf16 v[114:117], v[202:205], v[186:189], v[114:117]
	v_mfma_f32_16x16x32_bf16 v[110:113], v[210:213], v[166:169], v[110:113]
	v_mfma_f32_16x16x32_bf16 v[106:109], v[210:213], v[186:189], v[106:109]
	s_waitcnt lgkmcnt(0)
	v_mfma_f32_16x16x32_bf16 v[102:105], v[218:221], v[166:169], v[102:105]
	v_mfma_f32_16x16x32_bf16 v[98:101], v[218:221], v[186:189], v[98:101]
	s_setprio 1
	s_barrier
	ds_read_b128 v[150:153], v149
	ds_read_b128 v[222:225], v149 offset:1024
	ds_read_b128 v[226:229], v149 offset:2048
	ds_read_b128 v[146:149], v149 offset:3072
	s_barrier
	s_waitcnt lgkmcnt(0)
	s_setprio 0
	s_waitcnt lgkmcnt(3)
	v_mfma_f32_16x16x32_bf16 v[78:81], v[206:209], v[150:153], v[78:81]
	s_waitcnt lgkmcnt(1)
	v_mfma_f32_16x16x32_bf16 v[74:77], v[206:209], v[226:229], v[74:77]
	v_mfma_f32_16x16x32_bf16 v[70:73], v[214:217], v[150:153], v[70:73]
	v_mfma_f32_16x16x32_bf16 v[66:69], v[214:217], v[226:229], v[66:69]
	v_mfma_f32_16x16x32_bf16 v[94:97], v[190:193], v[150:153], v[94:97]
	v_mfma_f32_16x16x32_bf16 v[90:93], v[190:193], v[226:229], v[90:93]
	v_mfma_f32_16x16x32_bf16 v[86:89], v[198:201], v[150:153], v[86:89]
	v_mfma_f32_16x16x32_bf16 v[82:85], v[198:201], v[226:229], v[82:85]
	v_mfma_f32_16x16x32_bf16 v[78:81], v[210:213], v[222:225], v[78:81]
	s_waitcnt lgkmcnt(0)
	v_mfma_f32_16x16x32_bf16 v[74:77], v[210:213], v[146:149], v[74:77]
	v_mfma_f32_16x16x32_bf16 v[70:73], v[218:221], v[222:225], v[70:73]
	v_mfma_f32_16x16x32_bf16 v[66:69], v[218:221], v[146:149], v[66:69]
	v_mfma_f32_16x16x32_bf16 v[230:233], v[194:197], v[222:225], v[94:97]
	v_mfma_f32_16x16x32_bf16 v[190:193], v[194:197], v[146:149], v[90:93]
	v_mfma_f32_16x16x32_bf16 v[194:197], v[202:205], v[222:225], v[86:89]
	v_mfma_f32_16x16x32_bf16 v[198:201], v[202:205], v[146:149], v[82:85]
	s_setprio 1
	s_barrier
	s_nop 0
	ds_read_b128 v[82:85], v143 offset:16384
	ds_read_b128 v[86:89], v143 offset:17408
	ds_read_b128 v[90:93], v142 offset:16384
	ds_read_b128 v[94:97], v142 offset:17408
	ds_read_b128 v[202:205], v141 offset:16384
	ds_read_b128 v[206:209], v141 offset:17408
	ds_read_b128 v[210:213], v140 offset:16384
	ds_read_b128 v[214:217], v140 offset:17408
	s_waitcnt vmcnt(4)
	s_barrier
	s_waitcnt lgkmcnt(0)
	s_setprio 0
	s_waitcnt lgkmcnt(3)
	v_mfma_f32_16x16x32_bf16 v[46:49], v[202:205], v[156:159], v[46:49]
	v_mfma_f32_16x16x32_bf16 v[42:45], v[202:205], v[170:173], v[42:45]
	s_waitcnt lgkmcnt(1)
	v_mfma_f32_16x16x32_bf16 v[38:41], v[210:213], v[156:159], v[38:41]
	v_mfma_f32_16x16x32_bf16 v[34:37], v[210:213], v[170:173], v[34:37]
	v_mfma_f32_16x16x32_bf16 v[62:65], v[82:85], v[156:159], v[62:65]
	v_mfma_f32_16x16x32_bf16 v[58:61], v[82:85], v[170:173], v[58:61]
	v_mfma_f32_16x16x32_bf16 v[54:57], v[90:93], v[156:159], v[54:57]
	v_mfma_f32_16x16x32_bf16 v[50:53], v[90:93], v[170:173], v[50:53]
	v_mfma_f32_16x16x32_bf16 v[46:49], v[206:209], v[166:169], v[46:49]
	v_mfma_f32_16x16x32_bf16 v[42:45], v[206:209], v[186:189], v[42:45]
	s_waitcnt lgkmcnt(0)
	v_mfma_f32_16x16x32_bf16 v[38:41], v[214:217], v[166:169], v[38:41]
	v_mfma_f32_16x16x32_bf16 v[34:37], v[214:217], v[186:189], v[34:37]
	v_mfma_f32_16x16x32_bf16 v[218:221], v[86:89], v[166:169], v[62:65]
	v_mfma_f32_16x16x32_bf16 v[234:237], v[86:89], v[186:189], v[58:61]
	v_mfma_f32_16x16x32_bf16 v[238:241], v[94:97], v[166:169], v[54:57]
	v_mfma_f32_16x16x32_bf16 v[242:245], v[94:97], v[186:189], v[50:53]
	s_setprio 1
	s_setprio 0
	v_mfma_f32_16x16x32_bf16 v[0:3], v[210:213], v[226:229], v[0:3]
	v_mfma_f32_16x16x32_bf16 v[28:31], v[82:85], v[150:153], v[28:31]
	v_mfma_f32_16x16x32_bf16 v[24:27], v[82:85], v[226:229], v[24:27]
	v_mfma_f32_16x16x32_bf16 v[20:23], v[90:93], v[150:153], v[20:23]
	v_mfma_f32_16x16x32_bf16 v[16:19], v[90:93], v[226:229], v[16:19]
	v_mfma_f32_16x16x32_bf16 v[12:15], v[202:205], v[150:153], v[12:15]
	v_mfma_f32_16x16x32_bf16 v[8:11], v[202:205], v[226:229], v[8:11]
	v_mfma_f32_16x16x32_bf16 v[4:7], v[210:213], v[150:153], v[4:7]
	v_mfma_f32_16x16x32_bf16 v[0:3], v[214:217], v[146:149], v[0:3]
	v_mfma_f32_16x16x32_bf16 v[154:157], v[86:89], v[222:225], v[28:31]
	v_mfma_f32_16x16x32_bf16 v[158:161], v[86:89], v[146:149], v[24:27]
	v_mfma_f32_16x16x32_bf16 v[166:169], v[94:97], v[222:225], v[20:23]
	v_mfma_f32_16x16x32_bf16 v[170:173], v[94:97], v[146:149], v[16:19]
	v_mfma_f32_16x16x32_bf16 v[186:189], v[206:209], v[222:225], v[12:15]
	v_mfma_f32_16x16x32_bf16 v[202:205], v[206:209], v[146:149], v[8:11]
	v_mfma_f32_16x16x32_bf16 v[150:153], v[214:217], v[222:225], v[4:7]
	s_setprio 1
	s_barrier
; #define LDA(dst, b, h) _Pragma("unroll") for (int m = 0; m < 4; ++m) _Pragma("unroll") for (int k = 0; k < 2; ++k) \
;     dst[m][k] = *reinterpret_cast<const bf16x8*>((char*)SA(b, h) + lds_byte(wr * 64 + m * 16 + fr, k * 32 + fq * 8))
; #define LDB(dst, b, h) _Pragma("unroll") for (int n = 0; n < 2; ++n) _Pragma("unroll") for (int k = 0; k < 2; ++k) \
;     dst[n][k] = *reinterpret_cast<const bf16x8*>((char*)SB(b, h) + lds_byte(wc * 32 + n * 16 + fr, k * 32 + fq * 8))
; #define MMA(ai, bj, At, Bt_) do { __builtin_amdgcn_s_setprio(1); \
;     _Pragma("unroll") for (int m = 0; m < 4; ++m) _Pragma("unroll") for (int n = 0; n < 2; ++n) _Pragma("unroll") for (int k = 0; k < 2; ++k) \
;       acc[ai][bj][m][n] = __builtin_amdgcn_mfma_f32_16x16x32_bf16(At[m][k], Bt_[n][k], acc[ai][bj][m][n], 0, 0, 0); \
;     __builtin_amdgcn_s_setprio(0); } while (0)
; #define WAIT_V(n) asm volatile("s_waitcnt vmcnt(" #n ")" ::: "memory")
; #define WAIT_L(n) asm volatile("s_waitcnt lgkmcnt(" #n ")" ::: "memory")
; #define BAR __builtin_amdgcn_s_barrier()
; template <class Epi> ...
;     ...
;   { LDB(B0, 1, 0); LDA(At, 1, 0); WAIT_V(2); BAR; WAIT_L(0); MMA(0, 0, At, B0); BAR;
;     LDB(B1, 1, 1); WAIT_V(0); BAR; WAIT_L(0); MMA(0, 1, At, B1); BAR;
;     LDA(At, 1, 1); BAR; WAIT_L(0); MMA(1, 0, At, B0); MMA(1, 1, At, B1); BAR; }
;   if (wr == 0) BAR;
	s_nop 0
	ds_read_b128 v[4:7], v145
	ds_read_b128 v[8:11], v145 offset:1024
	ds_read_b128 v[12:15], v145 offset:2048
	ds_read_b128 v[146:149], v145 offset:3072
	ds_read_b128 v[16:19], v143 offset:32768
	ds_read_b128 v[20:23], v143 offset:33792
	ds_read_b128 v[24:27], v142 offset:32768
	ds_read_b128 v[50:53], v142 offset:33792
	ds_read_b128 v[206:209], v141 offset:32768
	ds_read_b128 v[210:213], v141 offset:33792
	ds_read_b128 v[214:217], v140 offset:32768
	ds_read_b128 v[222:225], v140 offset:33792
	s_waitcnt vmcnt(2)
	s_barrier
	s_waitcnt lgkmcnt(0)
	s_setprio 0
	s_waitcnt lgkmcnt(7)
	v_mfma_f32_16x16x32_bf16 v[28:31], v[16:19], v[4:7], v[126:129]
	s_waitcnt lgkmcnt(6)
	v_mfma_f32_16x16x32_bf16 v[126:129], v[20:23], v[8:11], v[28:31]
	v_mfma_f32_16x16x32_bf16 v[28:31], v[16:19], v[12:15], v[122:125]
	v_mfma_f32_16x16x32_bf16 v[94:97], v[20:23], v[146:149], v[28:31]
	s_waitcnt lgkmcnt(5)
	v_mfma_f32_16x16x32_bf16 v[28:31], v[24:27], v[4:7], v[118:121]
	s_waitcnt lgkmcnt(4)
	v_mfma_f32_16x16x32_bf16 v[122:125], v[50:53], v[8:11], v[28:31]
	v_mfma_f32_16x16x32_bf16 v[28:31], v[24:27], v[12:15], v[114:117]
	v_mfma_f32_16x16x32_bf16 v[90:93], v[50:53], v[146:149], v[28:31]
	s_waitcnt lgkmcnt(3)
	v_mfma_f32_16x16x32_bf16 v[28:31], v[206:209], v[4:7], v[110:113]
	s_waitcnt lgkmcnt(2)
	v_mfma_f32_16x16x32_bf16 v[118:121], v[210:213], v[8:11], v[28:31]
	v_mfma_f32_16x16x32_bf16 v[28:31], v[206:209], v[12:15], v[106:109]
	v_mfma_f32_16x16x32_bf16 v[86:89], v[210:213], v[146:149], v[28:31]
	s_waitcnt lgkmcnt(1)
	v_mfma_f32_16x16x32_bf16 v[28:31], v[214:217], v[4:7], v[102:105]
	s_waitcnt lgkmcnt(0)
	v_mfma_f32_16x16x32_bf16 v[114:117], v[222:225], v[8:11], v[28:31]
	v_mfma_f32_16x16x32_bf16 v[28:31], v[214:217], v[12:15], v[98:101]
	v_mfma_f32_16x16x32_bf16 v[82:85], v[222:225], v[146:149], v[28:31]
	s_setprio 1
	s_barrier
	ds_read_b128 v[226:229], v144
	ds_read_b128 v[246:249], v144 offset:1024
	ds_read_b128 v[250:253], v144 offset:2048
	ds_read_b128 v[174:177], v144 offset:3072
	s_waitcnt vmcnt(0)
	s_barrier
	s_waitcnt lgkmcnt(0)
	s_setprio 0
	s_waitcnt lgkmcnt(3)
	v_mfma_f32_16x16x32_bf16 v[28:31], v[16:19], v[226:229], v[230:233]
	s_waitcnt lgkmcnt(1)
	v_mfma_f32_16x16x32_bf16 v[16:19], v[16:19], v[250:253], v[190:193]
	v_mfma_f32_16x16x32_bf16 v[62:65], v[20:23], v[246:249], v[28:31]
	s_waitcnt lgkmcnt(0)
	v_mfma_f32_16x16x32_bf16 v[28:31], v[20:23], v[174:177], v[16:19]
	v_mfma_f32_16x16x32_bf16 v[16:19], v[24:27], v[226:229], v[194:197]
	v_mfma_f32_16x16x32_bf16 v[58:61], v[50:53], v[246:249], v[16:19]
	v_mfma_f32_16x16x32_bf16 v[16:19], v[24:27], v[250:253], v[198:201]
	v_mfma_f32_16x16x32_bf16 v[24:27], v[50:53], v[174:177], v[16:19]
	v_mfma_f32_16x16x32_bf16 v[16:19], v[206:209], v[226:229], v[78:81]
	v_mfma_f32_16x16x32_bf16 v[54:57], v[210:213], v[246:249], v[16:19]
	v_mfma_f32_16x16x32_bf16 v[16:19], v[206:209], v[250:253], v[74:77]
	v_mfma_f32_16x16x32_bf16 v[20:23], v[210:213], v[174:177], v[16:19]
	v_mfma_f32_16x16x32_bf16 v[16:19], v[214:217], v[226:229], v[70:73]
	v_mfma_f32_16x16x32_bf16 v[50:53], v[222:225], v[246:249], v[16:19]
	v_mfma_f32_16x16x32_bf16 v[16:19], v[214:217], v[250:253], v[66:69]
	v_mfma_f32_16x16x32_bf16 v[16:19], v[222:225], v[174:177], v[16:19]
	s_setprio 1
	s_barrier
	ds_read_b128 v[190:193], v143 offset:49152
	ds_read_b128 v[194:197], v143 offset:50176
	ds_read_b128 v[198:201], v142 offset:49152
	ds_read_b128 v[142:145], v142 offset:50176
	ds_read_b128 v[206:209], v141 offset:49152
	ds_read_b128 v[210:213], v141 offset:50176
	ds_read_b128 v[214:217], v140 offset:49152
	ds_read_b128 v[222:225], v140 offset:50176
	s_barrier
	s_waitcnt lgkmcnt(0)
	s_setprio 0
	s_waitcnt lgkmcnt(7)
	v_mfma_f32_16x16x32_bf16 v[66:69], v[190:193], v[4:7], v[218:221]
	s_waitcnt lgkmcnt(6)
	v_mfma_f32_16x16x32_bf16 v[110:113], v[194:197], v[8:11], v[66:69]
	v_mfma_f32_16x16x32_bf16 v[66:69], v[190:193], v[12:15], v[234:237]
	v_mfma_f32_16x16x32_bf16 v[78:81], v[194:197], v[146:149], v[66:69]
	s_waitcnt lgkmcnt(5)
	v_mfma_f32_16x16x32_bf16 v[66:69], v[198:201], v[4:7], v[238:241]
	s_waitcnt lgkmcnt(3)
	v_mfma_f32_16x16x32_bf16 v[46:49], v[206:209], v[4:7], v[46:49]
	s_waitcnt lgkmcnt(1)
	v_mfma_f32_16x16x32_bf16 v[4:7], v[214:217], v[4:7], v[38:41]
	v_mfma_f32_16x16x32_bf16 v[106:109], v[142:145], v[8:11], v[66:69]
	v_mfma_f32_16x16x32_bf16 v[66:69], v[198:201], v[12:15], v[242:245]
	v_mfma_f32_16x16x32_bf16 v[42:45], v[206:209], v[12:15], v[42:45]
	s_waitcnt lgkmcnt(0)
	v_mfma_f32_16x16x32_bf16 v[98:101], v[222:225], v[8:11], v[4:7]
	v_mfma_f32_16x16x32_bf16 v[4:7], v[214:217], v[12:15], v[34:37]
	v_mfma_f32_16x16x32_bf16 v[74:77], v[142:145], v[146:149], v[66:69]
	v_mfma_f32_16x16x32_bf16 v[102:105], v[210:213], v[8:11], v[46:49]
	v_mfma_f32_16x16x32_bf16 v[70:73], v[210:213], v[146:149], v[42:45]
	v_mfma_f32_16x16x32_bf16 v[66:69], v[222:225], v[146:149], v[4:7]
	s_setprio 1
	s_setprio 0
	v_mfma_f32_16x16x32_bf16 v[4:7], v[190:193], v[226:229], v[154:157]
	v_mfma_f32_16x16x32_bf16 v[46:49], v[194:197], v[246:249], v[4:7]
	v_mfma_f32_16x16x32_bf16 v[4:7], v[190:193], v[250:253], v[158:161]
	v_mfma_f32_16x16x32_bf16 v[12:15], v[194:197], v[174:177], v[4:7]
	v_mfma_f32_16x16x32_bf16 v[4:7], v[198:201], v[226:229], v[166:169]
	v_mfma_f32_16x16x32_bf16 v[42:45], v[142:145], v[246:249], v[4:7]
	v_mfma_f32_16x16x32_bf16 v[4:7], v[198:201], v[250:253], v[170:173]
	v_mfma_f32_16x16x32_bf16 v[8:11], v[142:145], v[174:177], v[4:7]
	v_mfma_f32_16x16x32_bf16 v[4:7], v[206:209], v[226:229], v[186:189]
	v_mfma_f32_16x16x32_bf16 v[38:41], v[210:213], v[246:249], v[4:7]
	v_mfma_f32_16x16x32_bf16 v[4:7], v[206:209], v[250:253], v[202:205]
	v_mfma_f32_16x16x32_bf16 v[34:37], v[214:217], v[226:229], v[150:153]
	v_mfma_f32_16x16x32_bf16 v[0:3], v[214:217], v[250:253], v[0:3]
	v_mfma_f32_16x16x32_bf16 v[4:7], v[210:213], v[174:177], v[4:7]
	v_mfma_f32_16x16x32_bf16 v[34:37], v[222:225], v[246:249], v[34:37]
	v_mfma_f32_16x16x32_bf16 v[0:3], v[222:225], v[174:177], v[0:3]
	s_setprio 1
	v_cmp_gt_u32_e32 vcc, s59, v133
	s_barrier
	s_and_saveexec_b64 s[4:5], vcc
	s_cbranch_execz .LBB0_77
	s_barrier

; #define STAGE(P, BASE, br, kt) do { int _so = ((br) * K + (kt) * BK) * 2; \
;     __builtin_amdgcn_raw_ptr_buffer_load_lds(rs_##BASE, (__attribute__((address_space(3))) void*)((char*)(P) + tx * 16), 16, voff0, _so, 0, 0); \
;     __builtin_amdgcn_raw_ptr_buffer_load_lds(rs_##BASE, (__attribute__((address_space(3))) void*)((char*)(P) + tx * 16 + 8192), 16, voff1, _so, 0, 0); } while (0)
; #define LDA(dst, b, h) _Pragma("unroll") for (int m = 0; m < 4; ++m) _Pragma("unroll") for (int k = 0; k < 2; ++k) \
;     dst[m][k] = *reinterpret_cast<const bf16x8*>((char*)SA(b, h) + lds_byte(wr * 64 + m * 16 + fr, k * 32 + fq * 8))
; #define LDB(dst, b, h) _Pragma("unroll") for (int n = 0; n < 2; ++n) _Pragma("unroll") for (int k = 0; k < 2; ++k) \
;     dst[n][k] = *reinterpret_cast<const bf16x8*>((char*)SB(b, h) + lds_byte(wc * 32 + n * 16 + fr, k * 32 + fq * 8))
; #define MMA(ai, bj, At, Bt_) do { __builtin_amdgcn_s_setprio(1); \
;     _Pragma("unroll") for (int m = 0; m < 4; ++m) _Pragma("unroll") for (int n = 0; n < 2; ++n) _Pragma("unroll") for (int k = 0; k < 2; ++k) \
;       acc[ai][bj][m][n] = __builtin_amdgcn_mfma_f32_16x16x32_bf16(At[m][k], Bt_[n][k], acc[ai][bj][m][n], 0, 0, 0); \
;     __builtin_amdgcn_s_setprio(0); } while (0)
; #define WAIT_V(n) asm volatile("s_waitcnt vmcnt(" #n ")" ::: "memory")
; #define WAIT_L(n) asm volatile("s_waitcnt lgkmcnt(" #n ")" ::: "memory")
; #define BAR __builtin_amdgcn_s_barrier()
; template <class Epi> ...
;     ...
;   { LDB(B0, 0, 0); LDA(At, 0, 0); STAGE(SA(1, 1), A, brow + HALF, nt - 1);
;     BAR; WAIT_L(0); MMA(0, 0, At, B0); BAR;
;     LDB(B1, 0, 1); BAR; WAIT_L(0); MMA(0, 1, At, B1); BAR;
;     LDA(At, 0, 1); WAIT_V(4); BAR; WAIT_L(0); MMA(1, 0, At, B0); MMA(1, 1, At, B1); BAR; }
.Lpx1:
	v_readfirstlane_b32 s20, v152
	s_add_i32 s21, s21, 0x40780
	s_mov_b32 s6, s78
	s_mov_b32 s7, s79
	s_mov_b32 m0, s20
	v_readfirstlane_b32 s20, v151
	ds_read_b128 v[156:159], v155
	ds_read_b128 v[166:169], v155 offset:1024
	ds_read_b128 v[170:173], v155 offset:2048
	ds_read_b128 v[186:189], v155 offset:3072
	ds_read_b128 v[190:193], v143
	ds_read_b128 v[194:197], v143 offset:1024
	ds_read_b128 v[198:201], v142
	ds_read_b128 v[202:205], v142 offset:1024
	ds_read_b128 v[206:209], v141
	ds_read_b128 v[210:213], v141 offset:1024
	ds_read_b128 v[214:217], v140
	ds_read_b128 v[218:221], v140 offset:1024
	buffer_load_dwordx4 v32, s[4:7], s21 offen lds
	s_mov_b32 m0, s20
	s_nop 0
	buffer_load_dwordx4 v130, s[4:7], s21 offen lds
	s_barrier
	s_waitcnt lgkmcnt(0)
	s_setprio 0
	s_waitcnt lgkmcnt(7)
	v_mfma_f32_16x16x32_bf16 v[126:129], v[190:193], v[156:159], v[126:129]
	v_mfma_f32_16x16x32_bf16 v[122:125], v[190:193], v[170:173], v[122:125]
	s_waitcnt lgkmcnt(5)
	v_mfma_f32_16x16x32_bf16 v[114:117], v[198:201], v[170:173], v[114:117]
	s_waitcnt lgkmcnt(3)
	v_mfma_f32_16x16x32_bf16 v[106:109], v[206:209], v[170:173], v[106:109]
	s_waitcnt lgkmcnt(1)
	v_mfma_f32_16x16x32_bf16 v[102:105], v[214:217], v[156:159], v[102:105]
	v_mfma_f32_16x16x32_bf16 v[126:129], v[194:197], v[166:169], v[126:129]
	v_mfma_f32_16x16x32_bf16 v[122:125], v[194:197], v[186:189], v[122:125]
	v_mfma_f32_16x16x32_bf16 v[118:121], v[198:201], v[156:159], v[118:121]
	v_mfma_f32_16x16x32_bf16 v[114:117], v[202:205], v[186:189], v[114:117]
	v_mfma_f32_16x16x32_bf16 v[110:113], v[206:209], v[156:159], v[110:113]
	v_mfma_f32_16x16x32_bf16 v[106:109], v[210:213], v[186:189], v[106:109]
	s_waitcnt lgkmcnt(0)
	v_mfma_f32_16x16x32_bf16 v[102:105], v[218:221], v[166:169], v[102:105]
	v_mfma_f32_16x16x32_bf16 v[98:101], v[214:217], v[170:173], v[98:101]
	v_mfma_f32_16x16x32_bf16 v[150:153], v[202:205], v[166:169], v[118:121]
	v_mfma_f32_16x16x32_bf16 v[222:225], v[210:213], v[166:169], v[110:113]
	v_mfma_f32_16x16x32_bf16 v[226:229], v[218:221], v[186:189], v[98:101]
	s_setprio 1
	s_barrier
	s_nop 2
	ds_read_b128 v[98:101], v149
	ds_read_b128 v[110:113], v149 offset:1024
	ds_read_b128 v[118:121], v149 offset:2048
	ds_read_b128 v[146:149], v149 offset:3072
	s_barrier
	s_waitcnt lgkmcnt(0)
	s_setprio 0
	s_waitcnt lgkmcnt(1)
	v_mfma_f32_16x16x32_bf16 v[90:93], v[190:193], v[118:121], v[90:93]
	v_mfma_f32_16x16x32_bf16 v[86:89], v[198:201], v[98:101], v[86:89]
	v_mfma_f32_16x16x32_bf16 v[74:77], v[206:209], v[118:121], v[74:77]
	v_mfma_f32_16x16x32_bf16 v[70:73], v[214:217], v[98:101], v[70:73]
	v_mfma_f32_16x16x32_bf16 v[94:97], v[190:193], v[98:101], v[94:97]
	s_waitcnt lgkmcnt(0)
	v_mfma_f32_16x16x32_bf16 v[90:93], v[194:197], v[146:149], v[90:93]
	v_mfma_f32_16x16x32_bf16 v[86:89], v[202:205], v[110:113], v[86:89]
	v_mfma_f32_16x16x32_bf16 v[82:85], v[198:201], v[118:121], v[82:85]
	v_mfma_f32_16x16x32_bf16 v[78:81], v[206:209], v[98:101], v[78:81]
	v_mfma_f32_16x16x32_bf16 v[74:77], v[210:213], v[146:149], v[74:77]
	v_mfma_f32_16x16x32_bf16 v[70:73], v[218:221], v[110:113], v[70:73]
	v_mfma_f32_16x16x32_bf16 v[66:69], v[214:217], v[118:121], v[66:69]
	v_mfma_f32_16x16x32_bf16 v[230:233], v[194:197], v[110:113], v[94:97]
	v_mfma_f32_16x16x32_bf16 v[190:193], v[202:205], v[146:149], v[82:85]
	v_mfma_f32_16x16x32_bf16 v[194:197], v[210:213], v[110:113], v[78:81]
	v_mfma_f32_16x16x32_bf16 v[198:201], v[218:221], v[146:149], v[66:69]
	s_setprio 1
	s_barrier
	s_nop 1
	ds_read_b128 v[66:69], v143 offset:16384
	ds_read_b128 v[78:81], v143 offset:17408
	ds_read_b128 v[82:85], v142 offset:16384
	ds_read_b128 v[94:97], v142 offset:17408
	ds_read_b128 v[202:205], v141 offset:16384
	ds_read_b128 v[206:209], v141 offset:17408
	ds_read_b128 v[210:213], v140 offset:16384
	ds_read_b128 v[214:217], v140 offset:17408
	s_waitcnt vmcnt(4)
	s_barrier
	s_waitcnt lgkmcnt(0)
	s_setprio 0
	s_waitcnt lgkmcnt(7)
	v_mfma_f32_16x16x32_bf16 v[62:65], v[66:69], v[156:159], v[62:65]
	v_mfma_f32_16x16x32_bf16 v[58:61], v[66:69], v[170:173], v[58:61]
	s_waitcnt lgkmcnt(5)
	v_mfma_f32_16x16x32_bf16 v[54:57], v[82:85], v[156:159], v[54:57]
	v_mfma_f32_16x16x32_bf16 v[50:53], v[82:85], v[170:173], v[50:53]
	s_waitcnt lgkmcnt(3)
	v_mfma_f32_16x16x32_bf16 v[42:45], v[202:205], v[170:173], v[42:45]
	s_waitcnt lgkmcnt(1)
	v_mfma_f32_16x16x32_bf16 v[34:37], v[210:213], v[170:173], v[34:37]
	v_mfma_f32_16x16x32_bf16 v[62:65], v[78:81], v[166:169], v[62:65]
	v_mfma_f32_16x16x32_bf16 v[58:61], v[78:81], v[186:189], v[58:61]
	v_mfma_f32_16x16x32_bf16 v[54:57], v[94:97], v[166:169], v[54:57]
	v_mfma_f32_16x16x32_bf16 v[50:53], v[94:97], v[186:189], v[50:53]
	v_mfma_f32_16x16x32_bf16 v[46:49], v[202:205], v[156:159], v[46:49]
	v_mfma_f32_16x16x32_bf16 v[42:45], v[206:209], v[186:189], v[42:45]
	v_mfma_f32_16x16x32_bf16 v[38:41], v[210:213], v[156:159], v[38:41]
	s_waitcnt lgkmcnt(0)
	v_mfma_f32_16x16x32_bf16 v[34:37], v[214:217], v[186:189], v[34:37]
	v_mfma_f32_16x16x32_bf16 v[218:221], v[206:209], v[166:169], v[46:49]
	v_mfma_f32_16x16x32_bf16 v[154:157], v[214:217], v[166:169], v[38:41]
	s_setprio 1
	s_setprio 0
	v_mfma_f32_16x16x32_bf16 v[24:27], v[66:69], v[118:121], v[24:27]
	v_mfma_f32_16x16x32_bf16 v[16:19], v[82:85], v[118:121], v[16:19]
	v_mfma_f32_16x16x32_bf16 v[8:11], v[202:205], v[118:121], v[8:11]
	v_mfma_f32_16x16x32_bf16 v[0:3], v[210:213], v[118:121], v[0:3]
	v_mfma_f32_16x16x32_bf16 v[28:31], v[66:69], v[98:101], v[28:31]
	v_mfma_f32_16x16x32_bf16 v[24:27], v[78:81], v[146:149], v[24:27]
	v_mfma_f32_16x16x32_bf16 v[20:23], v[82:85], v[98:101], v[20:23]
	v_mfma_f32_16x16x32_bf16 v[16:19], v[94:97], v[146:149], v[16:19]
	v_mfma_f32_16x16x32_bf16 v[12:15], v[202:205], v[98:101], v[12:15]
	v_mfma_f32_16x16x32_bf16 v[8:11], v[206:209], v[146:149], v[8:11]
	v_mfma_f32_16x16x32_bf16 v[4:7], v[210:213], v[98:101], v[4:7]
	v_mfma_f32_16x16x32_bf16 v[0:3], v[214:217], v[146:149], v[0:3]
	v_mfma_f32_16x16x32_bf16 v[158:161], v[78:81], v[110:113], v[28:31]
	v_mfma_f32_16x16x32_bf16 v[166:169], v[94:97], v[110:113], v[20:23]
	v_mfma_f32_16x16x32_bf16 v[170:173], v[206:209], v[110:113], v[12:15]
	v_mfma_f32_16x16x32_bf16 v[186:189], v[214:217], v[110:113], v[4:7]
	s_setprio 1
	s_barrier
; #define LDA(dst, b, h) _Pragma("unroll") for (int m = 0; m < 4; ++m) _Pragma("unroll") for (int k = 0; k < 2; ++k) \
;     dst[m][k] = *reinterpret_cast<const bf16x8*>((char*)SA(b, h) + lds_byte(wr * 64 + m * 16 + fr, k * 32 + fq * 8))
; #define LDB(dst, b, h) _Pragma("unroll") for (int n = 0; n < 2; ++n) _Pragma("unroll") for (int k = 0; k < 2; ++k) \
;     dst[n][k] = *reinterpret_cast<const bf16x8*>((char*)SB(b, h) + lds_byte(wc * 32 + n * 16 + fr, k * 32 + fq * 8))
; #define MMA(ai, bj, At, Bt_) do { __builtin_amdgcn_s_setprio(1); \
;     _Pragma("unroll") for (int m = 0; m < 4; ++m) _Pragma("unroll") for (int n = 0; n < 2; ++n) _Pragma("unroll") for (int k = 0; k < 2; ++k) \
;       acc[ai][bj][m][n] = __builtin_amdgcn_mfma_f32_16x16x32_bf16(At[m][k], Bt_[n][k], acc[ai][bj][m][n], 0, 0, 0); \
;     __builtin_amdgcn_s_setprio(0); } while (0)
; #define WAIT_V(n) asm volatile("s_waitcnt vmcnt(" #n ")" ::: "memory")
; #define WAIT_L(n) asm volatile("s_waitcnt lgkmcnt(" #n ")" ::: "memory")
; #define BAR __builtin_amdgcn_s_barrier()
; template <class Epi> ...
;     ...
;   { LDB(B0, 1, 0); LDA(At, 1, 0); WAIT_V(2); BAR; WAIT_L(0); MMA(0, 0, At, B0); BAR;
;     LDB(B1, 1, 1); WAIT_V(0); BAR; WAIT_L(0); MMA(0, 1, At, B1); BAR;
;     LDA(At, 1, 1); BAR; WAIT_L(0); MMA(1, 0, At, B0); MMA(1, 1, At, B1); BAR; }
;   if (wr == 0) BAR;
	s_nop 0
	ds_read_b128 v[4:7], v145
	ds_read_b128 v[12:15], v145 offset:1024
	ds_read_b128 v[146:149], v145 offset:2048
	ds_read_b128 v[202:205], v145 offset:3072
	ds_read_b128 v[20:23], v143 offset:32768
	ds_read_b128 v[28:31], v143 offset:33792
	ds_read_b128 v[38:41], v142 offset:32768
	ds_read_b128 v[46:49], v142 offset:33792
	ds_read_b128 v[206:209], v141 offset:32768
	ds_read_b128 v[210:213], v141 offset:33792
	ds_read_b128 v[214:217], v140 offset:32768
	ds_read_b128 v[234:237], v140 offset:33792
	s_waitcnt vmcnt(2)
	s_barrier
	s_waitcnt lgkmcnt(0)
	s_setprio 0
	s_waitcnt lgkmcnt(7)
	v_mfma_f32_16x16x32_bf16 v[66:69], v[20:23], v[4:7], v[126:129]
	s_waitcnt lgkmcnt(6)
	v_mfma_f32_16x16x32_bf16 v[126:129], v[28:31], v[12:15], v[66:69]
	v_mfma_f32_16x16x32_bf16 v[66:69], v[20:23], v[146:149], v[122:125]
	v_mfma_f32_16x16x32_bf16 v[118:121], v[28:31], v[202:205], v[66:69]
	s_waitcnt lgkmcnt(5)
	v_mfma_f32_16x16x32_bf16 v[66:69], v[38:41], v[4:7], v[150:153]
	s_waitcnt lgkmcnt(4)
	v_mfma_f32_16x16x32_bf16 v[110:113], v[46:49], v[12:15], v[66:69]
	v_mfma_f32_16x16x32_bf16 v[66:69], v[38:41], v[146:149], v[114:117]
	v_mfma_f32_16x16x32_bf16 v[98:101], v[46:49], v[202:205], v[66:69]
	s_waitcnt lgkmcnt(3)
	v_mfma_f32_16x16x32_bf16 v[66:69], v[206:209], v[4:7], v[222:225]
	s_waitcnt lgkmcnt(2)
	v_mfma_f32_16x16x32_bf16 v[94:97], v[210:213], v[12:15], v[66:69]
	v_mfma_f32_16x16x32_bf16 v[66:69], v[206:209], v[146:149], v[106:109]
	v_mfma_f32_16x16x32_bf16 v[82:85], v[210:213], v[202:205], v[66:69]
	s_waitcnt lgkmcnt(1)
	v_mfma_f32_16x16x32_bf16 v[66:69], v[214:217], v[4:7], v[102:105]
	s_waitcnt lgkmcnt(0)
	v_mfma_f32_16x16x32_bf16 v[78:81], v[234:237], v[12:15], v[66:69]
	v_mfma_f32_16x16x32_bf16 v[66:69], v[214:217], v[146:149], v[226:229]
	v_mfma_f32_16x16x32_bf16 v[66:69], v[234:237], v[202:205], v[66:69]
	s_setprio 1
	s_barrier
	ds_read_b128 v[150:153], v144
	ds_read_b128 v[222:225], v144 offset:1024
	ds_read_b128 v[226:229], v144 offset:2048
	ds_read_b128 v[238:241], v144 offset:3072
	s_waitcnt vmcnt(0)
	s_barrier
	s_waitcnt lgkmcnt(0)
	s_setprio 0
	s_waitcnt lgkmcnt(3)
	v_mfma_f32_16x16x32_bf16 v[102:105], v[20:23], v[150:153], v[230:233]
	s_waitcnt lgkmcnt(1)
	v_mfma_f32_16x16x32_bf16 v[20:23], v[20:23], v[226:229], v[90:93]
	s_waitcnt lgkmcnt(0)
	v_mfma_f32_16x16x32_bf16 v[114:117], v[28:31], v[238:241], v[20:23]
	v_mfma_f32_16x16x32_bf16 v[20:23], v[38:41], v[150:153], v[86:89]
	v_mfma_f32_16x16x32_bf16 v[106:109], v[46:49], v[222:225], v[20:23]
	v_mfma_f32_16x16x32_bf16 v[20:23], v[38:41], v[226:229], v[190:193]
	v_mfma_f32_16x16x32_bf16 v[122:125], v[28:31], v[222:225], v[102:105]
	v_mfma_f32_16x16x32_bf16 v[102:105], v[46:49], v[238:241], v[20:23]
	v_mfma_f32_16x16x32_bf16 v[20:23], v[206:209], v[150:153], v[194:197]
	v_mfma_f32_16x16x32_bf16 v[90:93], v[210:213], v[222:225], v[20:23]
	v_mfma_f32_16x16x32_bf16 v[20:23], v[206:209], v[226:229], v[74:77]
	v_mfma_f32_16x16x32_bf16 v[86:89], v[210:213], v[238:241], v[20:23]
	v_mfma_f32_16x16x32_bf16 v[20:23], v[214:217], v[150:153], v[70:73]
	v_mfma_f32_16x16x32_bf16 v[74:77], v[234:237], v[222:225], v[20:23]
	v_mfma_f32_16x16x32_bf16 v[20:23], v[214:217], v[226:229], v[198:201]
	v_mfma_f32_16x16x32_bf16 v[70:73], v[234:237], v[238:241], v[20:23]
	s_setprio 1
	s_barrier
	ds_read_b128 v[190:193], v143 offset:49152
	ds_read_b128 v[194:197], v143 offset:50176
	ds_read_b128 v[198:201], v142 offset:49152
	ds_read_b128 v[142:145], v142 offset:50176
	ds_read_b128 v[206:209], v141 offset:49152
	ds_read_b128 v[210:213], v141 offset:50176
	ds_read_b128 v[214:217], v140 offset:49152
	ds_read_b128 v[230:233], v140 offset:50176
	s_barrier
	s_waitcnt lgkmcnt(0)
	s_setprio 0
	s_waitcnt lgkmcnt(7)
	v_mfma_f32_16x16x32_bf16 v[20:23], v[190:193], v[4:7], v[62:65]
	s_waitcnt lgkmcnt(6)
	v_mfma_f32_16x16x32_bf16 v[62:65], v[194:197], v[12:15], v[20:23]
	v_mfma_f32_16x16x32_bf16 v[20:23], v[190:193], v[146:149], v[58:61]
	v_mfma_f32_16x16x32_bf16 v[58:61], v[194:197], v[202:205], v[20:23]
	s_waitcnt lgkmcnt(5)
	v_mfma_f32_16x16x32_bf16 v[20:23], v[198:201], v[4:7], v[54:57]
	s_waitcnt lgkmcnt(4)
	v_mfma_f32_16x16x32_bf16 v[46:49], v[142:145], v[12:15], v[20:23]
	v_mfma_f32_16x16x32_bf16 v[20:23], v[198:201], v[146:149], v[50:53]
	v_mfma_f32_16x16x32_bf16 v[38:41], v[142:145], v[202:205], v[20:23]
	s_waitcnt lgkmcnt(3)
	v_mfma_f32_16x16x32_bf16 v[20:23], v[206:209], v[4:7], v[218:221]
	s_waitcnt lgkmcnt(1)
	v_mfma_f32_16x16x32_bf16 v[4:7], v[214:217], v[4:7], v[154:157]
	v_mfma_f32_16x16x32_bf16 v[28:31], v[210:213], v[12:15], v[20:23]
	v_mfma_f32_16x16x32_bf16 v[20:23], v[206:209], v[146:149], v[42:45]
	s_waitcnt lgkmcnt(0)
	v_mfma_f32_16x16x32_bf16 v[12:15], v[230:233], v[12:15], v[4:7]
	v_mfma_f32_16x16x32_bf16 v[4:7], v[214:217], v[146:149], v[34:37]
	v_mfma_f32_16x16x32_bf16 v[20:23], v[210:213], v[202:205], v[20:23]
	v_mfma_f32_16x16x32_bf16 v[4:7], v[230:233], v[202:205], v[4:7]
	s_setprio 1
	s_setprio 0
	v_mfma_f32_16x16x32_bf16 v[34:37], v[190:193], v[150:153], v[158:161]
	v_mfma_f32_16x16x32_bf16 v[24:27], v[190:193], v[226:229], v[24:27]
	v_mfma_f32_16x16x32_bf16 v[16:19], v[198:201], v[226:229], v[16:19]
	v_mfma_f32_16x16x32_bf16 v[54:57], v[194:197], v[222:225], v[34:37]
	v_mfma_f32_16x16x32_bf16 v[50:53], v[194:197], v[238:241], v[24:27]
	v_mfma_f32_16x16x32_bf16 v[24:27], v[198:201], v[150:153], v[166:169]
	v_mfma_f32_16x16x32_bf16 v[34:37], v[142:145], v[238:241], v[16:19]
	v_mfma_f32_16x16x32_bf16 v[16:19], v[206:209], v[150:153], v[170:173]
	v_mfma_f32_16x16x32_bf16 v[8:11], v[206:209], v[226:229], v[8:11]
	v_mfma_f32_16x16x32_bf16 v[42:45], v[142:145], v[222:225], v[24:27]
	v_mfma_f32_16x16x32_bf16 v[24:27], v[210:213], v[222:225], v[16:19]
	v_mfma_f32_16x16x32_bf16 v[16:19], v[210:213], v[238:241], v[8:11]
	v_mfma_f32_16x16x32_bf16 v[8:11], v[214:217], v[150:153], v[186:189]
	v_mfma_f32_16x16x32_bf16 v[0:3], v[214:217], v[226:229], v[0:3]
	v_mfma_f32_16x16x32_bf16 v[8:11], v[230:233], v[222:225], v[8:11]
	v_mfma_f32_16x16x32_bf16 v[0:3], v[230:233], v[238:241], v[0:3]
	s_setprio 1
	v_cmp_gt_u32_e32 vcc, s59, v133
	s_barrier
	s_and_saveexec_b64 s[4:5], vcc
	s_cbranch_execz .LBB0_1370
	s_barrier

; #define STAGE(P, BASE, br, kt) do { int _so = ((br) * K + (kt) * BK) * 2; \
;     __builtin_amdgcn_raw_ptr_buffer_load_lds(rs_##BASE, (__attribute__((address_space(3))) void*)((char*)(P) + tx * 16), 16, voff0, _so, 0, 0); \
;     __builtin_amdgcn_raw_ptr_buffer_load_lds(rs_##BASE, (__attribute__((address_space(3))) void*)((char*)(P) + tx * 16 + 8192), 16, voff1, _so, 0, 0); } while (0)
; #define LDA(dst, b, h) _Pragma("unroll") for (int m = 0; m < 4; ++m) _Pragma("unroll") for (int k = 0; k < 2; ++k) \
;     dst[m][k] = *reinterpret_cast<const bf16x8*>((char*)SA(b, h) + lds_byte(wr * 64 + m * 16 + fr, k * 32 + fq * 8))
; #define LDB(dst, b, h) _Pragma("unroll") for (int n = 0; n < 2; ++n) _Pragma("unroll") for (int k = 0; k < 2; ++k) \
;     dst[n][k] = *reinterpret_cast<const bf16x8*>((char*)SB(b, h) + lds_byte(wc * 32 + n * 16 + fr, k * 32 + fq * 8))
; #define MMA(ai, bj, At, Bt_) do { __builtin_amdgcn_s_setprio(1); \
;     _Pragma("unroll") for (int m = 0; m < 4; ++m) _Pragma("unroll") for (int n = 0; n < 2; ++n) _Pragma("unroll") for (int k = 0; k < 2; ++k) \
;       acc[ai][bj][m][n] = __builtin_amdgcn_mfma_f32_16x16x32_bf16(At[m][k], Bt_[n][k], acc[ai][bj][m][n], 0, 0, 0); \
;     __builtin_amdgcn_s_setprio(0); } while (0)
; #define WAIT_V(n) asm volatile("s_waitcnt vmcnt(" #n ")" ::: "memory")
; #define WAIT_L(n) asm volatile("s_waitcnt lgkmcnt(" #n ")" ::: "memory")
; #define BAR __builtin_amdgcn_s_barrier()
; #define SCHED __builtin_amdgcn_sched_barrier(0)
; template <class Epi> ...
;     ...
;     LDB(B0, 0, 0); SCHED; LDA(At, 0, 0); STAGE(SA(1, 1), A, brow + HALF, t + 1);
;     WAIT_L(8); BAR; WAIT_L(0); MMA(0, 0, At, B0); BAR; SCHED;
;     LDB(B1, 0, 1); STAGE(SB(0, 0), Bt, bcol, t + 2);
;     BAR; WAIT_L(0); MMA(0, 1, At, B1); BAR;
;     LDA(At, 0, 1); STAGE(SA(0, 0), A, brow, t + 2);
;     BAR; WAIT_L(0); MMA(1, 0, At, B0); BAR; SCHED;
;     STAGE(SB(0, 1), Bt, bcol + HALF, t + 2);
;     WAIT_V(6); BAR; MMA(1, 1, At, B1); BAR;
.Lpk2:
	ds_read_b128 v[156:159], v153
	ds_read_b128 v[166:169], v153 offset:1024
	ds_read_b128 v[170:173], v153 offset:2048
	ds_read_b128 v[186:189], v153 offset:3072
	s_add_i32 s28, s24, s27
	v_readfirstlane_b32 s30, v155
	s_add_i32 s29, s28, 0x40080
	s_mov_b32 m0, s30
	v_readfirstlane_b32 s30, v154
	ds_read_b128 v[190:193], v133
	ds_read_b128 v[194:197], v133 offset:1024
	ds_read_b128 v[198:201], v132
	ds_read_b128 v[202:205], v132 offset:1024
	ds_read_b128 v[206:209], v131
	ds_read_b128 v[210:213], v131 offset:1024
	ds_read_b128 v[214:217], v130
	ds_read_b128 v[218:221], v130 offset:1024
	buffer_load_dwordx4 v134, s[4:7], s29 offen lds
	s_mov_b32 m0, s30
	s_nop 0
	buffer_load_dwordx4 v135, s[4:7], s29 offen lds
	s_waitcnt lgkmcnt(8)
	s_barrier
	s_waitcnt lgkmcnt(0)
	s_setprio 0
	s_waitcnt lgkmcnt(7)
	v_mfma_f32_16x16x32_bf16 v[126:129], v[190:193], v[156:159], 0
	v_mfma_f32_16x16x32_bf16 v[122:125], v[190:193], v[170:173], 0
	s_waitcnt lgkmcnt(5)
	v_mfma_f32_16x16x32_bf16 v[118:121], v[198:201], v[156:159], 0
	v_mfma_f32_16x16x32_bf16 v[114:117], v[198:201], v[170:173], 0
	s_waitcnt lgkmcnt(3)
	v_mfma_f32_16x16x32_bf16 v[110:113], v[206:209], v[156:159], 0
	v_mfma_f32_16x16x32_bf16 v[106:109], v[206:209], v[170:173], 0
	s_waitcnt lgkmcnt(1)
	v_mfma_f32_16x16x32_bf16 v[102:105], v[214:217], v[156:159], 0
	v_mfma_f32_16x16x32_bf16 v[98:101], v[214:217], v[170:173], 0
	v_mfma_f32_16x16x32_bf16 v[126:129], v[194:197], v[166:169], v[126:129]
	v_mfma_f32_16x16x32_bf16 v[122:125], v[194:197], v[186:189], v[122:125]
	v_mfma_f32_16x16x32_bf16 v[118:121], v[202:205], v[166:169], v[118:121]
	v_mfma_f32_16x16x32_bf16 v[114:117], v[202:205], v[186:189], v[114:117]
	v_mfma_f32_16x16x32_bf16 v[110:113], v[210:213], v[166:169], v[110:113]
	v_mfma_f32_16x16x32_bf16 v[106:109], v[210:213], v[186:189], v[106:109]
	s_waitcnt lgkmcnt(0)
	v_mfma_f32_16x16x32_bf16 v[102:105], v[218:221], v[166:169], v[102:105]
	v_mfma_f32_16x16x32_bf16 v[98:101], v[218:221], v[186:189], v[98:101]
	s_setprio 1
	s_barrier
	s_add_i32 s29, s25, s27
	v_readfirstlane_b32 s31, v138
	s_add_i32 s30, s29, 0x100
	s_mov_b32 m0, s31
	v_readfirstlane_b32 s31, v139
	ds_read_b128 v[222:225], v149
	ds_read_b128 v[226:229], v149 offset:1024
	ds_read_b128 v[230:233], v149 offset:2048
	ds_read_b128 v[234:237], v149 offset:3072
	buffer_load_dwordx4 v134, s[76:79], s30 offen lds
	s_mov_b32 m0, s31
	s_nop 0
	buffer_load_dwordx4 v135, s[76:79], s30 offen lds
	s_barrier
	s_waitcnt lgkmcnt(0)
	s_setprio 0
	s_waitcnt lgkmcnt(3)
	v_mfma_f32_16x16x32_bf16 v[94:97], v[190:193], v[222:225], 0
	s_waitcnt lgkmcnt(1)
	v_mfma_f32_16x16x32_bf16 v[90:93], v[190:193], v[230:233], 0
	v_mfma_f32_16x16x32_bf16 v[86:89], v[198:201], v[222:225], 0
	v_mfma_f32_16x16x32_bf16 v[82:85], v[198:201], v[230:233], 0
	v_mfma_f32_16x16x32_bf16 v[78:81], v[206:209], v[222:225], 0
	v_mfma_f32_16x16x32_bf16 v[74:77], v[206:209], v[230:233], 0
	v_mfma_f32_16x16x32_bf16 v[70:73], v[214:217], v[222:225], 0
	v_mfma_f32_16x16x32_bf16 v[66:69], v[214:217], v[230:233], 0
	v_mfma_f32_16x16x32_bf16 v[94:97], v[194:197], v[226:229], v[94:97]
	s_waitcnt lgkmcnt(0)
	v_mfma_f32_16x16x32_bf16 v[90:93], v[194:197], v[234:237], v[90:93]
	v_mfma_f32_16x16x32_bf16 v[86:89], v[202:205], v[226:229], v[86:89]
	v_mfma_f32_16x16x32_bf16 v[82:85], v[202:205], v[234:237], v[82:85]
	v_mfma_f32_16x16x32_bf16 v[78:81], v[210:213], v[226:229], v[78:81]
	v_mfma_f32_16x16x32_bf16 v[74:77], v[210:213], v[234:237], v[74:77]
	v_mfma_f32_16x16x32_bf16 v[70:73], v[218:221], v[226:229], v[70:73]
	v_mfma_f32_16x16x32_bf16 v[66:69], v[218:221], v[234:237], v[66:69]
	s_setprio 1
	v_readfirstlane_b32 s31, v140
	s_add_i32 s30, s28, 0x100
	s_mov_b32 m0, s31
	v_readfirstlane_b32 s31, v141
	s_barrier
	ds_read_b128 v[190:193], v133 offset:16384
	ds_read_b128 v[194:197], v133 offset:17408
	ds_read_b128 v[198:201], v132 offset:16384
	ds_read_b128 v[202:205], v132 offset:17408
	ds_read_b128 v[206:209], v131 offset:16384
	ds_read_b128 v[210:213], v131 offset:17408
	ds_read_b128 v[214:217], v130 offset:16384
	ds_read_b128 v[218:221], v130 offset:17408
	buffer_load_dwordx4 v134, s[4:7], s30 offen lds
	s_mov_b32 m0, s31
	s_nop 0
	buffer_load_dwordx4 v135, s[4:7], s30 offen lds
	s_barrier
	s_waitcnt lgkmcnt(0)
	s_setprio 0
	s_waitcnt lgkmcnt(7)
	v_mfma_f32_16x16x32_bf16 v[62:65], v[190:193], v[156:159], 0
	v_mfma_f32_16x16x32_bf16 v[58:61], v[190:193], v[170:173], 0
	s_waitcnt lgkmcnt(5)
	v_mfma_f32_16x16x32_bf16 v[54:57], v[198:201], v[156:159], 0
	v_mfma_f32_16x16x32_bf16 v[50:53], v[198:201], v[170:173], 0
	s_waitcnt lgkmcnt(3)
	v_mfma_f32_16x16x32_bf16 v[46:49], v[206:209], v[156:159], 0
	v_mfma_f32_16x16x32_bf16 v[42:45], v[206:209], v[170:173], 0
	s_waitcnt lgkmcnt(1)
	v_mfma_f32_16x16x32_bf16 v[38:41], v[214:217], v[156:159], 0
	v_mfma_f32_16x16x32_bf16 v[34:37], v[214:217], v[170:173], 0
	v_mfma_f32_16x16x32_bf16 v[62:65], v[194:197], v[166:169], v[62:65]
	v_mfma_f32_16x16x32_bf16 v[58:61], v[194:197], v[186:189], v[58:61]
	v_mfma_f32_16x16x32_bf16 v[54:57], v[202:205], v[166:169], v[54:57]
	v_mfma_f32_16x16x32_bf16 v[50:53], v[202:205], v[186:189], v[50:53]
	v_mfma_f32_16x16x32_bf16 v[46:49], v[210:213], v[166:169], v[46:49]
	v_mfma_f32_16x16x32_bf16 v[42:45], v[210:213], v[186:189], v[42:45]
	s_waitcnt lgkmcnt(0)
	v_mfma_f32_16x16x32_bf16 v[38:41], v[218:221], v[166:169], v[38:41]
	v_mfma_f32_16x16x32_bf16 v[34:37], v[218:221], v[186:189], v[34:37]
	s_setprio 1
	s_barrier
	v_readfirstlane_b32 s31, v142
	s_add_i32 s30, s29, 0x40100
	s_mov_b32 m0, s31
	v_readfirstlane_b32 s31, v143
	buffer_load_dwordx4 v134, s[76:79], s30 offen lds
	s_mov_b32 m0, s31
	s_nop 0
	buffer_load_dwordx4 v135, s[76:79], s30 offen lds
	s_waitcnt vmcnt(6)
	s_barrier
; #define STAGE(P, BASE, br, kt) do { int _so = ((br) * K + (kt) * BK) * 2; \
;     __builtin_amdgcn_raw_ptr_buffer_load_lds(rs_##BASE, (__attribute__((address_space(3))) void*)((char*)(P) + tx * 16), 16, voff0, _so, 0, 0); \
;     __builtin_amdgcn_raw_ptr_buffer_load_lds(rs_##BASE, (__attribute__((address_space(3))) void*)((char*)(P) + tx * 16 + 8192), 16, voff1, _so, 0, 0); } while (0)
; #define LDA(dst, b, h) _Pragma("unroll") for (int m = 0; m < 4; ++m) _Pragma("unroll") for (int k = 0; k < 2; ++k) \
;     dst[m][k] = *reinterpret_cast<const bf16x8*>((char*)SA(b, h) + lds_byte(wr * 64 + m * 16 + fr, k * 32 + fq * 8))
; #define LDB(dst, b, h) _Pragma("unroll") for (int n = 0; n < 2; ++n) _Pragma("unroll") for (int k = 0; k < 2; ++k) \
;     dst[n][k] = *reinterpret_cast<const bf16x8*>((char*)SB(b, h) + lds_byte(wc * 32 + n * 16 + fr, k * 32 + fq * 8))
; #define MMA(ai, bj, At, Bt_) do { __builtin_amdgcn_s_setprio(1); \
;     _Pragma("unroll") for (int m = 0; m < 4; ++m) _Pragma("unroll") for (int n = 0; n < 2; ++n) _Pragma("unroll") for (int k = 0; k < 2; ++k) \
;       acc[ai][bj][m][n] = __builtin_amdgcn_mfma_f32_16x16x32_bf16(At[m][k], Bt_[n][k], acc[ai][bj][m][n], 0, 0, 0); \
;     __builtin_amdgcn_s_setprio(0); } while (0)
; #define WAIT_V(n) asm volatile("s_waitcnt vmcnt(" #n ")" ::: "memory")
; #define WAIT_L(n) asm volatile("s_waitcnt lgkmcnt(" #n ")" ::: "memory")
; #define BAR __builtin_amdgcn_s_barrier()
; #define SCHED __builtin_amdgcn_sched_barrier(0)
; template <class Epi> ...
;     ...
;     WAIT_V(6); BAR; MMA(1, 1, At, B1); BAR;
;     LDB(B0, 1, 0); SCHED; LDA(At, 1, 0); STAGE(SA(0, 1), A, brow + HALF, t + 2);
;     WAIT_L(8); BAR; WAIT_L(0); MMA(0, 0, At, B0); BAR; SCHED;
;     LDB(B1, 1, 1); STAGE(SB(1, 0), Bt, bcol, t + 3);
;     BAR; WAIT_L(0); MMA(0, 1, At, B1); BAR;
;     LDA(At, 1, 1); STAGE(SA(1, 0), A, brow, t + 3);
;     BAR; WAIT_L(0); MMA(1, 0, At, B0); BAR; SCHED;
;     STAGE(SB(1, 1), Bt, bcol + HALF, t + 3);
;     WAIT_V(6); BAR; MMA(1, 1, At, B1); BAR;
	s_setprio 0
	v_mfma_f32_16x16x32_bf16 v[28:31], v[190:193], v[222:225], 0
	v_mfma_f32_16x16x32_bf16 v[24:27], v[190:193], v[230:233], 0
	v_mfma_f32_16x16x32_bf16 v[20:23], v[198:201], v[222:225], 0
	v_mfma_f32_16x16x32_bf16 v[16:19], v[198:201], v[230:233], 0
	v_mfma_f32_16x16x32_bf16 v[12:15], v[206:209], v[222:225], 0
	v_mfma_f32_16x16x32_bf16 v[8:11], v[206:209], v[230:233], 0
	v_mfma_f32_16x16x32_bf16 v[4:7], v[214:217], v[222:225], 0
	v_mfma_f32_16x16x32_bf16 v[0:3], v[214:217], v[230:233], 0
	v_mfma_f32_16x16x32_bf16 v[28:31], v[194:197], v[226:229], v[28:31]
	v_mfma_f32_16x16x32_bf16 v[24:27], v[194:197], v[234:237], v[24:27]
	v_mfma_f32_16x16x32_bf16 v[20:23], v[202:205], v[226:229], v[20:23]
	v_mfma_f32_16x16x32_bf16 v[16:19], v[202:205], v[234:237], v[16:19]
	v_mfma_f32_16x16x32_bf16 v[12:15], v[210:213], v[226:229], v[12:15]
	v_mfma_f32_16x16x32_bf16 v[8:11], v[210:213], v[234:237], v[8:11]
	v_mfma_f32_16x16x32_bf16 v[4:7], v[218:221], v[226:229], v[4:7]
	v_mfma_f32_16x16x32_bf16 v[0:3], v[218:221], v[234:237], v[0:3]
	s_setprio 1
	s_barrier
	ds_read_b128 v[156:159], v137
	ds_read_b128 v[166:169], v137 offset:1024
	ds_read_b128 v[170:173], v137 offset:2048
	ds_read_b128 v[186:189], v137 offset:3072
	v_readfirstlane_b32 s31, v144
	s_add_i32 s30, s28, 0x40100
	s_mov_b32 m0, s31
	v_readfirstlane_b32 s31, v145
	ds_read_b128 v[190:193], v133 offset:32768
	ds_read_b128 v[194:197], v133 offset:33792
	ds_read_b128 v[198:201], v132 offset:32768
	ds_read_b128 v[202:205], v132 offset:33792
	ds_read_b128 v[206:209], v131 offset:32768
	ds_read_b128 v[210:213], v131 offset:33792
	ds_read_b128 v[214:217], v130 offset:32768
	ds_read_b128 v[218:221], v130 offset:33792
	buffer_load_dwordx4 v134, s[4:7], s30 offen lds
	s_mov_b32 m0, s31
	s_nop 0
	buffer_load_dwordx4 v135, s[4:7], s30 offen lds
	s_waitcnt lgkmcnt(8)
	s_barrier
	s_waitcnt lgkmcnt(0)
	s_setprio 0
	s_waitcnt lgkmcnt(7)
	v_mfma_f32_16x16x32_bf16 v[126:129], v[190:193], v[156:159], v[126:129]
	v_mfma_f32_16x16x32_bf16 v[122:125], v[190:193], v[170:173], v[122:125]
	s_waitcnt lgkmcnt(5)
	v_mfma_f32_16x16x32_bf16 v[118:121], v[198:201], v[156:159], v[118:121]
	v_mfma_f32_16x16x32_bf16 v[114:117], v[198:201], v[170:173], v[114:117]
	s_waitcnt lgkmcnt(3)
	v_mfma_f32_16x16x32_bf16 v[110:113], v[206:209], v[156:159], v[110:113]
	v_mfma_f32_16x16x32_bf16 v[106:109], v[206:209], v[170:173], v[106:109]
	s_waitcnt lgkmcnt(1)
	v_mfma_f32_16x16x32_bf16 v[102:105], v[214:217], v[156:159], v[102:105]
	v_mfma_f32_16x16x32_bf16 v[98:101], v[214:217], v[170:173], v[98:101]
	v_mfma_f32_16x16x32_bf16 v[126:129], v[194:197], v[166:169], v[126:129]
	v_mfma_f32_16x16x32_bf16 v[122:125], v[194:197], v[186:189], v[122:125]
	v_mfma_f32_16x16x32_bf16 v[118:121], v[202:205], v[166:169], v[118:121]
	v_mfma_f32_16x16x32_bf16 v[114:117], v[202:205], v[186:189], v[114:117]
	v_mfma_f32_16x16x32_bf16 v[110:113], v[210:213], v[166:169], v[110:113]
	v_mfma_f32_16x16x32_bf16 v[106:109], v[210:213], v[186:189], v[106:109]
	s_waitcnt lgkmcnt(0)
	v_mfma_f32_16x16x32_bf16 v[102:105], v[218:221], v[166:169], v[102:105]
	v_mfma_f32_16x16x32_bf16 v[98:101], v[218:221], v[186:189], v[98:101]
	s_setprio 1
	s_barrier
	v_readfirstlane_b32 s31, v146
	s_add_i32 s30, s29, 0x180
	s_mov_b32 m0, s31
	v_readfirstlane_b32 s31, v147
	ds_read_b128 v[222:225], v136
	ds_read_b128 v[226:229], v136 offset:1024
	ds_read_b128 v[230:233], v136 offset:2048
	ds_read_b128 v[234:237], v136 offset:3072
	buffer_load_dwordx4 v134, s[76:79], s30 offen lds
	s_mov_b32 m0, s31
	s_nop 0
	buffer_load_dwordx4 v135, s[76:79], s30 offen lds
	s_barrier
	s_waitcnt lgkmcnt(0)
	s_setprio 0
	s_waitcnt lgkmcnt(3)
	v_mfma_f32_16x16x32_bf16 v[94:97], v[190:193], v[222:225], v[94:97]
	s_waitcnt lgkmcnt(1)
	v_mfma_f32_16x16x32_bf16 v[90:93], v[190:193], v[230:233], v[90:93]
	v_mfma_f32_16x16x32_bf16 v[86:89], v[198:201], v[222:225], v[86:89]
	v_mfma_f32_16x16x32_bf16 v[82:85], v[198:201], v[230:233], v[82:85]
	v_mfma_f32_16x16x32_bf16 v[78:81], v[206:209], v[222:225], v[78:81]
	v_mfma_f32_16x16x32_bf16 v[74:77], v[206:209], v[230:233], v[74:77]
	v_mfma_f32_16x16x32_bf16 v[70:73], v[214:217], v[222:225], v[70:73]
	v_mfma_f32_16x16x32_bf16 v[66:69], v[214:217], v[230:233], v[66:69]
	v_mfma_f32_16x16x32_bf16 v[94:97], v[194:197], v[226:229], v[94:97]
	s_waitcnt lgkmcnt(0)
	v_mfma_f32_16x16x32_bf16 v[90:93], v[194:197], v[234:237], v[90:93]
	v_mfma_f32_16x16x32_bf16 v[86:89], v[202:205], v[226:229], v[86:89]
	v_mfma_f32_16x16x32_bf16 v[82:85], v[202:205], v[234:237], v[82:85]
	v_mfma_f32_16x16x32_bf16 v[78:81], v[210:213], v[226:229], v[78:81]
	v_mfma_f32_16x16x32_bf16 v[74:77], v[210:213], v[234:237], v[74:77]
	v_mfma_f32_16x16x32_bf16 v[70:73], v[218:221], v[226:229], v[70:73]
	v_mfma_f32_16x16x32_bf16 v[66:69], v[218:221], v[234:237], v[66:69]
	s_setprio 1
	v_readfirstlane_b32 s30, v148
	s_addk_i32 s28, 0x180
	s_mov_b32 m0, s30
	v_readfirstlane_b32 s30, v150
	s_barrier
	ds_read_b128 v[190:193], v133 offset:49152
	ds_read_b128 v[194:197], v133 offset:50176
	ds_read_b128 v[198:201], v132 offset:49152
	ds_read_b128 v[202:205], v132 offset:50176
	ds_read_b128 v[206:209], v131 offset:49152
	ds_read_b128 v[210:213], v131 offset:50176
	ds_read_b128 v[214:217], v130 offset:49152
	ds_read_b128 v[218:221], v130 offset:50176
	buffer_load_dwordx4 v134, s[4:7], s28 offen lds
	s_mov_b32 m0, s30
	s_nop 0
	buffer_load_dwordx4 v135, s[4:7], s28 offen lds
	s_barrier
; #define STAGE(P, BASE, br, kt) do { int _so = ((br) * K + (kt) * BK) * 2; \
;     __builtin_amdgcn_raw_ptr_buffer_load_lds(rs_##BASE, (__attribute__((address_space(3))) void*)((char*)(P) + tx * 16), 16, voff0, _so, 0, 0); \
;     __builtin_amdgcn_raw_ptr_buffer_load_lds(rs_##BASE, (__attribute__((address_space(3))) void*)((char*)(P) + tx * 16 + 8192), 16, voff1, _so, 0, 0); } while (0)
; #define LDA(dst, b, h) _Pragma("unroll") for (int m = 0; m < 4; ++m) _Pragma("unroll") for (int k = 0; k < 2; ++k) \
;     dst[m][k] = *reinterpret_cast<const bf16x8*>((char*)SA(b, h) + lds_byte(wr * 64 + m * 16 + fr, k * 32 + fq * 8))
; #define LDB(dst, b, h) _Pragma("unroll") for (int n = 0; n < 2; ++n) _Pragma("unroll") for (int k = 0; k < 2; ++k) \
;     dst[n][k] = *reinterpret_cast<const bf16x8*>((char*)SB(b, h) + lds_byte(wc * 32 + n * 16 + fr, k * 32 + fq * 8))
; #define MMA(ai, bj, At, Bt_) do { __builtin_amdgcn_s_setprio(1); \
;     _Pragma("unroll") for (int m = 0; m < 4; ++m) _Pragma("unroll") for (int n = 0; n < 2; ++n) _Pragma("unroll") for (int k = 0; k < 2; ++k) \
;       acc[ai][bj][m][n] = __builtin_amdgcn_mfma_f32_16x16x32_bf16(At[m][k], Bt_[n][k], acc[ai][bj][m][n], 0, 0, 0); \
;     __builtin_amdgcn_s_setprio(0); } while (0)
; #define WAIT_V(n) asm volatile("s_waitcnt vmcnt(" #n ")" ::: "memory")
; #define WAIT_L(n) asm volatile("s_waitcnt lgkmcnt(" #n ")" ::: "memory")
; #define BAR __builtin_amdgcn_s_barrier()
; #define SCHED __builtin_amdgcn_sched_barrier(0)
; template <class Epi> ...
;     ...
;     LDB(B0, 0, 0); SCHED; LDA(At, 0, 0); STAGE(SA(1, 1), A, brow + HALF, t + 1);
;     WAIT_L(8); BAR; WAIT_L(0); MMA(0, 0, At, B0); BAR; SCHED;
;     LDB(B1, 0, 1); STAGE(SB(0, 0), Bt, bcol, t + 2);
;     ...
;     BAR; WAIT_L(0); MMA(1, 0, At, B0); BAR; SCHED;
;     STAGE(SB(1, 1), Bt, bcol + HALF, t + 3);
;     WAIT_V(6); BAR; MMA(1, 1, At, B1); BAR;
;   }
	s_waitcnt lgkmcnt(0)
	s_setprio 0
	s_waitcnt lgkmcnt(7)
	v_mfma_f32_16x16x32_bf16 v[62:65], v[190:193], v[156:159], v[62:65]
	v_mfma_f32_16x16x32_bf16 v[58:61], v[190:193], v[170:173], v[58:61]
	s_waitcnt lgkmcnt(5)
	v_mfma_f32_16x16x32_bf16 v[54:57], v[198:201], v[156:159], v[54:57]
	v_mfma_f32_16x16x32_bf16 v[50:53], v[198:201], v[170:173], v[50:53]
	s_waitcnt lgkmcnt(3)
	v_mfma_f32_16x16x32_bf16 v[46:49], v[206:209], v[156:159], v[46:49]
	v_mfma_f32_16x16x32_bf16 v[42:45], v[206:209], v[170:173], v[42:45]
	s_waitcnt lgkmcnt(1)
	v_mfma_f32_16x16x32_bf16 v[38:41], v[214:217], v[156:159], v[38:41]
	v_mfma_f32_16x16x32_bf16 v[34:37], v[214:217], v[170:173], v[34:37]
	v_mfma_f32_16x16x32_bf16 v[62:65], v[194:197], v[166:169], v[62:65]
	v_mfma_f32_16x16x32_bf16 v[58:61], v[194:197], v[186:189], v[58:61]
	v_mfma_f32_16x16x32_bf16 v[54:57], v[202:205], v[166:169], v[54:57]
	v_mfma_f32_16x16x32_bf16 v[50:53], v[202:205], v[186:189], v[50:53]
	v_mfma_f32_16x16x32_bf16 v[46:49], v[210:213], v[166:169], v[46:49]
	v_mfma_f32_16x16x32_bf16 v[42:45], v[210:213], v[186:189], v[42:45]
	s_waitcnt lgkmcnt(0)
	v_mfma_f32_16x16x32_bf16 v[38:41], v[218:221], v[166:169], v[38:41]
	v_mfma_f32_16x16x32_bf16 v[34:37], v[218:221], v[186:189], v[34:37]
	s_setprio 1
	s_barrier
	v_readfirstlane_b32 s28, v151
	s_add_i32 s29, s29, 0x40180
	s_mov_b32 m0, s28
	v_readfirstlane_b32 s28, v152
	buffer_load_dwordx4 v134, s[76:79], s29 offen lds
	s_mov_b32 m0, s28
	s_nop 0
	buffer_load_dwordx4 v135, s[76:79], s29 offen lds
	s_waitcnt vmcnt(6)
	s_barrier
	s_setprio 0
	v_mfma_f32_16x16x32_bf16 v[28:31], v[190:193], v[222:225], v[28:31]
	v_mfma_f32_16x16x32_bf16 v[24:27], v[190:193], v[230:233], v[24:27]
	v_mfma_f32_16x16x32_bf16 v[20:23], v[198:201], v[222:225], v[20:23]
	v_mfma_f32_16x16x32_bf16 v[16:19], v[198:201], v[230:233], v[16:19]
	v_mfma_f32_16x16x32_bf16 v[12:15], v[206:209], v[222:225], v[12:15]
	v_mfma_f32_16x16x32_bf16 v[8:11], v[206:209], v[230:233], v[8:11]
	v_mfma_f32_16x16x32_bf16 v[4:7], v[214:217], v[222:225], v[4:7]
	v_mfma_f32_16x16x32_bf16 v[0:3], v[214:217], v[230:233], v[0:3]
	v_mfma_f32_16x16x32_bf16 v[28:31], v[194:197], v[226:229], v[28:31]
	v_mfma_f32_16x16x32_bf16 v[24:27], v[194:197], v[234:237], v[24:27]
	v_mfma_f32_16x16x32_bf16 v[20:23], v[202:205], v[226:229], v[20:23]
	v_mfma_f32_16x16x32_bf16 v[16:19], v[202:205], v[234:237], v[16:19]
	v_mfma_f32_16x16x32_bf16 v[12:15], v[210:213], v[226:229], v[12:15]
	v_mfma_f32_16x16x32_bf16 v[8:11], v[210:213], v[234:237], v[8:11]
	v_mfma_f32_16x16x32_bf16 v[4:7], v[218:221], v[226:229], v[4:7]
	v_mfma_f32_16x16x32_bf16 v[0:3], v[218:221], v[234:237], v[0:3]
	s_setprio 1
	s_add_i32 s26, s26, 2
	s_addk_i32 s27, 0x100
	s_cmp_lt_u32 s26, 12
	s_barrier
	s_cbranch_scc1 .LBB0_1657
	s_branch .Lpx2
.LBB0_1657:
	ds_read_b128 v[156:159], v153
	ds_read_b128 v[166:169], v153 offset:1024
	ds_read_b128 v[170:173], v153 offset:2048
	ds_read_b128 v[186:189], v153 offset:3072
	s_add_i32 s28, s24, s27
	v_readfirstlane_b32 s30, v155
	s_add_i32 s29, s28, 0x40080
	s_mov_b32 m0, s30
	v_readfirstlane_b32 s30, v154
	ds_read_b128 v[190:193], v133
	ds_read_b128 v[194:197], v133 offset:1024
	ds_read_b128 v[198:201], v132
	ds_read_b128 v[202:205], v132 offset:1024
	ds_read_b128 v[206:209], v131
	ds_read_b128 v[210:213], v131 offset:1024
	ds_read_b128 v[214:217], v130
	ds_read_b128 v[218:221], v130 offset:1024
	buffer_load_dwordx4 v134, s[4:7], s29 offen lds
	s_mov_b32 m0, s30
	s_nop 0
	buffer_load_dwordx4 v135, s[4:7], s29 offen lds
	s_waitcnt lgkmcnt(8)
	s_barrier
	s_waitcnt lgkmcnt(0)
	s_setprio 0
	s_waitcnt lgkmcnt(7)
	v_mfma_f32_16x16x32_bf16 v[126:129], v[190:193], v[156:159], v[126:129]
	v_mfma_f32_16x16x32_bf16 v[122:125], v[190:193], v[170:173], v[122:125]
	s_waitcnt lgkmcnt(5)
	v_mfma_f32_16x16x32_bf16 v[118:121], v[198:201], v[156:159], v[118:121]
	v_mfma_f32_16x16x32_bf16 v[114:117], v[198:201], v[170:173], v[114:117]
	s_waitcnt lgkmcnt(3)
	v_mfma_f32_16x16x32_bf16 v[110:113], v[206:209], v[156:159], v[110:113]
	v_mfma_f32_16x16x32_bf16 v[106:109], v[206:209], v[170:173], v[106:109]
	s_waitcnt lgkmcnt(1)
	v_mfma_f32_16x16x32_bf16 v[102:105], v[214:217], v[156:159], v[102:105]
	v_mfma_f32_16x16x32_bf16 v[98:101], v[214:217], v[170:173], v[98:101]
	v_mfma_f32_16x16x32_bf16 v[126:129], v[194:197], v[166:169], v[126:129]
	v_mfma_f32_16x16x32_bf16 v[122:125], v[194:197], v[186:189], v[122:125]
	v_mfma_f32_16x16x32_bf16 v[118:121], v[202:205], v[166:169], v[118:121]
	v_mfma_f32_16x16x32_bf16 v[114:117], v[202:205], v[186:189], v[114:117]
	v_mfma_f32_16x16x32_bf16 v[110:113], v[210:213], v[166:169], v[110:113]
	v_mfma_f32_16x16x32_bf16 v[106:109], v[210:213], v[186:189], v[106:109]
	s_waitcnt lgkmcnt(0)
	v_mfma_f32_16x16x32_bf16 v[102:105], v[218:221], v[166:169], v[102:105]
	v_mfma_f32_16x16x32_bf16 v[98:101], v[218:221], v[186:189], v[98:101]
	s_setprio 1
	s_barrier
	s_add_i32 s29, s25, s27
	v_readfirstlane_b32 s31, v138
	s_add_i32 s30, s29, 0x100
	s_mov_b32 m0, s31
	v_readfirstlane_b32 s31, v139
	ds_read_b128 v[222:225], v149
	ds_read_b128 v[226:229], v149 offset:1024
	ds_read_b128 v[230:233], v149 offset:2048
	ds_read_b128 v[234:237], v149 offset:3072
	buffer_load_dwordx4 v134, s[76:79], s30 offen lds
	s_mov_b32 m0, s31
	s_nop 0
	buffer_load_dwordx4 v135, s[76:79], s30 offen lds
	s_barrier
; #define STAGE(P, BASE, br, kt) do { int _so = ((br) * K + (kt) * BK) * 2; \
;     __builtin_amdgcn_raw_ptr_buffer_load_lds(rs_##BASE, (__attribute__((address_space(3))) void*)((char*)(P) + tx * 16), 16, voff0, _so, 0, 0); \
;     __builtin_amdgcn_raw_ptr_buffer_load_lds(rs_##BASE, (__attribute__((address_space(3))) void*)((char*)(P) + tx * 16 + 8192), 16, voff1, _so, 0, 0); } while (0)
; #define LDA(dst, b, h) _Pragma("unroll") for (int m = 0; m < 4; ++m) _Pragma("unroll") for (int k = 0; k < 2; ++k) \
;     dst[m][k] = *reinterpret_cast<const bf16x8*>((char*)SA(b, h) + lds_byte(wr * 64 + m * 16 + fr, k * 32 + fq * 8))
; #define LDB(dst, b, h) _Pragma("unroll") for (int n = 0; n < 2; ++n) _Pragma("unroll") for (int k = 0; k < 2; ++k) \
;     dst[n][k] = *reinterpret_cast<const bf16x8*>((char*)SB(b, h) + lds_byte(wc * 32 + n * 16 + fr, k * 32 + fq * 8))
; #define MMA(ai, bj, At, Bt_) do { __builtin_amdgcn_s_setprio(1); \
;     _Pragma("unroll") for (int m = 0; m < 4; ++m) _Pragma("unroll") for (int n = 0; n < 2; ++n) _Pragma("unroll") for (int k = 0; k < 2; ++k) \
;       acc[ai][bj][m][n] = __builtin_amdgcn_mfma_f32_16x16x32_bf16(At[m][k], Bt_[n][k], acc[ai][bj][m][n], 0, 0, 0); \
;     __builtin_amdgcn_s_setprio(0); } while (0)
; #define WAIT_V(n) asm volatile("s_waitcnt vmcnt(" #n ")" ::: "memory")
; #define WAIT_L(n) asm volatile("s_waitcnt lgkmcnt(" #n ")" ::: "memory")
; #define BAR __builtin_amdgcn_s_barrier()
; #define SCHED __builtin_amdgcn_sched_barrier(0)
; template <class Epi> ...
;     ...
;     BAR; WAIT_L(0); MMA(0, 1, At, B1); BAR;
;     LDA(At, 0, 1); STAGE(SA(0, 0), A, brow, t + 2);
;     BAR; WAIT_L(0); MMA(1, 0, At, B0); BAR; SCHED;
;     STAGE(SB(0, 1), Bt, bcol + HALF, t + 2);
;     WAIT_V(6); BAR; MMA(1, 1, At, B1); BAR;
;     LDB(B0, 1, 0); SCHED; LDA(At, 1, 0); STAGE(SA(0, 1), A, brow + HALF, t + 2);
	s_waitcnt lgkmcnt(0)
	s_setprio 0
	s_waitcnt lgkmcnt(3)
	v_mfma_f32_16x16x32_bf16 v[94:97], v[190:193], v[222:225], v[94:97]
	s_waitcnt lgkmcnt(1)
	v_mfma_f32_16x16x32_bf16 v[90:93], v[190:193], v[230:233], v[90:93]
	v_mfma_f32_16x16x32_bf16 v[86:89], v[198:201], v[222:225], v[86:89]
	v_mfma_f32_16x16x32_bf16 v[82:85], v[198:201], v[230:233], v[82:85]
	v_mfma_f32_16x16x32_bf16 v[78:81], v[206:209], v[222:225], v[78:81]
	v_mfma_f32_16x16x32_bf16 v[74:77], v[206:209], v[230:233], v[74:77]
	v_mfma_f32_16x16x32_bf16 v[70:73], v[214:217], v[222:225], v[70:73]
	v_mfma_f32_16x16x32_bf16 v[66:69], v[214:217], v[230:233], v[66:69]
	v_mfma_f32_16x16x32_bf16 v[94:97], v[194:197], v[226:229], v[94:97]
	s_waitcnt lgkmcnt(0)
	v_mfma_f32_16x16x32_bf16 v[90:93], v[194:197], v[234:237], v[90:93]
	v_mfma_f32_16x16x32_bf16 v[86:89], v[202:205], v[226:229], v[86:89]
	v_mfma_f32_16x16x32_bf16 v[82:85], v[202:205], v[234:237], v[82:85]
	v_mfma_f32_16x16x32_bf16 v[78:81], v[210:213], v[226:229], v[78:81]
	v_mfma_f32_16x16x32_bf16 v[74:77], v[210:213], v[234:237], v[74:77]
	v_mfma_f32_16x16x32_bf16 v[70:73], v[218:221], v[226:229], v[70:73]
	v_mfma_f32_16x16x32_bf16 v[66:69], v[218:221], v[234:237], v[66:69]
	s_setprio 1
	v_readfirstlane_b32 s31, v140
	s_add_i32 s30, s28, 0x100
	s_mov_b32 m0, s31
	v_readfirstlane_b32 s31, v141
	s_barrier
	ds_read_b128 v[190:193], v133 offset:16384
	ds_read_b128 v[194:197], v133 offset:17408
	ds_read_b128 v[198:201], v132 offset:16384
	ds_read_b128 v[202:205], v132 offset:17408
	ds_read_b128 v[206:209], v131 offset:16384
	ds_read_b128 v[210:213], v131 offset:17408
	ds_read_b128 v[214:217], v130 offset:16384
	ds_read_b128 v[218:221], v130 offset:17408
	buffer_load_dwordx4 v134, s[4:7], s30 offen lds
	s_mov_b32 m0, s31
	s_nop 0
	buffer_load_dwordx4 v135, s[4:7], s30 offen lds
	s_barrier
	s_waitcnt lgkmcnt(0)
	s_setprio 0
	s_waitcnt lgkmcnt(7)
	v_mfma_f32_16x16x32_bf16 v[62:65], v[190:193], v[156:159], v[62:65]
	v_mfma_f32_16x16x32_bf16 v[58:61], v[190:193], v[170:173], v[58:61]
	s_waitcnt lgkmcnt(5)
	v_mfma_f32_16x16x32_bf16 v[54:57], v[198:201], v[156:159], v[54:57]
	v_mfma_f32_16x16x32_bf16 v[50:53], v[198:201], v[170:173], v[50:53]
	s_waitcnt lgkmcnt(3)
	v_mfma_f32_16x16x32_bf16 v[46:49], v[206:209], v[156:159], v[46:49]
	v_mfma_f32_16x16x32_bf16 v[42:45], v[206:209], v[170:173], v[42:45]
	s_waitcnt lgkmcnt(1)
	v_mfma_f32_16x16x32_bf16 v[38:41], v[214:217], v[156:159], v[38:41]
	v_mfma_f32_16x16x32_bf16 v[34:37], v[214:217], v[170:173], v[34:37]
	v_mfma_f32_16x16x32_bf16 v[62:65], v[194:197], v[166:169], v[62:65]
	v_mfma_f32_16x16x32_bf16 v[58:61], v[194:197], v[186:189], v[58:61]
	v_mfma_f32_16x16x32_bf16 v[54:57], v[202:205], v[166:169], v[54:57]
	v_mfma_f32_16x16x32_bf16 v[50:53], v[202:205], v[186:189], v[50:53]
	v_mfma_f32_16x16x32_bf16 v[46:49], v[210:213], v[166:169], v[46:49]
	v_mfma_f32_16x16x32_bf16 v[42:45], v[210:213], v[186:189], v[42:45]
	s_waitcnt lgkmcnt(0)
	v_mfma_f32_16x16x32_bf16 v[38:41], v[218:221], v[166:169], v[38:41]
	v_mfma_f32_16x16x32_bf16 v[34:37], v[218:221], v[186:189], v[34:37]
	s_setprio 1
	s_barrier
	v_readfirstlane_b32 s31, v142
	s_add_i32 s30, s29, 0x40100
	s_mov_b32 m0, s31
	v_readfirstlane_b32 s31, v143
	buffer_load_dwordx4 v134, s[76:79], s30 offen lds
	s_mov_b32 m0, s31
	s_nop 0
	buffer_load_dwordx4 v135, s[76:79], s30 offen lds
	s_waitcnt vmcnt(6)
	s_barrier
	s_setprio 0
	v_mfma_f32_16x16x32_bf16 v[28:31], v[190:193], v[222:225], v[28:31]
	v_mfma_f32_16x16x32_bf16 v[24:27], v[190:193], v[230:233], v[24:27]
	v_mfma_f32_16x16x32_bf16 v[20:23], v[198:201], v[222:225], v[20:23]
	v_mfma_f32_16x16x32_bf16 v[16:19], v[198:201], v[230:233], v[16:19]
	v_mfma_f32_16x16x32_bf16 v[12:15], v[206:209], v[222:225], v[12:15]
	v_mfma_f32_16x16x32_bf16 v[8:11], v[206:209], v[230:233], v[8:11]
	v_mfma_f32_16x16x32_bf16 v[4:7], v[214:217], v[222:225], v[4:7]
	v_mfma_f32_16x16x32_bf16 v[0:3], v[214:217], v[230:233], v[0:3]
	v_mfma_f32_16x16x32_bf16 v[28:31], v[194:197], v[226:229], v[28:31]
	v_mfma_f32_16x16x32_bf16 v[24:27], v[194:197], v[234:237], v[24:27]
	v_mfma_f32_16x16x32_bf16 v[20:23], v[202:205], v[226:229], v[20:23]
	v_mfma_f32_16x16x32_bf16 v[16:19], v[202:205], v[234:237], v[16:19]
	v_mfma_f32_16x16x32_bf16 v[12:15], v[210:213], v[226:229], v[12:15]
	v_mfma_f32_16x16x32_bf16 v[8:11], v[210:213], v[234:237], v[8:11]
	v_mfma_f32_16x16x32_bf16 v[4:7], v[218:221], v[226:229], v[4:7]
	v_mfma_f32_16x16x32_bf16 v[0:3], v[218:221], v[234:237], v[0:3]
	s_setprio 1
	s_barrier
	ds_read_b128 v[156:159], v137
	ds_read_b128 v[166:169], v137 offset:1024
	ds_read_b128 v[170:173], v137 offset:2048
	ds_read_b128 v[186:189], v137 offset:3072
	v_readfirstlane_b32 s31, v144
	s_add_i32 s30, s28, 0x40100
	s_mov_b32 m0, s31
	v_readfirstlane_b32 s31, v145
	ds_read_b128 v[190:193], v133 offset:32768
	ds_read_b128 v[194:197], v133 offset:33792
	ds_read_b128 v[198:201], v132 offset:32768
	ds_read_b128 v[202:205], v132 offset:33792
	ds_read_b128 v[206:209], v131 offset:32768
	ds_read_b128 v[210:213], v131 offset:33792
	ds_read_b128 v[214:217], v130 offset:32768
	ds_read_b128 v[218:221], v130 offset:33792
	buffer_load_dwordx4 v134, s[4:7], s30 offen lds
	s_mov_b32 m0, s31
	s_nop 0
	buffer_load_dwordx4 v135, s[4:7], s30 offen lds
	s_waitcnt lgkmcnt(8)
	s_barrier
; #define STAGE(P, BASE, br, kt) do { int _so = ((br) * K + (kt) * BK) * 2; \
;     __builtin_amdgcn_raw_ptr_buffer_load_lds(rs_##BASE, (__attribute__((address_space(3))) void*)((char*)(P) + tx * 16), 16, voff0, _so, 0, 0); \
;     __builtin_amdgcn_raw_ptr_buffer_load_lds(rs_##BASE, (__attribute__((address_space(3))) void*)((char*)(P) + tx * 16 + 8192), 16, voff1, _so, 0, 0); } while (0)
; #define LDA(dst, b, h) _Pragma("unroll") for (int m = 0; m < 4; ++m) _Pragma("unroll") for (int k = 0; k < 2; ++k) \
;     dst[m][k] = *reinterpret_cast<const bf16x8*>((char*)SA(b, h) + lds_byte(wr * 64 + m * 16 + fr, k * 32 + fq * 8))
; #define LDB(dst, b, h) _Pragma("unroll") for (int n = 0; n < 2; ++n) _Pragma("unroll") for (int k = 0; k < 2; ++k) \
;     dst[n][k] = *reinterpret_cast<const bf16x8*>((char*)SB(b, h) + lds_byte(wc * 32 + n * 16 + fr, k * 32 + fq * 8))
; #define MMA(ai, bj, At, Bt_) do { __builtin_amdgcn_s_setprio(1); \
;     _Pragma("unroll") for (int m = 0; m < 4; ++m) _Pragma("unroll") for (int n = 0; n < 2; ++n) _Pragma("unroll") for (int k = 0; k < 2; ++k) \
;       acc[ai][bj][m][n] = __builtin_amdgcn_mfma_f32_16x16x32_bf16(At[m][k], Bt_[n][k], acc[ai][bj][m][n], 0, 0, 0); \
;     __builtin_amdgcn_s_setprio(0); } while (0)
; #define WAIT_V(n) asm volatile("s_waitcnt vmcnt(" #n ")" ::: "memory")
; #define WAIT_L(n) asm volatile("s_waitcnt lgkmcnt(" #n ")" ::: "memory")
; #define BAR __builtin_amdgcn_s_barrier()
; #define SCHED __builtin_amdgcn_sched_barrier(0)
; template <class Epi> ...
;     ...
;     WAIT_L(8); BAR; WAIT_L(0); MMA(0, 0, At, B0); BAR; SCHED;
;     LDB(B1, 1, 1); STAGE(SB(1, 0), Bt, bcol, t + 3);
;     BAR; WAIT_L(0); MMA(0, 1, At, B1); BAR;
;     LDA(At, 1, 1); STAGE(SA(1, 0), A, brow, t + 3);
;     BAR; WAIT_L(0); MMA(1, 0, At, B0); BAR; SCHED;
;     STAGE(SB(1, 1), Bt, bcol + HALF, t + 3);
;     WAIT_V(6); BAR; MMA(1, 1, At, B1); BAR;
	s_waitcnt lgkmcnt(0)
	s_setprio 0
	s_waitcnt lgkmcnt(7)
	v_mfma_f32_16x16x32_bf16 v[126:129], v[190:193], v[156:159], v[126:129]
	v_mfma_f32_16x16x32_bf16 v[122:125], v[190:193], v[170:173], v[122:125]
	s_waitcnt lgkmcnt(5)
	v_mfma_f32_16x16x32_bf16 v[118:121], v[198:201], v[156:159], v[118:121]
	v_mfma_f32_16x16x32_bf16 v[114:117], v[198:201], v[170:173], v[114:117]
	s_waitcnt lgkmcnt(3)
	v_mfma_f32_16x16x32_bf16 v[110:113], v[206:209], v[156:159], v[110:113]
	v_mfma_f32_16x16x32_bf16 v[106:109], v[206:209], v[170:173], v[106:109]
	s_waitcnt lgkmcnt(1)
	v_mfma_f32_16x16x32_bf16 v[102:105], v[214:217], v[156:159], v[102:105]
	v_mfma_f32_16x16x32_bf16 v[98:101], v[214:217], v[170:173], v[98:101]
	v_mfma_f32_16x16x32_bf16 v[126:129], v[194:197], v[166:169], v[126:129]
	v_mfma_f32_16x16x32_bf16 v[122:125], v[194:197], v[186:189], v[122:125]
	v_mfma_f32_16x16x32_bf16 v[118:121], v[202:205], v[166:169], v[118:121]
	v_mfma_f32_16x16x32_bf16 v[114:117], v[202:205], v[186:189], v[114:117]
	v_mfma_f32_16x16x32_bf16 v[110:113], v[210:213], v[166:169], v[110:113]
	v_mfma_f32_16x16x32_bf16 v[106:109], v[210:213], v[186:189], v[106:109]
	s_waitcnt lgkmcnt(0)
	v_mfma_f32_16x16x32_bf16 v[102:105], v[218:221], v[166:169], v[102:105]
	v_mfma_f32_16x16x32_bf16 v[98:101], v[218:221], v[186:189], v[98:101]
	s_setprio 1
	s_barrier
	v_readfirstlane_b32 s31, v146
	s_add_i32 s30, s29, 0x180
	s_mov_b32 m0, s31
	v_readfirstlane_b32 s31, v147
	ds_read_b128 v[222:225], v136
	ds_read_b128 v[226:229], v136 offset:1024
	ds_read_b128 v[230:233], v136 offset:2048
	ds_read_b128 v[234:237], v136 offset:3072
	buffer_load_dwordx4 v134, s[76:79], s30 offen lds
	s_mov_b32 m0, s31
	s_nop 0
	buffer_load_dwordx4 v135, s[76:79], s30 offen lds
	s_barrier
	s_waitcnt lgkmcnt(0)
	s_setprio 0
	s_waitcnt lgkmcnt(3)
	v_mfma_f32_16x16x32_bf16 v[94:97], v[190:193], v[222:225], v[94:97]
	s_waitcnt lgkmcnt(1)
	v_mfma_f32_16x16x32_bf16 v[90:93], v[190:193], v[230:233], v[90:93]
	v_mfma_f32_16x16x32_bf16 v[86:89], v[198:201], v[222:225], v[86:89]
	v_mfma_f32_16x16x32_bf16 v[82:85], v[198:201], v[230:233], v[82:85]
	v_mfma_f32_16x16x32_bf16 v[78:81], v[206:209], v[222:225], v[78:81]
	v_mfma_f32_16x16x32_bf16 v[74:77], v[206:209], v[230:233], v[74:77]
	v_mfma_f32_16x16x32_bf16 v[70:73], v[214:217], v[222:225], v[70:73]
	v_mfma_f32_16x16x32_bf16 v[66:69], v[214:217], v[230:233], v[66:69]
	v_mfma_f32_16x16x32_bf16 v[94:97], v[194:197], v[226:229], v[94:97]
	s_waitcnt lgkmcnt(0)
	v_mfma_f32_16x16x32_bf16 v[90:93], v[194:197], v[234:237], v[90:93]
	v_mfma_f32_16x16x32_bf16 v[86:89], v[202:205], v[226:229], v[86:89]
	v_mfma_f32_16x16x32_bf16 v[82:85], v[202:205], v[234:237], v[82:85]
	v_mfma_f32_16x16x32_bf16 v[78:81], v[210:213], v[226:229], v[78:81]
	v_mfma_f32_16x16x32_bf16 v[74:77], v[210:213], v[234:237], v[74:77]
	v_mfma_f32_16x16x32_bf16 v[70:73], v[218:221], v[226:229], v[70:73]
	v_mfma_f32_16x16x32_bf16 v[66:69], v[218:221], v[234:237], v[66:69]
	s_setprio 1
	v_readfirstlane_b32 s30, v148
	s_addk_i32 s28, 0x180
	s_mov_b32 m0, s30
	v_readfirstlane_b32 s30, v150
	s_barrier
	ds_read_b128 v[190:193], v133 offset:49152
	ds_read_b128 v[194:197], v133 offset:50176
	ds_read_b128 v[198:201], v132 offset:49152
	ds_read_b128 v[202:205], v132 offset:50176
	ds_read_b128 v[206:209], v131 offset:49152
	ds_read_b128 v[210:213], v131 offset:50176
	ds_read_b128 v[214:217], v130 offset:49152
	ds_read_b128 v[218:221], v130 offset:50176
	buffer_load_dwordx4 v134, s[4:7], s28 offen lds
	s_mov_b32 m0, s30
	s_nop 0
	buffer_load_dwordx4 v135, s[4:7], s28 offen lds
	s_barrier
	s_waitcnt lgkmcnt(0)
	s_setprio 0
	s_waitcnt lgkmcnt(7)
	v_mfma_f32_16x16x32_bf16 v[62:65], v[190:193], v[156:159], v[62:65]
	v_mfma_f32_16x16x32_bf16 v[58:61], v[190:193], v[170:173], v[58:61]
	s_waitcnt lgkmcnt(5)
	v_mfma_f32_16x16x32_bf16 v[54:57], v[198:201], v[156:159], v[54:57]
	v_mfma_f32_16x16x32_bf16 v[50:53], v[198:201], v[170:173], v[50:53]
	s_waitcnt lgkmcnt(3)
	v_mfma_f32_16x16x32_bf16 v[46:49], v[206:209], v[156:159], v[46:49]
	v_mfma_f32_16x16x32_bf16 v[42:45], v[206:209], v[170:173], v[42:45]
	s_waitcnt lgkmcnt(1)
	v_mfma_f32_16x16x32_bf16 v[38:41], v[214:217], v[156:159], v[38:41]
	v_mfma_f32_16x16x32_bf16 v[34:37], v[214:217], v[170:173], v[34:37]
	v_mfma_f32_16x16x32_bf16 v[62:65], v[194:197], v[166:169], v[62:65]
	v_mfma_f32_16x16x32_bf16 v[58:61], v[194:197], v[186:189], v[58:61]
	v_mfma_f32_16x16x32_bf16 v[54:57], v[202:205], v[166:169], v[54:57]
	v_mfma_f32_16x16x32_bf16 v[50:53], v[202:205], v[186:189], v[50:53]
	v_mfma_f32_16x16x32_bf16 v[46:49], v[210:213], v[166:169], v[46:49]
	v_mfma_f32_16x16x32_bf16 v[42:45], v[210:213], v[186:189], v[42:45]
	s_waitcnt lgkmcnt(0)
	v_mfma_f32_16x16x32_bf16 v[38:41], v[218:221], v[166:169], v[38:41]
	v_mfma_f32_16x16x32_bf16 v[34:37], v[218:221], v[186:189], v[34:37]
	s_setprio 1
	s_barrier
	v_readfirstlane_b32 s28, v151
	s_add_i32 s29, s29, 0x40180
	s_mov_b32 m0, s28
	v_readfirstlane_b32 s28, v152
	buffer_load_dwordx4 v134, s[76:79], s29 offen lds
	s_mov_b32 m0, s28
	s_nop 0
	buffer_load_dwordx4 v135, s[76:79], s29 offen lds
	s_waitcnt vmcnt(6)
	s_barrier
	s_setprio 0
	v_mfma_f32_16x16x32_bf16 v[28:31], v[190:193], v[222:225], v[28:31]
	v_mfma_f32_16x16x32_bf16 v[24:27], v[190:193], v[230:233], v[24:27]
	v_mfma_f32_16x16x32_bf16 v[20:23], v[198:201], v[222:225], v[20:23]
	v_mfma_f32_16x16x32_bf16 v[16:19], v[198:201], v[230:233], v[16:19]
	v_mfma_f32_16x16x32_bf16 v[12:15], v[206:209], v[222:225], v[12:15]
	v_mfma_f32_16x16x32_bf16 v[8:11], v[206:209], v[230:233], v[8:11]
	v_mfma_f32_16x16x32_bf16 v[4:7], v[214:217], v[222:225], v[4:7]
	v_mfma_f32_16x16x32_bf16 v[0:3], v[214:217], v[230:233], v[0:3]
	v_mfma_f32_16x16x32_bf16 v[28:31], v[194:197], v[226:229], v[28:31]
	v_mfma_f32_16x16x32_bf16 v[24:27], v[194:197], v[234:237], v[24:27]
	v_mfma_f32_16x16x32_bf16 v[20:23], v[202:205], v[226:229], v[20:23]
	v_mfma_f32_16x16x32_bf16 v[16:19], v[202:205], v[234:237], v[16:19]
	v_mfma_f32_16x16x32_bf16 v[12:15], v[210:213], v[226:229], v[12:15]
	v_mfma_f32_16x16x32_bf16 v[8:11], v[210:213], v[234:237], v[8:11]
	v_mfma_f32_16x16x32_bf16 v[4:7], v[218:221], v[226:229], v[4:7]
	v_mfma_f32_16x16x32_bf16 v[0:3], v[218:221], v[234:237], v[0:3]
	s_setprio 1
	s_add_i32 s26, s26, 2
	s_addk_i32 s27, 0x100
	s_cmp_lt_u32 s26, 12
	s_barrier
	s_cbranch_scc1 .LBB0_1657
; #define STAGE(P, BASE, br, kt) do { int _so = ((br) * K + (kt) * BK) * 2; \
;     __builtin_amdgcn_raw_ptr_buffer_load_lds(rs_##BASE, (__attribute__((address_space(3))) void*)((char*)(P) + tx * 16), 16, voff0, _so, 0, 0); \
;     __builtin_amdgcn_raw_ptr_buffer_load_lds(rs_##BASE, (__attribute__((address_space(3))) void*)((char*)(P) + tx * 16 + 8192), 16, voff1, _so, 0, 0); } while (0)
; #define LDA(dst, b, h) _Pragma("unroll") for (int m = 0; m < 4; ++m) _Pragma("unroll") for (int k = 0; k < 2; ++k) \
;     dst[m][k] = *reinterpret_cast<const bf16x8*>((char*)SA(b, h) + lds_byte(wr * 64 + m * 16 + fr, k * 32 + fq * 8))
; #define LDB(dst, b, h) _Pragma("unroll") for (int n = 0; n < 2; ++n) _Pragma("unroll") for (int k = 0; k < 2; ++k) \
;     dst[n][k] = *reinterpret_cast<const bf16x8*>((char*)SB(b, h) + lds_byte(wc * 32 + n * 16 + fr, k * 32 + fq * 8))
; #define MMA(ai, bj, At, Bt_) do { __builtin_amdgcn_s_setprio(1); \
;     _Pragma("unroll") for (int m = 0; m < 4; ++m) _Pragma("unroll") for (int n = 0; n < 2; ++n) _Pragma("unroll") for (int k = 0; k < 2; ++k) \
;       acc[ai][bj][m][n] = __builtin_amdgcn_mfma_f32_16x16x32_bf16(At[m][k], Bt_[n][k], acc[ai][bj][m][n], 0, 0, 0); \
;     __builtin_amdgcn_s_setprio(0); } while (0)
; #define WAIT_V(n) asm volatile("s_waitcnt vmcnt(" #n ")" ::: "memory")
; #define WAIT_L(n) asm volatile("s_waitcnt lgkmcnt(" #n ")" ::: "memory")
; #define BAR __builtin_amdgcn_s_barrier()
; template <class Epi> ...
;     ...
;   { LDB(B0, 0, 0); LDA(At, 0, 0); STAGE(SA(1, 1), A, brow + HALF, nt - 1);
;     BAR; WAIT_L(0); MMA(0, 0, At, B0); BAR;
;     LDB(B1, 0, 1); BAR; WAIT_L(0); MMA(0, 1, At, B1); BAR;
;     LDA(At, 0, 1); WAIT_V(4); BAR; WAIT_L(0); MMA(1, 0, At, B0); MMA(1, 1, At, B1); BAR; }
.Lpx2:
	v_readfirstlane_b32 s25, v155
	s_or_b32 s24, s24, 0x40780
	s_mov_b32 s6, s78
	s_mov_b32 s7, s79
	s_mov_b32 m0, s25
	v_readfirstlane_b32 s25, v154
	ds_read_b128 v[138:141], v153
	ds_read_b128 v[142:145], v153 offset:1024
	ds_read_b128 v[156:159], v153 offset:2048
	ds_read_b128 v[150:153], v153 offset:3072
	ds_read_b128 v[166:169], v133
	ds_read_b128 v[170:173], v133 offset:1024
	ds_read_b128 v[186:189], v132
	ds_read_b128 v[190:193], v132 offset:1024
	ds_read_b128 v[194:197], v131
	ds_read_b128 v[198:201], v131 offset:1024
	ds_read_b128 v[202:205], v130
	ds_read_b128 v[206:209], v130 offset:1024
	buffer_load_dwordx4 v134, s[4:7], s24 offen lds
	s_mov_b32 m0, s25
	s_nop 0
	buffer_load_dwordx4 v135, s[4:7], s24 offen lds
	s_barrier
	s_waitcnt lgkmcnt(0)
	s_setprio 0
	s_waitcnt lgkmcnt(7)
	v_mfma_f32_16x16x32_bf16 v[126:129], v[166:169], v[138:141], v[126:129]
	v_mfma_f32_16x16x32_bf16 v[122:125], v[166:169], v[156:159], v[122:125]
	s_waitcnt lgkmcnt(5)
	v_mfma_f32_16x16x32_bf16 v[118:121], v[186:189], v[138:141], v[118:121]
	v_mfma_f32_16x16x32_bf16 v[114:117], v[186:189], v[156:159], v[114:117]
	s_waitcnt lgkmcnt(3)
	v_mfma_f32_16x16x32_bf16 v[110:113], v[194:197], v[138:141], v[110:113]
	v_mfma_f32_16x16x32_bf16 v[106:109], v[194:197], v[156:159], v[106:109]
	s_waitcnt lgkmcnt(1)
	v_mfma_f32_16x16x32_bf16 v[102:105], v[202:205], v[138:141], v[102:105]
	v_mfma_f32_16x16x32_bf16 v[98:101], v[202:205], v[156:159], v[98:101]
	v_mfma_f32_16x16x32_bf16 v[126:129], v[170:173], v[142:145], v[126:129]
	v_mfma_f32_16x16x32_bf16 v[122:125], v[170:173], v[150:153], v[122:125]
	v_mfma_f32_16x16x32_bf16 v[118:121], v[190:193], v[142:145], v[118:121]
	v_mfma_f32_16x16x32_bf16 v[114:117], v[190:193], v[150:153], v[114:117]
	v_mfma_f32_16x16x32_bf16 v[110:113], v[198:201], v[142:145], v[110:113]
	v_mfma_f32_16x16x32_bf16 v[106:109], v[198:201], v[150:153], v[106:109]
	s_waitcnt lgkmcnt(0)
	v_mfma_f32_16x16x32_bf16 v[102:105], v[206:209], v[142:145], v[102:105]
	v_mfma_f32_16x16x32_bf16 v[98:101], v[206:209], v[150:153], v[98:101]
	s_setprio 1
	s_barrier
	ds_read_b128 v[210:213], v149
	ds_read_b128 v[214:217], v149 offset:1024
	ds_read_b128 v[218:221], v149 offset:2048
	ds_read_b128 v[146:149], v149 offset:3072
	s_barrier
	s_waitcnt lgkmcnt(0)
	s_setprio 0
	s_waitcnt lgkmcnt(3)
	v_mfma_f32_16x16x32_bf16 v[94:97], v[166:169], v[210:213], v[94:97]
	s_waitcnt lgkmcnt(1)
	v_mfma_f32_16x16x32_bf16 v[90:93], v[166:169], v[218:221], v[90:93]
	v_mfma_f32_16x16x32_bf16 v[82:85], v[186:189], v[218:221], v[82:85]
	v_mfma_f32_16x16x32_bf16 v[78:81], v[194:197], v[210:213], v[78:81]
	v_mfma_f32_16x16x32_bf16 v[66:69], v[202:205], v[218:221], v[66:69]
	v_mfma_f32_16x16x32_bf16 v[94:97], v[170:173], v[214:217], v[94:97]
	s_waitcnt lgkmcnt(0)
	v_mfma_f32_16x16x32_bf16 v[90:93], v[170:173], v[146:149], v[90:93]
	v_mfma_f32_16x16x32_bf16 v[86:89], v[186:189], v[210:213], v[86:89]
	v_mfma_f32_16x16x32_bf16 v[82:85], v[190:193], v[146:149], v[82:85]
	v_mfma_f32_16x16x32_bf16 v[78:81], v[198:201], v[214:217], v[78:81]
	v_mfma_f32_16x16x32_bf16 v[74:77], v[194:197], v[218:221], v[74:77]
	v_mfma_f32_16x16x32_bf16 v[70:73], v[202:205], v[210:213], v[70:73]
	v_mfma_f32_16x16x32_bf16 v[66:69], v[206:209], v[146:149], v[66:69]
	v_mfma_f32_16x16x32_bf16 v[166:169], v[190:193], v[214:217], v[86:89]
	v_mfma_f32_16x16x32_bf16 v[170:173], v[198:201], v[146:149], v[74:77]
	v_mfma_f32_16x16x32_bf16 v[186:189], v[206:209], v[214:217], v[70:73]
	s_setprio 1
	s_barrier
	s_nop 1
	ds_read_b128 v[70:73], v133 offset:16384
	ds_read_b128 v[74:77], v133 offset:17408
	ds_read_b128 v[86:89], v132 offset:16384
	ds_read_b128 v[190:193], v132 offset:17408
	ds_read_b128 v[194:197], v131 offset:16384
	ds_read_b128 v[198:201], v131 offset:17408
	ds_read_b128 v[202:205], v130 offset:16384
	ds_read_b128 v[206:209], v130 offset:17408
	s_waitcnt vmcnt(4)
	s_barrier
	s_waitcnt lgkmcnt(0)
	s_setprio 0
	s_waitcnt lgkmcnt(7)
	v_mfma_f32_16x16x32_bf16 v[62:65], v[70:73], v[138:141], v[62:65]
	s_waitcnt lgkmcnt(5)
	v_mfma_f32_16x16x32_bf16 v[50:53], v[86:89], v[156:159], v[50:53]
	s_waitcnt lgkmcnt(3)
	v_mfma_f32_16x16x32_bf16 v[46:49], v[194:197], v[138:141], v[46:49]
	v_mfma_f32_16x16x32_bf16 v[62:65], v[74:77], v[142:145], v[62:65]
	v_mfma_f32_16x16x32_bf16 v[58:61], v[70:73], v[156:159], v[58:61]
	v_mfma_f32_16x16x32_bf16 v[54:57], v[86:89], v[138:141], v[54:57]
	v_mfma_f32_16x16x32_bf16 v[50:53], v[190:193], v[150:153], v[50:53]
	s_waitcnt lgkmcnt(2)
	v_mfma_f32_16x16x32_bf16 v[46:49], v[198:201], v[142:145], v[46:49]
	v_mfma_f32_16x16x32_bf16 v[42:45], v[194:197], v[156:159], v[42:45]
	s_waitcnt lgkmcnt(1)
	v_mfma_f32_16x16x32_bf16 v[38:41], v[202:205], v[138:141], v[38:41]
	v_mfma_f32_16x16x32_bf16 v[34:37], v[202:205], v[156:159], v[34:37]
	v_mfma_f32_16x16x32_bf16 v[222:225], v[74:77], v[150:153], v[58:61]
	v_mfma_f32_16x16x32_bf16 v[226:229], v[190:193], v[142:145], v[54:57]
	v_mfma_f32_16x16x32_bf16 v[230:233], v[198:201], v[150:153], v[42:45]
	s_waitcnt lgkmcnt(0)
	v_mfma_f32_16x16x32_bf16 v[138:141], v[206:209], v[142:145], v[38:41]
	v_mfma_f32_16x16x32_bf16 v[142:145], v[206:209], v[150:153], v[34:37]
	s_setprio 1
	s_setprio 0
	v_mfma_f32_16x16x32_bf16 v[0:3], v[202:205], v[218:221], v[0:3]
	v_mfma_f32_16x16x32_bf16 v[28:31], v[70:73], v[210:213], v[28:31]
	v_mfma_f32_16x16x32_bf16 v[24:27], v[70:73], v[218:221], v[24:27]
	v_mfma_f32_16x16x32_bf16 v[20:23], v[86:89], v[210:213], v[20:23]
	v_mfma_f32_16x16x32_bf16 v[16:19], v[86:89], v[218:221], v[16:19]
	v_mfma_f32_16x16x32_bf16 v[12:15], v[194:197], v[210:213], v[12:15]
	v_mfma_f32_16x16x32_bf16 v[8:11], v[194:197], v[218:221], v[8:11]
	v_mfma_f32_16x16x32_bf16 v[4:7], v[202:205], v[210:213], v[4:7]
	v_mfma_f32_16x16x32_bf16 v[0:3], v[206:209], v[146:149], v[0:3]
	v_mfma_f32_16x16x32_bf16 v[150:153], v[74:77], v[214:217], v[28:31]
	v_mfma_f32_16x16x32_bf16 v[154:157], v[74:77], v[146:149], v[24:27]
	v_mfma_f32_16x16x32_bf16 v[158:161], v[190:193], v[214:217], v[20:23]
	v_mfma_f32_16x16x32_bf16 v[190:193], v[190:193], v[146:149], v[16:19]
	v_mfma_f32_16x16x32_bf16 v[234:237], v[198:201], v[214:217], v[12:15]
	v_mfma_f32_16x16x32_bf16 v[194:197], v[198:201], v[146:149], v[8:11]
	v_mfma_f32_16x16x32_bf16 v[198:201], v[206:209], v[214:217], v[4:7]
	s_setprio 1
	s_barrier
; #define LDA(dst, b, h) _Pragma("unroll") for (int m = 0; m < 4; ++m) _Pragma("unroll") for (int k = 0; k < 2; ++k) \
;     dst[m][k] = *reinterpret_cast<const bf16x8*>((char*)SA(b, h) + lds_byte(wr * 64 + m * 16 + fr, k * 32 + fq * 8))
; #define LDB(dst, b, h) _Pragma("unroll") for (int n = 0; n < 2; ++n) _Pragma("unroll") for (int k = 0; k < 2; ++k) \
;     dst[n][k] = *reinterpret_cast<const bf16x8*>((char*)SB(b, h) + lds_byte(wc * 32 + n * 16 + fr, k * 32 + fq * 8))
; #define MMA(ai, bj, At, Bt_) do { __builtin_amdgcn_s_setprio(1); \
;     _Pragma("unroll") for (int m = 0; m < 4; ++m) _Pragma("unroll") for (int n = 0; n < 2; ++n) _Pragma("unroll") for (int k = 0; k < 2; ++k) \
;       acc[ai][bj][m][n] = __builtin_amdgcn_mfma_f32_16x16x32_bf16(At[m][k], Bt_[n][k], acc[ai][bj][m][n], 0, 0, 0); \
;     __builtin_amdgcn_s_setprio(0); } while (0)
; #define WAIT_V(n) asm volatile("s_waitcnt vmcnt(" #n ")" ::: "memory")
; #define WAIT_L(n) asm volatile("s_waitcnt lgkmcnt(" #n ")" ::: "memory")
; #define BAR __builtin_amdgcn_s_barrier()
; template <class Epi> ...
;     ...
;   { LDB(B0, 1, 0); LDA(At, 1, 0); WAIT_V(2); BAR; WAIT_L(0); MMA(0, 0, At, B0); BAR;
;     LDB(B1, 1, 1); WAIT_V(0); BAR; WAIT_L(0); MMA(0, 1, At, B1); BAR;
;     LDA(At, 1, 1); BAR; WAIT_L(0); MMA(1, 0, At, B0); MMA(1, 1, At, B1); BAR; }
;   if (wr == 0) BAR;
	ds_read_b128 v[146:149], v137
	ds_read_b128 v[202:205], v137 offset:1024
	ds_read_b128 v[206:209], v137 offset:2048
	ds_read_b128 v[210:213], v137 offset:3072
	ds_read_b128 v[38:41], v133 offset:32768
	ds_read_b128 v[42:45], v133 offset:33792
	ds_read_b128 v[54:57], v132 offset:32768
	ds_read_b128 v[58:61], v132 offset:33792
	ds_read_b128 v[214:217], v131 offset:32768
	ds_read_b128 v[218:221], v131 offset:33792
	ds_read_b128 v[238:241], v130 offset:32768
	ds_read_b128 v[242:245], v130 offset:33792
	s_waitcnt vmcnt(2)
	s_barrier
	s_waitcnt lgkmcnt(0)
	s_setprio 0
	s_waitcnt lgkmcnt(7)
	v_mfma_f32_16x16x32_bf16 v[4:7], v[38:41], v[146:149], v[126:129]
	s_waitcnt lgkmcnt(6)
	v_mfma_f32_16x16x32_bf16 v[28:31], v[42:45], v[202:205], v[4:7]
	v_mfma_f32_16x16x32_bf16 v[4:7], v[38:41], v[206:209], v[122:125]
	v_mfma_f32_16x16x32_bf16 v[34:37], v[42:45], v[210:213], v[4:7]
	s_waitcnt lgkmcnt(5)
	v_mfma_f32_16x16x32_bf16 v[4:7], v[54:57], v[146:149], v[118:121]
	s_waitcnt lgkmcnt(4)
	v_mfma_f32_16x16x32_bf16 v[20:23], v[58:61], v[202:205], v[4:7]
	v_mfma_f32_16x16x32_bf16 v[4:7], v[54:57], v[206:209], v[114:117]
	v_mfma_f32_16x16x32_bf16 v[24:27], v[58:61], v[210:213], v[4:7]
	s_waitcnt lgkmcnt(3)
	v_mfma_f32_16x16x32_bf16 v[4:7], v[214:217], v[146:149], v[110:113]
	s_waitcnt lgkmcnt(2)
	v_mfma_f32_16x16x32_bf16 v[12:15], v[218:221], v[202:205], v[4:7]
	v_mfma_f32_16x16x32_bf16 v[4:7], v[214:217], v[206:209], v[106:109]
	v_mfma_f32_16x16x32_bf16 v[16:19], v[218:221], v[210:213], v[4:7]
	s_waitcnt lgkmcnt(1)
	v_mfma_f32_16x16x32_bf16 v[4:7], v[238:241], v[146:149], v[102:105]
	v_mfma_f32_16x16x32_bf16 v[8:11], v[238:241], v[206:209], v[98:101]
	s_waitcnt lgkmcnt(0)
	v_mfma_f32_16x16x32_bf16 v[4:7], v[242:245], v[202:205], v[4:7]
	v_mfma_f32_16x16x32_bf16 v[8:11], v[242:245], v[210:213], v[8:11]
	s_setprio 1
	s_barrier
	ds_read_b128 v[102:105], v136
	ds_read_b128 v[246:249], v136 offset:1024
	ds_read_b128 v[250:253], v136 offset:2048
	ds_read_b128 v[134:137], v136 offset:3072
	s_waitcnt vmcnt(0)
	s_barrier
	s_waitcnt lgkmcnt(0)
	s_setprio 0
	s_waitcnt lgkmcnt(3)
	v_mfma_f32_16x16x32_bf16 v[70:73], v[38:41], v[102:105], v[94:97]
	s_waitcnt lgkmcnt(1)
	v_mfma_f32_16x16x32_bf16 v[38:41], v[38:41], v[250:253], v[90:93]
	s_waitcnt lgkmcnt(0)
	v_mfma_f32_16x16x32_bf16 v[90:93], v[42:45], v[134:137], v[38:41]
	v_mfma_f32_16x16x32_bf16 v[38:41], v[54:57], v[102:105], v[166:169]
	v_mfma_f32_16x16x32_bf16 v[86:89], v[42:45], v[246:249], v[70:73]
	v_mfma_f32_16x16x32_bf16 v[70:73], v[58:61], v[246:249], v[38:41]
	v_mfma_f32_16x16x32_bf16 v[38:41], v[54:57], v[250:253], v[82:85]
	v_mfma_f32_16x16x32_bf16 v[74:77], v[58:61], v[134:137], v[38:41]
	v_mfma_f32_16x16x32_bf16 v[38:41], v[214:217], v[102:105], v[78:81]
	v_mfma_f32_16x16x32_bf16 v[54:57], v[218:221], v[246:249], v[38:41]
	v_mfma_f32_16x16x32_bf16 v[38:41], v[214:217], v[250:253], v[170:173]
	v_mfma_f32_16x16x32_bf16 v[58:61], v[218:221], v[134:137], v[38:41]
	v_mfma_f32_16x16x32_bf16 v[38:41], v[238:241], v[102:105], v[186:189]
	v_mfma_f32_16x16x32_bf16 v[42:45], v[238:241], v[250:253], v[66:69]
	v_mfma_f32_16x16x32_bf16 v[38:41], v[242:245], v[246:249], v[38:41]
	v_mfma_f32_16x16x32_bf16 v[42:45], v[242:245], v[134:137], v[42:45]
	s_setprio 1
	s_barrier
	ds_read_b128 v[106:109], v133 offset:49152
	ds_read_b128 v[110:113], v133 offset:50176
	ds_read_b128 v[118:121], v132 offset:49152
	ds_read_b128 v[166:169], v132 offset:50176
	ds_read_b128 v[170:173], v131 offset:49152
	ds_read_b128 v[186:189], v131 offset:50176
	ds_read_b128 v[214:217], v130 offset:49152
	ds_read_b128 v[130:133], v130 offset:50176
	s_barrier
	s_waitcnt lgkmcnt(0)
	s_setprio 0
	s_waitcnt lgkmcnt(7)
	v_mfma_f32_16x16x32_bf16 v[62:65], v[106:109], v[146:149], v[62:65]
	s_waitcnt lgkmcnt(6)
	v_mfma_f32_16x16x32_bf16 v[94:97], v[110:113], v[202:205], v[62:65]
	v_mfma_f32_16x16x32_bf16 v[62:65], v[106:109], v[206:209], v[222:225]
	v_mfma_f32_16x16x32_bf16 v[98:101], v[110:113], v[210:213], v[62:65]
	s_waitcnt lgkmcnt(5)
	v_mfma_f32_16x16x32_bf16 v[62:65], v[118:121], v[146:149], v[226:229]
	s_waitcnt lgkmcnt(3)
	v_mfma_f32_16x16x32_bf16 v[46:49], v[170:173], v[146:149], v[46:49]
	v_mfma_f32_16x16x32_bf16 v[78:81], v[166:169], v[202:205], v[62:65]
	v_mfma_f32_16x16x32_bf16 v[50:53], v[118:121], v[206:209], v[50:53]
	s_waitcnt lgkmcnt(2)
	v_mfma_f32_16x16x32_bf16 v[62:65], v[186:189], v[202:205], v[46:49]
	v_mfma_f32_16x16x32_bf16 v[46:49], v[170:173], v[206:209], v[230:233]
	v_mfma_f32_16x16x32_bf16 v[82:85], v[166:169], v[210:213], v[50:53]
	v_mfma_f32_16x16x32_bf16 v[66:69], v[186:189], v[210:213], v[46:49]
	s_waitcnt lgkmcnt(1)
	v_mfma_f32_16x16x32_bf16 v[46:49], v[214:217], v[146:149], v[138:141]
	v_mfma_f32_16x16x32_bf16 v[50:53], v[214:217], v[206:209], v[142:145]
	s_waitcnt lgkmcnt(0)
	v_mfma_f32_16x16x32_bf16 v[46:49], v[130:133], v[202:205], v[46:49]
	v_mfma_f32_16x16x32_bf16 v[50:53], v[130:133], v[210:213], v[50:53]
	s_setprio 1
	s_setprio 0
	v_mfma_f32_16x16x32_bf16 v[114:117], v[106:109], v[102:105], v[150:153]
	v_mfma_f32_16x16x32_bf16 v[106:109], v[106:109], v[250:253], v[154:157]
	v_mfma_f32_16x16x32_bf16 v[126:129], v[110:113], v[134:137], v[106:109]
	v_mfma_f32_16x16x32_bf16 v[106:109], v[118:121], v[102:105], v[158:161]
	v_mfma_f32_16x16x32_bf16 v[122:125], v[110:113], v[246:249], v[114:117]
	v_mfma_f32_16x16x32_bf16 v[114:117], v[166:169], v[246:249], v[106:109]
	v_mfma_f32_16x16x32_bf16 v[106:109], v[118:121], v[250:253], v[190:193]
	v_mfma_f32_16x16x32_bf16 v[118:121], v[166:169], v[134:137], v[106:109]
	v_mfma_f32_16x16x32_bf16 v[106:109], v[170:173], v[102:105], v[234:237]
	v_mfma_f32_16x16x32_bf16 v[110:113], v[170:173], v[250:253], v[194:197]
	v_mfma_f32_16x16x32_bf16 v[102:105], v[214:217], v[102:105], v[198:201]
	v_mfma_f32_16x16x32_bf16 v[0:3], v[214:217], v[250:253], v[0:3]
	v_mfma_f32_16x16x32_bf16 v[106:109], v[186:189], v[246:249], v[106:109]
	v_mfma_f32_16x16x32_bf16 v[110:113], v[186:189], v[134:137], v[110:113]
	v_mfma_f32_16x16x32_bf16 v[102:105], v[130:133], v[246:249], v[102:105]
	v_mfma_f32_16x16x32_bf16 v[0:3], v[130:133], v[134:137], v[0:3]
	s_setprio 1
	v_cmp_gt_u32_e32 vcc, s59, v32
	s_barrier
	s_and_saveexec_b64 s[4:5], vcc
	s_cbranch_execz .LBB0_1660
	s_barrier

; #define STAGE(P, BASE, br, kt) do { int _so = ((br) * K + (kt) * BK) * 2; \
;     __builtin_amdgcn_raw_ptr_buffer_load_lds(rs_##BASE, (__attribute__((address_space(3))) void*)((char*)(P) + tx * 16), 16, voff0, _so, 0, 0); \
;     __builtin_amdgcn_raw_ptr_buffer_load_lds(rs_##BASE, (__attribute__((address_space(3))) void*)((char*)(P) + tx * 16 + 8192), 16, voff1, _so, 0, 0); } while (0)
; #define LDA(dst, b, h) _Pragma("unroll") for (int m = 0; m < 4; ++m) _Pragma("unroll") for (int k = 0; k < 2; ++k) \
;     dst[m][k] = *reinterpret_cast<const bf16x8*>((char*)SA(b, h) + lds_byte(wr * 64 + m * 16 + fr, k * 32 + fq * 8))
; #define LDB(dst, b, h) _Pragma("unroll") for (int n = 0; n < 2; ++n) _Pragma("unroll") for (int k = 0; k < 2; ++k) \
;     dst[n][k] = *reinterpret_cast<const bf16x8*>((char*)SB(b, h) + lds_byte(wc * 32 + n * 16 + fr, k * 32 + fq * 8))
; #define MMA(ai, bj, At, Bt_) do { __builtin_amdgcn_s_setprio(1); \
;     _Pragma("unroll") for (int m = 0; m < 4; ++m) _Pragma("unroll") for (int n = 0; n < 2; ++n) _Pragma("unroll") for (int k = 0; k < 2; ++k) \
;       acc[ai][bj][m][n] = __builtin_amdgcn_mfma_f32_16x16x32_bf16(At[m][k], Bt_[n][k], acc[ai][bj][m][n], 0, 0, 0); \
;     __builtin_amdgcn_s_setprio(0); } while (0)
; #define WAIT_V(n) asm volatile("s_waitcnt vmcnt(" #n ")" ::: "memory")
; #define WAIT_L(n) asm volatile("s_waitcnt lgkmcnt(" #n ")" ::: "memory")
; #define BAR __builtin_amdgcn_s_barrier()
; #define SCHED __builtin_amdgcn_sched_barrier(0)
; template <class Epi> ...
;     ...
;     LDB(B0, 0, 0); SCHED; LDA(At, 0, 0); STAGE(SA(1, 1), A, brow + HALF, t + 1);
;     WAIT_L(8); BAR; WAIT_L(0); MMA(0, 0, At, B0); BAR; SCHED;
;     LDB(B1, 0, 1); STAGE(SB(0, 0), Bt, bcol, t + 2);
;     BAR; WAIT_L(0); MMA(0, 1, At, B1); BAR;
;     LDA(At, 0, 1); STAGE(SA(0, 0), A, brow, t + 2);
;     BAR; WAIT_L(0); MMA(1, 0, At, B0); BAR; SCHED;
;     STAGE(SB(0, 1), Bt, bcol + HALF, t + 2);
;     WAIT_V(6); BAR; MMA(1, 1, At, B1); BAR;
.Lpk3:
	ds_read_b128 v[156:159], v155
	ds_read_b128 v[166:169], v155 offset:1024
	ds_read_b128 v[170:173], v155 offset:2048
	ds_read_b128 v[186:189], v155 offset:3072
	s_add_i32 s29, s19, s28
	v_readfirstlane_b32 s31, v152
	s_add_i32 s30, s29, 0x40080
	s_mov_b32 m0, s31
	v_readfirstlane_b32 s31, v151
	ds_read_b128 v[190:193], v143
	ds_read_b128 v[194:197], v143 offset:1024
	ds_read_b128 v[198:201], v142
	ds_read_b128 v[202:205], v142 offset:1024
	ds_read_b128 v[206:209], v141
	ds_read_b128 v[210:213], v141 offset:1024
	ds_read_b128 v[214:217], v140
	ds_read_b128 v[218:221], v140 offset:1024
	buffer_load_dwordx4 v32, s[4:7], s30 offen lds
	s_mov_b32 m0, s31
	s_nop 0
	buffer_load_dwordx4 v130, s[4:7], s30 offen lds
	s_waitcnt lgkmcnt(8)
	s_barrier
	s_waitcnt lgkmcnt(0)
	s_setprio 0
	s_waitcnt lgkmcnt(7)
	v_mfma_f32_16x16x32_bf16 v[126:129], v[190:193], v[156:159], 0
	v_mfma_f32_16x16x32_bf16 v[122:125], v[190:193], v[170:173], 0
	s_waitcnt lgkmcnt(5)
	v_mfma_f32_16x16x32_bf16 v[118:121], v[198:201], v[156:159], 0
	v_mfma_f32_16x16x32_bf16 v[114:117], v[198:201], v[170:173], 0
	s_waitcnt lgkmcnt(3)
	v_mfma_f32_16x16x32_bf16 v[110:113], v[206:209], v[156:159], 0
	v_mfma_f32_16x16x32_bf16 v[106:109], v[206:209], v[170:173], 0
	s_waitcnt lgkmcnt(1)
	v_mfma_f32_16x16x32_bf16 v[102:105], v[214:217], v[156:159], 0
	v_mfma_f32_16x16x32_bf16 v[98:101], v[214:217], v[170:173], 0
	v_mfma_f32_16x16x32_bf16 v[126:129], v[194:197], v[166:169], v[126:129]
	v_mfma_f32_16x16x32_bf16 v[122:125], v[194:197], v[186:189], v[122:125]
	v_mfma_f32_16x16x32_bf16 v[118:121], v[202:205], v[166:169], v[118:121]
	v_mfma_f32_16x16x32_bf16 v[114:117], v[202:205], v[186:189], v[114:117]
	v_mfma_f32_16x16x32_bf16 v[110:113], v[210:213], v[166:169], v[110:113]
	v_mfma_f32_16x16x32_bf16 v[106:109], v[210:213], v[186:189], v[106:109]
	s_waitcnt lgkmcnt(0)
	v_mfma_f32_16x16x32_bf16 v[102:105], v[218:221], v[166:169], v[102:105]
	v_mfma_f32_16x16x32_bf16 v[98:101], v[218:221], v[186:189], v[98:101]
	s_setprio 1
	s_barrier
	s_add_i32 s30, s18, s28
	v_readfirstlane_b32 s34, v137
	s_add_i32 s31, s30, 0x100
	s_mov_b32 m0, s34
	v_readfirstlane_b32 s34, v139
	ds_read_b128 v[222:225], v149
	ds_read_b128 v[226:229], v149 offset:1024
	ds_read_b128 v[230:233], v149 offset:2048
	ds_read_b128 v[234:237], v149 offset:3072
	buffer_load_dwordx4 v32, s[76:79], s31 offen lds
	s_mov_b32 m0, s34
	s_nop 0
	buffer_load_dwordx4 v130, s[76:79], s31 offen lds
	s_barrier
	s_waitcnt lgkmcnt(0)
	s_setprio 0
	s_waitcnt lgkmcnt(3)
	v_mfma_f32_16x16x32_bf16 v[94:97], v[190:193], v[222:225], 0
	s_waitcnt lgkmcnt(1)
	v_mfma_f32_16x16x32_bf16 v[90:93], v[190:193], v[230:233], 0
	v_mfma_f32_16x16x32_bf16 v[86:89], v[198:201], v[222:225], 0
	v_mfma_f32_16x16x32_bf16 v[82:85], v[198:201], v[230:233], 0
	v_mfma_f32_16x16x32_bf16 v[78:81], v[206:209], v[222:225], 0
	v_mfma_f32_16x16x32_bf16 v[74:77], v[206:209], v[230:233], 0
	v_mfma_f32_16x16x32_bf16 v[70:73], v[214:217], v[222:225], 0
	v_mfma_f32_16x16x32_bf16 v[66:69], v[214:217], v[230:233], 0
	v_mfma_f32_16x16x32_bf16 v[94:97], v[194:197], v[226:229], v[94:97]
	s_waitcnt lgkmcnt(0)
	v_mfma_f32_16x16x32_bf16 v[90:93], v[194:197], v[234:237], v[90:93]
	v_mfma_f32_16x16x32_bf16 v[86:89], v[202:205], v[226:229], v[86:89]
	v_mfma_f32_16x16x32_bf16 v[82:85], v[202:205], v[234:237], v[82:85]
	v_mfma_f32_16x16x32_bf16 v[78:81], v[210:213], v[226:229], v[78:81]
	v_mfma_f32_16x16x32_bf16 v[74:77], v[210:213], v[234:237], v[74:77]
	v_mfma_f32_16x16x32_bf16 v[70:73], v[218:221], v[226:229], v[70:73]
	v_mfma_f32_16x16x32_bf16 v[66:69], v[218:221], v[234:237], v[66:69]
	s_setprio 1
	v_readfirstlane_b32 s34, v136
	s_add_i32 s31, s29, 0x100
	s_mov_b32 m0, s34
	v_readfirstlane_b32 s34, v135
	s_barrier
	ds_read_b128 v[190:193], v143 offset:16384
	ds_read_b128 v[194:197], v143 offset:17408
	ds_read_b128 v[198:201], v142 offset:16384
	ds_read_b128 v[202:205], v142 offset:17408
	ds_read_b128 v[206:209], v141 offset:16384
	ds_read_b128 v[210:213], v141 offset:17408
	ds_read_b128 v[214:217], v140 offset:16384
	ds_read_b128 v[218:221], v140 offset:17408
	buffer_load_dwordx4 v32, s[4:7], s31 offen lds
	s_mov_b32 m0, s34
	s_nop 0
	buffer_load_dwordx4 v130, s[4:7], s31 offen lds
	s_barrier
	s_waitcnt lgkmcnt(0)
	s_setprio 0
	s_waitcnt lgkmcnt(7)
	v_mfma_f32_16x16x32_bf16 v[62:65], v[190:193], v[156:159], 0
	v_mfma_f32_16x16x32_bf16 v[58:61], v[190:193], v[170:173], 0
	s_waitcnt lgkmcnt(5)
	v_mfma_f32_16x16x32_bf16 v[54:57], v[198:201], v[156:159], 0
	v_mfma_f32_16x16x32_bf16 v[50:53], v[198:201], v[170:173], 0
	s_waitcnt lgkmcnt(3)
	v_mfma_f32_16x16x32_bf16 v[46:49], v[206:209], v[156:159], 0
	v_mfma_f32_16x16x32_bf16 v[42:45], v[206:209], v[170:173], 0
	s_waitcnt lgkmcnt(1)
	v_mfma_f32_16x16x32_bf16 v[38:41], v[214:217], v[156:159], 0
	v_mfma_f32_16x16x32_bf16 v[34:37], v[214:217], v[170:173], 0
	v_mfma_f32_16x16x32_bf16 v[62:65], v[194:197], v[166:169], v[62:65]
	v_mfma_f32_16x16x32_bf16 v[58:61], v[194:197], v[186:189], v[58:61]
	v_mfma_f32_16x16x32_bf16 v[54:57], v[202:205], v[166:169], v[54:57]
	v_mfma_f32_16x16x32_bf16 v[50:53], v[202:205], v[186:189], v[50:53]
	v_mfma_f32_16x16x32_bf16 v[46:49], v[210:213], v[166:169], v[46:49]
	v_mfma_f32_16x16x32_bf16 v[42:45], v[210:213], v[186:189], v[42:45]
	s_waitcnt lgkmcnt(0)
	v_mfma_f32_16x16x32_bf16 v[38:41], v[218:221], v[166:169], v[38:41]
	v_mfma_f32_16x16x32_bf16 v[34:37], v[218:221], v[186:189], v[34:37]
	s_setprio 1
	s_barrier
	v_readfirstlane_b32 s34, v134
	s_add_i32 s31, s30, 0x40100
	s_mov_b32 m0, s34
	v_readfirstlane_b32 s34, v138
	buffer_load_dwordx4 v32, s[76:79], s31 offen lds
	s_mov_b32 m0, s34
	s_nop 0
	buffer_load_dwordx4 v130, s[76:79], s31 offen lds
	s_waitcnt vmcnt(6)
	s_barrier
; #define STAGE(P, BASE, br, kt) do { int _so = ((br) * K + (kt) * BK) * 2; \
;     __builtin_amdgcn_raw_ptr_buffer_load_lds(rs_##BASE, (__attribute__((address_space(3))) void*)((char*)(P) + tx * 16), 16, voff0, _so, 0, 0); \
;     __builtin_amdgcn_raw_ptr_buffer_load_lds(rs_##BASE, (__attribute__((address_space(3))) void*)((char*)(P) + tx * 16 + 8192), 16, voff1, _so, 0, 0); } while (0)
; #define LDA(dst, b, h) _Pragma("unroll") for (int m = 0; m < 4; ++m) _Pragma("unroll") for (int k = 0; k < 2; ++k) \
;     dst[m][k] = *reinterpret_cast<const bf16x8*>((char*)SA(b, h) + lds_byte(wr * 64 + m * 16 + fr, k * 32 + fq * 8))
; #define LDB(dst, b, h) _Pragma("unroll") for (int n = 0; n < 2; ++n) _Pragma("unroll") for (int k = 0; k < 2; ++k) \
;     dst[n][k] = *reinterpret_cast<const bf16x8*>((char*)SB(b, h) + lds_byte(wc * 32 + n * 16 + fr, k * 32 + fq * 8))
; #define MMA(ai, bj, At, Bt_) do { __builtin_amdgcn_s_setprio(1); \
;     _Pragma("unroll") for (int m = 0; m < 4; ++m) _Pragma("unroll") for (int n = 0; n < 2; ++n) _Pragma("unroll") for (int k = 0; k < 2; ++k) \
;       acc[ai][bj][m][n] = __builtin_amdgcn_mfma_f32_16x16x32_bf16(At[m][k], Bt_[n][k], acc[ai][bj][m][n], 0, 0, 0); \
;     __builtin_amdgcn_s_setprio(0); } while (0)
; #define WAIT_V(n) asm volatile("s_waitcnt vmcnt(" #n ")" ::: "memory")
; #define WAIT_L(n) asm volatile("s_waitcnt lgkmcnt(" #n ")" ::: "memory")
; #define BAR __builtin_amdgcn_s_barrier()
; #define SCHED __builtin_amdgcn_sched_barrier(0)
; template <class Epi> ...
;     ...
;     WAIT_V(6); BAR; MMA(1, 1, At, B1); BAR;
;     LDB(B0, 1, 0); SCHED; LDA(At, 1, 0); STAGE(SA(0, 1), A, brow + HALF, t + 2);
;     WAIT_L(8); BAR; WAIT_L(0); MMA(0, 0, At, B0); BAR; SCHED;
;     LDB(B1, 1, 1); STAGE(SB(1, 0), Bt, bcol, t + 3);
;     BAR; WAIT_L(0); MMA(0, 1, At, B1); BAR;
;     LDA(At, 1, 1); STAGE(SA(1, 0), A, brow, t + 3);
	s_setprio 0
	v_mfma_f32_16x16x32_bf16 v[28:31], v[190:193], v[222:225], 0
	v_mfma_f32_16x16x32_bf16 v[24:27], v[190:193], v[230:233], 0
	v_mfma_f32_16x16x32_bf16 v[20:23], v[198:201], v[222:225], 0
	v_mfma_f32_16x16x32_bf16 v[16:19], v[198:201], v[230:233], 0
	v_mfma_f32_16x16x32_bf16 v[12:15], v[206:209], v[222:225], 0
	v_mfma_f32_16x16x32_bf16 v[8:11], v[206:209], v[230:233], 0
	v_mfma_f32_16x16x32_bf16 v[4:7], v[214:217], v[222:225], 0
	v_mfma_f32_16x16x32_bf16 v[0:3], v[214:217], v[230:233], 0
	v_mfma_f32_16x16x32_bf16 v[28:31], v[194:197], v[226:229], v[28:31]
	v_mfma_f32_16x16x32_bf16 v[24:27], v[194:197], v[234:237], v[24:27]
	v_mfma_f32_16x16x32_bf16 v[20:23], v[202:205], v[226:229], v[20:23]
	v_mfma_f32_16x16x32_bf16 v[16:19], v[202:205], v[234:237], v[16:19]
	v_mfma_f32_16x16x32_bf16 v[12:15], v[210:213], v[226:229], v[12:15]
	v_mfma_f32_16x16x32_bf16 v[8:11], v[210:213], v[234:237], v[8:11]
	v_mfma_f32_16x16x32_bf16 v[4:7], v[218:221], v[226:229], v[4:7]
	v_mfma_f32_16x16x32_bf16 v[0:3], v[218:221], v[234:237], v[0:3]
	s_setprio 1
	s_barrier
	ds_read_b128 v[156:159], v145
	ds_read_b128 v[166:169], v145 offset:1024
	ds_read_b128 v[170:173], v145 offset:2048
	ds_read_b128 v[186:189], v145 offset:3072
	v_readfirstlane_b32 s34, v132
	s_add_i32 s31, s29, 0x40100
	s_mov_b32 m0, s34
	v_readfirstlane_b32 s34, v131
	ds_read_b128 v[190:193], v143 offset:32768
	ds_read_b128 v[194:197], v143 offset:33792
	ds_read_b128 v[198:201], v142 offset:32768
	ds_read_b128 v[202:205], v142 offset:33792
	ds_read_b128 v[206:209], v141 offset:32768
	ds_read_b128 v[210:213], v141 offset:33792
	ds_read_b128 v[214:217], v140 offset:32768
	ds_read_b128 v[218:221], v140 offset:33792
	buffer_load_dwordx4 v32, s[4:7], s31 offen lds
	s_mov_b32 m0, s34
	s_nop 0
	buffer_load_dwordx4 v130, s[4:7], s31 offen lds
	s_waitcnt lgkmcnt(8)
	s_barrier
	s_waitcnt lgkmcnt(0)
	s_setprio 0
	s_waitcnt lgkmcnt(7)
	v_mfma_f32_16x16x32_bf16 v[126:129], v[190:193], v[156:159], v[126:129]
	v_mfma_f32_16x16x32_bf16 v[122:125], v[190:193], v[170:173], v[122:125]
	s_waitcnt lgkmcnt(5)
	v_mfma_f32_16x16x32_bf16 v[118:121], v[198:201], v[156:159], v[118:121]
	v_mfma_f32_16x16x32_bf16 v[114:117], v[198:201], v[170:173], v[114:117]
	s_waitcnt lgkmcnt(3)
	v_mfma_f32_16x16x32_bf16 v[110:113], v[206:209], v[156:159], v[110:113]
	v_mfma_f32_16x16x32_bf16 v[106:109], v[206:209], v[170:173], v[106:109]
	s_waitcnt lgkmcnt(1)
	v_mfma_f32_16x16x32_bf16 v[102:105], v[214:217], v[156:159], v[102:105]
	v_mfma_f32_16x16x32_bf16 v[98:101], v[214:217], v[170:173], v[98:101]
	v_mfma_f32_16x16x32_bf16 v[126:129], v[194:197], v[166:169], v[126:129]
	v_mfma_f32_16x16x32_bf16 v[122:125], v[194:197], v[186:189], v[122:125]
	v_mfma_f32_16x16x32_bf16 v[118:121], v[202:205], v[166:169], v[118:121]
	v_mfma_f32_16x16x32_bf16 v[114:117], v[202:205], v[186:189], v[114:117]
	v_mfma_f32_16x16x32_bf16 v[110:113], v[210:213], v[166:169], v[110:113]
	v_mfma_f32_16x16x32_bf16 v[106:109], v[210:213], v[186:189], v[106:109]
	s_waitcnt lgkmcnt(0)
	v_mfma_f32_16x16x32_bf16 v[102:105], v[218:221], v[166:169], v[102:105]
	v_mfma_f32_16x16x32_bf16 v[98:101], v[218:221], v[186:189], v[98:101]
	s_setprio 1
	s_barrier
	v_readfirstlane_b32 s34, v146
	s_add_i32 s31, s30, 0x180
	s_mov_b32 m0, s34
	v_readfirstlane_b32 s34, v147
	ds_read_b128 v[222:225], v144
	ds_read_b128 v[226:229], v144 offset:1024
	ds_read_b128 v[230:233], v144 offset:2048
	ds_read_b128 v[234:237], v144 offset:3072
	buffer_load_dwordx4 v32, s[76:79], s31 offen lds
	s_mov_b32 m0, s34
	s_nop 0
	buffer_load_dwordx4 v130, s[76:79], s31 offen lds
	s_barrier
	s_waitcnt lgkmcnt(0)
	s_setprio 0
	s_waitcnt lgkmcnt(3)
	v_mfma_f32_16x16x32_bf16 v[94:97], v[190:193], v[222:225], v[94:97]
	s_waitcnt lgkmcnt(1)
	v_mfma_f32_16x16x32_bf16 v[90:93], v[190:193], v[230:233], v[90:93]
	v_mfma_f32_16x16x32_bf16 v[86:89], v[198:201], v[222:225], v[86:89]
	v_mfma_f32_16x16x32_bf16 v[82:85], v[198:201], v[230:233], v[82:85]
	v_mfma_f32_16x16x32_bf16 v[78:81], v[206:209], v[222:225], v[78:81]
	v_mfma_f32_16x16x32_bf16 v[74:77], v[206:209], v[230:233], v[74:77]
	v_mfma_f32_16x16x32_bf16 v[70:73], v[214:217], v[222:225], v[70:73]
	v_mfma_f32_16x16x32_bf16 v[66:69], v[214:217], v[230:233], v[66:69]
	v_mfma_f32_16x16x32_bf16 v[94:97], v[194:197], v[226:229], v[94:97]
	s_waitcnt lgkmcnt(0)
	v_mfma_f32_16x16x32_bf16 v[90:93], v[194:197], v[234:237], v[90:93]
	v_mfma_f32_16x16x32_bf16 v[86:89], v[202:205], v[226:229], v[86:89]
	v_mfma_f32_16x16x32_bf16 v[82:85], v[202:205], v[234:237], v[82:85]
	v_mfma_f32_16x16x32_bf16 v[78:81], v[210:213], v[226:229], v[78:81]
	v_mfma_f32_16x16x32_bf16 v[74:77], v[210:213], v[234:237], v[74:77]
	v_mfma_f32_16x16x32_bf16 v[70:73], v[218:221], v[226:229], v[70:73]
	v_mfma_f32_16x16x32_bf16 v[66:69], v[218:221], v[234:237], v[66:69]
	s_setprio 1
	v_readfirstlane_b32 s31, v148
	s_addk_i32 s29, 0x180
	s_mov_b32 m0, s31
	v_readfirstlane_b32 s31, v150
	s_barrier
	ds_read_b128 v[190:193], v143 offset:49152
	ds_read_b128 v[194:197], v143 offset:50176
	ds_read_b128 v[198:201], v142 offset:49152
	ds_read_b128 v[202:205], v142 offset:50176
	ds_read_b128 v[206:209], v141 offset:49152
	ds_read_b128 v[210:213], v141 offset:50176
	ds_read_b128 v[214:217], v140 offset:49152
	ds_read_b128 v[218:221], v140 offset:50176
	buffer_load_dwordx4 v32, s[4:7], s29 offen lds
	s_mov_b32 m0, s31
	s_nop 0
	buffer_load_dwordx4 v130, s[4:7], s29 offen lds
	s_barrier
; #define STAGE(P, BASE, br, kt) do { int _so = ((br) * K + (kt) * BK) * 2; \
;     __builtin_amdgcn_raw_ptr_buffer_load_lds(rs_##BASE, (__attribute__((address_space(3))) void*)((char*)(P) + tx * 16), 16, voff0, _so, 0, 0); \
;     __builtin_amdgcn_raw_ptr_buffer_load_lds(rs_##BASE, (__attribute__((address_space(3))) void*)((char*)(P) + tx * 16 + 8192), 16, voff1, _so, 0, 0); } while (0)
; #define LDA(dst, b, h) _Pragma("unroll") for (int m = 0; m < 4; ++m) _Pragma("unroll") for (int k = 0; k < 2; ++k) \
;     dst[m][k] = *reinterpret_cast<const bf16x8*>((char*)SA(b, h) + lds_byte(wr * 64 + m * 16 + fr, k * 32 + fq * 8))
; #define LDB(dst, b, h) _Pragma("unroll") for (int n = 0; n < 2; ++n) _Pragma("unroll") for (int k = 0; k < 2; ++k) \
;     dst[n][k] = *reinterpret_cast<const bf16x8*>((char*)SB(b, h) + lds_byte(wc * 32 + n * 16 + fr, k * 32 + fq * 8))
; #define MMA(ai, bj, At, Bt_) do { __builtin_amdgcn_s_setprio(1); \
;     _Pragma("unroll") for (int m = 0; m < 4; ++m) _Pragma("unroll") for (int n = 0; n < 2; ++n) _Pragma("unroll") for (int k = 0; k < 2; ++k) \
;       acc[ai][bj][m][n] = __builtin_amdgcn_mfma_f32_16x16x32_bf16(At[m][k], Bt_[n][k], acc[ai][bj][m][n], 0, 0, 0); \
;     __builtin_amdgcn_s_setprio(0); } while (0)
; #define WAIT_V(n) asm volatile("s_waitcnt vmcnt(" #n ")" ::: "memory")
; #define WAIT_L(n) asm volatile("s_waitcnt lgkmcnt(" #n ")" ::: "memory")
; #define BAR __builtin_amdgcn_s_barrier()
; template <class Epi> ...
;     ...
;     LDB(B0, 0, 0); SCHED; LDA(At, 0, 0); STAGE(SA(1, 1), A, brow + HALF, t + 1);
;     WAIT_L(8); BAR; WAIT_L(0); MMA(0, 0, At, B0); BAR; SCHED;
;     LDB(B1, 0, 1); STAGE(SB(0, 0), Bt, bcol, t + 2);
;     BAR; WAIT_L(0); MMA(0, 1, At, B1); BAR;
;     LDA(At, 0, 1); STAGE(SA(0, 0), A, brow, t + 2);
;     BAR; WAIT_L(0); MMA(1, 0, At, B0); BAR; SCHED;
;     STAGE(SB(0, 1), Bt, bcol + HALF, t + 2);
;     WAIT_V(6); BAR; MMA(1, 1, At, B1); BAR;
;     LDB(B0, 1, 0); SCHED; LDA(At, 1, 0); STAGE(SA(0, 1), A, brow + HALF, t + 2);
;     WAIT_L(8); BAR; WAIT_L(0); MMA(0, 0, At, B0); BAR; SCHED;
;     LDB(B1, 1, 1); STAGE(SB(1, 0), Bt, bcol, t + 3);
;     BAR; WAIT_L(0); MMA(0, 1, At, B1); BAR;
;     LDA(At, 1, 1); STAGE(SA(1, 0), A, brow, t + 3);
;     BAR; WAIT_L(0); MMA(1, 0, At, B0); BAR; SCHED;
;     STAGE(SB(1, 1), Bt, bcol + HALF, t + 3);
;     WAIT_V(6); BAR; MMA(1, 1, At, B1); BAR;
	s_waitcnt lgkmcnt(0)
	s_setprio 0
	s_waitcnt lgkmcnt(7)
	v_mfma_f32_16x16x32_bf16 v[62:65], v[190:193], v[156:159], v[62:65]
	v_mfma_f32_16x16x32_bf16 v[58:61], v[190:193], v[170:173], v[58:61]
	s_waitcnt lgkmcnt(5)
	v_mfma_f32_16x16x32_bf16 v[54:57], v[198:201], v[156:159], v[54:57]
	v_mfma_f32_16x16x32_bf16 v[50:53], v[198:201], v[170:173], v[50:53]
	s_waitcnt lgkmcnt(3)
	v_mfma_f32_16x16x32_bf16 v[46:49], v[206:209], v[156:159], v[46:49]
	v_mfma_f32_16x16x32_bf16 v[42:45], v[206:209], v[170:173], v[42:45]
	s_waitcnt lgkmcnt(1)
	v_mfma_f32_16x16x32_bf16 v[38:41], v[214:217], v[156:159], v[38:41]
	v_mfma_f32_16x16x32_bf16 v[34:37], v[214:217], v[170:173], v[34:37]
	v_mfma_f32_16x16x32_bf16 v[62:65], v[194:197], v[166:169], v[62:65]
	v_mfma_f32_16x16x32_bf16 v[58:61], v[194:197], v[186:189], v[58:61]
	v_mfma_f32_16x16x32_bf16 v[54:57], v[202:205], v[166:169], v[54:57]
	v_mfma_f32_16x16x32_bf16 v[50:53], v[202:205], v[186:189], v[50:53]
	v_mfma_f32_16x16x32_bf16 v[46:49], v[210:213], v[166:169], v[46:49]
	v_mfma_f32_16x16x32_bf16 v[42:45], v[210:213], v[186:189], v[42:45]
	s_waitcnt lgkmcnt(0)
	v_mfma_f32_16x16x32_bf16 v[38:41], v[218:221], v[166:169], v[38:41]
	v_mfma_f32_16x16x32_bf16 v[34:37], v[218:221], v[186:189], v[34:37]
	s_setprio 1
	s_barrier
	v_readfirstlane_b32 s29, v153
	s_add_i32 s30, s30, 0x40180
	s_mov_b32 m0, s29
	v_readfirstlane_b32 s29, v154
	buffer_load_dwordx4 v32, s[76:79], s30 offen lds
	s_mov_b32 m0, s29
	s_nop 0
	buffer_load_dwordx4 v130, s[76:79], s30 offen lds
	s_waitcnt vmcnt(6)
	s_barrier
	s_setprio 0
	v_mfma_f32_16x16x32_bf16 v[28:31], v[190:193], v[222:225], v[28:31]
	v_mfma_f32_16x16x32_bf16 v[24:27], v[190:193], v[230:233], v[24:27]
	v_mfma_f32_16x16x32_bf16 v[20:23], v[198:201], v[222:225], v[20:23]
	v_mfma_f32_16x16x32_bf16 v[16:19], v[198:201], v[230:233], v[16:19]
	v_mfma_f32_16x16x32_bf16 v[12:15], v[206:209], v[222:225], v[12:15]
	v_mfma_f32_16x16x32_bf16 v[8:11], v[206:209], v[230:233], v[8:11]
	v_mfma_f32_16x16x32_bf16 v[4:7], v[214:217], v[222:225], v[4:7]
	v_mfma_f32_16x16x32_bf16 v[0:3], v[214:217], v[230:233], v[0:3]
	v_mfma_f32_16x16x32_bf16 v[28:31], v[194:197], v[226:229], v[28:31]
	v_mfma_f32_16x16x32_bf16 v[24:27], v[194:197], v[234:237], v[24:27]
	v_mfma_f32_16x16x32_bf16 v[20:23], v[202:205], v[226:229], v[20:23]
	v_mfma_f32_16x16x32_bf16 v[16:19], v[202:205], v[234:237], v[16:19]
	v_mfma_f32_16x16x32_bf16 v[12:15], v[210:213], v[226:229], v[12:15]
	v_mfma_f32_16x16x32_bf16 v[8:11], v[210:213], v[234:237], v[8:11]
	v_mfma_f32_16x16x32_bf16 v[4:7], v[218:221], v[226:229], v[4:7]
	v_mfma_f32_16x16x32_bf16 v[0:3], v[218:221], v[234:237], v[0:3]
	s_setprio 1
	s_add_i32 s27, s27, 2
	s_addk_i32 s28, 0x100
	s_cmp_lt_u32 s27, 12
	s_barrier
	s_cbranch_scc1 .LBB0_1682
	s_branch .Lpx3
.LBB0_1682:
	ds_read_b128 v[156:159], v155
	ds_read_b128 v[166:169], v155 offset:1024
	ds_read_b128 v[170:173], v155 offset:2048
	ds_read_b128 v[186:189], v155 offset:3072
	s_add_i32 s29, s19, s28
	v_readfirstlane_b32 s31, v152
	s_add_i32 s30, s29, 0x40080
	s_mov_b32 m0, s31
	v_readfirstlane_b32 s31, v151
	ds_read_b128 v[190:193], v143
	ds_read_b128 v[194:197], v143 offset:1024
	ds_read_b128 v[198:201], v142
	ds_read_b128 v[202:205], v142 offset:1024
	ds_read_b128 v[206:209], v141
	ds_read_b128 v[210:213], v141 offset:1024
	ds_read_b128 v[214:217], v140
	ds_read_b128 v[218:221], v140 offset:1024
	buffer_load_dwordx4 v32, s[4:7], s30 offen lds
	s_mov_b32 m0, s31
	s_nop 0
	buffer_load_dwordx4 v130, s[4:7], s30 offen lds
	s_waitcnt lgkmcnt(8)
	s_barrier
	s_waitcnt lgkmcnt(0)
	s_setprio 0
	s_waitcnt lgkmcnt(7)
	v_mfma_f32_16x16x32_bf16 v[126:129], v[190:193], v[156:159], v[126:129]
	v_mfma_f32_16x16x32_bf16 v[122:125], v[190:193], v[170:173], v[122:125]
	s_waitcnt lgkmcnt(5)
	v_mfma_f32_16x16x32_bf16 v[118:121], v[198:201], v[156:159], v[118:121]
	v_mfma_f32_16x16x32_bf16 v[114:117], v[198:201], v[170:173], v[114:117]
	s_waitcnt lgkmcnt(3)
	v_mfma_f32_16x16x32_bf16 v[110:113], v[206:209], v[156:159], v[110:113]
	v_mfma_f32_16x16x32_bf16 v[106:109], v[206:209], v[170:173], v[106:109]
	s_waitcnt lgkmcnt(1)
	v_mfma_f32_16x16x32_bf16 v[102:105], v[214:217], v[156:159], v[102:105]
	v_mfma_f32_16x16x32_bf16 v[98:101], v[214:217], v[170:173], v[98:101]
	v_mfma_f32_16x16x32_bf16 v[126:129], v[194:197], v[166:169], v[126:129]
	v_mfma_f32_16x16x32_bf16 v[122:125], v[194:197], v[186:189], v[122:125]
	v_mfma_f32_16x16x32_bf16 v[118:121], v[202:205], v[166:169], v[118:121]
	v_mfma_f32_16x16x32_bf16 v[114:117], v[202:205], v[186:189], v[114:117]
	v_mfma_f32_16x16x32_bf16 v[110:113], v[210:213], v[166:169], v[110:113]
	v_mfma_f32_16x16x32_bf16 v[106:109], v[210:213], v[186:189], v[106:109]
	s_waitcnt lgkmcnt(0)
	v_mfma_f32_16x16x32_bf16 v[102:105], v[218:221], v[166:169], v[102:105]
	v_mfma_f32_16x16x32_bf16 v[98:101], v[218:221], v[186:189], v[98:101]
	s_setprio 1
	s_barrier
	s_add_i32 s30, s18, s28
	v_readfirstlane_b32 s34, v137
	s_add_i32 s31, s30, 0x100
	s_mov_b32 m0, s34
	v_readfirstlane_b32 s34, v139
	ds_read_b128 v[222:225], v149
	ds_read_b128 v[226:229], v149 offset:1024
	ds_read_b128 v[230:233], v149 offset:2048
	ds_read_b128 v[234:237], v149 offset:3072
	buffer_load_dwordx4 v32, s[76:79], s31 offen lds
	s_mov_b32 m0, s34
	s_nop 0
	buffer_load_dwordx4 v130, s[76:79], s31 offen lds
	s_barrier
; #define STAGE(P, BASE, br, kt) do { int _so = ((br) * K + (kt) * BK) * 2; \
;     __builtin_amdgcn_raw_ptr_buffer_load_lds(rs_##BASE, (__attribute__((address_space(3))) void*)((char*)(P) + tx * 16), 16, voff0, _so, 0, 0); \
;     __builtin_amdgcn_raw_ptr_buffer_load_lds(rs_##BASE, (__attribute__((address_space(3))) void*)((char*)(P) + tx * 16 + 8192), 16, voff1, _so, 0, 0); } while (0)
; #define LDA(dst, b, h) _Pragma("unroll") for (int m = 0; m < 4; ++m) _Pragma("unroll") for (int k = 0; k < 2; ++k) \
;     dst[m][k] = *reinterpret_cast<const bf16x8*>((char*)SA(b, h) + lds_byte(wr * 64 + m * 16 + fr, k * 32 + fq * 8))
; #define LDB(dst, b, h) _Pragma("unroll") for (int n = 0; n < 2; ++n) _Pragma("unroll") for (int k = 0; k < 2; ++k) \
;     dst[n][k] = *reinterpret_cast<const bf16x8*>((char*)SB(b, h) + lds_byte(wc * 32 + n * 16 + fr, k * 32 + fq * 8))
; #define MMA(ai, bj, At, Bt_) do { __builtin_amdgcn_s_setprio(1); \
;     _Pragma("unroll") for (int m = 0; m < 4; ++m) _Pragma("unroll") for (int n = 0; n < 2; ++n) _Pragma("unroll") for (int k = 0; k < 2; ++k) \
;       acc[ai][bj][m][n] = __builtin_amdgcn_mfma_f32_16x16x32_bf16(At[m][k], Bt_[n][k], acc[ai][bj][m][n], 0, 0, 0); \
;     __builtin_amdgcn_s_setprio(0); } while (0)
; #define WAIT_V(n) asm volatile("s_waitcnt vmcnt(" #n ")" ::: "memory")
; #define WAIT_L(n) asm volatile("s_waitcnt lgkmcnt(" #n ")" ::: "memory")
; #define BAR __builtin_amdgcn_s_barrier()
; #define SCHED __builtin_amdgcn_sched_barrier(0)
; template <class Epi> ...
;     ...
;     BAR; WAIT_L(0); MMA(0, 1, At, B1); BAR;
;     LDA(At, 0, 1); STAGE(SA(0, 0), A, brow, t + 2);
;     BAR; WAIT_L(0); MMA(1, 0, At, B0); BAR; SCHED;
;     STAGE(SB(0, 1), Bt, bcol + HALF, t + 2);
;     WAIT_V(6); BAR; MMA(1, 1, At, B1); BAR;
;     LDB(B0, 1, 0); SCHED; LDA(At, 1, 0); STAGE(SA(0, 1), A, brow + HALF, t + 2);
	s_waitcnt lgkmcnt(0)
	s_setprio 0
	s_waitcnt lgkmcnt(3)
	v_mfma_f32_16x16x32_bf16 v[94:97], v[190:193], v[222:225], v[94:97]
	s_waitcnt lgkmcnt(1)
	v_mfma_f32_16x16x32_bf16 v[90:93], v[190:193], v[230:233], v[90:93]
	v_mfma_f32_16x16x32_bf16 v[86:89], v[198:201], v[222:225], v[86:89]
	v_mfma_f32_16x16x32_bf16 v[82:85], v[198:201], v[230:233], v[82:85]
	v_mfma_f32_16x16x32_bf16 v[78:81], v[206:209], v[222:225], v[78:81]
	v_mfma_f32_16x16x32_bf16 v[74:77], v[206:209], v[230:233], v[74:77]
	v_mfma_f32_16x16x32_bf16 v[70:73], v[214:217], v[222:225], v[70:73]
	v_mfma_f32_16x16x32_bf16 v[66:69], v[214:217], v[230:233], v[66:69]
	v_mfma_f32_16x16x32_bf16 v[94:97], v[194:197], v[226:229], v[94:97]
	s_waitcnt lgkmcnt(0)
	v_mfma_f32_16x16x32_bf16 v[90:93], v[194:197], v[234:237], v[90:93]
	v_mfma_f32_16x16x32_bf16 v[86:89], v[202:205], v[226:229], v[86:89]
	v_mfma_f32_16x16x32_bf16 v[82:85], v[202:205], v[234:237], v[82:85]
	v_mfma_f32_16x16x32_bf16 v[78:81], v[210:213], v[226:229], v[78:81]
	v_mfma_f32_16x16x32_bf16 v[74:77], v[210:213], v[234:237], v[74:77]
	v_mfma_f32_16x16x32_bf16 v[70:73], v[218:221], v[226:229], v[70:73]
	v_mfma_f32_16x16x32_bf16 v[66:69], v[218:221], v[234:237], v[66:69]
	s_setprio 1
	v_readfirstlane_b32 s34, v136
	s_add_i32 s31, s29, 0x100
	s_mov_b32 m0, s34
	v_readfirstlane_b32 s34, v135
	s_barrier
	ds_read_b128 v[190:193], v143 offset:16384
	ds_read_b128 v[194:197], v143 offset:17408
	ds_read_b128 v[198:201], v142 offset:16384
	ds_read_b128 v[202:205], v142 offset:17408
	ds_read_b128 v[206:209], v141 offset:16384
	ds_read_b128 v[210:213], v141 offset:17408
	ds_read_b128 v[214:217], v140 offset:16384
	ds_read_b128 v[218:221], v140 offset:17408
	buffer_load_dwordx4 v32, s[4:7], s31 offen lds
	s_mov_b32 m0, s34
	s_nop 0
	buffer_load_dwordx4 v130, s[4:7], s31 offen lds
	s_barrier
	s_waitcnt lgkmcnt(0)
	s_setprio 0
	s_waitcnt lgkmcnt(7)
	v_mfma_f32_16x16x32_bf16 v[62:65], v[190:193], v[156:159], v[62:65]
	v_mfma_f32_16x16x32_bf16 v[58:61], v[190:193], v[170:173], v[58:61]
	s_waitcnt lgkmcnt(5)
	v_mfma_f32_16x16x32_bf16 v[54:57], v[198:201], v[156:159], v[54:57]
	v_mfma_f32_16x16x32_bf16 v[50:53], v[198:201], v[170:173], v[50:53]
	s_waitcnt lgkmcnt(3)
	v_mfma_f32_16x16x32_bf16 v[46:49], v[206:209], v[156:159], v[46:49]
	v_mfma_f32_16x16x32_bf16 v[42:45], v[206:209], v[170:173], v[42:45]
	s_waitcnt lgkmcnt(1)
	v_mfma_f32_16x16x32_bf16 v[38:41], v[214:217], v[156:159], v[38:41]
	v_mfma_f32_16x16x32_bf16 v[34:37], v[214:217], v[170:173], v[34:37]
	v_mfma_f32_16x16x32_bf16 v[62:65], v[194:197], v[166:169], v[62:65]
	v_mfma_f32_16x16x32_bf16 v[58:61], v[194:197], v[186:189], v[58:61]
	v_mfma_f32_16x16x32_bf16 v[54:57], v[202:205], v[166:169], v[54:57]
	v_mfma_f32_16x16x32_bf16 v[50:53], v[202:205], v[186:189], v[50:53]
	v_mfma_f32_16x16x32_bf16 v[46:49], v[210:213], v[166:169], v[46:49]
	v_mfma_f32_16x16x32_bf16 v[42:45], v[210:213], v[186:189], v[42:45]
	s_waitcnt lgkmcnt(0)
	v_mfma_f32_16x16x32_bf16 v[38:41], v[218:221], v[166:169], v[38:41]
	v_mfma_f32_16x16x32_bf16 v[34:37], v[218:221], v[186:189], v[34:37]
	s_setprio 1
	s_barrier
	v_readfirstlane_b32 s34, v134
	s_add_i32 s31, s30, 0x40100
	s_mov_b32 m0, s34
	v_readfirstlane_b32 s34, v138
	buffer_load_dwordx4 v32, s[76:79], s31 offen lds
	s_mov_b32 m0, s34
	s_nop 0
	buffer_load_dwordx4 v130, s[76:79], s31 offen lds
	s_waitcnt vmcnt(6)
	s_barrier
	s_setprio 0
	v_mfma_f32_16x16x32_bf16 v[28:31], v[190:193], v[222:225], v[28:31]
	v_mfma_f32_16x16x32_bf16 v[24:27], v[190:193], v[230:233], v[24:27]
	v_mfma_f32_16x16x32_bf16 v[20:23], v[198:201], v[222:225], v[20:23]
	v_mfma_f32_16x16x32_bf16 v[16:19], v[198:201], v[230:233], v[16:19]
	v_mfma_f32_16x16x32_bf16 v[12:15], v[206:209], v[222:225], v[12:15]
	v_mfma_f32_16x16x32_bf16 v[8:11], v[206:209], v[230:233], v[8:11]
	v_mfma_f32_16x16x32_bf16 v[4:7], v[214:217], v[222:225], v[4:7]
	v_mfma_f32_16x16x32_bf16 v[0:3], v[214:217], v[230:233], v[0:3]
	v_mfma_f32_16x16x32_bf16 v[28:31], v[194:197], v[226:229], v[28:31]
	v_mfma_f32_16x16x32_bf16 v[24:27], v[194:197], v[234:237], v[24:27]
	v_mfma_f32_16x16x32_bf16 v[20:23], v[202:205], v[226:229], v[20:23]
	v_mfma_f32_16x16x32_bf16 v[16:19], v[202:205], v[234:237], v[16:19]
	v_mfma_f32_16x16x32_bf16 v[12:15], v[210:213], v[226:229], v[12:15]
	v_mfma_f32_16x16x32_bf16 v[8:11], v[210:213], v[234:237], v[8:11]
	v_mfma_f32_16x16x32_bf16 v[4:7], v[218:221], v[226:229], v[4:7]
	v_mfma_f32_16x16x32_bf16 v[0:3], v[218:221], v[234:237], v[0:3]
	s_setprio 1
	s_barrier
	ds_read_b128 v[156:159], v145
	ds_read_b128 v[166:169], v145 offset:1024
	ds_read_b128 v[170:173], v145 offset:2048
	ds_read_b128 v[186:189], v145 offset:3072
	v_readfirstlane_b32 s34, v132
	s_add_i32 s31, s29, 0x40100
	s_mov_b32 m0, s34
	v_readfirstlane_b32 s34, v131
	ds_read_b128 v[190:193], v143 offset:32768
	ds_read_b128 v[194:197], v143 offset:33792
	ds_read_b128 v[198:201], v142 offset:32768
	ds_read_b128 v[202:205], v142 offset:33792
	ds_read_b128 v[206:209], v141 offset:32768
	ds_read_b128 v[210:213], v141 offset:33792
	ds_read_b128 v[214:217], v140 offset:32768
	ds_read_b128 v[218:221], v140 offset:33792
	buffer_load_dwordx4 v32, s[4:7], s31 offen lds
	s_mov_b32 m0, s34
	s_nop 0
	buffer_load_dwordx4 v130, s[4:7], s31 offen lds
	s_waitcnt lgkmcnt(8)
	s_barrier
; #define STAGE(P, BASE, br, kt) do { int _so = ((br) * K + (kt) * BK) * 2; \
;     __builtin_amdgcn_raw_ptr_buffer_load_lds(rs_##BASE, (__attribute__((address_space(3))) void*)((char*)(P) + tx * 16), 16, voff0, _so, 0, 0); \
;     __builtin_amdgcn_raw_ptr_buffer_load_lds(rs_##BASE, (__attribute__((address_space(3))) void*)((char*)(P) + tx * 16 + 8192), 16, voff1, _so, 0, 0); } while (0)
; #define LDA(dst, b, h) _Pragma("unroll") for (int m = 0; m < 4; ++m) _Pragma("unroll") for (int k = 0; k < 2; ++k) \
;     dst[m][k] = *reinterpret_cast<const bf16x8*>((char*)SA(b, h) + lds_byte(wr * 64 + m * 16 + fr, k * 32 + fq * 8))
; #define LDB(dst, b, h) _Pragma("unroll") for (int n = 0; n < 2; ++n) _Pragma("unroll") for (int k = 0; k < 2; ++k) \
;     dst[n][k] = *reinterpret_cast<const bf16x8*>((char*)SB(b, h) + lds_byte(wc * 32 + n * 16 + fr, k * 32 + fq * 8))
; #define MMA(ai, bj, At, Bt_) do { __builtin_amdgcn_s_setprio(1); \
;     _Pragma("unroll") for (int m = 0; m < 4; ++m) _Pragma("unroll") for (int n = 0; n < 2; ++n) _Pragma("unroll") for (int k = 0; k < 2; ++k) \
;       acc[ai][bj][m][n] = __builtin_amdgcn_mfma_f32_16x16x32_bf16(At[m][k], Bt_[n][k], acc[ai][bj][m][n], 0, 0, 0); \
;     __builtin_amdgcn_s_setprio(0); } while (0)
; #define WAIT_V(n) asm volatile("s_waitcnt vmcnt(" #n ")" ::: "memory")
; #define WAIT_L(n) asm volatile("s_waitcnt lgkmcnt(" #n ")" ::: "memory")
; #define BAR __builtin_amdgcn_s_barrier()
; #define SCHED __builtin_amdgcn_sched_barrier(0)
; template <class Epi> ...
;     ...
;     WAIT_L(8); BAR; WAIT_L(0); MMA(0, 0, At, B0); BAR; SCHED;
;     LDB(B1, 1, 1); STAGE(SB(1, 0), Bt, bcol, t + 3);
;     BAR; WAIT_L(0); MMA(0, 1, At, B1); BAR;
;     LDA(At, 1, 1); STAGE(SA(1, 0), A, brow, t + 3);
;     BAR; WAIT_L(0); MMA(1, 0, At, B0); BAR; SCHED;
;     STAGE(SB(1, 1), Bt, bcol + HALF, t + 3);
;     WAIT_V(6); BAR; MMA(1, 1, At, B1); BAR;
	s_waitcnt lgkmcnt(0)
	s_setprio 0
	s_waitcnt lgkmcnt(7)
	v_mfma_f32_16x16x32_bf16 v[126:129], v[190:193], v[156:159], v[126:129]
	v_mfma_f32_16x16x32_bf16 v[122:125], v[190:193], v[170:173], v[122:125]
	s_waitcnt lgkmcnt(5)
	v_mfma_f32_16x16x32_bf16 v[118:121], v[198:201], v[156:159], v[118:121]
	v_mfma_f32_16x16x32_bf16 v[114:117], v[198:201], v[170:173], v[114:117]
	s_waitcnt lgkmcnt(3)
	v_mfma_f32_16x16x32_bf16 v[110:113], v[206:209], v[156:159], v[110:113]
	v_mfma_f32_16x16x32_bf16 v[106:109], v[206:209], v[170:173], v[106:109]
	s_waitcnt lgkmcnt(1)
	v_mfma_f32_16x16x32_bf16 v[102:105], v[214:217], v[156:159], v[102:105]
	v_mfma_f32_16x16x32_bf16 v[98:101], v[214:217], v[170:173], v[98:101]
	v_mfma_f32_16x16x32_bf16 v[126:129], v[194:197], v[166:169], v[126:129]
	v_mfma_f32_16x16x32_bf16 v[122:125], v[194:197], v[186:189], v[122:125]
	v_mfma_f32_16x16x32_bf16 v[118:121], v[202:205], v[166:169], v[118:121]
	v_mfma_f32_16x16x32_bf16 v[114:117], v[202:205], v[186:189], v[114:117]
	v_mfma_f32_16x16x32_bf16 v[110:113], v[210:213], v[166:169], v[110:113]
	v_mfma_f32_16x16x32_bf16 v[106:109], v[210:213], v[186:189], v[106:109]
	s_waitcnt lgkmcnt(0)
	v_mfma_f32_16x16x32_bf16 v[102:105], v[218:221], v[166:169], v[102:105]
	v_mfma_f32_16x16x32_bf16 v[98:101], v[218:221], v[186:189], v[98:101]
	s_setprio 1
	s_barrier
	v_readfirstlane_b32 s34, v146
	s_add_i32 s31, s30, 0x180
	s_mov_b32 m0, s34
	v_readfirstlane_b32 s34, v147
	ds_read_b128 v[222:225], v144
	ds_read_b128 v[226:229], v144 offset:1024
	ds_read_b128 v[230:233], v144 offset:2048
	ds_read_b128 v[234:237], v144 offset:3072
	buffer_load_dwordx4 v32, s[76:79], s31 offen lds
	s_mov_b32 m0, s34
	s_nop 0
	buffer_load_dwordx4 v130, s[76:79], s31 offen lds
	s_barrier
	s_waitcnt lgkmcnt(0)
	s_setprio 0
	s_waitcnt lgkmcnt(3)
	v_mfma_f32_16x16x32_bf16 v[94:97], v[190:193], v[222:225], v[94:97]
	s_waitcnt lgkmcnt(1)
	v_mfma_f32_16x16x32_bf16 v[90:93], v[190:193], v[230:233], v[90:93]
	v_mfma_f32_16x16x32_bf16 v[86:89], v[198:201], v[222:225], v[86:89]
	v_mfma_f32_16x16x32_bf16 v[82:85], v[198:201], v[230:233], v[82:85]
	v_mfma_f32_16x16x32_bf16 v[78:81], v[206:209], v[222:225], v[78:81]
	v_mfma_f32_16x16x32_bf16 v[74:77], v[206:209], v[230:233], v[74:77]
	v_mfma_f32_16x16x32_bf16 v[70:73], v[214:217], v[222:225], v[70:73]
	v_mfma_f32_16x16x32_bf16 v[66:69], v[214:217], v[230:233], v[66:69]
	v_mfma_f32_16x16x32_bf16 v[94:97], v[194:197], v[226:229], v[94:97]
	s_waitcnt lgkmcnt(0)
	v_mfma_f32_16x16x32_bf16 v[90:93], v[194:197], v[234:237], v[90:93]
	v_mfma_f32_16x16x32_bf16 v[86:89], v[202:205], v[226:229], v[86:89]
	v_mfma_f32_16x16x32_bf16 v[82:85], v[202:205], v[234:237], v[82:85]
	v_mfma_f32_16x16x32_bf16 v[78:81], v[210:213], v[226:229], v[78:81]
	v_mfma_f32_16x16x32_bf16 v[74:77], v[210:213], v[234:237], v[74:77]
	v_mfma_f32_16x16x32_bf16 v[70:73], v[218:221], v[226:229], v[70:73]
	v_mfma_f32_16x16x32_bf16 v[66:69], v[218:221], v[234:237], v[66:69]
	s_setprio 1
	v_readfirstlane_b32 s31, v148
	s_addk_i32 s29, 0x180
	s_mov_b32 m0, s31
	v_readfirstlane_b32 s31, v150
	s_barrier
	ds_read_b128 v[190:193], v143 offset:49152
	ds_read_b128 v[194:197], v143 offset:50176
	ds_read_b128 v[198:201], v142 offset:49152
	ds_read_b128 v[202:205], v142 offset:50176
	ds_read_b128 v[206:209], v141 offset:49152
	ds_read_b128 v[210:213], v141 offset:50176
	ds_read_b128 v[214:217], v140 offset:49152
	ds_read_b128 v[218:221], v140 offset:50176
	buffer_load_dwordx4 v32, s[4:7], s29 offen lds
	s_mov_b32 m0, s31
	s_nop 0
	buffer_load_dwordx4 v130, s[4:7], s29 offen lds
	s_barrier
	s_waitcnt lgkmcnt(0)
	s_setprio 0
	s_waitcnt lgkmcnt(7)
	v_mfma_f32_16x16x32_bf16 v[62:65], v[190:193], v[156:159], v[62:65]
	v_mfma_f32_16x16x32_bf16 v[58:61], v[190:193], v[170:173], v[58:61]
	s_waitcnt lgkmcnt(5)
	v_mfma_f32_16x16x32_bf16 v[54:57], v[198:201], v[156:159], v[54:57]
	v_mfma_f32_16x16x32_bf16 v[50:53], v[198:201], v[170:173], v[50:53]
	s_waitcnt lgkmcnt(3)
	v_mfma_f32_16x16x32_bf16 v[46:49], v[206:209], v[156:159], v[46:49]
	v_mfma_f32_16x16x32_bf16 v[42:45], v[206:209], v[170:173], v[42:45]
	s_waitcnt lgkmcnt(1)
	v_mfma_f32_16x16x32_bf16 v[38:41], v[214:217], v[156:159], v[38:41]
	v_mfma_f32_16x16x32_bf16 v[34:37], v[214:217], v[170:173], v[34:37]
	v_mfma_f32_16x16x32_bf16 v[62:65], v[194:197], v[166:169], v[62:65]
	v_mfma_f32_16x16x32_bf16 v[58:61], v[194:197], v[186:189], v[58:61]
	v_mfma_f32_16x16x32_bf16 v[54:57], v[202:205], v[166:169], v[54:57]
	v_mfma_f32_16x16x32_bf16 v[50:53], v[202:205], v[186:189], v[50:53]
	v_mfma_f32_16x16x32_bf16 v[46:49], v[210:213], v[166:169], v[46:49]
	v_mfma_f32_16x16x32_bf16 v[42:45], v[210:213], v[186:189], v[42:45]
	s_waitcnt lgkmcnt(0)
	v_mfma_f32_16x16x32_bf16 v[38:41], v[218:221], v[166:169], v[38:41]
	v_mfma_f32_16x16x32_bf16 v[34:37], v[218:221], v[186:189], v[34:37]
	s_setprio 1
	s_barrier
	v_readfirstlane_b32 s29, v153
	s_add_i32 s30, s30, 0x40180
	s_mov_b32 m0, s29
	v_readfirstlane_b32 s29, v154
	buffer_load_dwordx4 v32, s[76:79], s30 offen lds
	s_mov_b32 m0, s29
	s_nop 0
	buffer_load_dwordx4 v130, s[76:79], s30 offen lds
	s_waitcnt vmcnt(6)
	s_barrier
	s_setprio 0
	v_mfma_f32_16x16x32_bf16 v[28:31], v[190:193], v[222:225], v[28:31]
	v_mfma_f32_16x16x32_bf16 v[24:27], v[190:193], v[230:233], v[24:27]
	v_mfma_f32_16x16x32_bf16 v[20:23], v[198:201], v[222:225], v[20:23]
	v_mfma_f32_16x16x32_bf16 v[16:19], v[198:201], v[230:233], v[16:19]
	v_mfma_f32_16x16x32_bf16 v[12:15], v[206:209], v[222:225], v[12:15]
	v_mfma_f32_16x16x32_bf16 v[8:11], v[206:209], v[230:233], v[8:11]
	v_mfma_f32_16x16x32_bf16 v[4:7], v[214:217], v[222:225], v[4:7]
	v_mfma_f32_16x16x32_bf16 v[0:3], v[214:217], v[230:233], v[0:3]
	v_mfma_f32_16x16x32_bf16 v[28:31], v[194:197], v[226:229], v[28:31]
	v_mfma_f32_16x16x32_bf16 v[24:27], v[194:197], v[234:237], v[24:27]
	v_mfma_f32_16x16x32_bf16 v[20:23], v[202:205], v[226:229], v[20:23]
	v_mfma_f32_16x16x32_bf16 v[16:19], v[202:205], v[234:237], v[16:19]
	v_mfma_f32_16x16x32_bf16 v[12:15], v[210:213], v[226:229], v[12:15]
	v_mfma_f32_16x16x32_bf16 v[8:11], v[210:213], v[234:237], v[8:11]
	v_mfma_f32_16x16x32_bf16 v[4:7], v[218:221], v[226:229], v[4:7]
	v_mfma_f32_16x16x32_bf16 v[0:3], v[218:221], v[234:237], v[0:3]
	s_setprio 1
	s_add_i32 s27, s27, 2
	s_addk_i32 s28, 0x100
	s_cmp_lt_u32 s27, 12
	s_barrier
	s_cbranch_scc1 .LBB0_1682
; #define STAGE(P, BASE, br, kt) do { int _so = ((br) * K + (kt) * BK) * 2; \
;     __builtin_amdgcn_raw_ptr_buffer_load_lds(rs_##BASE, (__attribute__((address_space(3))) void*)((char*)(P) + tx * 16), 16, voff0, _so, 0, 0); \
;     __builtin_amdgcn_raw_ptr_buffer_load_lds(rs_##BASE, (__attribute__((address_space(3))) void*)((char*)(P) + tx * 16 + 8192), 16, voff1, _so, 0, 0); } while (0)
; #define LDA(dst, b, h) _Pragma("unroll") for (int m = 0; m < 4; ++m) _Pragma("unroll") for (int k = 0; k < 2; ++k) \
;     dst[m][k] = *reinterpret_cast<const bf16x8*>((char*)SA(b, h) + lds_byte(wr * 64 + m * 16 + fr, k * 32 + fq * 8))
; #define LDB(dst, b, h) _Pragma("unroll") for (int n = 0; n < 2; ++n) _Pragma("unroll") for (int k = 0; k < 2; ++k) \
;     dst[n][k] = *reinterpret_cast<const bf16x8*>((char*)SB(b, h) + lds_byte(wc * 32 + n * 16 + fr, k * 32 + fq * 8))
; #define MMA(ai, bj, At, Bt_) do { __builtin_amdgcn_s_setprio(1); \
;     _Pragma("unroll") for (int m = 0; m < 4; ++m) _Pragma("unroll") for (int n = 0; n < 2; ++n) _Pragma("unroll") for (int k = 0; k < 2; ++k) \
;       acc[ai][bj][m][n] = __builtin_amdgcn_mfma_f32_16x16x32_bf16(At[m][k], Bt_[n][k], acc[ai][bj][m][n], 0, 0, 0); \
;     __builtin_amdgcn_s_setprio(0); } while (0)
; #define WAIT_V(n) asm volatile("s_waitcnt vmcnt(" #n ")" ::: "memory")
; #define WAIT_L(n) asm volatile("s_waitcnt lgkmcnt(" #n ")" ::: "memory")
; #define BAR __builtin_amdgcn_s_barrier()
; template <class Epi> ...
;     ...
;   { LDB(B0, 0, 0); LDA(At, 0, 0); STAGE(SA(1, 1), A, brow + HALF, nt - 1);
;     BAR; WAIT_L(0); MMA(0, 0, At, B0); BAR;
;     LDB(B1, 0, 1); BAR; WAIT_L(0); MMA(0, 1, At, B1); BAR;
;     LDA(At, 0, 1); WAIT_V(4); BAR; WAIT_L(0); MMA(1, 0, At, B0); MMA(1, 1, At, B1); BAR; }
.Lpx3:
	v_readfirstlane_b32 s18, v152
	s_add_i32 s19, s19, 0x40780
	s_mov_b32 s6, s78
	s_mov_b32 s7, s79
	s_mov_b32 m0, s18
	v_readfirstlane_b32 s18, v151
	ds_read_b128 v[156:159], v155
	ds_read_b128 v[166:169], v155 offset:1024
	ds_read_b128 v[170:173], v155 offset:2048
	ds_read_b128 v[186:189], v155 offset:3072
	ds_read_b128 v[190:193], v143
	ds_read_b128 v[194:197], v143 offset:1024
	ds_read_b128 v[198:201], v142
	ds_read_b128 v[202:205], v142 offset:1024
	ds_read_b128 v[206:209], v141
	ds_read_b128 v[210:213], v141 offset:1024
	ds_read_b128 v[214:217], v140
	ds_read_b128 v[218:221], v140 offset:1024
	buffer_load_dwordx4 v32, s[4:7], s19 offen lds
	s_mov_b32 m0, s18
	s_nop 0
	buffer_load_dwordx4 v130, s[4:7], s19 offen lds
	s_barrier
	s_waitcnt lgkmcnt(0)
	s_setprio 0
	s_waitcnt lgkmcnt(7)
	v_mfma_f32_16x16x32_bf16 v[126:129], v[190:193], v[156:159], v[126:129]
	v_mfma_f32_16x16x32_bf16 v[122:125], v[190:193], v[170:173], v[122:125]
	s_waitcnt lgkmcnt(5)
	v_mfma_f32_16x16x32_bf16 v[118:121], v[198:201], v[156:159], v[118:121]
	v_mfma_f32_16x16x32_bf16 v[114:117], v[198:201], v[170:173], v[114:117]
	s_waitcnt lgkmcnt(3)
	v_mfma_f32_16x16x32_bf16 v[110:113], v[206:209], v[156:159], v[110:113]
	v_mfma_f32_16x16x32_bf16 v[126:129], v[194:197], v[166:169], v[126:129]
	v_mfma_f32_16x16x32_bf16 v[122:125], v[194:197], v[186:189], v[122:125]
	v_mfma_f32_16x16x32_bf16 v[118:121], v[202:205], v[166:169], v[118:121]
	v_mfma_f32_16x16x32_bf16 v[114:117], v[202:205], v[186:189], v[114:117]
	s_waitcnt lgkmcnt(2)
	v_mfma_f32_16x16x32_bf16 v[110:113], v[210:213], v[166:169], v[110:113]
	v_mfma_f32_16x16x32_bf16 v[106:109], v[206:209], v[170:173], v[106:109]
	s_waitcnt lgkmcnt(1)
	v_mfma_f32_16x16x32_bf16 v[102:105], v[214:217], v[156:159], v[102:105]
	v_mfma_f32_16x16x32_bf16 v[98:101], v[214:217], v[170:173], v[98:101]
	v_mfma_f32_16x16x32_bf16 v[150:153], v[210:213], v[186:189], v[106:109]
	s_waitcnt lgkmcnt(0)
	v_mfma_f32_16x16x32_bf16 v[222:225], v[218:221], v[166:169], v[102:105]
	v_mfma_f32_16x16x32_bf16 v[226:229], v[218:221], v[186:189], v[98:101]
	s_setprio 1
	s_barrier
	s_nop 1
	ds_read_b128 v[98:101], v149
	ds_read_b128 v[102:105], v149 offset:1024
	ds_read_b128 v[106:109], v149 offset:2048
	ds_read_b128 v[146:149], v149 offset:3072
	s_barrier
	s_waitcnt lgkmcnt(0)
	s_setprio 0
	s_waitcnt lgkmcnt(3)
	v_mfma_f32_16x16x32_bf16 v[94:97], v[190:193], v[98:101], v[94:97]
	s_waitcnt lgkmcnt(1)
	v_mfma_f32_16x16x32_bf16 v[90:93], v[190:193], v[106:109], v[90:93]
	v_mfma_f32_16x16x32_bf16 v[86:89], v[198:201], v[98:101], v[86:89]
	v_mfma_f32_16x16x32_bf16 v[82:85], v[198:201], v[106:109], v[82:85]
	v_mfma_f32_16x16x32_bf16 v[94:97], v[194:197], v[102:105], v[94:97]
	s_waitcnt lgkmcnt(0)
	v_mfma_f32_16x16x32_bf16 v[90:93], v[194:197], v[146:149], v[90:93]
	v_mfma_f32_16x16x32_bf16 v[86:89], v[202:205], v[102:105], v[86:89]
	v_mfma_f32_16x16x32_bf16 v[82:85], v[202:205], v[146:149], v[82:85]
	v_mfma_f32_16x16x32_bf16 v[78:81], v[206:209], v[98:101], v[78:81]
	v_mfma_f32_16x16x32_bf16 v[74:77], v[206:209], v[106:109], v[74:77]
	v_mfma_f32_16x16x32_bf16 v[70:73], v[214:217], v[98:101], v[70:73]
	v_mfma_f32_16x16x32_bf16 v[66:69], v[214:217], v[106:109], v[66:69]
	v_mfma_f32_16x16x32_bf16 v[190:193], v[210:213], v[102:105], v[78:81]
	v_mfma_f32_16x16x32_bf16 v[194:197], v[210:213], v[146:149], v[74:77]
	v_mfma_f32_16x16x32_bf16 v[198:201], v[218:221], v[102:105], v[70:73]
	v_mfma_f32_16x16x32_bf16 v[202:205], v[218:221], v[146:149], v[66:69]
	s_setprio 1
	s_barrier
	s_nop 1
	ds_read_b128 v[66:69], v143 offset:16384
	ds_read_b128 v[70:73], v143 offset:17408
	ds_read_b128 v[74:77], v142 offset:16384
	ds_read_b128 v[78:81], v142 offset:17408
	ds_read_b128 v[206:209], v141 offset:16384
	ds_read_b128 v[210:213], v141 offset:17408
	ds_read_b128 v[214:217], v140 offset:16384
	ds_read_b128 v[218:221], v140 offset:17408
	s_waitcnt vmcnt(4)
	s_barrier
	s_waitcnt lgkmcnt(0)
	s_setprio 0
	s_waitcnt lgkmcnt(7)
	v_mfma_f32_16x16x32_bf16 v[62:65], v[66:69], v[156:159], v[62:65]
	v_mfma_f32_16x16x32_bf16 v[58:61], v[66:69], v[170:173], v[58:61]
	s_waitcnt lgkmcnt(5)
	v_mfma_f32_16x16x32_bf16 v[54:57], v[74:77], v[156:159], v[54:57]
	v_mfma_f32_16x16x32_bf16 v[50:53], v[74:77], v[170:173], v[50:53]
	v_mfma_f32_16x16x32_bf16 v[62:65], v[70:73], v[166:169], v[62:65]
	v_mfma_f32_16x16x32_bf16 v[58:61], v[70:73], v[186:189], v[58:61]
	s_waitcnt lgkmcnt(4)
	v_mfma_f32_16x16x32_bf16 v[54:57], v[78:81], v[166:169], v[54:57]
	v_mfma_f32_16x16x32_bf16 v[50:53], v[78:81], v[186:189], v[50:53]
	s_waitcnt lgkmcnt(3)
	v_mfma_f32_16x16x32_bf16 v[46:49], v[206:209], v[156:159], v[46:49]
	v_mfma_f32_16x16x32_bf16 v[42:45], v[206:209], v[170:173], v[42:45]
	s_waitcnt lgkmcnt(1)
	v_mfma_f32_16x16x32_bf16 v[38:41], v[214:217], v[156:159], v[38:41]
	v_mfma_f32_16x16x32_bf16 v[34:37], v[214:217], v[170:173], v[34:37]
	v_mfma_f32_16x16x32_bf16 v[230:233], v[210:213], v[166:169], v[46:49]
	v_mfma_f32_16x16x32_bf16 v[234:237], v[210:213], v[186:189], v[42:45]
	s_waitcnt lgkmcnt(0)
	v_mfma_f32_16x16x32_bf16 v[154:157], v[218:221], v[166:169], v[38:41]
	v_mfma_f32_16x16x32_bf16 v[158:161], v[218:221], v[186:189], v[34:37]
	s_setprio 1
	s_setprio 0
	v_mfma_f32_16x16x32_bf16 v[28:31], v[66:69], v[98:101], v[28:31]
	v_mfma_f32_16x16x32_bf16 v[24:27], v[66:69], v[106:109], v[24:27]
	v_mfma_f32_16x16x32_bf16 v[20:23], v[74:77], v[98:101], v[20:23]
	v_mfma_f32_16x16x32_bf16 v[12:15], v[206:209], v[98:101], v[12:15]
	v_mfma_f32_16x16x32_bf16 v[28:31], v[70:73], v[102:105], v[28:31]
	v_mfma_f32_16x16x32_bf16 v[24:27], v[70:73], v[146:149], v[24:27]
	v_mfma_f32_16x16x32_bf16 v[20:23], v[78:81], v[102:105], v[20:23]
	v_mfma_f32_16x16x32_bf16 v[16:19], v[74:77], v[106:109], v[16:19]
	v_mfma_f32_16x16x32_bf16 v[12:15], v[210:213], v[102:105], v[12:15]
	v_mfma_f32_16x16x32_bf16 v[8:11], v[206:209], v[106:109], v[8:11]
	v_mfma_f32_16x16x32_bf16 v[4:7], v[214:217], v[98:101], v[4:7]
	v_mfma_f32_16x16x32_bf16 v[0:3], v[214:217], v[106:109], v[0:3]
	v_mfma_f32_16x16x32_bf16 v[166:169], v[78:81], v[146:149], v[16:19]
	v_mfma_f32_16x16x32_bf16 v[170:173], v[210:213], v[146:149], v[8:11]
	v_mfma_f32_16x16x32_bf16 v[186:189], v[218:221], v[102:105], v[4:7]
	v_mfma_f32_16x16x32_bf16 v[146:149], v[218:221], v[146:149], v[0:3]
	s_setprio 1
	s_barrier
; #define LDA(dst, b, h) _Pragma("unroll") for (int m = 0; m < 4; ++m) _Pragma("unroll") for (int k = 0; k < 2; ++k) \
;     dst[m][k] = *reinterpret_cast<const bf16x8*>((char*)SA(b, h) + lds_byte(wr * 64 + m * 16 + fr, k * 32 + fq * 8))
; #define LDB(dst, b, h) _Pragma("unroll") for (int n = 0; n < 2; ++n) _Pragma("unroll") for (int k = 0; k < 2; ++k) \
;     dst[n][k] = *reinterpret_cast<const bf16x8*>((char*)SB(b, h) + lds_byte(wc * 32 + n * 16 + fr, k * 32 + fq * 8))
; #define MMA(ai, bj, At, Bt_) do { __builtin_amdgcn_s_setprio(1); \
;     _Pragma("unroll") for (int m = 0; m < 4; ++m) _Pragma("unroll") for (int n = 0; n < 2; ++n) _Pragma("unroll") for (int k = 0; k < 2; ++k) \
;       acc[ai][bj][m][n] = __builtin_amdgcn_mfma_f32_16x16x32_bf16(At[m][k], Bt_[n][k], acc[ai][bj][m][n], 0, 0, 0); \
;     __builtin_amdgcn_s_setprio(0); } while (0)
; #define WAIT_V(n) asm volatile("s_waitcnt vmcnt(" #n ")" ::: "memory")
; #define WAIT_L(n) asm volatile("s_waitcnt lgkmcnt(" #n ")" ::: "memory")
; #define BAR __builtin_amdgcn_s_barrier()
; template <class Epi> ...
;     ...
;   { LDB(B0, 1, 0); LDA(At, 1, 0); WAIT_V(2); BAR; WAIT_L(0); MMA(0, 0, At, B0); BAR;
;     LDB(B1, 1, 1); WAIT_V(0); BAR; WAIT_L(0); MMA(0, 1, At, B1); BAR;
;     LDA(At, 1, 1); BAR; WAIT_L(0); MMA(1, 0, At, B0); MMA(1, 1, At, B1); BAR; }
;   if (wr == 0) BAR;
	ds_read_b128 v[206:209], v145
	ds_read_b128 v[210:213], v145 offset:1024
	ds_read_b128 v[214:217], v145 offset:2048
	ds_read_b128 v[218:221], v145 offset:3072
	ds_read_b128 v[0:3], v143 offset:32768
	ds_read_b128 v[4:7], v143 offset:33792
	ds_read_b128 v[8:11], v142 offset:32768
	ds_read_b128 v[42:45], v142 offset:33792
	ds_read_b128 v[46:49], v141 offset:32768
	ds_read_b128 v[238:241], v141 offset:33792
	ds_read_b128 v[242:245], v140 offset:32768
	ds_read_b128 v[246:249], v140 offset:33792
	s_waitcnt vmcnt(2)
	s_barrier
	s_waitcnt lgkmcnt(0)
	s_setprio 0
	s_waitcnt lgkmcnt(7)
	v_mfma_f32_16x16x32_bf16 v[16:19], v[0:3], v[206:209], v[126:129]
	s_waitcnt lgkmcnt(6)
	v_mfma_f32_16x16x32_bf16 v[98:101], v[4:7], v[210:213], v[16:19]
	v_mfma_f32_16x16x32_bf16 v[16:19], v[0:3], v[214:217], v[122:125]
	v_mfma_f32_16x16x32_bf16 v[66:69], v[4:7], v[218:221], v[16:19]
	s_waitcnt lgkmcnt(5)
	v_mfma_f32_16x16x32_bf16 v[16:19], v[8:11], v[206:209], v[118:121]
	s_waitcnt lgkmcnt(4)
	v_mfma_f32_16x16x32_bf16 v[102:105], v[42:45], v[210:213], v[16:19]
	v_mfma_f32_16x16x32_bf16 v[16:19], v[8:11], v[214:217], v[114:117]
	v_mfma_f32_16x16x32_bf16 v[70:73], v[42:45], v[218:221], v[16:19]
	s_waitcnt lgkmcnt(3)
	v_mfma_f32_16x16x32_bf16 v[16:19], v[46:49], v[206:209], v[110:113]
	s_waitcnt lgkmcnt(2)
	v_mfma_f32_16x16x32_bf16 v[106:109], v[238:241], v[210:213], v[16:19]
	v_mfma_f32_16x16x32_bf16 v[16:19], v[46:49], v[214:217], v[150:153]
	v_mfma_f32_16x16x32_bf16 v[74:77], v[238:241], v[218:221], v[16:19]
	s_waitcnt lgkmcnt(1)
	v_mfma_f32_16x16x32_bf16 v[16:19], v[242:245], v[206:209], v[222:225]
	s_waitcnt lgkmcnt(0)
	v_mfma_f32_16x16x32_bf16 v[110:113], v[246:249], v[210:213], v[16:19]
	v_mfma_f32_16x16x32_bf16 v[16:19], v[242:245], v[214:217], v[226:229]
	v_mfma_f32_16x16x32_bf16 v[78:81], v[246:249], v[218:221], v[16:19]
	s_setprio 1
	s_barrier
	ds_read_b128 v[150:153], v144
	ds_read_b128 v[222:225], v144 offset:1024
	ds_read_b128 v[226:229], v144 offset:2048
	ds_read_b128 v[250:253], v144 offset:3072
	s_waitcnt vmcnt(0)
	s_barrier
	s_waitcnt lgkmcnt(0)
	s_setprio 0
	s_waitcnt lgkmcnt(3)
	v_mfma_f32_16x16x32_bf16 v[16:19], v[0:3], v[150:153], v[94:97]
	s_waitcnt lgkmcnt(1)
	v_mfma_f32_16x16x32_bf16 v[0:3], v[0:3], v[226:229], v[90:93]
	v_mfma_f32_16x16x32_bf16 v[34:37], v[4:7], v[222:225], v[16:19]
	s_waitcnt lgkmcnt(0)
	v_mfma_f32_16x16x32_bf16 v[16:19], v[4:7], v[250:253], v[0:3]
	v_mfma_f32_16x16x32_bf16 v[0:3], v[8:11], v[150:153], v[86:89]
	v_mfma_f32_16x16x32_bf16 v[38:41], v[42:45], v[222:225], v[0:3]
	v_mfma_f32_16x16x32_bf16 v[0:3], v[8:11], v[226:229], v[82:85]
	v_mfma_f32_16x16x32_bf16 v[8:11], v[42:45], v[250:253], v[0:3]
	v_mfma_f32_16x16x32_bf16 v[0:3], v[46:49], v[150:153], v[190:193]
	v_mfma_f32_16x16x32_bf16 v[42:45], v[238:241], v[222:225], v[0:3]
	v_mfma_f32_16x16x32_bf16 v[0:3], v[46:49], v[226:229], v[194:197]
	v_mfma_f32_16x16x32_bf16 v[4:7], v[238:241], v[250:253], v[0:3]
	v_mfma_f32_16x16x32_bf16 v[0:3], v[242:245], v[150:153], v[198:201]
	v_mfma_f32_16x16x32_bf16 v[46:49], v[246:249], v[222:225], v[0:3]
	v_mfma_f32_16x16x32_bf16 v[0:3], v[242:245], v[226:229], v[202:205]
	v_mfma_f32_16x16x32_bf16 v[0:3], v[246:249], v[250:253], v[0:3]
	s_setprio 1
	s_barrier
	ds_read_b128 v[190:193], v143 offset:49152
	ds_read_b128 v[194:197], v143 offset:50176
	ds_read_b128 v[198:201], v142 offset:49152
	ds_read_b128 v[142:145], v142 offset:50176
	ds_read_b128 v[202:205], v141 offset:49152
	ds_read_b128 v[238:241], v141 offset:50176
	ds_read_b128 v[242:245], v140 offset:49152
	ds_read_b128 v[246:249], v140 offset:50176
	s_barrier
	s_waitcnt lgkmcnt(0)
	s_setprio 0
	s_waitcnt lgkmcnt(5)
	v_mfma_f32_16x16x32_bf16 v[50:53], v[198:201], v[214:217], v[50:53]
	s_waitcnt lgkmcnt(4)
	v_mfma_f32_16x16x32_bf16 v[86:89], v[142:145], v[218:221], v[50:53]
	s_waitcnt lgkmcnt(3)
	v_mfma_f32_16x16x32_bf16 v[50:53], v[202:205], v[206:209], v[230:233]
	s_waitcnt lgkmcnt(2)
	v_mfma_f32_16x16x32_bf16 v[122:125], v[238:241], v[210:213], v[50:53]
	v_mfma_f32_16x16x32_bf16 v[50:53], v[202:205], v[214:217], v[234:237]
	v_mfma_f32_16x16x32_bf16 v[90:93], v[238:241], v[218:221], v[50:53]
	s_waitcnt lgkmcnt(1)
	v_mfma_f32_16x16x32_bf16 v[50:53], v[242:245], v[206:209], v[154:157]
	v_mfma_f32_16x16x32_bf16 v[62:65], v[190:193], v[206:209], v[62:65]
	v_mfma_f32_16x16x32_bf16 v[58:61], v[190:193], v[214:217], v[58:61]
	v_mfma_f32_16x16x32_bf16 v[54:57], v[198:201], v[206:209], v[54:57]
	s_waitcnt lgkmcnt(0)
	v_mfma_f32_16x16x32_bf16 v[126:129], v[246:249], v[210:213], v[50:53]
	v_mfma_f32_16x16x32_bf16 v[50:53], v[242:245], v[214:217], v[158:161]
	v_mfma_f32_16x16x32_bf16 v[114:117], v[194:197], v[210:213], v[62:65]
	v_mfma_f32_16x16x32_bf16 v[82:85], v[194:197], v[218:221], v[58:61]
	v_mfma_f32_16x16x32_bf16 v[118:121], v[142:145], v[210:213], v[54:57]
	v_mfma_f32_16x16x32_bf16 v[94:97], v[246:249], v[218:221], v[50:53]
	s_setprio 1
	s_setprio 0
	v_mfma_f32_16x16x32_bf16 v[20:23], v[198:201], v[150:153], v[20:23]
	v_mfma_f32_16x16x32_bf16 v[12:15], v[202:205], v[150:153], v[12:15]
	v_mfma_f32_16x16x32_bf16 v[28:31], v[190:193], v[150:153], v[28:31]
	v_mfma_f32_16x16x32_bf16 v[24:27], v[190:193], v[226:229], v[24:27]
	v_mfma_f32_16x16x32_bf16 v[54:57], v[142:145], v[222:225], v[20:23]
	v_mfma_f32_16x16x32_bf16 v[20:23], v[198:201], v[226:229], v[166:169]
	v_mfma_f32_16x16x32_bf16 v[58:61], v[238:241], v[222:225], v[12:15]
	v_mfma_f32_16x16x32_bf16 v[12:15], v[202:205], v[226:229], v[170:173]
	v_mfma_f32_16x16x32_bf16 v[50:53], v[194:197], v[222:225], v[28:31]
	v_mfma_f32_16x16x32_bf16 v[28:31], v[194:197], v[250:253], v[24:27]
	v_mfma_f32_16x16x32_bf16 v[24:27], v[142:145], v[250:253], v[20:23]
	v_mfma_f32_16x16x32_bf16 v[20:23], v[238:241], v[250:253], v[12:15]
	v_mfma_f32_16x16x32_bf16 v[12:15], v[242:245], v[150:153], v[186:189]
	v_mfma_f32_16x16x32_bf16 v[62:65], v[246:249], v[222:225], v[12:15]
	v_mfma_f32_16x16x32_bf16 v[12:15], v[242:245], v[226:229], v[146:149]
	v_mfma_f32_16x16x32_bf16 v[12:15], v[246:249], v[250:253], v[12:15]
	s_setprio 1
	v_cmp_gt_u32_e32 vcc, s59, v133
	s_barrier
	s_and_saveexec_b64 s[4:5], vcc
	s_cbranch_execz .LBB0_1685
	s_barrier

; #define STAGE(P, BASE, br, kt) do { int _so = ((br) * K + (kt) * BK) * 2; \
;     __builtin_amdgcn_raw_ptr_buffer_load_lds(rs_##BASE, (__attribute__((address_space(3))) void*)((char*)(P) + tx * 16), 16, voff0, _so, 0, 0); \
;     __builtin_amdgcn_raw_ptr_buffer_load_lds(rs_##BASE, (__attribute__((address_space(3))) void*)((char*)(P) + tx * 16 + 8192), 16, voff1, _so, 0, 0); } while (0)
; #define LDA(dst, b, h) _Pragma("unroll") for (int m = 0; m < 4; ++m) _Pragma("unroll") for (int k = 0; k < 2; ++k) \
;     dst[m][k] = *reinterpret_cast<const bf16x8*>((char*)SA(b, h) + lds_byte(wr * 64 + m * 16 + fr, k * 32 + fq * 8))
; #define LDB(dst, b, h) _Pragma("unroll") for (int n = 0; n < 2; ++n) _Pragma("unroll") for (int k = 0; k < 2; ++k) \
;     dst[n][k] = *reinterpret_cast<const bf16x8*>((char*)SB(b, h) + lds_byte(wc * 32 + n * 16 + fr, k * 32 + fq * 8))
; #define MMA(ai, bj, At, Bt_) do { __builtin_amdgcn_s_setprio(1); \
;     _Pragma("unroll") for (int m = 0; m < 4; ++m) _Pragma("unroll") for (int n = 0; n < 2; ++n) _Pragma("unroll") for (int k = 0; k < 2; ++k) \
;       acc[ai][bj][m][n] = __builtin_amdgcn_mfma_f32_16x16x32_bf16(At[m][k], Bt_[n][k], acc[ai][bj][m][n], 0, 0, 0); \
;     __builtin_amdgcn_s_setprio(0); } while (0)
; #define WAIT_V(n) asm volatile("s_waitcnt vmcnt(" #n ")" ::: "memory")
; #define WAIT_L(n) asm volatile("s_waitcnt lgkmcnt(" #n ")" ::: "memory")
; #define BAR __builtin_amdgcn_s_barrier()
; #define SCHED __builtin_amdgcn_sched_barrier(0)
; template <class Epi> ...
;     ...
;     LDB(B0, 0, 0); SCHED; LDA(At, 0, 0); STAGE(SA(1, 1), A, brow + HALF, t + 1);
;     WAIT_L(8); BAR; WAIT_L(0); MMA(0, 0, At, B0); BAR; SCHED;
;     LDB(B1, 0, 1); STAGE(SB(0, 0), Bt, bcol, t + 2);
;     BAR; WAIT_L(0); MMA(0, 1, At, B1); BAR;
;     LDA(At, 0, 1); STAGE(SA(0, 0), A, brow, t + 2);
;     BAR; WAIT_L(0); MMA(1, 0, At, B0); BAR; SCHED;
;     STAGE(SB(0, 1), Bt, bcol + HALF, t + 2);
;     WAIT_V(6); BAR; MMA(1, 1, At, B1); BAR;
.Lpk4:
	ds_read_b128 v[156:159], v155
	ds_read_b128 v[166:169], v155 offset:1024
	ds_read_b128 v[170:173], v155 offset:2048
	ds_read_b128 v[174:177], v155 offset:3072
	s_add_i32 s25, s17, s24
	v_readfirstlane_b32 s27, v152
	s_add_i32 s26, s25, 0x40080
	s_mov_b32 m0, s27
	v_readfirstlane_b32 s27, v151
	ds_read_b128 v[186:189], v143
	ds_read_b128 v[190:193], v143 offset:1024
	ds_read_b128 v[194:197], v142
	ds_read_b128 v[198:201], v142 offset:1024
	ds_read_b128 v[202:205], v141
	ds_read_b128 v[206:209], v141 offset:1024
	ds_read_b128 v[210:213], v140
	ds_read_b128 v[214:217], v140 offset:1024
	buffer_load_dwordx4 v32, s[8:11], s26 offen lds
	s_mov_b32 m0, s27
	s_nop 0
	buffer_load_dwordx4 v131, s[8:11], s26 offen lds
	s_waitcnt lgkmcnt(8)
	s_barrier
	s_waitcnt lgkmcnt(0)
	s_setprio 0
	s_waitcnt lgkmcnt(7)
	v_mfma_f32_16x16x32_bf16 v[126:129], v[186:189], v[156:159], 0
	v_mfma_f32_16x16x32_bf16 v[122:125], v[186:189], v[170:173], 0
	s_waitcnt lgkmcnt(5)
	v_mfma_f32_16x16x32_bf16 v[118:121], v[194:197], v[156:159], 0
	v_mfma_f32_16x16x32_bf16 v[114:117], v[194:197], v[170:173], 0
	s_waitcnt lgkmcnt(3)
	v_mfma_f32_16x16x32_bf16 v[110:113], v[202:205], v[156:159], 0
	v_mfma_f32_16x16x32_bf16 v[106:109], v[202:205], v[170:173], 0
	s_waitcnt lgkmcnt(1)
	v_mfma_f32_16x16x32_bf16 v[102:105], v[210:213], v[156:159], 0
	v_mfma_f32_16x16x32_bf16 v[98:101], v[210:213], v[170:173], 0
	v_mfma_f32_16x16x32_bf16 v[126:129], v[190:193], v[166:169], v[126:129]
	v_mfma_f32_16x16x32_bf16 v[122:125], v[190:193], v[174:177], v[122:125]
	v_mfma_f32_16x16x32_bf16 v[118:121], v[198:201], v[166:169], v[118:121]
	v_mfma_f32_16x16x32_bf16 v[114:117], v[198:201], v[174:177], v[114:117]
	v_mfma_f32_16x16x32_bf16 v[110:113], v[206:209], v[166:169], v[110:113]
	v_mfma_f32_16x16x32_bf16 v[106:109], v[206:209], v[174:177], v[106:109]
	s_waitcnt lgkmcnt(0)
	v_mfma_f32_16x16x32_bf16 v[102:105], v[214:217], v[166:169], v[102:105]
	v_mfma_f32_16x16x32_bf16 v[98:101], v[214:217], v[174:177], v[98:101]
	s_setprio 1
	s_barrier
	s_add_i32 s26, s16, s24
	v_readfirstlane_b32 s28, v137
	s_add_i32 s27, s26, 0x100
	s_mov_b32 m0, s28
	v_readfirstlane_b32 s28, v139
	ds_read_b128 v[218:221], v149
	ds_read_b128 v[222:225], v149 offset:1024
	ds_read_b128 v[226:229], v149 offset:2048
	ds_read_b128 v[230:233], v149 offset:3072
	buffer_load_dwordx4 v32, s[76:79], s27 offen lds
	s_mov_b32 m0, s28
	s_nop 0
	buffer_load_dwordx4 v131, s[76:79], s27 offen lds
	s_barrier
	s_waitcnt lgkmcnt(0)
	s_setprio 0
	s_waitcnt lgkmcnt(3)
	v_mfma_f32_16x16x32_bf16 v[94:97], v[186:189], v[218:221], 0
	s_waitcnt lgkmcnt(1)
	v_mfma_f32_16x16x32_bf16 v[90:93], v[186:189], v[226:229], 0
	v_mfma_f32_16x16x32_bf16 v[86:89], v[194:197], v[218:221], 0
	v_mfma_f32_16x16x32_bf16 v[82:85], v[194:197], v[226:229], 0
	v_mfma_f32_16x16x32_bf16 v[78:81], v[202:205], v[218:221], 0
	v_mfma_f32_16x16x32_bf16 v[74:77], v[202:205], v[226:229], 0
	v_mfma_f32_16x16x32_bf16 v[70:73], v[210:213], v[218:221], 0
	v_mfma_f32_16x16x32_bf16 v[66:69], v[210:213], v[226:229], 0
	v_mfma_f32_16x16x32_bf16 v[94:97], v[190:193], v[222:225], v[94:97]
	s_waitcnt lgkmcnt(0)
	v_mfma_f32_16x16x32_bf16 v[90:93], v[190:193], v[230:233], v[90:93]
	v_mfma_f32_16x16x32_bf16 v[86:89], v[198:201], v[222:225], v[86:89]
	v_mfma_f32_16x16x32_bf16 v[82:85], v[198:201], v[230:233], v[82:85]
	v_mfma_f32_16x16x32_bf16 v[78:81], v[206:209], v[222:225], v[78:81]
	v_mfma_f32_16x16x32_bf16 v[74:77], v[206:209], v[230:233], v[74:77]
	v_mfma_f32_16x16x32_bf16 v[70:73], v[214:217], v[222:225], v[70:73]
	v_mfma_f32_16x16x32_bf16 v[66:69], v[214:217], v[230:233], v[66:69]
	s_setprio 1
	v_readfirstlane_b32 s28, v136
	s_add_i32 s27, s25, 0x100
	s_mov_b32 m0, s28
	v_readfirstlane_b32 s28, v135
	s_barrier
	ds_read_b128 v[186:189], v143 offset:16384
	ds_read_b128 v[190:193], v143 offset:17408
	ds_read_b128 v[194:197], v142 offset:16384
	ds_read_b128 v[198:201], v142 offset:17408
	ds_read_b128 v[202:205], v141 offset:16384
	ds_read_b128 v[206:209], v141 offset:17408
	ds_read_b128 v[210:213], v140 offset:16384
	ds_read_b128 v[214:217], v140 offset:17408
	buffer_load_dwordx4 v32, s[8:11], s27 offen lds
	s_mov_b32 m0, s28
	s_nop 0
	buffer_load_dwordx4 v131, s[8:11], s27 offen lds
	s_barrier
	s_waitcnt lgkmcnt(0)
	s_setprio 0
	s_waitcnt lgkmcnt(7)
	v_mfma_f32_16x16x32_bf16 v[62:65], v[186:189], v[156:159], 0
	v_mfma_f32_16x16x32_bf16 v[58:61], v[186:189], v[170:173], 0
	s_waitcnt lgkmcnt(5)
	v_mfma_f32_16x16x32_bf16 v[54:57], v[194:197], v[156:159], 0
	v_mfma_f32_16x16x32_bf16 v[50:53], v[194:197], v[170:173], 0
	s_waitcnt lgkmcnt(3)
	v_mfma_f32_16x16x32_bf16 v[46:49], v[202:205], v[156:159], 0
	v_mfma_f32_16x16x32_bf16 v[42:45], v[202:205], v[170:173], 0
	s_waitcnt lgkmcnt(1)
	v_mfma_f32_16x16x32_bf16 v[38:41], v[210:213], v[156:159], 0
	v_mfma_f32_16x16x32_bf16 v[34:37], v[210:213], v[170:173], 0
	v_mfma_f32_16x16x32_bf16 v[62:65], v[190:193], v[166:169], v[62:65]
	v_mfma_f32_16x16x32_bf16 v[58:61], v[190:193], v[174:177], v[58:61]
	v_mfma_f32_16x16x32_bf16 v[54:57], v[198:201], v[166:169], v[54:57]
	v_mfma_f32_16x16x32_bf16 v[50:53], v[198:201], v[174:177], v[50:53]
	v_mfma_f32_16x16x32_bf16 v[46:49], v[206:209], v[166:169], v[46:49]
	v_mfma_f32_16x16x32_bf16 v[42:45], v[206:209], v[174:177], v[42:45]
	s_waitcnt lgkmcnt(0)
	v_mfma_f32_16x16x32_bf16 v[38:41], v[214:217], v[166:169], v[38:41]
	v_mfma_f32_16x16x32_bf16 v[34:37], v[214:217], v[174:177], v[34:37]
	s_setprio 1
	s_barrier
	v_readfirstlane_b32 s28, v134
	s_add_i32 s27, s26, 0x40100
	s_mov_b32 m0, s28
	v_readfirstlane_b32 s28, v138
	buffer_load_dwordx4 v32, s[76:79], s27 offen lds
	s_mov_b32 m0, s28
	s_nop 0
	buffer_load_dwordx4 v131, s[76:79], s27 offen lds
	s_waitcnt vmcnt(6)
	s_barrier
; #define STAGE(P, BASE, br, kt) do { int _so = ((br) * K + (kt) * BK) * 2; \
;     __builtin_amdgcn_raw_ptr_buffer_load_lds(rs_##BASE, (__attribute__((address_space(3))) void*)((char*)(P) + tx * 16), 16, voff0, _so, 0, 0); \
;     __builtin_amdgcn_raw_ptr_buffer_load_lds(rs_##BASE, (__attribute__((address_space(3))) void*)((char*)(P) + tx * 16 + 8192), 16, voff1, _so, 0, 0); } while (0)
; #define LDA(dst, b, h) _Pragma("unroll") for (int m = 0; m < 4; ++m) _Pragma("unroll") for (int k = 0; k < 2; ++k) \
;     dst[m][k] = *reinterpret_cast<const bf16x8*>((char*)SA(b, h) + lds_byte(wr * 64 + m * 16 + fr, k * 32 + fq * 8))
; #define LDB(dst, b, h) _Pragma("unroll") for (int n = 0; n < 2; ++n) _Pragma("unroll") for (int k = 0; k < 2; ++k) \
;     dst[n][k] = *reinterpret_cast<const bf16x8*>((char*)SB(b, h) + lds_byte(wc * 32 + n * 16 + fr, k * 32 + fq * 8))
; #define MMA(ai, bj, At, Bt_) do { __builtin_amdgcn_s_setprio(1); \
;     _Pragma("unroll") for (int m = 0; m < 4; ++m) _Pragma("unroll") for (int n = 0; n < 2; ++n) _Pragma("unroll") for (int k = 0; k < 2; ++k) \
;       acc[ai][bj][m][n] = __builtin_amdgcn_mfma_f32_16x16x32_bf16(At[m][k], Bt_[n][k], acc[ai][bj][m][n], 0, 0, 0); \
;     __builtin_amdgcn_s_setprio(0); } while (0)
; #define WAIT_V(n) asm volatile("s_waitcnt vmcnt(" #n ")" ::: "memory")
; #define WAIT_L(n) asm volatile("s_waitcnt lgkmcnt(" #n ")" ::: "memory")
; #define BAR __builtin_amdgcn_s_barrier()
; #define SCHED __builtin_amdgcn_sched_barrier(0)
; template <class Epi> ...
;     ...
;     WAIT_V(6); BAR; MMA(1, 1, At, B1); BAR;
;     LDB(B0, 1, 0); SCHED; LDA(At, 1, 0); STAGE(SA(0, 1), A, brow + HALF, t + 2);
;     WAIT_L(8); BAR; WAIT_L(0); MMA(0, 0, At, B0); BAR; SCHED;
;     LDB(B1, 1, 1); STAGE(SB(1, 0), Bt, bcol, t + 3);
;     BAR; WAIT_L(0); MMA(0, 1, At, B1); BAR;
;     LDA(At, 1, 1); STAGE(SA(1, 0), A, brow, t + 3);
	s_setprio 0
	v_mfma_f32_16x16x32_bf16 v[28:31], v[186:189], v[218:221], 0
	v_mfma_f32_16x16x32_bf16 v[24:27], v[186:189], v[226:229], 0
	v_mfma_f32_16x16x32_bf16 v[20:23], v[194:197], v[218:221], 0
	v_mfma_f32_16x16x32_bf16 v[16:19], v[194:197], v[226:229], 0
	v_mfma_f32_16x16x32_bf16 v[12:15], v[202:205], v[218:221], 0
	v_mfma_f32_16x16x32_bf16 v[8:11], v[202:205], v[226:229], 0
	v_mfma_f32_16x16x32_bf16 v[4:7], v[210:213], v[218:221], 0
	v_mfma_f32_16x16x32_bf16 v[0:3], v[210:213], v[226:229], 0
	v_mfma_f32_16x16x32_bf16 v[28:31], v[190:193], v[222:225], v[28:31]
	v_mfma_f32_16x16x32_bf16 v[24:27], v[190:193], v[230:233], v[24:27]
	v_mfma_f32_16x16x32_bf16 v[20:23], v[198:201], v[222:225], v[20:23]
	v_mfma_f32_16x16x32_bf16 v[16:19], v[198:201], v[230:233], v[16:19]
	v_mfma_f32_16x16x32_bf16 v[12:15], v[206:209], v[222:225], v[12:15]
	v_mfma_f32_16x16x32_bf16 v[8:11], v[206:209], v[230:233], v[8:11]
	v_mfma_f32_16x16x32_bf16 v[4:7], v[214:217], v[222:225], v[4:7]
	v_mfma_f32_16x16x32_bf16 v[0:3], v[214:217], v[230:233], v[0:3]
	s_setprio 1
	s_barrier
	ds_read_b128 v[156:159], v145
	ds_read_b128 v[166:169], v145 offset:1024
	ds_read_b128 v[170:173], v145 offset:2048
	ds_read_b128 v[174:177], v145 offset:3072
	v_readfirstlane_b32 s28, v133
	s_add_i32 s27, s25, 0x40100
	s_mov_b32 m0, s28
	v_readfirstlane_b32 s28, v132
	ds_read_b128 v[186:189], v143 offset:32768
	ds_read_b128 v[190:193], v143 offset:33792
	ds_read_b128 v[194:197], v142 offset:32768
	ds_read_b128 v[198:201], v142 offset:33792
	ds_read_b128 v[202:205], v141 offset:32768
	ds_read_b128 v[206:209], v141 offset:33792
	ds_read_b128 v[210:213], v140 offset:32768
	ds_read_b128 v[214:217], v140 offset:33792
	buffer_load_dwordx4 v32, s[8:11], s27 offen lds
	s_mov_b32 m0, s28
	s_nop 0
	buffer_load_dwordx4 v131, s[8:11], s27 offen lds
	s_waitcnt lgkmcnt(8)
	s_barrier
	s_waitcnt lgkmcnt(0)
	s_setprio 0
	s_waitcnt lgkmcnt(7)
	v_mfma_f32_16x16x32_bf16 v[126:129], v[186:189], v[156:159], v[126:129]
	v_mfma_f32_16x16x32_bf16 v[122:125], v[186:189], v[170:173], v[122:125]
	s_waitcnt lgkmcnt(5)
	v_mfma_f32_16x16x32_bf16 v[118:121], v[194:197], v[156:159], v[118:121]
	v_mfma_f32_16x16x32_bf16 v[114:117], v[194:197], v[170:173], v[114:117]
	s_waitcnt lgkmcnt(3)
	v_mfma_f32_16x16x32_bf16 v[110:113], v[202:205], v[156:159], v[110:113]
	v_mfma_f32_16x16x32_bf16 v[106:109], v[202:205], v[170:173], v[106:109]
	s_waitcnt lgkmcnt(1)
	v_mfma_f32_16x16x32_bf16 v[102:105], v[210:213], v[156:159], v[102:105]
	v_mfma_f32_16x16x32_bf16 v[98:101], v[210:213], v[170:173], v[98:101]
	v_mfma_f32_16x16x32_bf16 v[126:129], v[190:193], v[166:169], v[126:129]
	v_mfma_f32_16x16x32_bf16 v[122:125], v[190:193], v[174:177], v[122:125]
	v_mfma_f32_16x16x32_bf16 v[118:121], v[198:201], v[166:169], v[118:121]
	v_mfma_f32_16x16x32_bf16 v[114:117], v[198:201], v[174:177], v[114:117]
	v_mfma_f32_16x16x32_bf16 v[110:113], v[206:209], v[166:169], v[110:113]
	v_mfma_f32_16x16x32_bf16 v[106:109], v[206:209], v[174:177], v[106:109]
	s_waitcnt lgkmcnt(0)
	v_mfma_f32_16x16x32_bf16 v[102:105], v[214:217], v[166:169], v[102:105]
	v_mfma_f32_16x16x32_bf16 v[98:101], v[214:217], v[174:177], v[98:101]
	s_setprio 1
	s_barrier
	v_readfirstlane_b32 s28, v146
	s_add_i32 s27, s26, 0x180
	s_mov_b32 m0, s28
	v_readfirstlane_b32 s28, v147
	ds_read_b128 v[218:221], v144
	ds_read_b128 v[222:225], v144 offset:1024
	ds_read_b128 v[226:229], v144 offset:2048
	ds_read_b128 v[230:233], v144 offset:3072
	buffer_load_dwordx4 v32, s[76:79], s27 offen lds
	s_mov_b32 m0, s28
	s_nop 0
	buffer_load_dwordx4 v131, s[76:79], s27 offen lds
	s_barrier
	s_waitcnt lgkmcnt(0)
	s_setprio 0
	s_waitcnt lgkmcnt(3)
	v_mfma_f32_16x16x32_bf16 v[94:97], v[186:189], v[218:221], v[94:97]
	s_waitcnt lgkmcnt(1)
	v_mfma_f32_16x16x32_bf16 v[90:93], v[186:189], v[226:229], v[90:93]
	v_mfma_f32_16x16x32_bf16 v[86:89], v[194:197], v[218:221], v[86:89]
	v_mfma_f32_16x16x32_bf16 v[82:85], v[194:197], v[226:229], v[82:85]
	v_mfma_f32_16x16x32_bf16 v[78:81], v[202:205], v[218:221], v[78:81]
	v_mfma_f32_16x16x32_bf16 v[74:77], v[202:205], v[226:229], v[74:77]
	v_mfma_f32_16x16x32_bf16 v[70:73], v[210:213], v[218:221], v[70:73]
	v_mfma_f32_16x16x32_bf16 v[66:69], v[210:213], v[226:229], v[66:69]
	v_mfma_f32_16x16x32_bf16 v[94:97], v[190:193], v[222:225], v[94:97]
	s_waitcnt lgkmcnt(0)
	v_mfma_f32_16x16x32_bf16 v[90:93], v[190:193], v[230:233], v[90:93]
	v_mfma_f32_16x16x32_bf16 v[86:89], v[198:201], v[222:225], v[86:89]
	v_mfma_f32_16x16x32_bf16 v[82:85], v[198:201], v[230:233], v[82:85]
	v_mfma_f32_16x16x32_bf16 v[78:81], v[206:209], v[222:225], v[78:81]
	v_mfma_f32_16x16x32_bf16 v[74:77], v[206:209], v[230:233], v[74:77]
	v_mfma_f32_16x16x32_bf16 v[70:73], v[214:217], v[222:225], v[70:73]
	v_mfma_f32_16x16x32_bf16 v[66:69], v[214:217], v[230:233], v[66:69]
	s_setprio 1
	v_readfirstlane_b32 s27, v148
	s_addk_i32 s25, 0x180
	s_mov_b32 m0, s27
	v_readfirstlane_b32 s27, v150
	s_barrier
	ds_read_b128 v[186:189], v143 offset:49152
	ds_read_b128 v[190:193], v143 offset:50176
	ds_read_b128 v[194:197], v142 offset:49152
	ds_read_b128 v[198:201], v142 offset:50176
	ds_read_b128 v[202:205], v141 offset:49152
	ds_read_b128 v[206:209], v141 offset:50176
	ds_read_b128 v[210:213], v140 offset:49152
	ds_read_b128 v[214:217], v140 offset:50176
	buffer_load_dwordx4 v32, s[8:11], s25 offen lds
	s_mov_b32 m0, s27
	s_nop 0
	buffer_load_dwordx4 v131, s[8:11], s25 offen lds
	s_barrier
; #define STAGE(P, BASE, br, kt) do { int _so = ((br) * K + (kt) * BK) * 2; \
;     __builtin_amdgcn_raw_ptr_buffer_load_lds(rs_##BASE, (__attribute__((address_space(3))) void*)((char*)(P) + tx * 16), 16, voff0, _so, 0, 0); \
;     __builtin_amdgcn_raw_ptr_buffer_load_lds(rs_##BASE, (__attribute__((address_space(3))) void*)((char*)(P) + tx * 16 + 8192), 16, voff1, _so, 0, 0); } while (0)
; #define LDA(dst, b, h) _Pragma("unroll") for (int m = 0; m < 4; ++m) _Pragma("unroll") for (int k = 0; k < 2; ++k) \
;     dst[m][k] = *reinterpret_cast<const bf16x8*>((char*)SA(b, h) + lds_byte(wr * 64 + m * 16 + fr, k * 32 + fq * 8))
; #define LDB(dst, b, h) _Pragma("unroll") for (int n = 0; n < 2; ++n) _Pragma("unroll") for (int k = 0; k < 2; ++k) \
;     dst[n][k] = *reinterpret_cast<const bf16x8*>((char*)SB(b, h) + lds_byte(wc * 32 + n * 16 + fr, k * 32 + fq * 8))
; #define MMA(ai, bj, At, Bt_) do { __builtin_amdgcn_s_setprio(1); \
;     _Pragma("unroll") for (int m = 0; m < 4; ++m) _Pragma("unroll") for (int n = 0; n < 2; ++n) _Pragma("unroll") for (int k = 0; k < 2; ++k) \
;       acc[ai][bj][m][n] = __builtin_amdgcn_mfma_f32_16x16x32_bf16(At[m][k], Bt_[n][k], acc[ai][bj][m][n], 0, 0, 0); \
;     __builtin_amdgcn_s_setprio(0); } while (0)
; #define WAIT_V(n) asm volatile("s_waitcnt vmcnt(" #n ")" ::: "memory")
; #define WAIT_L(n) asm volatile("s_waitcnt lgkmcnt(" #n ")" ::: "memory")
; #define BAR __builtin_amdgcn_s_barrier()
; template <class Epi> ...
;     ...
;     LDB(B0, 0, 0); SCHED; LDA(At, 0, 0); STAGE(SA(1, 1), A, brow + HALF, t + 1);
;     WAIT_L(8); BAR; WAIT_L(0); MMA(0, 0, At, B0); BAR; SCHED;
;     LDB(B1, 0, 1); STAGE(SB(0, 0), Bt, bcol, t + 2);
;     BAR; WAIT_L(0); MMA(0, 1, At, B1); BAR;
;     LDA(At, 0, 1); STAGE(SA(0, 0), A, brow, t + 2);
;     BAR; WAIT_L(0); MMA(1, 0, At, B0); BAR; SCHED;
;     STAGE(SB(0, 1), Bt, bcol + HALF, t + 2);
;     WAIT_V(6); BAR; MMA(1, 1, At, B1); BAR;
;     LDB(B0, 1, 0); SCHED; LDA(At, 1, 0); STAGE(SA(0, 1), A, brow + HALF, t + 2);
;     WAIT_L(8); BAR; WAIT_L(0); MMA(0, 0, At, B0); BAR; SCHED;
;     LDB(B1, 1, 1); STAGE(SB(1, 0), Bt, bcol, t + 3);
;     BAR; WAIT_L(0); MMA(0, 1, At, B1); BAR;
;     LDA(At, 1, 1); STAGE(SA(1, 0), A, brow, t + 3);
;     BAR; WAIT_L(0); MMA(1, 0, At, B0); BAR; SCHED;
;     STAGE(SB(1, 1), Bt, bcol + HALF, t + 3);
;     WAIT_V(6); BAR; MMA(1, 1, At, B1); BAR;
	s_waitcnt lgkmcnt(0)
	s_setprio 0
	s_waitcnt lgkmcnt(7)
	v_mfma_f32_16x16x32_bf16 v[62:65], v[186:189], v[156:159], v[62:65]
	v_mfma_f32_16x16x32_bf16 v[58:61], v[186:189], v[170:173], v[58:61]
	s_waitcnt lgkmcnt(5)
	v_mfma_f32_16x16x32_bf16 v[54:57], v[194:197], v[156:159], v[54:57]
	v_mfma_f32_16x16x32_bf16 v[50:53], v[194:197], v[170:173], v[50:53]
	s_waitcnt lgkmcnt(3)
	v_mfma_f32_16x16x32_bf16 v[46:49], v[202:205], v[156:159], v[46:49]
	v_mfma_f32_16x16x32_bf16 v[42:45], v[202:205], v[170:173], v[42:45]
	s_waitcnt lgkmcnt(1)
	v_mfma_f32_16x16x32_bf16 v[38:41], v[210:213], v[156:159], v[38:41]
	v_mfma_f32_16x16x32_bf16 v[34:37], v[210:213], v[170:173], v[34:37]
	v_mfma_f32_16x16x32_bf16 v[62:65], v[190:193], v[166:169], v[62:65]
	v_mfma_f32_16x16x32_bf16 v[58:61], v[190:193], v[174:177], v[58:61]
	v_mfma_f32_16x16x32_bf16 v[54:57], v[198:201], v[166:169], v[54:57]
	v_mfma_f32_16x16x32_bf16 v[50:53], v[198:201], v[174:177], v[50:53]
	v_mfma_f32_16x16x32_bf16 v[46:49], v[206:209], v[166:169], v[46:49]
	v_mfma_f32_16x16x32_bf16 v[42:45], v[206:209], v[174:177], v[42:45]
	s_waitcnt lgkmcnt(0)
	v_mfma_f32_16x16x32_bf16 v[38:41], v[214:217], v[166:169], v[38:41]
	v_mfma_f32_16x16x32_bf16 v[34:37], v[214:217], v[174:177], v[34:37]
	s_setprio 1
	s_barrier
	v_readfirstlane_b32 s25, v153
	s_add_i32 s26, s26, 0x40180
	s_mov_b32 m0, s25
	v_readfirstlane_b32 s25, v154
	buffer_load_dwordx4 v32, s[76:79], s26 offen lds
	s_mov_b32 m0, s25
	s_nop 0
	buffer_load_dwordx4 v131, s[76:79], s26 offen lds
	s_waitcnt vmcnt(6)
	s_barrier
	s_setprio 0
	v_mfma_f32_16x16x32_bf16 v[28:31], v[186:189], v[218:221], v[28:31]
	v_mfma_f32_16x16x32_bf16 v[24:27], v[186:189], v[226:229], v[24:27]
	v_mfma_f32_16x16x32_bf16 v[20:23], v[194:197], v[218:221], v[20:23]
	v_mfma_f32_16x16x32_bf16 v[16:19], v[194:197], v[226:229], v[16:19]
	v_mfma_f32_16x16x32_bf16 v[12:15], v[202:205], v[218:221], v[12:15]
	v_mfma_f32_16x16x32_bf16 v[8:11], v[202:205], v[226:229], v[8:11]
	v_mfma_f32_16x16x32_bf16 v[4:7], v[210:213], v[218:221], v[4:7]
	v_mfma_f32_16x16x32_bf16 v[0:3], v[210:213], v[226:229], v[0:3]
	v_mfma_f32_16x16x32_bf16 v[28:31], v[190:193], v[222:225], v[28:31]
	v_mfma_f32_16x16x32_bf16 v[24:27], v[190:193], v[230:233], v[24:27]
	v_mfma_f32_16x16x32_bf16 v[20:23], v[198:201], v[222:225], v[20:23]
	v_mfma_f32_16x16x32_bf16 v[16:19], v[198:201], v[230:233], v[16:19]
	v_mfma_f32_16x16x32_bf16 v[12:15], v[206:209], v[222:225], v[12:15]
	v_mfma_f32_16x16x32_bf16 v[8:11], v[206:209], v[230:233], v[8:11]
	v_mfma_f32_16x16x32_bf16 v[4:7], v[214:217], v[222:225], v[4:7]
	v_mfma_f32_16x16x32_bf16 v[0:3], v[214:217], v[230:233], v[0:3]
	s_setprio 1
	s_add_i32 s23, s23, 2
	s_addk_i32 s24, 0x100
	s_cmp_lt_u32 s23, 12
	s_barrier
	s_cbranch_scc1 .LBB0_1927
	s_branch .Lpx4
.LBB0_1927:
	ds_read_b128 v[156:159], v155
	ds_read_b128 v[166:169], v155 offset:1024
	ds_read_b128 v[170:173], v155 offset:2048
	ds_read_b128 v[174:177], v155 offset:3072
	s_add_i32 s25, s17, s24
	v_readfirstlane_b32 s27, v152
	s_add_i32 s26, s25, 0x40080
	s_mov_b32 m0, s27
	v_readfirstlane_b32 s27, v151
	ds_read_b128 v[186:189], v143
	ds_read_b128 v[190:193], v143 offset:1024
	ds_read_b128 v[194:197], v142
	ds_read_b128 v[198:201], v142 offset:1024
	ds_read_b128 v[202:205], v141
	ds_read_b128 v[206:209], v141 offset:1024
	ds_read_b128 v[210:213], v140
	ds_read_b128 v[214:217], v140 offset:1024
	buffer_load_dwordx4 v32, s[8:11], s26 offen lds
	s_mov_b32 m0, s27
	s_nop 0
	buffer_load_dwordx4 v131, s[8:11], s26 offen lds
	s_waitcnt lgkmcnt(8)
	s_barrier
	s_waitcnt lgkmcnt(0)
	s_setprio 0
	s_waitcnt lgkmcnt(7)
	v_mfma_f32_16x16x32_bf16 v[126:129], v[186:189], v[156:159], v[126:129]
	v_mfma_f32_16x16x32_bf16 v[122:125], v[186:189], v[170:173], v[122:125]
	s_waitcnt lgkmcnt(5)
	v_mfma_f32_16x16x32_bf16 v[118:121], v[194:197], v[156:159], v[118:121]
	v_mfma_f32_16x16x32_bf16 v[114:117], v[194:197], v[170:173], v[114:117]
	s_waitcnt lgkmcnt(3)
	v_mfma_f32_16x16x32_bf16 v[110:113], v[202:205], v[156:159], v[110:113]
	v_mfma_f32_16x16x32_bf16 v[106:109], v[202:205], v[170:173], v[106:109]
	s_waitcnt lgkmcnt(1)
	v_mfma_f32_16x16x32_bf16 v[102:105], v[210:213], v[156:159], v[102:105]
	v_mfma_f32_16x16x32_bf16 v[98:101], v[210:213], v[170:173], v[98:101]
	v_mfma_f32_16x16x32_bf16 v[126:129], v[190:193], v[166:169], v[126:129]
	v_mfma_f32_16x16x32_bf16 v[122:125], v[190:193], v[174:177], v[122:125]
	v_mfma_f32_16x16x32_bf16 v[118:121], v[198:201], v[166:169], v[118:121]
	v_mfma_f32_16x16x32_bf16 v[114:117], v[198:201], v[174:177], v[114:117]
	v_mfma_f32_16x16x32_bf16 v[110:113], v[206:209], v[166:169], v[110:113]
	v_mfma_f32_16x16x32_bf16 v[106:109], v[206:209], v[174:177], v[106:109]
	s_waitcnt lgkmcnt(0)
	v_mfma_f32_16x16x32_bf16 v[102:105], v[214:217], v[166:169], v[102:105]
	v_mfma_f32_16x16x32_bf16 v[98:101], v[214:217], v[174:177], v[98:101]
	s_setprio 1
	s_barrier
	s_add_i32 s26, s16, s24
	v_readfirstlane_b32 s28, v137
	s_add_i32 s27, s26, 0x100
	s_mov_b32 m0, s28
	v_readfirstlane_b32 s28, v139
	ds_read_b128 v[218:221], v149
	ds_read_b128 v[222:225], v149 offset:1024
	ds_read_b128 v[226:229], v149 offset:2048
	ds_read_b128 v[230:233], v149 offset:3072
	buffer_load_dwordx4 v32, s[76:79], s27 offen lds
	s_mov_b32 m0, s28
	s_nop 0
	buffer_load_dwordx4 v131, s[76:79], s27 offen lds
	s_barrier
; #define STAGE(P, BASE, br, kt) do { int _so = ((br) * K + (kt) * BK) * 2; \
;     __builtin_amdgcn_raw_ptr_buffer_load_lds(rs_##BASE, (__attribute__((address_space(3))) void*)((char*)(P) + tx * 16), 16, voff0, _so, 0, 0); \
;     __builtin_amdgcn_raw_ptr_buffer_load_lds(rs_##BASE, (__attribute__((address_space(3))) void*)((char*)(P) + tx * 16 + 8192), 16, voff1, _so, 0, 0); } while (0)
; #define LDA(dst, b, h) _Pragma("unroll") for (int m = 0; m < 4; ++m) _Pragma("unroll") for (int k = 0; k < 2; ++k) \
;     dst[m][k] = *reinterpret_cast<const bf16x8*>((char*)SA(b, h) + lds_byte(wr * 64 + m * 16 + fr, k * 32 + fq * 8))
; #define LDB(dst, b, h) _Pragma("unroll") for (int n = 0; n < 2; ++n) _Pragma("unroll") for (int k = 0; k < 2; ++k) \
;     dst[n][k] = *reinterpret_cast<const bf16x8*>((char*)SB(b, h) + lds_byte(wc * 32 + n * 16 + fr, k * 32 + fq * 8))
; #define MMA(ai, bj, At, Bt_) do { __builtin_amdgcn_s_setprio(1); \
;     _Pragma("unroll") for (int m = 0; m < 4; ++m) _Pragma("unroll") for (int n = 0; n < 2; ++n) _Pragma("unroll") for (int k = 0; k < 2; ++k) \
;       acc[ai][bj][m][n] = __builtin_amdgcn_mfma_f32_16x16x32_bf16(At[m][k], Bt_[n][k], acc[ai][bj][m][n], 0, 0, 0); \
;     __builtin_amdgcn_s_setprio(0); } while (0)
; #define WAIT_V(n) asm volatile("s_waitcnt vmcnt(" #n ")" ::: "memory")
; #define WAIT_L(n) asm volatile("s_waitcnt lgkmcnt(" #n ")" ::: "memory")
; #define BAR __builtin_amdgcn_s_barrier()
; #define SCHED __builtin_amdgcn_sched_barrier(0)
; template <class Epi> ...
;     ...
;     BAR; WAIT_L(0); MMA(0, 1, At, B1); BAR;
;     LDA(At, 0, 1); STAGE(SA(0, 0), A, brow, t + 2);
;     BAR; WAIT_L(0); MMA(1, 0, At, B0); BAR; SCHED;
;     STAGE(SB(0, 1), Bt, bcol + HALF, t + 2);
;     WAIT_V(6); BAR; MMA(1, 1, At, B1); BAR;
;     LDB(B0, 1, 0); SCHED; LDA(At, 1, 0); STAGE(SA(0, 1), A, brow + HALF, t + 2);
	s_waitcnt lgkmcnt(0)
	s_setprio 0
	s_waitcnt lgkmcnt(3)
	v_mfma_f32_16x16x32_bf16 v[94:97], v[186:189], v[218:221], v[94:97]
	s_waitcnt lgkmcnt(1)
	v_mfma_f32_16x16x32_bf16 v[90:93], v[186:189], v[226:229], v[90:93]
	v_mfma_f32_16x16x32_bf16 v[86:89], v[194:197], v[218:221], v[86:89]
	v_mfma_f32_16x16x32_bf16 v[82:85], v[194:197], v[226:229], v[82:85]
	v_mfma_f32_16x16x32_bf16 v[78:81], v[202:205], v[218:221], v[78:81]
	v_mfma_f32_16x16x32_bf16 v[74:77], v[202:205], v[226:229], v[74:77]
	v_mfma_f32_16x16x32_bf16 v[70:73], v[210:213], v[218:221], v[70:73]
	v_mfma_f32_16x16x32_bf16 v[66:69], v[210:213], v[226:229], v[66:69]
	v_mfma_f32_16x16x32_bf16 v[94:97], v[190:193], v[222:225], v[94:97]
	s_waitcnt lgkmcnt(0)
	v_mfma_f32_16x16x32_bf16 v[90:93], v[190:193], v[230:233], v[90:93]
	v_mfma_f32_16x16x32_bf16 v[86:89], v[198:201], v[222:225], v[86:89]
	v_mfma_f32_16x16x32_bf16 v[82:85], v[198:201], v[230:233], v[82:85]
	v_mfma_f32_16x16x32_bf16 v[78:81], v[206:209], v[222:225], v[78:81]
	v_mfma_f32_16x16x32_bf16 v[74:77], v[206:209], v[230:233], v[74:77]
	v_mfma_f32_16x16x32_bf16 v[70:73], v[214:217], v[222:225], v[70:73]
	v_mfma_f32_16x16x32_bf16 v[66:69], v[214:217], v[230:233], v[66:69]
	s_setprio 1
	v_readfirstlane_b32 s28, v136
	s_add_i32 s27, s25, 0x100
	s_mov_b32 m0, s28
	v_readfirstlane_b32 s28, v135
	s_barrier
	ds_read_b128 v[186:189], v143 offset:16384
	ds_read_b128 v[190:193], v143 offset:17408
	ds_read_b128 v[194:197], v142 offset:16384
	ds_read_b128 v[198:201], v142 offset:17408
	ds_read_b128 v[202:205], v141 offset:16384
	ds_read_b128 v[206:209], v141 offset:17408
	ds_read_b128 v[210:213], v140 offset:16384
	ds_read_b128 v[214:217], v140 offset:17408
	buffer_load_dwordx4 v32, s[8:11], s27 offen lds
	s_mov_b32 m0, s28
	s_nop 0
	buffer_load_dwordx4 v131, s[8:11], s27 offen lds
	s_barrier
	s_waitcnt lgkmcnt(0)
	s_setprio 0
	s_waitcnt lgkmcnt(7)
	v_mfma_f32_16x16x32_bf16 v[62:65], v[186:189], v[156:159], v[62:65]
	v_mfma_f32_16x16x32_bf16 v[58:61], v[186:189], v[170:173], v[58:61]
	s_waitcnt lgkmcnt(5)
	v_mfma_f32_16x16x32_bf16 v[54:57], v[194:197], v[156:159], v[54:57]
	v_mfma_f32_16x16x32_bf16 v[50:53], v[194:197], v[170:173], v[50:53]
	s_waitcnt lgkmcnt(3)
	v_mfma_f32_16x16x32_bf16 v[46:49], v[202:205], v[156:159], v[46:49]
	v_mfma_f32_16x16x32_bf16 v[42:45], v[202:205], v[170:173], v[42:45]
	s_waitcnt lgkmcnt(1)
	v_mfma_f32_16x16x32_bf16 v[38:41], v[210:213], v[156:159], v[38:41]
	v_mfma_f32_16x16x32_bf16 v[34:37], v[210:213], v[170:173], v[34:37]
	v_mfma_f32_16x16x32_bf16 v[62:65], v[190:193], v[166:169], v[62:65]
	v_mfma_f32_16x16x32_bf16 v[58:61], v[190:193], v[174:177], v[58:61]
	v_mfma_f32_16x16x32_bf16 v[54:57], v[198:201], v[166:169], v[54:57]
	v_mfma_f32_16x16x32_bf16 v[50:53], v[198:201], v[174:177], v[50:53]
	v_mfma_f32_16x16x32_bf16 v[46:49], v[206:209], v[166:169], v[46:49]
	v_mfma_f32_16x16x32_bf16 v[42:45], v[206:209], v[174:177], v[42:45]
	s_waitcnt lgkmcnt(0)
	v_mfma_f32_16x16x32_bf16 v[38:41], v[214:217], v[166:169], v[38:41]
	v_mfma_f32_16x16x32_bf16 v[34:37], v[214:217], v[174:177], v[34:37]
	s_setprio 1
	s_barrier
	v_readfirstlane_b32 s28, v134
	s_add_i32 s27, s26, 0x40100
	s_mov_b32 m0, s28
	v_readfirstlane_b32 s28, v138
	buffer_load_dwordx4 v32, s[76:79], s27 offen lds
	s_mov_b32 m0, s28
	s_nop 0
	buffer_load_dwordx4 v131, s[76:79], s27 offen lds
	s_waitcnt vmcnt(6)
	s_barrier
	s_setprio 0
	v_mfma_f32_16x16x32_bf16 v[28:31], v[186:189], v[218:221], v[28:31]
	v_mfma_f32_16x16x32_bf16 v[24:27], v[186:189], v[226:229], v[24:27]
	v_mfma_f32_16x16x32_bf16 v[20:23], v[194:197], v[218:221], v[20:23]
	v_mfma_f32_16x16x32_bf16 v[16:19], v[194:197], v[226:229], v[16:19]
	v_mfma_f32_16x16x32_bf16 v[12:15], v[202:205], v[218:221], v[12:15]
	v_mfma_f32_16x16x32_bf16 v[8:11], v[202:205], v[226:229], v[8:11]
	v_mfma_f32_16x16x32_bf16 v[4:7], v[210:213], v[218:221], v[4:7]
	v_mfma_f32_16x16x32_bf16 v[0:3], v[210:213], v[226:229], v[0:3]
	v_mfma_f32_16x16x32_bf16 v[28:31], v[190:193], v[222:225], v[28:31]
	v_mfma_f32_16x16x32_bf16 v[24:27], v[190:193], v[230:233], v[24:27]
	v_mfma_f32_16x16x32_bf16 v[20:23], v[198:201], v[222:225], v[20:23]
	v_mfma_f32_16x16x32_bf16 v[16:19], v[198:201], v[230:233], v[16:19]
	v_mfma_f32_16x16x32_bf16 v[12:15], v[206:209], v[222:225], v[12:15]
	v_mfma_f32_16x16x32_bf16 v[8:11], v[206:209], v[230:233], v[8:11]
	v_mfma_f32_16x16x32_bf16 v[4:7], v[214:217], v[222:225], v[4:7]
	v_mfma_f32_16x16x32_bf16 v[0:3], v[214:217], v[230:233], v[0:3]
	s_setprio 1
	s_barrier
	ds_read_b128 v[156:159], v145
	ds_read_b128 v[166:169], v145 offset:1024
	ds_read_b128 v[170:173], v145 offset:2048
	ds_read_b128 v[174:177], v145 offset:3072
	v_readfirstlane_b32 s28, v133
	s_add_i32 s27, s25, 0x40100
	s_mov_b32 m0, s28
	v_readfirstlane_b32 s28, v132
	ds_read_b128 v[186:189], v143 offset:32768
	ds_read_b128 v[190:193], v143 offset:33792
	ds_read_b128 v[194:197], v142 offset:32768
	ds_read_b128 v[198:201], v142 offset:33792
	ds_read_b128 v[202:205], v141 offset:32768
	ds_read_b128 v[206:209], v141 offset:33792
	ds_read_b128 v[210:213], v140 offset:32768
	ds_read_b128 v[214:217], v140 offset:33792
	buffer_load_dwordx4 v32, s[8:11], s27 offen lds
	s_mov_b32 m0, s28
	s_nop 0
	buffer_load_dwordx4 v131, s[8:11], s27 offen lds
	s_waitcnt lgkmcnt(8)
	s_barrier
; #define STAGE(P, BASE, br, kt) do { int _so = ((br) * K + (kt) * BK) * 2; \
;     __builtin_amdgcn_raw_ptr_buffer_load_lds(rs_##BASE, (__attribute__((address_space(3))) void*)((char*)(P) + tx * 16), 16, voff0, _so, 0, 0); \
;     __builtin_amdgcn_raw_ptr_buffer_load_lds(rs_##BASE, (__attribute__((address_space(3))) void*)((char*)(P) + tx * 16 + 8192), 16, voff1, _so, 0, 0); } while (0)
; #define LDA(dst, b, h) _Pragma("unroll") for (int m = 0; m < 4; ++m) _Pragma("unroll") for (int k = 0; k < 2; ++k) \
;     dst[m][k] = *reinterpret_cast<const bf16x8*>((char*)SA(b, h) + lds_byte(wr * 64 + m * 16 + fr, k * 32 + fq * 8))
; #define LDB(dst, b, h) _Pragma("unroll") for (int n = 0; n < 2; ++n) _Pragma("unroll") for (int k = 0; k < 2; ++k) \
;     dst[n][k] = *reinterpret_cast<const bf16x8*>((char*)SB(b, h) + lds_byte(wc * 32 + n * 16 + fr, k * 32 + fq * 8))
; #define MMA(ai, bj, At, Bt_) do { __builtin_amdgcn_s_setprio(1); \
;     _Pragma("unroll") for (int m = 0; m < 4; ++m) _Pragma("unroll") for (int n = 0; n < 2; ++n) _Pragma("unroll") for (int k = 0; k < 2; ++k) \
;       acc[ai][bj][m][n] = __builtin_amdgcn_mfma_f32_16x16x32_bf16(At[m][k], Bt_[n][k], acc[ai][bj][m][n], 0, 0, 0); \
;     __builtin_amdgcn_s_setprio(0); } while (0)
; #define WAIT_V(n) asm volatile("s_waitcnt vmcnt(" #n ")" ::: "memory")
; #define WAIT_L(n) asm volatile("s_waitcnt lgkmcnt(" #n ")" ::: "memory")
; #define BAR __builtin_amdgcn_s_barrier()
; #define SCHED __builtin_amdgcn_sched_barrier(0)
; template <class Epi> ...
;     ...
;     WAIT_L(8); BAR; WAIT_L(0); MMA(0, 0, At, B0); BAR; SCHED;
;     LDB(B1, 1, 1); STAGE(SB(1, 0), Bt, bcol, t + 3);
;     BAR; WAIT_L(0); MMA(0, 1, At, B1); BAR;
;     LDA(At, 1, 1); STAGE(SA(1, 0), A, brow, t + 3);
;     BAR; WAIT_L(0); MMA(1, 0, At, B0); BAR; SCHED;
;     STAGE(SB(1, 1), Bt, bcol + HALF, t + 3);
;     WAIT_V(6); BAR; MMA(1, 1, At, B1); BAR;
	s_waitcnt lgkmcnt(0)
	s_setprio 0
	s_waitcnt lgkmcnt(7)
	v_mfma_f32_16x16x32_bf16 v[126:129], v[186:189], v[156:159], v[126:129]
	v_mfma_f32_16x16x32_bf16 v[122:125], v[186:189], v[170:173], v[122:125]
	s_waitcnt lgkmcnt(5)
	v_mfma_f32_16x16x32_bf16 v[118:121], v[194:197], v[156:159], v[118:121]
	v_mfma_f32_16x16x32_bf16 v[114:117], v[194:197], v[170:173], v[114:117]
	s_waitcnt lgkmcnt(3)
	v_mfma_f32_16x16x32_bf16 v[110:113], v[202:205], v[156:159], v[110:113]
	v_mfma_f32_16x16x32_bf16 v[106:109], v[202:205], v[170:173], v[106:109]
	s_waitcnt lgkmcnt(1)
	v_mfma_f32_16x16x32_bf16 v[102:105], v[210:213], v[156:159], v[102:105]
	v_mfma_f32_16x16x32_bf16 v[98:101], v[210:213], v[170:173], v[98:101]
	v_mfma_f32_16x16x32_bf16 v[126:129], v[190:193], v[166:169], v[126:129]
	v_mfma_f32_16x16x32_bf16 v[122:125], v[190:193], v[174:177], v[122:125]
	v_mfma_f32_16x16x32_bf16 v[118:121], v[198:201], v[166:169], v[118:121]
	v_mfma_f32_16x16x32_bf16 v[114:117], v[198:201], v[174:177], v[114:117]
	v_mfma_f32_16x16x32_bf16 v[110:113], v[206:209], v[166:169], v[110:113]
	v_mfma_f32_16x16x32_bf16 v[106:109], v[206:209], v[174:177], v[106:109]
	s_waitcnt lgkmcnt(0)
	v_mfma_f32_16x16x32_bf16 v[102:105], v[214:217], v[166:169], v[102:105]
	v_mfma_f32_16x16x32_bf16 v[98:101], v[214:217], v[174:177], v[98:101]
	s_setprio 1
	s_barrier
	v_readfirstlane_b32 s28, v146
	s_add_i32 s27, s26, 0x180
	s_mov_b32 m0, s28
	v_readfirstlane_b32 s28, v147
	ds_read_b128 v[218:221], v144
	ds_read_b128 v[222:225], v144 offset:1024
	ds_read_b128 v[226:229], v144 offset:2048
	ds_read_b128 v[230:233], v144 offset:3072
	buffer_load_dwordx4 v32, s[76:79], s27 offen lds
	s_mov_b32 m0, s28
	s_nop 0
	buffer_load_dwordx4 v131, s[76:79], s27 offen lds
	s_barrier
	s_waitcnt lgkmcnt(0)
	s_setprio 0
	s_waitcnt lgkmcnt(3)
	v_mfma_f32_16x16x32_bf16 v[94:97], v[186:189], v[218:221], v[94:97]
	s_waitcnt lgkmcnt(1)
	v_mfma_f32_16x16x32_bf16 v[90:93], v[186:189], v[226:229], v[90:93]
	v_mfma_f32_16x16x32_bf16 v[86:89], v[194:197], v[218:221], v[86:89]
	v_mfma_f32_16x16x32_bf16 v[82:85], v[194:197], v[226:229], v[82:85]
	v_mfma_f32_16x16x32_bf16 v[78:81], v[202:205], v[218:221], v[78:81]
	v_mfma_f32_16x16x32_bf16 v[74:77], v[202:205], v[226:229], v[74:77]
	v_mfma_f32_16x16x32_bf16 v[70:73], v[210:213], v[218:221], v[70:73]
	v_mfma_f32_16x16x32_bf16 v[66:69], v[210:213], v[226:229], v[66:69]
	v_mfma_f32_16x16x32_bf16 v[94:97], v[190:193], v[222:225], v[94:97]
	s_waitcnt lgkmcnt(0)
	v_mfma_f32_16x16x32_bf16 v[90:93], v[190:193], v[230:233], v[90:93]
	v_mfma_f32_16x16x32_bf16 v[86:89], v[198:201], v[222:225], v[86:89]
	v_mfma_f32_16x16x32_bf16 v[82:85], v[198:201], v[230:233], v[82:85]
	v_mfma_f32_16x16x32_bf16 v[78:81], v[206:209], v[222:225], v[78:81]
	v_mfma_f32_16x16x32_bf16 v[74:77], v[206:209], v[230:233], v[74:77]
	v_mfma_f32_16x16x32_bf16 v[70:73], v[214:217], v[222:225], v[70:73]
	v_mfma_f32_16x16x32_bf16 v[66:69], v[214:217], v[230:233], v[66:69]
	s_setprio 1
	v_readfirstlane_b32 s27, v148
	s_addk_i32 s25, 0x180
	s_mov_b32 m0, s27
	v_readfirstlane_b32 s27, v150
	s_barrier
	ds_read_b128 v[186:189], v143 offset:49152
	ds_read_b128 v[190:193], v143 offset:50176
	ds_read_b128 v[194:197], v142 offset:49152
	ds_read_b128 v[198:201], v142 offset:50176
	ds_read_b128 v[202:205], v141 offset:49152
	ds_read_b128 v[206:209], v141 offset:50176
	ds_read_b128 v[210:213], v140 offset:49152
	ds_read_b128 v[214:217], v140 offset:50176
	buffer_load_dwordx4 v32, s[8:11], s25 offen lds
	s_mov_b32 m0, s27
	s_nop 0
	buffer_load_dwordx4 v131, s[8:11], s25 offen lds
	s_barrier
	s_waitcnt lgkmcnt(0)
	s_setprio 0
	s_waitcnt lgkmcnt(7)
	v_mfma_f32_16x16x32_bf16 v[62:65], v[186:189], v[156:159], v[62:65]
	v_mfma_f32_16x16x32_bf16 v[58:61], v[186:189], v[170:173], v[58:61]
	s_waitcnt lgkmcnt(5)
	v_mfma_f32_16x16x32_bf16 v[54:57], v[194:197], v[156:159], v[54:57]
	v_mfma_f32_16x16x32_bf16 v[50:53], v[194:197], v[170:173], v[50:53]
	s_waitcnt lgkmcnt(3)
	v_mfma_f32_16x16x32_bf16 v[46:49], v[202:205], v[156:159], v[46:49]
	v_mfma_f32_16x16x32_bf16 v[42:45], v[202:205], v[170:173], v[42:45]
	s_waitcnt lgkmcnt(1)
	v_mfma_f32_16x16x32_bf16 v[38:41], v[210:213], v[156:159], v[38:41]
	v_mfma_f32_16x16x32_bf16 v[34:37], v[210:213], v[170:173], v[34:37]
	v_mfma_f32_16x16x32_bf16 v[62:65], v[190:193], v[166:169], v[62:65]
	v_mfma_f32_16x16x32_bf16 v[58:61], v[190:193], v[174:177], v[58:61]
	v_mfma_f32_16x16x32_bf16 v[54:57], v[198:201], v[166:169], v[54:57]
	v_mfma_f32_16x16x32_bf16 v[50:53], v[198:201], v[174:177], v[50:53]
	v_mfma_f32_16x16x32_bf16 v[46:49], v[206:209], v[166:169], v[46:49]
	v_mfma_f32_16x16x32_bf16 v[42:45], v[206:209], v[174:177], v[42:45]
	s_waitcnt lgkmcnt(0)
	v_mfma_f32_16x16x32_bf16 v[38:41], v[214:217], v[166:169], v[38:41]
	v_mfma_f32_16x16x32_bf16 v[34:37], v[214:217], v[174:177], v[34:37]
	s_setprio 1
	s_barrier
	v_readfirstlane_b32 s25, v153
	s_add_i32 s26, s26, 0x40180
	s_mov_b32 m0, s25
	v_readfirstlane_b32 s25, v154
	buffer_load_dwordx4 v32, s[76:79], s26 offen lds
	s_mov_b32 m0, s25
	s_nop 0
	buffer_load_dwordx4 v131, s[76:79], s26 offen lds
	s_waitcnt vmcnt(6)
	s_barrier
	s_setprio 0
	v_mfma_f32_16x16x32_bf16 v[28:31], v[186:189], v[218:221], v[28:31]
	v_mfma_f32_16x16x32_bf16 v[24:27], v[186:189], v[226:229], v[24:27]
	v_mfma_f32_16x16x32_bf16 v[20:23], v[194:197], v[218:221], v[20:23]
	v_mfma_f32_16x16x32_bf16 v[16:19], v[194:197], v[226:229], v[16:19]
	v_mfma_f32_16x16x32_bf16 v[12:15], v[202:205], v[218:221], v[12:15]
	v_mfma_f32_16x16x32_bf16 v[8:11], v[202:205], v[226:229], v[8:11]
	v_mfma_f32_16x16x32_bf16 v[4:7], v[210:213], v[218:221], v[4:7]
	v_mfma_f32_16x16x32_bf16 v[0:3], v[210:213], v[226:229], v[0:3]
	v_mfma_f32_16x16x32_bf16 v[28:31], v[190:193], v[222:225], v[28:31]
	v_mfma_f32_16x16x32_bf16 v[24:27], v[190:193], v[230:233], v[24:27]
	v_mfma_f32_16x16x32_bf16 v[20:23], v[198:201], v[222:225], v[20:23]
	v_mfma_f32_16x16x32_bf16 v[16:19], v[198:201], v[230:233], v[16:19]
	v_mfma_f32_16x16x32_bf16 v[12:15], v[206:209], v[222:225], v[12:15]
	v_mfma_f32_16x16x32_bf16 v[8:11], v[206:209], v[230:233], v[8:11]
	v_mfma_f32_16x16x32_bf16 v[4:7], v[214:217], v[222:225], v[4:7]
	v_mfma_f32_16x16x32_bf16 v[0:3], v[214:217], v[230:233], v[0:3]
	s_setprio 1
	s_add_i32 s23, s23, 2
	s_addk_i32 s24, 0x100
	s_cmp_lt_u32 s23, 12
	s_barrier
	s_cbranch_scc1 .LBB0_1927
; #define STAGE(P, BASE, br, kt) do { int _so = ((br) * K + (kt) * BK) * 2; \
;     __builtin_amdgcn_raw_ptr_buffer_load_lds(rs_##BASE, (__attribute__((address_space(3))) void*)((char*)(P) + tx * 16), 16, voff0, _so, 0, 0); \
;     __builtin_amdgcn_raw_ptr_buffer_load_lds(rs_##BASE, (__attribute__((address_space(3))) void*)((char*)(P) + tx * 16 + 8192), 16, voff1, _so, 0, 0); } while (0)
; #define LDA(dst, b, h) _Pragma("unroll") for (int m = 0; m < 4; ++m) _Pragma("unroll") for (int k = 0; k < 2; ++k) \
;     dst[m][k] = *reinterpret_cast<const bf16x8*>((char*)SA(b, h) + lds_byte(wr * 64 + m * 16 + fr, k * 32 + fq * 8))
; #define LDB(dst, b, h) _Pragma("unroll") for (int n = 0; n < 2; ++n) _Pragma("unroll") for (int k = 0; k < 2; ++k) \
;     dst[n][k] = *reinterpret_cast<const bf16x8*>((char*)SB(b, h) + lds_byte(wc * 32 + n * 16 + fr, k * 32 + fq * 8))
; #define MMA(ai, bj, At, Bt_) do { __builtin_amdgcn_s_setprio(1); \
;     _Pragma("unroll") for (int m = 0; m < 4; ++m) _Pragma("unroll") for (int n = 0; n < 2; ++n) _Pragma("unroll") for (int k = 0; k < 2; ++k) \
;       acc[ai][bj][m][n] = __builtin_amdgcn_mfma_f32_16x16x32_bf16(At[m][k], Bt_[n][k], acc[ai][bj][m][n], 0, 0, 0); \
;     __builtin_amdgcn_s_setprio(0); } while (0)
; #define WAIT_V(n) asm volatile("s_waitcnt vmcnt(" #n ")" ::: "memory")
; #define WAIT_L(n) asm volatile("s_waitcnt lgkmcnt(" #n ")" ::: "memory")
; #define BAR __builtin_amdgcn_s_barrier()
; template <class Epi> ...
;     ...
;   { LDB(B0, 0, 0); LDA(At, 0, 0); STAGE(SA(1, 1), A, brow + HALF, nt - 1);
;     BAR; WAIT_L(0); MMA(0, 0, At, B0); BAR;
;     LDB(B1, 0, 1); BAR; WAIT_L(0); MMA(0, 1, At, B1); BAR;
;     LDA(At, 0, 1); WAIT_V(4); BAR; WAIT_L(0); MMA(1, 0, At, B0); MMA(1, 1, At, B1); BAR; }
.Lpx4:
	s_or_b32 s16, s17, 0x40780
	v_readfirstlane_b32 s17, v152
	s_mov_b32 s10, s78
	s_mov_b32 s11, s79
	s_mov_b32 m0, s17
	v_readfirstlane_b32 s17, v151
	ds_read_b128 v[156:159], v155
	ds_read_b128 v[166:169], v155 offset:1024
	ds_read_b128 v[170:173], v155 offset:2048
	ds_read_b128 v[174:177], v155 offset:3072
	ds_read_b128 v[186:189], v143
	ds_read_b128 v[190:193], v143 offset:1024
	ds_read_b128 v[194:197], v142
	ds_read_b128 v[198:201], v142 offset:1024
	ds_read_b128 v[202:205], v141
	ds_read_b128 v[206:209], v141 offset:1024
	ds_read_b128 v[210:213], v140
	ds_read_b128 v[214:217], v140 offset:1024
	buffer_load_dwordx4 v32, s[8:11], s16 offen lds
	s_mov_b32 m0, s17
	s_nop 0
	buffer_load_dwordx4 v131, s[8:11], s16 offen lds
	s_barrier
	s_waitcnt lgkmcnt(0)
	s_setprio 0
	s_waitcnt lgkmcnt(7)
	v_mfma_f32_16x16x32_bf16 v[126:129], v[186:189], v[156:159], v[126:129]
	v_mfma_f32_16x16x32_bf16 v[122:125], v[186:189], v[170:173], v[122:125]
	s_waitcnt lgkmcnt(5)
	v_mfma_f32_16x16x32_bf16 v[118:121], v[194:197], v[156:159], v[118:121]
	v_mfma_f32_16x16x32_bf16 v[114:117], v[194:197], v[170:173], v[114:117]
	s_waitcnt lgkmcnt(3)
	v_mfma_f32_16x16x32_bf16 v[110:113], v[202:205], v[156:159], v[110:113]
	v_mfma_f32_16x16x32_bf16 v[106:109], v[202:205], v[170:173], v[106:109]
	s_waitcnt lgkmcnt(1)
	v_mfma_f32_16x16x32_bf16 v[102:105], v[210:213], v[156:159], v[102:105]
	v_mfma_f32_16x16x32_bf16 v[98:101], v[210:213], v[170:173], v[98:101]
	v_mfma_f32_16x16x32_bf16 v[126:129], v[190:193], v[166:169], v[126:129]
	v_mfma_f32_16x16x32_bf16 v[122:125], v[190:193], v[174:177], v[122:125]
	v_mfma_f32_16x16x32_bf16 v[118:121], v[198:201], v[166:169], v[118:121]
	v_mfma_f32_16x16x32_bf16 v[114:117], v[198:201], v[174:177], v[114:117]
	v_mfma_f32_16x16x32_bf16 v[110:113], v[206:209], v[166:169], v[110:113]
	v_mfma_f32_16x16x32_bf16 v[106:109], v[206:209], v[174:177], v[106:109]
	s_waitcnt lgkmcnt(0)
	v_mfma_f32_16x16x32_bf16 v[102:105], v[214:217], v[166:169], v[102:105]
	v_mfma_f32_16x16x32_bf16 v[98:101], v[214:217], v[174:177], v[98:101]
	s_setprio 1
	s_barrier
	ds_read_b128 v[150:153], v149
	ds_read_b128 v[218:221], v149 offset:1024
	ds_read_b128 v[222:225], v149 offset:2048
	ds_read_b128 v[146:149], v149 offset:3072
	s_barrier
	s_waitcnt lgkmcnt(0)
	s_setprio 0
	s_waitcnt lgkmcnt(3)
	v_mfma_f32_16x16x32_bf16 v[78:81], v[202:205], v[150:153], v[78:81]
	s_waitcnt lgkmcnt(1)
	v_mfma_f32_16x16x32_bf16 v[74:77], v[202:205], v[222:225], v[74:77]
	v_mfma_f32_16x16x32_bf16 v[70:73], v[210:213], v[150:153], v[70:73]
	v_mfma_f32_16x16x32_bf16 v[66:69], v[210:213], v[222:225], v[66:69]
	v_mfma_f32_16x16x32_bf16 v[94:97], v[186:189], v[150:153], v[94:97]
	v_mfma_f32_16x16x32_bf16 v[90:93], v[186:189], v[222:225], v[90:93]
	v_mfma_f32_16x16x32_bf16 v[86:89], v[194:197], v[150:153], v[86:89]
	v_mfma_f32_16x16x32_bf16 v[82:85], v[194:197], v[222:225], v[82:85]
	v_mfma_f32_16x16x32_bf16 v[78:81], v[206:209], v[218:221], v[78:81]
	s_waitcnt lgkmcnt(0)
	v_mfma_f32_16x16x32_bf16 v[74:77], v[206:209], v[146:149], v[74:77]
	v_mfma_f32_16x16x32_bf16 v[70:73], v[214:217], v[218:221], v[70:73]
	v_mfma_f32_16x16x32_bf16 v[66:69], v[214:217], v[146:149], v[66:69]
	v_mfma_f32_16x16x32_bf16 v[226:229], v[190:193], v[218:221], v[94:97]
	v_mfma_f32_16x16x32_bf16 v[186:189], v[190:193], v[146:149], v[90:93]
	v_mfma_f32_16x16x32_bf16 v[190:193], v[198:201], v[218:221], v[86:89]
	v_mfma_f32_16x16x32_bf16 v[194:197], v[198:201], v[146:149], v[82:85]
	s_setprio 1
	s_barrier
	s_nop 0
	ds_read_b128 v[82:85], v143 offset:16384
	ds_read_b128 v[86:89], v143 offset:17408
	ds_read_b128 v[90:93], v142 offset:16384
	ds_read_b128 v[94:97], v142 offset:17408
	ds_read_b128 v[198:201], v141 offset:16384
	ds_read_b128 v[202:205], v141 offset:17408
	ds_read_b128 v[206:209], v140 offset:16384
	ds_read_b128 v[210:213], v140 offset:17408
	s_waitcnt vmcnt(4)
	s_barrier
	s_waitcnt lgkmcnt(0)
	s_setprio 0
	s_waitcnt lgkmcnt(3)
	v_mfma_f32_16x16x32_bf16 v[46:49], v[198:201], v[156:159], v[46:49]
	v_mfma_f32_16x16x32_bf16 v[42:45], v[198:201], v[170:173], v[42:45]
	s_waitcnt lgkmcnt(1)
	v_mfma_f32_16x16x32_bf16 v[38:41], v[206:209], v[156:159], v[38:41]
	v_mfma_f32_16x16x32_bf16 v[34:37], v[206:209], v[170:173], v[34:37]
	v_mfma_f32_16x16x32_bf16 v[62:65], v[82:85], v[156:159], v[62:65]
	v_mfma_f32_16x16x32_bf16 v[58:61], v[82:85], v[170:173], v[58:61]
	v_mfma_f32_16x16x32_bf16 v[54:57], v[90:93], v[156:159], v[54:57]
	v_mfma_f32_16x16x32_bf16 v[50:53], v[90:93], v[170:173], v[50:53]
	v_mfma_f32_16x16x32_bf16 v[46:49], v[202:205], v[166:169], v[46:49]
	v_mfma_f32_16x16x32_bf16 v[42:45], v[202:205], v[174:177], v[42:45]
	s_waitcnt lgkmcnt(0)
	v_mfma_f32_16x16x32_bf16 v[38:41], v[210:213], v[166:169], v[38:41]
	v_mfma_f32_16x16x32_bf16 v[34:37], v[210:213], v[174:177], v[34:37]
	v_mfma_f32_16x16x32_bf16 v[214:217], v[86:89], v[166:169], v[62:65]
	v_mfma_f32_16x16x32_bf16 v[230:233], v[86:89], v[174:177], v[58:61]
	v_mfma_f32_16x16x32_bf16 v[234:237], v[94:97], v[166:169], v[54:57]
	v_mfma_f32_16x16x32_bf16 v[238:241], v[94:97], v[174:177], v[50:53]
	s_setprio 1
	s_setprio 0
	v_mfma_f32_16x16x32_bf16 v[0:3], v[206:209], v[222:225], v[0:3]
	v_mfma_f32_16x16x32_bf16 v[28:31], v[82:85], v[150:153], v[28:31]
	v_mfma_f32_16x16x32_bf16 v[24:27], v[82:85], v[222:225], v[24:27]
	v_mfma_f32_16x16x32_bf16 v[20:23], v[90:93], v[150:153], v[20:23]
	v_mfma_f32_16x16x32_bf16 v[16:19], v[90:93], v[222:225], v[16:19]
	v_mfma_f32_16x16x32_bf16 v[12:15], v[198:201], v[150:153], v[12:15]
	v_mfma_f32_16x16x32_bf16 v[8:11], v[198:201], v[222:225], v[8:11]
	v_mfma_f32_16x16x32_bf16 v[4:7], v[206:209], v[150:153], v[4:7]
	v_mfma_f32_16x16x32_bf16 v[0:3], v[210:213], v[146:149], v[0:3]
	v_mfma_f32_16x16x32_bf16 v[154:157], v[86:89], v[218:221], v[28:31]
	v_mfma_f32_16x16x32_bf16 v[158:161], v[86:89], v[146:149], v[24:27]
	v_mfma_f32_16x16x32_bf16 v[166:169], v[94:97], v[218:221], v[20:23]
	v_mfma_f32_16x16x32_bf16 v[170:173], v[94:97], v[146:149], v[16:19]
	v_mfma_f32_16x16x32_bf16 v[174:177], v[202:205], v[218:221], v[12:15]
	v_mfma_f32_16x16x32_bf16 v[198:201], v[202:205], v[146:149], v[8:11]
	v_mfma_f32_16x16x32_bf16 v[150:153], v[210:213], v[218:221], v[4:7]
	s_setprio 1
	s_barrier
; #define LDA(dst, b, h) _Pragma("unroll") for (int m = 0; m < 4; ++m) _Pragma("unroll") for (int k = 0; k < 2; ++k) \
;     dst[m][k] = *reinterpret_cast<const bf16x8*>((char*)SA(b, h) + lds_byte(wr * 64 + m * 16 + fr, k * 32 + fq * 8))
; #define LDB(dst, b, h) _Pragma("unroll") for (int n = 0; n < 2; ++n) _Pragma("unroll") for (int k = 0; k < 2; ++k) \
;     dst[n][k] = *reinterpret_cast<const bf16x8*>((char*)SB(b, h) + lds_byte(wc * 32 + n * 16 + fr, k * 32 + fq * 8))
; #define MMA(ai, bj, At, Bt_) do { __builtin_amdgcn_s_setprio(1); \
;     _Pragma("unroll") for (int m = 0; m < 4; ++m) _Pragma("unroll") for (int n = 0; n < 2; ++n) _Pragma("unroll") for (int k = 0; k < 2; ++k) \
;       acc[ai][bj][m][n] = __builtin_amdgcn_mfma_f32_16x16x32_bf16(At[m][k], Bt_[n][k], acc[ai][bj][m][n], 0, 0, 0); \
;     __builtin_amdgcn_s_setprio(0); } while (0)
; #define WAIT_V(n) asm volatile("s_waitcnt vmcnt(" #n ")" ::: "memory")
; #define WAIT_L(n) asm volatile("s_waitcnt lgkmcnt(" #n ")" ::: "memory")
; #define BAR __builtin_amdgcn_s_barrier()
; template <class Epi> ...
;     ...
;   { LDB(B0, 1, 0); LDA(At, 1, 0); WAIT_V(2); BAR; WAIT_L(0); MMA(0, 0, At, B0); BAR;
;     LDB(B1, 1, 1); WAIT_V(0); BAR; WAIT_L(0); MMA(0, 1, At, B1); BAR;
;     LDA(At, 1, 1); BAR; WAIT_L(0); MMA(1, 0, At, B0); MMA(1, 1, At, B1); BAR; }
;   if (wr == 0) BAR;
	s_nop 0
	ds_read_b128 v[4:7], v145
	ds_read_b128 v[8:11], v145 offset:1024
	ds_read_b128 v[12:15], v145 offset:2048
	ds_read_b128 v[146:149], v145 offset:3072
	ds_read_b128 v[16:19], v143 offset:32768
	ds_read_b128 v[20:23], v143 offset:33792
	ds_read_b128 v[24:27], v142 offset:32768
	ds_read_b128 v[50:53], v142 offset:33792
	ds_read_b128 v[202:205], v141 offset:32768
	ds_read_b128 v[206:209], v141 offset:33792
	ds_read_b128 v[210:213], v140 offset:32768
	ds_read_b128 v[218:221], v140 offset:33792
	s_waitcnt vmcnt(2)
	s_barrier
	s_waitcnt lgkmcnt(0)
	s_setprio 0
	s_waitcnt lgkmcnt(7)
	v_mfma_f32_16x16x32_bf16 v[28:31], v[16:19], v[4:7], v[126:129]
	s_waitcnt lgkmcnt(6)
	v_mfma_f32_16x16x32_bf16 v[126:129], v[20:23], v[8:11], v[28:31]
	v_mfma_f32_16x16x32_bf16 v[28:31], v[16:19], v[12:15], v[122:125]
	v_mfma_f32_16x16x32_bf16 v[94:97], v[20:23], v[146:149], v[28:31]
	s_waitcnt lgkmcnt(5)
	v_mfma_f32_16x16x32_bf16 v[28:31], v[24:27], v[4:7], v[118:121]
	s_waitcnt lgkmcnt(4)
	v_mfma_f32_16x16x32_bf16 v[122:125], v[50:53], v[8:11], v[28:31]
	v_mfma_f32_16x16x32_bf16 v[28:31], v[24:27], v[12:15], v[114:117]
	v_mfma_f32_16x16x32_bf16 v[90:93], v[50:53], v[146:149], v[28:31]
	s_waitcnt lgkmcnt(3)
	v_mfma_f32_16x16x32_bf16 v[28:31], v[202:205], v[4:7], v[110:113]
	s_waitcnt lgkmcnt(2)
	v_mfma_f32_16x16x32_bf16 v[118:121], v[206:209], v[8:11], v[28:31]
	v_mfma_f32_16x16x32_bf16 v[28:31], v[202:205], v[12:15], v[106:109]
	v_mfma_f32_16x16x32_bf16 v[86:89], v[206:209], v[146:149], v[28:31]
	s_waitcnt lgkmcnt(1)
	v_mfma_f32_16x16x32_bf16 v[28:31], v[210:213], v[4:7], v[102:105]
	s_waitcnt lgkmcnt(0)
	v_mfma_f32_16x16x32_bf16 v[114:117], v[218:221], v[8:11], v[28:31]
	v_mfma_f32_16x16x32_bf16 v[28:31], v[210:213], v[12:15], v[98:101]
	v_mfma_f32_16x16x32_bf16 v[82:85], v[218:221], v[146:149], v[28:31]
	s_setprio 1
	s_barrier
	ds_read_b128 v[222:225], v144
	ds_read_b128 v[242:245], v144 offset:1024
	ds_read_b128 v[246:249], v144 offset:2048
	ds_read_b128 v[250:253], v144 offset:3072
	s_waitcnt vmcnt(0)
	s_barrier
	s_waitcnt lgkmcnt(0)
	s_setprio 0
	s_waitcnt lgkmcnt(3)
	v_mfma_f32_16x16x32_bf16 v[28:31], v[16:19], v[222:225], v[226:229]
	s_waitcnt lgkmcnt(1)
	v_mfma_f32_16x16x32_bf16 v[16:19], v[16:19], v[246:249], v[186:189]
	v_mfma_f32_16x16x32_bf16 v[62:65], v[20:23], v[242:245], v[28:31]
	s_waitcnt lgkmcnt(0)
	v_mfma_f32_16x16x32_bf16 v[28:31], v[20:23], v[250:253], v[16:19]
	v_mfma_f32_16x16x32_bf16 v[16:19], v[24:27], v[222:225], v[190:193]
	v_mfma_f32_16x16x32_bf16 v[58:61], v[50:53], v[242:245], v[16:19]
	v_mfma_f32_16x16x32_bf16 v[16:19], v[24:27], v[246:249], v[194:197]
	v_mfma_f32_16x16x32_bf16 v[24:27], v[50:53], v[250:253], v[16:19]
	v_mfma_f32_16x16x32_bf16 v[16:19], v[202:205], v[222:225], v[78:81]
	v_mfma_f32_16x16x32_bf16 v[54:57], v[206:209], v[242:245], v[16:19]
	v_mfma_f32_16x16x32_bf16 v[16:19], v[202:205], v[246:249], v[74:77]
	v_mfma_f32_16x16x32_bf16 v[20:23], v[206:209], v[250:253], v[16:19]
	v_mfma_f32_16x16x32_bf16 v[16:19], v[210:213], v[222:225], v[70:73]
	v_mfma_f32_16x16x32_bf16 v[50:53], v[218:221], v[242:245], v[16:19]
	v_mfma_f32_16x16x32_bf16 v[16:19], v[210:213], v[246:249], v[66:69]
	v_mfma_f32_16x16x32_bf16 v[16:19], v[218:221], v[250:253], v[16:19]
	s_setprio 1
	s_barrier
	ds_read_b128 v[186:189], v143 offset:49152
	ds_read_b128 v[190:193], v143 offset:50176
	ds_read_b128 v[194:197], v142 offset:49152
	ds_read_b128 v[142:145], v142 offset:50176
	ds_read_b128 v[202:205], v141 offset:49152
	ds_read_b128 v[206:209], v141 offset:50176
	ds_read_b128 v[210:213], v140 offset:49152
	ds_read_b128 v[218:221], v140 offset:50176
	s_barrier
	s_waitcnt lgkmcnt(0)
	s_setprio 0
	s_waitcnt lgkmcnt(7)
	v_mfma_f32_16x16x32_bf16 v[66:69], v[186:189], v[4:7], v[214:217]
	s_waitcnt lgkmcnt(6)
	v_mfma_f32_16x16x32_bf16 v[110:113], v[190:193], v[8:11], v[66:69]
	v_mfma_f32_16x16x32_bf16 v[66:69], v[186:189], v[12:15], v[230:233]
	v_mfma_f32_16x16x32_bf16 v[78:81], v[190:193], v[146:149], v[66:69]
	s_waitcnt lgkmcnt(5)
	v_mfma_f32_16x16x32_bf16 v[66:69], v[194:197], v[4:7], v[234:237]
	s_waitcnt lgkmcnt(3)
	v_mfma_f32_16x16x32_bf16 v[46:49], v[202:205], v[4:7], v[46:49]
	s_waitcnt lgkmcnt(1)
	v_mfma_f32_16x16x32_bf16 v[4:7], v[210:213], v[4:7], v[38:41]
	v_mfma_f32_16x16x32_bf16 v[106:109], v[142:145], v[8:11], v[66:69]
	v_mfma_f32_16x16x32_bf16 v[66:69], v[194:197], v[12:15], v[238:241]
	v_mfma_f32_16x16x32_bf16 v[42:45], v[202:205], v[12:15], v[42:45]
	s_waitcnt lgkmcnt(0)
	v_mfma_f32_16x16x32_bf16 v[98:101], v[218:221], v[8:11], v[4:7]
	v_mfma_f32_16x16x32_bf16 v[4:7], v[210:213], v[12:15], v[34:37]
	v_mfma_f32_16x16x32_bf16 v[74:77], v[142:145], v[146:149], v[66:69]
	v_mfma_f32_16x16x32_bf16 v[102:105], v[206:209], v[8:11], v[46:49]
	v_mfma_f32_16x16x32_bf16 v[70:73], v[206:209], v[146:149], v[42:45]
	v_mfma_f32_16x16x32_bf16 v[66:69], v[218:221], v[146:149], v[4:7]
	s_setprio 1
	s_setprio 0
	v_mfma_f32_16x16x32_bf16 v[4:7], v[186:189], v[222:225], v[154:157]
	v_mfma_f32_16x16x32_bf16 v[46:49], v[190:193], v[242:245], v[4:7]
	v_mfma_f32_16x16x32_bf16 v[4:7], v[186:189], v[246:249], v[158:161]
	v_mfma_f32_16x16x32_bf16 v[12:15], v[190:193], v[250:253], v[4:7]
	v_mfma_f32_16x16x32_bf16 v[4:7], v[194:197], v[222:225], v[166:169]
	v_mfma_f32_16x16x32_bf16 v[42:45], v[142:145], v[242:245], v[4:7]
	v_mfma_f32_16x16x32_bf16 v[4:7], v[194:197], v[246:249], v[170:173]
	v_mfma_f32_16x16x32_bf16 v[8:11], v[142:145], v[250:253], v[4:7]
	v_mfma_f32_16x16x32_bf16 v[4:7], v[202:205], v[222:225], v[174:177]
	v_mfma_f32_16x16x32_bf16 v[38:41], v[206:209], v[242:245], v[4:7]
	v_mfma_f32_16x16x32_bf16 v[4:7], v[202:205], v[246:249], v[198:201]
	v_mfma_f32_16x16x32_bf16 v[34:37], v[210:213], v[222:225], v[150:153]
	v_mfma_f32_16x16x32_bf16 v[0:3], v[210:213], v[246:249], v[0:3]
	v_mfma_f32_16x16x32_bf16 v[4:7], v[206:209], v[250:253], v[4:7]
	v_mfma_f32_16x16x32_bf16 v[34:37], v[218:221], v[242:245], v[34:37]
	v_mfma_f32_16x16x32_bf16 v[0:3], v[218:221], v[250:253], v[0:3]
	s_setprio 1
	v_cmp_gt_u32_e32 vcc, s59, v130
	s_barrier
	s_and_saveexec_b64 s[10:11], vcc
	s_cbranch_execz .LBB0_1930
	s_barrier

; #define STAGE(P, BASE, br, kt) do { int _so = ((br) * K + (kt) * BK) * 2; \
;     __builtin_amdgcn_raw_ptr_buffer_load_lds(rs_##BASE, (__attribute__((address_space(3))) void*)((char*)(P) + tx * 16), 16, voff0, _so, 0, 0); \
;     __builtin_amdgcn_raw_ptr_buffer_load_lds(rs_##BASE, (__attribute__((address_space(3))) void*)((char*)(P) + tx * 16 + 8192), 16, voff1, _so, 0, 0); } while (0)
; #define LDA(dst, b, h) _Pragma("unroll") for (int m = 0; m < 4; ++m) _Pragma("unroll") for (int k = 0; k < 2; ++k) \
;     dst[m][k] = *reinterpret_cast<const bf16x8*>((char*)SA(b, h) + lds_byte(wr * 64 + m * 16 + fr, k * 32 + fq * 8))
; #define LDB(dst, b, h) _Pragma("unroll") for (int n = 0; n < 2; ++n) _Pragma("unroll") for (int k = 0; k < 2; ++k) \
;     dst[n][k] = *reinterpret_cast<const bf16x8*>((char*)SB(b, h) + lds_byte(wc * 32 + n * 16 + fr, k * 32 + fq * 8))
; #define MMA(ai, bj, At, Bt_) do { __builtin_amdgcn_s_setprio(1); \
;     _Pragma("unroll") for (int m = 0; m < 4; ++m) _Pragma("unroll") for (int n = 0; n < 2; ++n) _Pragma("unroll") for (int k = 0; k < 2; ++k) \
;       acc[ai][bj][m][n] = __builtin_amdgcn_mfma_f32_16x16x32_bf16(At[m][k], Bt_[n][k], acc[ai][bj][m][n], 0, 0, 0); \
;     __builtin_amdgcn_s_setprio(0); } while (0)
; #define WAIT_V(n) asm volatile("s_waitcnt vmcnt(" #n ")" ::: "memory")
; #define WAIT_L(n) asm volatile("s_waitcnt lgkmcnt(" #n ")" ::: "memory")
; #define BAR __builtin_amdgcn_s_barrier()
; template <class Epi> ...
;     ...
;   { LDB(B0, 0, 0); LDA(At, 0, 0); STAGE(SA(1, 1), A, brow + HALF, nt - 1);
;     BAR; WAIT_L(0); MMA(0, 0, At, B0); BAR;
;     LDB(B1, 0, 1); BAR; WAIT_L(0); MMA(0, 1, At, B1); BAR;
;     LDA(At, 0, 1); WAIT_V(4); BAR; WAIT_L(0); MMA(1, 0, At, B0); MMA(1, 1, At, B1); BAR; }
.Lpx5:
	s_or_b32 s16, s17, 0x40780
	v_readfirstlane_b32 s17, v152
	s_mov_b32 s10, s78
	s_mov_b32 s11, s79
	s_mov_b32 m0, s17
	v_readfirstlane_b32 s17, v151
	ds_read_b128 v[156:159], v155
	ds_read_b128 v[166:169], v155 offset:1024
	ds_read_b128 v[170:173], v155 offset:2048
	ds_read_b128 v[174:177], v155 offset:3072
	ds_read_b128 v[186:189], v143
	ds_read_b128 v[190:193], v143 offset:1024
	ds_read_b128 v[194:197], v142
	ds_read_b128 v[198:201], v142 offset:1024
	ds_read_b128 v[202:205], v141
	ds_read_b128 v[206:209], v141 offset:1024
	ds_read_b128 v[210:213], v140
	ds_read_b128 v[214:217], v140 offset:1024
	buffer_load_dwordx4 v32, s[8:11], s16 offen lds
	s_mov_b32 m0, s17
	s_nop 0
	buffer_load_dwordx4 v131, s[8:11], s16 offen lds
	s_barrier
	s_waitcnt lgkmcnt(0)
	s_setprio 0
	s_waitcnt lgkmcnt(7)
	v_mfma_f32_16x16x32_bf16 v[126:129], v[186:189], v[156:159], v[126:129]
	v_mfma_f32_16x16x32_bf16 v[122:125], v[186:189], v[170:173], v[122:125]
	s_waitcnt lgkmcnt(5)
	v_mfma_f32_16x16x32_bf16 v[118:121], v[194:197], v[156:159], v[118:121]
	v_mfma_f32_16x16x32_bf16 v[114:117], v[194:197], v[170:173], v[114:117]
	v_mfma_f32_16x16x32_bf16 v[126:129], v[190:193], v[166:169], v[126:129]
	v_mfma_f32_16x16x32_bf16 v[122:125], v[190:193], v[174:177], v[122:125]
	s_waitcnt lgkmcnt(4)
	v_mfma_f32_16x16x32_bf16 v[118:121], v[198:201], v[166:169], v[118:121]
	v_mfma_f32_16x16x32_bf16 v[114:117], v[198:201], v[174:177], v[114:117]
	s_waitcnt lgkmcnt(3)
	v_mfma_f32_16x16x32_bf16 v[110:113], v[202:205], v[156:159], v[110:113]
	v_mfma_f32_16x16x32_bf16 v[106:109], v[202:205], v[170:173], v[106:109]
	s_waitcnt lgkmcnt(1)
	v_mfma_f32_16x16x32_bf16 v[102:105], v[210:213], v[156:159], v[102:105]
	v_mfma_f32_16x16x32_bf16 v[98:101], v[210:213], v[170:173], v[98:101]
	v_mfma_f32_16x16x32_bf16 v[150:153], v[206:209], v[166:169], v[110:113]
	v_mfma_f32_16x16x32_bf16 v[218:221], v[206:209], v[174:177], v[106:109]
	s_waitcnt lgkmcnt(0)
	v_mfma_f32_16x16x32_bf16 v[222:225], v[214:217], v[166:169], v[102:105]
	v_mfma_f32_16x16x32_bf16 v[226:229], v[214:217], v[174:177], v[98:101]
	s_setprio 1
	s_barrier
	s_nop 0
	ds_read_b128 v[98:101], v149
	ds_read_b128 v[102:105], v149 offset:1024
	ds_read_b128 v[106:109], v149 offset:2048
	ds_read_b128 v[110:113], v149 offset:3072
	s_barrier
	s_waitcnt lgkmcnt(0)
	s_setprio 0
	s_waitcnt lgkmcnt(3)
	v_mfma_f32_16x16x32_bf16 v[94:97], v[186:189], v[98:101], v[94:97]
	s_waitcnt lgkmcnt(1)
	v_mfma_f32_16x16x32_bf16 v[90:93], v[186:189], v[106:109], v[90:93]
	v_mfma_f32_16x16x32_bf16 v[86:89], v[194:197], v[98:101], v[86:89]
	v_mfma_f32_16x16x32_bf16 v[82:85], v[194:197], v[106:109], v[82:85]
	v_mfma_f32_16x16x32_bf16 v[94:97], v[190:193], v[102:105], v[94:97]
	s_waitcnt lgkmcnt(0)
	v_mfma_f32_16x16x32_bf16 v[90:93], v[190:193], v[110:113], v[90:93]
	v_mfma_f32_16x16x32_bf16 v[86:89], v[198:201], v[102:105], v[86:89]
	v_mfma_f32_16x16x32_bf16 v[82:85], v[198:201], v[110:113], v[82:85]
	v_mfma_f32_16x16x32_bf16 v[78:81], v[202:205], v[98:101], v[78:81]
	v_mfma_f32_16x16x32_bf16 v[74:77], v[202:205], v[106:109], v[74:77]
	v_mfma_f32_16x16x32_bf16 v[70:73], v[210:213], v[98:101], v[70:73]
	v_mfma_f32_16x16x32_bf16 v[66:69], v[210:213], v[106:109], v[66:69]
	v_mfma_f32_16x16x32_bf16 v[146:149], v[206:209], v[102:105], v[78:81]
	v_mfma_f32_16x16x32_bf16 v[186:189], v[206:209], v[110:113], v[74:77]
	v_mfma_f32_16x16x32_bf16 v[190:193], v[214:217], v[102:105], v[70:73]
	v_mfma_f32_16x16x32_bf16 v[194:197], v[214:217], v[110:113], v[66:69]
	s_setprio 1
	s_barrier
	s_nop 1
	ds_read_b128 v[66:69], v143 offset:16384
	ds_read_b128 v[70:73], v143 offset:17408
	ds_read_b128 v[74:77], v142 offset:16384
	ds_read_b128 v[78:81], v142 offset:17408
	ds_read_b128 v[198:201], v141 offset:16384
	ds_read_b128 v[202:205], v141 offset:17408
	ds_read_b128 v[206:209], v140 offset:16384
	ds_read_b128 v[210:213], v140 offset:17408
	s_waitcnt vmcnt(4)
	s_barrier
	s_waitcnt lgkmcnt(0)
	s_setprio 0
	s_waitcnt lgkmcnt(7)
	v_mfma_f32_16x16x32_bf16 v[62:65], v[66:69], v[156:159], v[62:65]
	v_mfma_f32_16x16x32_bf16 v[58:61], v[66:69], v[170:173], v[58:61]
	s_waitcnt lgkmcnt(5)
	v_mfma_f32_16x16x32_bf16 v[54:57], v[74:77], v[156:159], v[54:57]
	v_mfma_f32_16x16x32_bf16 v[50:53], v[74:77], v[170:173], v[50:53]
	v_mfma_f32_16x16x32_bf16 v[62:65], v[70:73], v[166:169], v[62:65]
	v_mfma_f32_16x16x32_bf16 v[58:61], v[70:73], v[174:177], v[58:61]
	s_waitcnt lgkmcnt(4)
	v_mfma_f32_16x16x32_bf16 v[54:57], v[78:81], v[166:169], v[54:57]
	v_mfma_f32_16x16x32_bf16 v[50:53], v[78:81], v[174:177], v[50:53]
	s_waitcnt lgkmcnt(3)
	v_mfma_f32_16x16x32_bf16 v[46:49], v[198:201], v[156:159], v[46:49]
	v_mfma_f32_16x16x32_bf16 v[42:45], v[198:201], v[170:173], v[42:45]
	s_waitcnt lgkmcnt(1)
	v_mfma_f32_16x16x32_bf16 v[38:41], v[206:209], v[156:159], v[38:41]
	v_mfma_f32_16x16x32_bf16 v[34:37], v[206:209], v[170:173], v[34:37]
	v_mfma_f32_16x16x32_bf16 v[214:217], v[202:205], v[166:169], v[46:49]
	v_mfma_f32_16x16x32_bf16 v[230:233], v[202:205], v[174:177], v[42:45]
	s_waitcnt lgkmcnt(0)
	v_mfma_f32_16x16x32_bf16 v[154:157], v[210:213], v[166:169], v[38:41]
	v_mfma_f32_16x16x32_bf16 v[158:161], v[210:213], v[174:177], v[34:37]
	s_setprio 1
	s_setprio 0
	v_mfma_f32_16x16x32_bf16 v[28:31], v[66:69], v[98:101], v[28:31]
	v_mfma_f32_16x16x32_bf16 v[24:27], v[66:69], v[106:109], v[24:27]
	v_mfma_f32_16x16x32_bf16 v[20:23], v[74:77], v[98:101], v[20:23]
	v_mfma_f32_16x16x32_bf16 v[16:19], v[74:77], v[106:109], v[16:19]
	v_mfma_f32_16x16x32_bf16 v[28:31], v[70:73], v[102:105], v[28:31]
	v_mfma_f32_16x16x32_bf16 v[24:27], v[70:73], v[110:113], v[24:27]
	v_mfma_f32_16x16x32_bf16 v[20:23], v[78:81], v[102:105], v[20:23]
	v_mfma_f32_16x16x32_bf16 v[16:19], v[78:81], v[110:113], v[16:19]
	v_mfma_f32_16x16x32_bf16 v[12:15], v[198:201], v[98:101], v[12:15]
	v_mfma_f32_16x16x32_bf16 v[8:11], v[198:201], v[106:109], v[8:11]
	v_mfma_f32_16x16x32_bf16 v[4:7], v[206:209], v[98:101], v[4:7]
	v_mfma_f32_16x16x32_bf16 v[0:3], v[206:209], v[106:109], v[0:3]
	v_mfma_f32_16x16x32_bf16 v[166:169], v[202:205], v[102:105], v[12:15]
	v_mfma_f32_16x16x32_bf16 v[170:173], v[202:205], v[110:113], v[8:11]
	v_mfma_f32_16x16x32_bf16 v[174:177], v[210:213], v[102:105], v[4:7]
	v_mfma_f32_16x16x32_bf16 v[198:201], v[210:213], v[110:113], v[0:3]
	s_setprio 1
	s_barrier
; #define LDA(dst, b, h) _Pragma("unroll") for (int m = 0; m < 4; ++m) _Pragma("unroll") for (int k = 0; k < 2; ++k) \
;     dst[m][k] = *reinterpret_cast<const bf16x8*>((char*)SA(b, h) + lds_byte(wr * 64 + m * 16 + fr, k * 32 + fq * 8))
; #define LDB(dst, b, h) _Pragma("unroll") for (int n = 0; n < 2; ++n) _Pragma("unroll") for (int k = 0; k < 2; ++k) \
;     dst[n][k] = *reinterpret_cast<const bf16x8*>((char*)SB(b, h) + lds_byte(wc * 32 + n * 16 + fr, k * 32 + fq * 8))
; #define MMA(ai, bj, At, Bt_) do { __builtin_amdgcn_s_setprio(1); \
;     _Pragma("unroll") for (int m = 0; m < 4; ++m) _Pragma("unroll") for (int n = 0; n < 2; ++n) _Pragma("unroll") for (int k = 0; k < 2; ++k) \
;       acc[ai][bj][m][n] = __builtin_amdgcn_mfma_f32_16x16x32_bf16(At[m][k], Bt_[n][k], acc[ai][bj][m][n], 0, 0, 0); \
;     __builtin_amdgcn_s_setprio(0); } while (0)
; #define WAIT_V(n) asm volatile("s_waitcnt vmcnt(" #n ")" ::: "memory")
; #define WAIT_L(n) asm volatile("s_waitcnt lgkmcnt(" #n ")" ::: "memory")
; #define BAR __builtin_amdgcn_s_barrier()
; template <class Epi> ...
;     ...
;   { LDB(B0, 1, 0); LDA(At, 1, 0); WAIT_V(2); BAR; WAIT_L(0); MMA(0, 0, At, B0); BAR;
;     LDB(B1, 1, 1); WAIT_V(0); BAR; WAIT_L(0); MMA(0, 1, At, B1); BAR;
;     LDA(At, 1, 1); BAR; WAIT_L(0); MMA(1, 0, At, B0); MMA(1, 1, At, B1); BAR; }
;   if (wr == 0) BAR;
	ds_read_b128 v[202:205], v145
	ds_read_b128 v[206:209], v145 offset:1024
	ds_read_b128 v[210:213], v145 offset:2048
	ds_read_b128 v[234:237], v145 offset:3072
	ds_read_b128 v[0:3], v143 offset:32768
	ds_read_b128 v[4:7], v143 offset:33792
	ds_read_b128 v[8:11], v142 offset:32768
	ds_read_b128 v[34:37], v142 offset:33792
	ds_read_b128 v[238:241], v141 offset:32768
	ds_read_b128 v[242:245], v141 offset:33792
	ds_read_b128 v[246:249], v140 offset:32768
	ds_read_b128 v[250:253], v140 offset:33792
	s_waitcnt vmcnt(2)
	s_barrier
	s_waitcnt lgkmcnt(0)
	s_setprio 0
	s_waitcnt lgkmcnt(7)
	v_mfma_f32_16x16x32_bf16 v[12:15], v[0:3], v[202:205], v[126:129]
	s_waitcnt lgkmcnt(6)
	v_mfma_f32_16x16x32_bf16 v[110:113], v[4:7], v[206:209], v[12:15]
	v_mfma_f32_16x16x32_bf16 v[12:15], v[0:3], v[210:213], v[122:125]
	v_mfma_f32_16x16x32_bf16 v[78:81], v[4:7], v[234:237], v[12:15]
	s_waitcnt lgkmcnt(5)
	v_mfma_f32_16x16x32_bf16 v[12:15], v[8:11], v[202:205], v[118:121]
	s_waitcnt lgkmcnt(4)
	v_mfma_f32_16x16x32_bf16 v[106:109], v[34:37], v[206:209], v[12:15]
	v_mfma_f32_16x16x32_bf16 v[12:15], v[8:11], v[210:213], v[114:117]
	v_mfma_f32_16x16x32_bf16 v[74:77], v[34:37], v[234:237], v[12:15]
	s_waitcnt lgkmcnt(3)
	v_mfma_f32_16x16x32_bf16 v[12:15], v[238:241], v[202:205], v[150:153]
	s_waitcnt lgkmcnt(2)
	v_mfma_f32_16x16x32_bf16 v[102:105], v[242:245], v[206:209], v[12:15]
	v_mfma_f32_16x16x32_bf16 v[12:15], v[238:241], v[210:213], v[218:221]
	v_mfma_f32_16x16x32_bf16 v[70:73], v[242:245], v[234:237], v[12:15]
	s_waitcnt lgkmcnt(1)
	v_mfma_f32_16x16x32_bf16 v[12:15], v[246:249], v[202:205], v[222:225]
	s_waitcnt lgkmcnt(0)
	v_mfma_f32_16x16x32_bf16 v[98:101], v[250:253], v[206:209], v[12:15]
	v_mfma_f32_16x16x32_bf16 v[12:15], v[246:249], v[210:213], v[226:229]
	v_mfma_f32_16x16x32_bf16 v[66:69], v[250:253], v[234:237], v[12:15]
	s_setprio 1
	s_barrier
	ds_read_b128 v[150:153], v144
	ds_read_b128 v[218:221], v144 offset:1024
	ds_read_b128 v[222:225], v144 offset:2048
	ds_read_b128 v[226:229], v144 offset:3072
	s_waitcnt vmcnt(0)
	s_barrier
	s_waitcnt lgkmcnt(0)
	s_setprio 0
	s_waitcnt lgkmcnt(3)
	v_mfma_f32_16x16x32_bf16 v[12:15], v[0:3], v[150:153], v[94:97]
	s_waitcnt lgkmcnt(1)
	v_mfma_f32_16x16x32_bf16 v[0:3], v[0:3], v[222:225], v[90:93]
	v_mfma_f32_16x16x32_bf16 v[46:49], v[4:7], v[218:221], v[12:15]
	s_waitcnt lgkmcnt(0)
	v_mfma_f32_16x16x32_bf16 v[12:15], v[4:7], v[226:229], v[0:3]
	v_mfma_f32_16x16x32_bf16 v[0:3], v[8:11], v[150:153], v[86:89]
	v_mfma_f32_16x16x32_bf16 v[42:45], v[34:37], v[218:221], v[0:3]
	v_mfma_f32_16x16x32_bf16 v[0:3], v[8:11], v[222:225], v[82:85]
	v_mfma_f32_16x16x32_bf16 v[8:11], v[34:37], v[226:229], v[0:3]
	v_mfma_f32_16x16x32_bf16 v[0:3], v[238:241], v[150:153], v[146:149]
	v_mfma_f32_16x16x32_bf16 v[38:41], v[242:245], v[218:221], v[0:3]
	v_mfma_f32_16x16x32_bf16 v[0:3], v[238:241], v[222:225], v[186:189]
	v_mfma_f32_16x16x32_bf16 v[4:7], v[242:245], v[226:229], v[0:3]
	v_mfma_f32_16x16x32_bf16 v[0:3], v[246:249], v[150:153], v[190:193]
	v_mfma_f32_16x16x32_bf16 v[34:37], v[250:253], v[218:221], v[0:3]
	v_mfma_f32_16x16x32_bf16 v[0:3], v[246:249], v[222:225], v[194:197]
	v_mfma_f32_16x16x32_bf16 v[0:3], v[250:253], v[226:229], v[0:3]
	s_setprio 1
	s_barrier
	ds_read_b128 v[144:147], v143 offset:49152
	ds_read_b128 v[186:189], v143 offset:50176
	ds_read_b128 v[190:193], v142 offset:49152
	ds_read_b128 v[194:197], v142 offset:50176
	ds_read_b128 v[238:241], v141 offset:49152
	ds_read_b128 v[242:245], v141 offset:50176
	ds_read_b128 v[246:249], v140 offset:49152
	ds_read_b128 v[140:143], v140 offset:50176
	s_barrier
	s_waitcnt lgkmcnt(0)
	s_setprio 0
	s_waitcnt lgkmcnt(5)
	v_mfma_f32_16x16x32_bf16 v[50:53], v[190:193], v[210:213], v[50:53]
	s_waitcnt lgkmcnt(4)
	v_mfma_f32_16x16x32_bf16 v[90:93], v[194:197], v[234:237], v[50:53]
	s_waitcnt lgkmcnt(3)
	v_mfma_f32_16x16x32_bf16 v[50:53], v[238:241], v[202:205], v[214:217]
	s_waitcnt lgkmcnt(2)
	v_mfma_f32_16x16x32_bf16 v[118:121], v[242:245], v[206:209], v[50:53]
	v_mfma_f32_16x16x32_bf16 v[50:53], v[238:241], v[210:213], v[230:233]
	v_mfma_f32_16x16x32_bf16 v[86:89], v[242:245], v[234:237], v[50:53]
	s_waitcnt lgkmcnt(1)
	v_mfma_f32_16x16x32_bf16 v[50:53], v[246:249], v[202:205], v[154:157]
	v_mfma_f32_16x16x32_bf16 v[62:65], v[144:147], v[202:205], v[62:65]
	v_mfma_f32_16x16x32_bf16 v[58:61], v[144:147], v[210:213], v[58:61]
	v_mfma_f32_16x16x32_bf16 v[54:57], v[190:193], v[202:205], v[54:57]
	s_waitcnt lgkmcnt(0)
	v_mfma_f32_16x16x32_bf16 v[114:117], v[140:143], v[206:209], v[50:53]
	v_mfma_f32_16x16x32_bf16 v[50:53], v[246:249], v[210:213], v[158:161]
	v_mfma_f32_16x16x32_bf16 v[126:129], v[186:189], v[206:209], v[62:65]
	v_mfma_f32_16x16x32_bf16 v[94:97], v[186:189], v[234:237], v[58:61]
	v_mfma_f32_16x16x32_bf16 v[122:125], v[194:197], v[206:209], v[54:57]
	v_mfma_f32_16x16x32_bf16 v[82:85], v[140:143], v[234:237], v[50:53]
	s_setprio 1
	s_setprio 0
	v_mfma_f32_16x16x32_bf16 v[28:31], v[144:147], v[150:153], v[28:31]
	v_mfma_f32_16x16x32_bf16 v[24:27], v[144:147], v[222:225], v[24:27]
	v_mfma_f32_16x16x32_bf16 v[16:19], v[190:193], v[222:225], v[16:19]
	v_mfma_f32_16x16x32_bf16 v[62:65], v[186:189], v[218:221], v[28:31]
	v_mfma_f32_16x16x32_bf16 v[28:31], v[186:189], v[226:229], v[24:27]
	v_mfma_f32_16x16x32_bf16 v[24:27], v[194:197], v[226:229], v[16:19]
	v_mfma_f32_16x16x32_bf16 v[16:19], v[238:241], v[150:153], v[166:169]
	v_mfma_f32_16x16x32_bf16 v[20:23], v[190:193], v[150:153], v[20:23]
	v_mfma_f32_16x16x32_bf16 v[54:57], v[242:245], v[218:221], v[16:19]
	v_mfma_f32_16x16x32_bf16 v[16:19], v[238:241], v[222:225], v[170:173]
	v_mfma_f32_16x16x32_bf16 v[58:61], v[194:197], v[218:221], v[20:23]
	v_mfma_f32_16x16x32_bf16 v[20:23], v[242:245], v[226:229], v[16:19]
	v_mfma_f32_16x16x32_bf16 v[16:19], v[246:249], v[150:153], v[174:177]
	v_mfma_f32_16x16x32_bf16 v[50:53], v[140:143], v[218:221], v[16:19]
	v_mfma_f32_16x16x32_bf16 v[16:19], v[246:249], v[222:225], v[198:201]
	v_mfma_f32_16x16x32_bf16 v[16:19], v[140:143], v[226:229], v[16:19]
	s_setprio 1
	v_cmp_gt_u32_e32 vcc, s59, v130
	s_barrier
	s_and_saveexec_b64 s[10:11], vcc
	s_cbranch_execz .LBB0_2021
	s_barrier

; #define STAGE(P, BASE, br, kt) do { int _so = ((br) * K + (kt) * BK) * 2; \
;     __builtin_amdgcn_raw_ptr_buffer_load_lds(rs_##BASE, (__attribute__((address_space(3))) void*)((char*)(P) + tx * 16), 16, voff0, _so, 0, 0); \
;     __builtin_amdgcn_raw_ptr_buffer_load_lds(rs_##BASE, (__attribute__((address_space(3))) void*)((char*)(P) + tx * 16 + 8192), 16, voff1, _so, 0, 0); } while (0)
; #define LDA(dst, b, h) _Pragma("unroll") for (int m = 0; m < 4; ++m) _Pragma("unroll") for (int k = 0; k < 2; ++k) \
;     dst[m][k] = *reinterpret_cast<const bf16x8*>((char*)SA(b, h) + lds_byte(wr * 64 + m * 16 + fr, k * 32 + fq * 8))
; #define LDB(dst, b, h) _Pragma("unroll") for (int n = 0; n < 2; ++n) _Pragma("unroll") for (int k = 0; k < 2; ++k) \
;     dst[n][k] = *reinterpret_cast<const bf16x8*>((char*)SB(b, h) + lds_byte(wc * 32 + n * 16 + fr, k * 32 + fq * 8))
; #define MMA(ai, bj, At, Bt_) do { __builtin_amdgcn_s_setprio(1); \
;     _Pragma("unroll") for (int m = 0; m < 4; ++m) _Pragma("unroll") for (int n = 0; n < 2; ++n) _Pragma("unroll") for (int k = 0; k < 2; ++k) \
;       acc[ai][bj][m][n] = __builtin_amdgcn_mfma_f32_16x16x32_bf16(At[m][k], Bt_[n][k], acc[ai][bj][m][n], 0, 0, 0); \
;     __builtin_amdgcn_s_setprio(0); } while (0)
; #define WAIT_V(n) asm volatile("s_waitcnt vmcnt(" #n ")" ::: "memory")
; #define WAIT_L(n) asm volatile("s_waitcnt lgkmcnt(" #n ")" ::: "memory")
; #define BAR __builtin_amdgcn_s_barrier()
; template <class Epi> ...
;     ...
;   { LDB(B0, 0, 0); LDA(At, 0, 0); STAGE(SA(1, 1), A, brow + HALF, nt - 1);
;     BAR; WAIT_L(0); MMA(0, 0, At, B0); BAR;
;     LDB(B1, 0, 1); BAR; WAIT_L(0); MMA(0, 1, At, B1); BAR;
;     LDA(At, 0, 1); WAIT_V(4); BAR; WAIT_L(0); MMA(1, 0, At, B0); MMA(1, 1, At, B1); BAR; }
.Lpx7:
	s_or_b32 s16, s17, 0x40780
	v_readfirstlane_b32 s17, v152
	s_mov_b32 s10, s78
	s_mov_b32 s11, s79
	s_mov_b32 m0, s17
	v_readfirstlane_b32 s17, v151
	ds_read_b128 v[156:159], v155
	ds_read_b128 v[166:169], v155 offset:1024
	ds_read_b128 v[170:173], v155 offset:2048
	ds_read_b128 v[174:177], v155 offset:3072
	ds_read_b128 v[186:189], v143
	ds_read_b128 v[190:193], v143 offset:1024
	ds_read_b128 v[194:197], v142
	ds_read_b128 v[198:201], v142 offset:1024
	ds_read_b128 v[202:205], v141
	ds_read_b128 v[206:209], v141 offset:1024
	ds_read_b128 v[210:213], v140
	ds_read_b128 v[214:217], v140 offset:1024
	buffer_load_dwordx4 v32, s[8:11], s16 offen lds
	s_mov_b32 m0, s17
	s_nop 0
	buffer_load_dwordx4 v131, s[8:11], s16 offen lds
	s_barrier
	s_waitcnt lgkmcnt(0)
	s_setprio 0
	s_waitcnt lgkmcnt(7)
	v_mfma_f32_16x16x32_bf16 v[126:129], v[186:189], v[156:159], v[126:129]
	s_waitcnt lgkmcnt(5)
	v_mfma_f32_16x16x32_bf16 v[118:121], v[194:197], v[156:159], v[118:121]
	s_waitcnt lgkmcnt(3)
	v_mfma_f32_16x16x32_bf16 v[110:113], v[202:205], v[156:159], v[110:113]
	v_mfma_f32_16x16x32_bf16 v[106:109], v[202:205], v[170:173], v[106:109]
	s_waitcnt lgkmcnt(1)
	v_mfma_f32_16x16x32_bf16 v[102:105], v[210:213], v[156:159], v[102:105]
	v_mfma_f32_16x16x32_bf16 v[126:129], v[190:193], v[166:169], v[126:129]
	v_mfma_f32_16x16x32_bf16 v[122:125], v[186:189], v[170:173], v[122:125]
	v_mfma_f32_16x16x32_bf16 v[118:121], v[198:201], v[166:169], v[118:121]
	v_mfma_f32_16x16x32_bf16 v[114:117], v[194:197], v[170:173], v[114:117]
	v_mfma_f32_16x16x32_bf16 v[110:113], v[206:209], v[166:169], v[110:113]
	v_mfma_f32_16x16x32_bf16 v[106:109], v[206:209], v[174:177], v[106:109]
	s_waitcnt lgkmcnt(0)
	v_mfma_f32_16x16x32_bf16 v[102:105], v[214:217], v[166:169], v[102:105]
	v_mfma_f32_16x16x32_bf16 v[98:101], v[210:213], v[170:173], v[98:101]
	v_mfma_f32_16x16x32_bf16 v[150:153], v[190:193], v[174:177], v[122:125]
	v_mfma_f32_16x16x32_bf16 v[218:221], v[198:201], v[174:177], v[114:117]
	v_mfma_f32_16x16x32_bf16 v[222:225], v[214:217], v[174:177], v[98:101]
	s_setprio 1
	s_barrier
	s_nop 2
	ds_read_b128 v[98:101], v149
	ds_read_b128 v[114:117], v149 offset:1024
	ds_read_b128 v[122:125], v149 offset:2048
	ds_read_b128 v[146:149], v149 offset:3072
	s_barrier
	s_waitcnt lgkmcnt(0)
	s_setprio 0
	s_waitcnt lgkmcnt(3)
	v_mfma_f32_16x16x32_bf16 v[94:97], v[186:189], v[98:101], v[94:97]
	s_waitcnt lgkmcnt(1)
	v_mfma_f32_16x16x32_bf16 v[82:85], v[194:197], v[122:125], v[82:85]
	v_mfma_f32_16x16x32_bf16 v[78:81], v[202:205], v[98:101], v[78:81]
	v_mfma_f32_16x16x32_bf16 v[70:73], v[210:213], v[98:101], v[70:73]
	v_mfma_f32_16x16x32_bf16 v[94:97], v[190:193], v[114:117], v[94:97]
	v_mfma_f32_16x16x32_bf16 v[90:93], v[186:189], v[122:125], v[90:93]
	v_mfma_f32_16x16x32_bf16 v[86:89], v[194:197], v[98:101], v[86:89]
	s_waitcnt lgkmcnt(0)
	v_mfma_f32_16x16x32_bf16 v[82:85], v[198:201], v[146:149], v[82:85]
	v_mfma_f32_16x16x32_bf16 v[78:81], v[206:209], v[114:117], v[78:81]
	v_mfma_f32_16x16x32_bf16 v[74:77], v[202:205], v[122:125], v[74:77]
	v_mfma_f32_16x16x32_bf16 v[70:73], v[214:217], v[114:117], v[70:73]
	v_mfma_f32_16x16x32_bf16 v[66:69], v[210:213], v[122:125], v[66:69]
	v_mfma_f32_16x16x32_bf16 v[186:189], v[190:193], v[146:149], v[90:93]
	v_mfma_f32_16x16x32_bf16 v[190:193], v[198:201], v[114:117], v[86:89]
	v_mfma_f32_16x16x32_bf16 v[194:197], v[206:209], v[146:149], v[74:77]
	v_mfma_f32_16x16x32_bf16 v[198:201], v[214:217], v[146:149], v[66:69]
	s_setprio 1
	s_barrier
	s_nop 1
	ds_read_b128 v[66:69], v143 offset:16384
	ds_read_b128 v[74:77], v143 offset:17408
	ds_read_b128 v[86:89], v142 offset:16384
	ds_read_b128 v[90:93], v142 offset:17408
	ds_read_b128 v[202:205], v141 offset:16384
	ds_read_b128 v[206:209], v141 offset:17408
	ds_read_b128 v[210:213], v140 offset:16384
	ds_read_b128 v[214:217], v140 offset:17408
	s_waitcnt vmcnt(4)
	s_barrier
	s_waitcnt lgkmcnt(0)
	s_setprio 0
	s_waitcnt lgkmcnt(7)
	v_mfma_f32_16x16x32_bf16 v[58:61], v[66:69], v[170:173], v[58:61]
	s_waitcnt lgkmcnt(5)
	v_mfma_f32_16x16x32_bf16 v[54:57], v[86:89], v[156:159], v[54:57]
	s_waitcnt lgkmcnt(3)
	v_mfma_f32_16x16x32_bf16 v[46:49], v[202:205], v[156:159], v[46:49]
	s_waitcnt lgkmcnt(1)
	v_mfma_f32_16x16x32_bf16 v[38:41], v[210:213], v[156:159], v[38:41]
	v_mfma_f32_16x16x32_bf16 v[62:65], v[66:69], v[156:159], v[62:65]
	v_mfma_f32_16x16x32_bf16 v[58:61], v[74:77], v[174:177], v[58:61]
	v_mfma_f32_16x16x32_bf16 v[54:57], v[90:93], v[166:169], v[54:57]
	v_mfma_f32_16x16x32_bf16 v[50:53], v[86:89], v[170:173], v[50:53]
	v_mfma_f32_16x16x32_bf16 v[46:49], v[206:209], v[166:169], v[46:49]
	v_mfma_f32_16x16x32_bf16 v[42:45], v[202:205], v[170:173], v[42:45]
	s_waitcnt lgkmcnt(0)
	v_mfma_f32_16x16x32_bf16 v[38:41], v[214:217], v[166:169], v[38:41]
	v_mfma_f32_16x16x32_bf16 v[34:37], v[210:213], v[170:173], v[34:37]
	v_mfma_f32_16x16x32_bf16 v[226:229], v[74:77], v[166:169], v[62:65]
	v_mfma_f32_16x16x32_bf16 v[230:233], v[90:93], v[174:177], v[50:53]
	v_mfma_f32_16x16x32_bf16 v[234:237], v[206:209], v[174:177], v[42:45]
	v_mfma_f32_16x16x32_bf16 v[154:157], v[214:217], v[174:177], v[34:37]
	s_setprio 1
	s_setprio 0
	v_mfma_f32_16x16x32_bf16 v[28:31], v[66:69], v[98:101], v[28:31]
	v_mfma_f32_16x16x32_bf16 v[20:23], v[86:89], v[98:101], v[20:23]
	v_mfma_f32_16x16x32_bf16 v[12:15], v[202:205], v[98:101], v[12:15]
	v_mfma_f32_16x16x32_bf16 v[4:7], v[210:213], v[98:101], v[4:7]
	v_mfma_f32_16x16x32_bf16 v[28:31], v[74:77], v[114:117], v[28:31]
	v_mfma_f32_16x16x32_bf16 v[24:27], v[66:69], v[122:125], v[24:27]
	v_mfma_f32_16x16x32_bf16 v[20:23], v[90:93], v[114:117], v[20:23]
	v_mfma_f32_16x16x32_bf16 v[16:19], v[86:89], v[122:125], v[16:19]
	v_mfma_f32_16x16x32_bf16 v[12:15], v[206:209], v[114:117], v[12:15]
	v_mfma_f32_16x16x32_bf16 v[8:11], v[202:205], v[122:125], v[8:11]
	v_mfma_f32_16x16x32_bf16 v[4:7], v[214:217], v[114:117], v[4:7]
	v_mfma_f32_16x16x32_bf16 v[0:3], v[210:213], v[122:125], v[0:3]
	v_mfma_f32_16x16x32_bf16 v[158:161], v[74:77], v[146:149], v[24:27]
	v_mfma_f32_16x16x32_bf16 v[166:169], v[90:93], v[146:149], v[16:19]
	v_mfma_f32_16x16x32_bf16 v[170:173], v[206:209], v[146:149], v[8:11]
	v_mfma_f32_16x16x32_bf16 v[146:149], v[214:217], v[146:149], v[0:3]
	s_setprio 1
	s_barrier
; #define LDA(dst, b, h) _Pragma("unroll") for (int m = 0; m < 4; ++m) _Pragma("unroll") for (int k = 0; k < 2; ++k) \
;     dst[m][k] = *reinterpret_cast<const bf16x8*>((char*)SA(b, h) + lds_byte(wr * 64 + m * 16 + fr, k * 32 + fq * 8))
; #define LDB(dst, b, h) _Pragma("unroll") for (int n = 0; n < 2; ++n) _Pragma("unroll") for (int k = 0; k < 2; ++k) \
;     dst[n][k] = *reinterpret_cast<const bf16x8*>((char*)SB(b, h) + lds_byte(wc * 32 + n * 16 + fr, k * 32 + fq * 8))
; #define MMA(ai, bj, At, Bt_) do { __builtin_amdgcn_s_setprio(1); \
;     _Pragma("unroll") for (int m = 0; m < 4; ++m) _Pragma("unroll") for (int n = 0; n < 2; ++n) _Pragma("unroll") for (int k = 0; k < 2; ++k) \
;       acc[ai][bj][m][n] = __builtin_amdgcn_mfma_f32_16x16x32_bf16(At[m][k], Bt_[n][k], acc[ai][bj][m][n], 0, 0, 0); \
;     __builtin_amdgcn_s_setprio(0); } while (0)
; #define WAIT_V(n) asm volatile("s_waitcnt vmcnt(" #n ")" ::: "memory")
; #define WAIT_L(n) asm volatile("s_waitcnt lgkmcnt(" #n ")" ::: "memory")
; #define BAR __builtin_amdgcn_s_barrier()
; template <class Epi> ...
;     ...
;   { LDB(B0, 1, 0); LDA(At, 1, 0); WAIT_V(2); BAR; WAIT_L(0); MMA(0, 0, At, B0); BAR;
;     LDB(B1, 1, 1); WAIT_V(0); BAR; WAIT_L(0); MMA(0, 1, At, B1); BAR;
;     LDA(At, 1, 1); BAR; WAIT_L(0); MMA(1, 0, At, B0); MMA(1, 1, At, B1); BAR; }
;   if (wr == 0) BAR;
	ds_read_b128 v[174:177], v145
	ds_read_b128 v[202:205], v145 offset:1024
	ds_read_b128 v[206:209], v145 offset:2048
	ds_read_b128 v[210:213], v145 offset:3072
	ds_read_b128 v[0:3], v143 offset:32768
	ds_read_b128 v[8:11], v143 offset:33792
	ds_read_b128 v[16:19], v142 offset:32768
	ds_read_b128 v[34:37], v142 offset:33792
	ds_read_b128 v[214:217], v141 offset:32768
	ds_read_b128 v[238:241], v141 offset:33792
	ds_read_b128 v[242:245], v140 offset:32768
	ds_read_b128 v[246:249], v140 offset:33792
	s_waitcnt vmcnt(2)
	s_barrier
	s_waitcnt lgkmcnt(0)
	s_setprio 0
	s_waitcnt lgkmcnt(7)
	v_mfma_f32_16x16x32_bf16 v[24:27], v[0:3], v[174:177], v[126:129]
	s_waitcnt lgkmcnt(6)
	v_mfma_f32_16x16x32_bf16 v[122:125], v[8:11], v[202:205], v[24:27]
	v_mfma_f32_16x16x32_bf16 v[24:27], v[0:3], v[206:209], v[150:153]
	v_mfma_f32_16x16x32_bf16 v[90:93], v[8:11], v[210:213], v[24:27]
	s_waitcnt lgkmcnt(5)
	v_mfma_f32_16x16x32_bf16 v[24:27], v[16:19], v[174:177], v[118:121]
	s_waitcnt lgkmcnt(4)
	v_mfma_f32_16x16x32_bf16 v[114:117], v[34:37], v[202:205], v[24:27]
	v_mfma_f32_16x16x32_bf16 v[24:27], v[16:19], v[206:209], v[218:221]
	v_mfma_f32_16x16x32_bf16 v[86:89], v[34:37], v[210:213], v[24:27]
	s_waitcnt lgkmcnt(3)
	v_mfma_f32_16x16x32_bf16 v[24:27], v[214:217], v[174:177], v[110:113]
	s_waitcnt lgkmcnt(2)
	v_mfma_f32_16x16x32_bf16 v[110:113], v[238:241], v[202:205], v[24:27]
	v_mfma_f32_16x16x32_bf16 v[24:27], v[214:217], v[206:209], v[106:109]
	v_mfma_f32_16x16x32_bf16 v[74:77], v[238:241], v[210:213], v[24:27]
	s_waitcnt lgkmcnt(1)
	v_mfma_f32_16x16x32_bf16 v[24:27], v[242:245], v[174:177], v[102:105]
	s_waitcnt lgkmcnt(0)
	v_mfma_f32_16x16x32_bf16 v[98:101], v[246:249], v[202:205], v[24:27]
	v_mfma_f32_16x16x32_bf16 v[24:27], v[242:245], v[206:209], v[222:225]
	v_mfma_f32_16x16x32_bf16 v[66:69], v[246:249], v[210:213], v[24:27]
	s_setprio 1
	s_barrier
	ds_read_b128 v[150:153], v144
	ds_read_b128 v[218:221], v144 offset:1024
	ds_read_b128 v[222:225], v144 offset:2048
	ds_read_b128 v[250:253], v144 offset:3072
	s_waitcnt vmcnt(0)
	s_barrier
	s_waitcnt lgkmcnt(0)
	s_setprio 0
	s_waitcnt lgkmcnt(3)
	v_mfma_f32_16x16x32_bf16 v[24:27], v[0:3], v[150:153], v[94:97]
	s_waitcnt lgkmcnt(1)
	v_mfma_f32_16x16x32_bf16 v[0:3], v[0:3], v[222:225], v[186:189]
	v_mfma_f32_16x16x32_bf16 v[62:65], v[8:11], v[218:221], v[24:27]
	s_waitcnt lgkmcnt(0)
	v_mfma_f32_16x16x32_bf16 v[24:27], v[8:11], v[250:253], v[0:3]
	v_mfma_f32_16x16x32_bf16 v[0:3], v[16:19], v[150:153], v[190:193]
	v_mfma_f32_16x16x32_bf16 v[50:53], v[34:37], v[218:221], v[0:3]
	v_mfma_f32_16x16x32_bf16 v[0:3], v[16:19], v[222:225], v[82:85]
	v_mfma_f32_16x16x32_bf16 v[16:19], v[34:37], v[250:253], v[0:3]
	v_mfma_f32_16x16x32_bf16 v[0:3], v[214:217], v[150:153], v[78:81]
	v_mfma_f32_16x16x32_bf16 v[42:45], v[238:241], v[218:221], v[0:3]
	v_mfma_f32_16x16x32_bf16 v[0:3], v[214:217], v[222:225], v[194:197]
	v_mfma_f32_16x16x32_bf16 v[8:11], v[238:241], v[250:253], v[0:3]
	v_mfma_f32_16x16x32_bf16 v[0:3], v[242:245], v[150:153], v[70:73]
	v_mfma_f32_16x16x32_bf16 v[34:37], v[246:249], v[218:221], v[0:3]
	v_mfma_f32_16x16x32_bf16 v[0:3], v[242:245], v[222:225], v[198:201]
	v_mfma_f32_16x16x32_bf16 v[0:3], v[246:249], v[250:253], v[0:3]
	s_setprio 1
	s_barrier
	ds_read_b128 v[186:189], v143 offset:49152
	ds_read_b128 v[190:193], v143 offset:50176
	ds_read_b128 v[194:197], v142 offset:49152
	ds_read_b128 v[142:145], v142 offset:50176
	ds_read_b128 v[198:201], v141 offset:49152
	ds_read_b128 v[214:217], v141 offset:50176
	ds_read_b128 v[238:241], v140 offset:49152
	ds_read_b128 v[242:245], v140 offset:50176
	s_barrier
	s_waitcnt lgkmcnt(0)
	s_setprio 0
	s_waitcnt lgkmcnt(5)
	v_mfma_f32_16x16x32_bf16 v[54:57], v[194:197], v[174:177], v[54:57]
	s_waitcnt lgkmcnt(3)
	v_mfma_f32_16x16x32_bf16 v[46:49], v[198:201], v[174:177], v[46:49]
	s_waitcnt lgkmcnt(1)
	v_mfma_f32_16x16x32_bf16 v[38:41], v[238:241], v[174:177], v[38:41]
	v_mfma_f32_16x16x32_bf16 v[70:73], v[186:189], v[174:177], v[226:229]
	v_mfma_f32_16x16x32_bf16 v[58:61], v[186:189], v[206:209], v[58:61]
	v_mfma_f32_16x16x32_bf16 v[118:121], v[142:145], v[202:205], v[54:57]
	v_mfma_f32_16x16x32_bf16 v[54:57], v[194:197], v[206:209], v[230:233]
	v_mfma_f32_16x16x32_bf16 v[106:109], v[214:217], v[202:205], v[46:49]
	v_mfma_f32_16x16x32_bf16 v[46:49], v[198:201], v[206:209], v[234:237]
	s_waitcnt lgkmcnt(0)
	v_mfma_f32_16x16x32_bf16 v[102:105], v[242:245], v[202:205], v[38:41]
	v_mfma_f32_16x16x32_bf16 v[38:41], v[238:241], v[206:209], v[154:157]
	v_mfma_f32_16x16x32_bf16 v[126:129], v[190:193], v[202:205], v[70:73]
	v_mfma_f32_16x16x32_bf16 v[94:97], v[190:193], v[210:213], v[58:61]
	v_mfma_f32_16x16x32_bf16 v[82:85], v[142:145], v[210:213], v[54:57]
	v_mfma_f32_16x16x32_bf16 v[78:81], v[214:217], v[210:213], v[46:49]
	v_mfma_f32_16x16x32_bf16 v[70:73], v[242:245], v[210:213], v[38:41]
	s_setprio 1
	s_setprio 0
	v_mfma_f32_16x16x32_bf16 v[28:31], v[186:189], v[150:153], v[28:31]
	v_mfma_f32_16x16x32_bf16 v[20:23], v[194:197], v[150:153], v[20:23]
	v_mfma_f32_16x16x32_bf16 v[12:15], v[198:201], v[150:153], v[12:15]
	v_mfma_f32_16x16x32_bf16 v[4:7], v[238:241], v[150:153], v[4:7]
	v_mfma_f32_16x16x32_bf16 v[58:61], v[190:193], v[218:221], v[28:31]
	v_mfma_f32_16x16x32_bf16 v[28:31], v[186:189], v[222:225], v[158:161]
	v_mfma_f32_16x16x32_bf16 v[54:57], v[142:145], v[218:221], v[20:23]
	v_mfma_f32_16x16x32_bf16 v[20:23], v[194:197], v[222:225], v[166:169]
	v_mfma_f32_16x16x32_bf16 v[46:49], v[214:217], v[218:221], v[12:15]
	v_mfma_f32_16x16x32_bf16 v[12:15], v[198:201], v[222:225], v[170:173]
	v_mfma_f32_16x16x32_bf16 v[38:41], v[242:245], v[218:221], v[4:7]
	v_mfma_f32_16x16x32_bf16 v[4:7], v[238:241], v[222:225], v[146:149]
	v_mfma_f32_16x16x32_bf16 v[28:31], v[190:193], v[250:253], v[28:31]
	v_mfma_f32_16x16x32_bf16 v[20:23], v[142:145], v[250:253], v[20:23]
	v_mfma_f32_16x16x32_bf16 v[12:15], v[214:217], v[250:253], v[12:15]
	v_mfma_f32_16x16x32_bf16 v[4:7], v[242:245], v[250:253], v[4:7]
	s_setprio 1
	v_cmp_gt_u32_e32 vcc, s59, v130
	s_barrier
	s_and_saveexec_b64 s[10:11], vcc
	s_cbranch_execz .LBB0_2256
	s_barrier

; #define STAGE(P, BASE, br, kt) do { int _so = ((br) * K + (kt) * BK) * 2; \
;     __builtin_amdgcn_raw_ptr_buffer_load_lds(rs_##BASE, (__attribute__((address_space(3))) void*)((char*)(P) + tx * 16), 16, voff0, _so, 0, 0); \
;     __builtin_amdgcn_raw_ptr_buffer_load_lds(rs_##BASE, (__attribute__((address_space(3))) void*)((char*)(P) + tx * 16 + 8192), 16, voff1, _so, 0, 0); } while (0)
; #define LDA(dst, b, h) _Pragma("unroll") for (int m = 0; m < 4; ++m) _Pragma("unroll") for (int k = 0; k < 2; ++k) \
;     dst[m][k] = *reinterpret_cast<const bf16x8*>((char*)SA(b, h) + lds_byte(wr * 64 + m * 16 + fr, k * 32 + fq * 8))
; #define LDB(dst, b, h) _Pragma("unroll") for (int n = 0; n < 2; ++n) _Pragma("unroll") for (int k = 0; k < 2; ++k) \
;     dst[n][k] = *reinterpret_cast<const bf16x8*>((char*)SB(b, h) + lds_byte(wc * 32 + n * 16 + fr, k * 32 + fq * 8))
; #define MMA(ai, bj, At, Bt_) do { __builtin_amdgcn_s_setprio(1); \
;     _Pragma("unroll") for (int m = 0; m < 4; ++m) _Pragma("unroll") for (int n = 0; n < 2; ++n) _Pragma("unroll") for (int k = 0; k < 2; ++k) \
;       acc[ai][bj][m][n] = __builtin_amdgcn_mfma_f32_16x16x32_bf16(At[m][k], Bt_[n][k], acc[ai][bj][m][n], 0, 0, 0); \
;     __builtin_amdgcn_s_setprio(0); } while (0)
; #define WAIT_V(n) asm volatile("s_waitcnt vmcnt(" #n ")" ::: "memory")
; #define WAIT_L(n) asm volatile("s_waitcnt lgkmcnt(" #n ")" ::: "memory")
; #define BAR __builtin_amdgcn_s_barrier()
; #define SCHED __builtin_amdgcn_sched_barrier(0)
; template <class Epi> ...
;     ...
;     LDB(B0, 0, 0); SCHED; LDA(At, 0, 0); STAGE(SA(1, 1), A, brow + HALF, t + 1);
;     WAIT_L(8); BAR; WAIT_L(0); MMA(0, 0, At, B0); BAR; SCHED;
;     LDB(B1, 0, 1); STAGE(SB(0, 0), Bt, bcol, t + 2);
;     BAR; WAIT_L(0); MMA(0, 1, At, B1); BAR;
;     LDA(At, 0, 1); STAGE(SA(0, 0), A, brow, t + 2);
;     BAR; WAIT_L(0); MMA(1, 0, At, B0); BAR; SCHED;
;     STAGE(SB(0, 1), Bt, bcol + HALF, t + 2);
;     WAIT_V(6); BAR; MMA(1, 1, At, B1); BAR;
.Lpk8:
	ds_read_b128 v[156:159], v155
	ds_read_b128 v[166:169], v155 offset:1024
	ds_read_b128 v[170:173], v155 offset:2048
	ds_read_b128 v[174:177], v155 offset:3072
	s_add_i32 s23, s21, s15
	v_readfirstlane_b32 s25, v152
	s_add_i32 s24, s23, 0xb0080
	s_mov_b32 m0, s25
	v_readfirstlane_b32 s25, v151
	ds_read_b128 v[186:189], v143
	ds_read_b128 v[190:193], v143 offset:1024
	ds_read_b128 v[194:197], v142
	ds_read_b128 v[198:201], v142 offset:1024
	ds_read_b128 v[202:205], v141
	ds_read_b128 v[206:209], v141 offset:1024
	ds_read_b128 v[210:213], v140
	ds_read_b128 v[214:217], v140 offset:1024
	buffer_load_dwordx4 v32, s[4:7], s24 offen lds
	s_mov_b32 m0, s25
	s_nop 0
	buffer_load_dwordx4 v131, s[4:7], s24 offen lds
	s_waitcnt lgkmcnt(8)
	s_barrier
	s_waitcnt lgkmcnt(0)
	s_setprio 0
	s_waitcnt lgkmcnt(7)
	v_mfma_f32_16x16x32_bf16 v[126:129], v[186:189], v[156:159], 0
	v_mfma_f32_16x16x32_bf16 v[122:125], v[186:189], v[170:173], 0
	s_waitcnt lgkmcnt(5)
	v_mfma_f32_16x16x32_bf16 v[118:121], v[194:197], v[156:159], 0
	v_mfma_f32_16x16x32_bf16 v[114:117], v[194:197], v[170:173], 0
	s_waitcnt lgkmcnt(3)
	v_mfma_f32_16x16x32_bf16 v[110:113], v[202:205], v[156:159], 0
	v_mfma_f32_16x16x32_bf16 v[106:109], v[202:205], v[170:173], 0
	s_waitcnt lgkmcnt(1)
	v_mfma_f32_16x16x32_bf16 v[102:105], v[210:213], v[156:159], 0
	v_mfma_f32_16x16x32_bf16 v[98:101], v[210:213], v[170:173], 0
	v_mfma_f32_16x16x32_bf16 v[126:129], v[190:193], v[166:169], v[126:129]
	v_mfma_f32_16x16x32_bf16 v[122:125], v[190:193], v[174:177], v[122:125]
	v_mfma_f32_16x16x32_bf16 v[118:121], v[198:201], v[166:169], v[118:121]
	v_mfma_f32_16x16x32_bf16 v[114:117], v[198:201], v[174:177], v[114:117]
	v_mfma_f32_16x16x32_bf16 v[110:113], v[206:209], v[166:169], v[110:113]
	v_mfma_f32_16x16x32_bf16 v[106:109], v[206:209], v[174:177], v[106:109]
	s_waitcnt lgkmcnt(0)
	v_mfma_f32_16x16x32_bf16 v[102:105], v[214:217], v[166:169], v[102:105]
	v_mfma_f32_16x16x32_bf16 v[98:101], v[214:217], v[174:177], v[98:101]
	s_setprio 1
	s_barrier
	s_add_i32 s24, s22, s15
	v_readfirstlane_b32 s26, v137
	s_add_i32 s25, s24, 0x100
	s_mov_b32 m0, s26
	v_readfirstlane_b32 s26, v139
	ds_read_b128 v[218:221], v149
	ds_read_b128 v[222:225], v149 offset:1024
	ds_read_b128 v[226:229], v149 offset:2048
	ds_read_b128 v[230:233], v149 offset:3072
	buffer_load_dwordx4 v32, s[76:79], s25 offen lds
	s_mov_b32 m0, s26
	s_nop 0
	buffer_load_dwordx4 v131, s[76:79], s25 offen lds
	s_barrier
	s_waitcnt lgkmcnt(0)
	s_setprio 0
	s_waitcnt lgkmcnt(3)
	v_mfma_f32_16x16x32_bf16 v[94:97], v[186:189], v[218:221], 0
	s_waitcnt lgkmcnt(1)
	v_mfma_f32_16x16x32_bf16 v[90:93], v[186:189], v[226:229], 0
	v_mfma_f32_16x16x32_bf16 v[86:89], v[194:197], v[218:221], 0
	v_mfma_f32_16x16x32_bf16 v[82:85], v[194:197], v[226:229], 0
	v_mfma_f32_16x16x32_bf16 v[78:81], v[202:205], v[218:221], 0
	v_mfma_f32_16x16x32_bf16 v[74:77], v[202:205], v[226:229], 0
	v_mfma_f32_16x16x32_bf16 v[70:73], v[210:213], v[218:221], 0
	v_mfma_f32_16x16x32_bf16 v[66:69], v[210:213], v[226:229], 0
	v_mfma_f32_16x16x32_bf16 v[94:97], v[190:193], v[222:225], v[94:97]
	s_waitcnt lgkmcnt(0)
	v_mfma_f32_16x16x32_bf16 v[90:93], v[190:193], v[230:233], v[90:93]
	v_mfma_f32_16x16x32_bf16 v[86:89], v[198:201], v[222:225], v[86:89]
	v_mfma_f32_16x16x32_bf16 v[82:85], v[198:201], v[230:233], v[82:85]
	v_mfma_f32_16x16x32_bf16 v[78:81], v[206:209], v[222:225], v[78:81]
	v_mfma_f32_16x16x32_bf16 v[74:77], v[206:209], v[230:233], v[74:77]
	v_mfma_f32_16x16x32_bf16 v[70:73], v[214:217], v[222:225], v[70:73]
	v_mfma_f32_16x16x32_bf16 v[66:69], v[214:217], v[230:233], v[66:69]
	s_setprio 1
	v_readfirstlane_b32 s26, v136
	s_add_i32 s25, s23, 0x100
	s_mov_b32 m0, s26
	v_readfirstlane_b32 s26, v135
	s_barrier
	ds_read_b128 v[186:189], v143 offset:16384
	ds_read_b128 v[190:193], v143 offset:17408
	ds_read_b128 v[194:197], v142 offset:16384
	ds_read_b128 v[198:201], v142 offset:17408
	ds_read_b128 v[202:205], v141 offset:16384
	ds_read_b128 v[206:209], v141 offset:17408
	ds_read_b128 v[210:213], v140 offset:16384
	ds_read_b128 v[214:217], v140 offset:17408
	buffer_load_dwordx4 v32, s[4:7], s25 offen lds
	s_mov_b32 m0, s26
	s_nop 0
	buffer_load_dwordx4 v131, s[4:7], s25 offen lds
	s_barrier
	s_waitcnt lgkmcnt(0)
	s_setprio 0
	s_waitcnt lgkmcnt(7)
	v_mfma_f32_16x16x32_bf16 v[62:65], v[186:189], v[156:159], 0
	v_mfma_f32_16x16x32_bf16 v[58:61], v[186:189], v[170:173], 0
	s_waitcnt lgkmcnt(5)
	v_mfma_f32_16x16x32_bf16 v[54:57], v[194:197], v[156:159], 0
	v_mfma_f32_16x16x32_bf16 v[50:53], v[194:197], v[170:173], 0
	s_waitcnt lgkmcnt(3)
	v_mfma_f32_16x16x32_bf16 v[46:49], v[202:205], v[156:159], 0
	v_mfma_f32_16x16x32_bf16 v[42:45], v[202:205], v[170:173], 0
	s_waitcnt lgkmcnt(1)
	v_mfma_f32_16x16x32_bf16 v[38:41], v[210:213], v[156:159], 0
	v_mfma_f32_16x16x32_bf16 v[34:37], v[210:213], v[170:173], 0
	v_mfma_f32_16x16x32_bf16 v[62:65], v[190:193], v[166:169], v[62:65]
	v_mfma_f32_16x16x32_bf16 v[58:61], v[190:193], v[174:177], v[58:61]
	v_mfma_f32_16x16x32_bf16 v[54:57], v[198:201], v[166:169], v[54:57]
	v_mfma_f32_16x16x32_bf16 v[50:53], v[198:201], v[174:177], v[50:53]
	v_mfma_f32_16x16x32_bf16 v[46:49], v[206:209], v[166:169], v[46:49]
	v_mfma_f32_16x16x32_bf16 v[42:45], v[206:209], v[174:177], v[42:45]
	s_waitcnt lgkmcnt(0)
	v_mfma_f32_16x16x32_bf16 v[38:41], v[214:217], v[166:169], v[38:41]
	v_mfma_f32_16x16x32_bf16 v[34:37], v[214:217], v[174:177], v[34:37]
	s_setprio 1
	s_barrier
	v_readfirstlane_b32 s26, v134
	s_add_i32 s25, s24, 0xb0100
	s_mov_b32 m0, s26
	v_readfirstlane_b32 s26, v138
	buffer_load_dwordx4 v32, s[76:79], s25 offen lds
	s_mov_b32 m0, s26
	s_nop 0
	buffer_load_dwordx4 v131, s[76:79], s25 offen lds
	s_waitcnt vmcnt(6)
	s_barrier
; #define STAGE(P, BASE, br, kt) do { int _so = ((br) * K + (kt) * BK) * 2; \
;     __builtin_amdgcn_raw_ptr_buffer_load_lds(rs_##BASE, (__attribute__((address_space(3))) void*)((char*)(P) + tx * 16), 16, voff0, _so, 0, 0); \
;     __builtin_amdgcn_raw_ptr_buffer_load_lds(rs_##BASE, (__attribute__((address_space(3))) void*)((char*)(P) + tx * 16 + 8192), 16, voff1, _so, 0, 0); } while (0)
; #define LDA(dst, b, h) _Pragma("unroll") for (int m = 0; m < 4; ++m) _Pragma("unroll") for (int k = 0; k < 2; ++k) \
;     dst[m][k] = *reinterpret_cast<const bf16x8*>((char*)SA(b, h) + lds_byte(wr * 64 + m * 16 + fr, k * 32 + fq * 8))
; #define LDB(dst, b, h) _Pragma("unroll") for (int n = 0; n < 2; ++n) _Pragma("unroll") for (int k = 0; k < 2; ++k) \
;     dst[n][k] = *reinterpret_cast<const bf16x8*>((char*)SB(b, h) + lds_byte(wc * 32 + n * 16 + fr, k * 32 + fq * 8))
; #define MMA(ai, bj, At, Bt_) do { __builtin_amdgcn_s_setprio(1); \
;     _Pragma("unroll") for (int m = 0; m < 4; ++m) _Pragma("unroll") for (int n = 0; n < 2; ++n) _Pragma("unroll") for (int k = 0; k < 2; ++k) \
;       acc[ai][bj][m][n] = __builtin_amdgcn_mfma_f32_16x16x32_bf16(At[m][k], Bt_[n][k], acc[ai][bj][m][n], 0, 0, 0); \
;     __builtin_amdgcn_s_setprio(0); } while (0)
; #define WAIT_V(n) asm volatile("s_waitcnt vmcnt(" #n ")" ::: "memory")
; #define WAIT_L(n) asm volatile("s_waitcnt lgkmcnt(" #n ")" ::: "memory")
; #define BAR __builtin_amdgcn_s_barrier()
; #define SCHED __builtin_amdgcn_sched_barrier(0)
; template <class Epi> ...
;     ...
;     WAIT_V(6); BAR; MMA(1, 1, At, B1); BAR;
;     LDB(B0, 1, 0); SCHED; LDA(At, 1, 0); STAGE(SA(0, 1), A, brow + HALF, t + 2);
;     WAIT_L(8); BAR; WAIT_L(0); MMA(0, 0, At, B0); BAR; SCHED;
;     LDB(B1, 1, 1); STAGE(SB(1, 0), Bt, bcol, t + 3);
;     BAR; WAIT_L(0); MMA(0, 1, At, B1); BAR;
;     LDA(At, 1, 1); STAGE(SA(1, 0), A, brow, t + 3);
;     BAR; WAIT_L(0); MMA(1, 0, At, B0); BAR; SCHED;
;     STAGE(SB(1, 1), Bt, bcol + HALF, t + 3);
	s_setprio 0
	v_mfma_f32_16x16x32_bf16 v[28:31], v[186:189], v[218:221], 0
	v_mfma_f32_16x16x32_bf16 v[24:27], v[186:189], v[226:229], 0
	v_mfma_f32_16x16x32_bf16 v[20:23], v[194:197], v[218:221], 0
	v_mfma_f32_16x16x32_bf16 v[16:19], v[194:197], v[226:229], 0
	v_mfma_f32_16x16x32_bf16 v[12:15], v[202:205], v[218:221], 0
	v_mfma_f32_16x16x32_bf16 v[8:11], v[202:205], v[226:229], 0
	v_mfma_f32_16x16x32_bf16 v[4:7], v[210:213], v[218:221], 0
	v_mfma_f32_16x16x32_bf16 v[0:3], v[210:213], v[226:229], 0
	v_mfma_f32_16x16x32_bf16 v[28:31], v[190:193], v[222:225], v[28:31]
	v_mfma_f32_16x16x32_bf16 v[24:27], v[190:193], v[230:233], v[24:27]
	v_mfma_f32_16x16x32_bf16 v[20:23], v[198:201], v[222:225], v[20:23]
	v_mfma_f32_16x16x32_bf16 v[16:19], v[198:201], v[230:233], v[16:19]
	v_mfma_f32_16x16x32_bf16 v[12:15], v[206:209], v[222:225], v[12:15]
	v_mfma_f32_16x16x32_bf16 v[8:11], v[206:209], v[230:233], v[8:11]
	v_mfma_f32_16x16x32_bf16 v[4:7], v[214:217], v[222:225], v[4:7]
	v_mfma_f32_16x16x32_bf16 v[0:3], v[214:217], v[230:233], v[0:3]
	s_setprio 1
	s_barrier
	ds_read_b128 v[156:159], v145
	ds_read_b128 v[166:169], v145 offset:1024
	ds_read_b128 v[170:173], v145 offset:2048
	ds_read_b128 v[174:177], v145 offset:3072
	v_readfirstlane_b32 s26, v133
	s_add_i32 s25, s23, 0xb0100
	s_mov_b32 m0, s26
	v_readfirstlane_b32 s26, v132
	ds_read_b128 v[186:189], v143 offset:32768
	ds_read_b128 v[190:193], v143 offset:33792
	ds_read_b128 v[194:197], v142 offset:32768
	ds_read_b128 v[198:201], v142 offset:33792
	ds_read_b128 v[202:205], v141 offset:32768
	ds_read_b128 v[206:209], v141 offset:33792
	ds_read_b128 v[210:213], v140 offset:32768
	ds_read_b128 v[214:217], v140 offset:33792
	buffer_load_dwordx4 v32, s[4:7], s25 offen lds
	s_mov_b32 m0, s26
	s_nop 0
	buffer_load_dwordx4 v131, s[4:7], s25 offen lds
	s_waitcnt lgkmcnt(8)
	s_barrier
	s_waitcnt lgkmcnt(0)
	s_setprio 0
	s_waitcnt lgkmcnt(7)
	v_mfma_f32_16x16x32_bf16 v[126:129], v[186:189], v[156:159], v[126:129]
	v_mfma_f32_16x16x32_bf16 v[122:125], v[186:189], v[170:173], v[122:125]
	s_waitcnt lgkmcnt(5)
	v_mfma_f32_16x16x32_bf16 v[118:121], v[194:197], v[156:159], v[118:121]
	v_mfma_f32_16x16x32_bf16 v[114:117], v[194:197], v[170:173], v[114:117]
	s_waitcnt lgkmcnt(3)
	v_mfma_f32_16x16x32_bf16 v[110:113], v[202:205], v[156:159], v[110:113]
	v_mfma_f32_16x16x32_bf16 v[106:109], v[202:205], v[170:173], v[106:109]
	s_waitcnt lgkmcnt(1)
	v_mfma_f32_16x16x32_bf16 v[102:105], v[210:213], v[156:159], v[102:105]
	v_mfma_f32_16x16x32_bf16 v[98:101], v[210:213], v[170:173], v[98:101]
	v_mfma_f32_16x16x32_bf16 v[126:129], v[190:193], v[166:169], v[126:129]
	v_mfma_f32_16x16x32_bf16 v[122:125], v[190:193], v[174:177], v[122:125]
	v_mfma_f32_16x16x32_bf16 v[118:121], v[198:201], v[166:169], v[118:121]
	v_mfma_f32_16x16x32_bf16 v[114:117], v[198:201], v[174:177], v[114:117]
	v_mfma_f32_16x16x32_bf16 v[110:113], v[206:209], v[166:169], v[110:113]
	v_mfma_f32_16x16x32_bf16 v[106:109], v[206:209], v[174:177], v[106:109]
	s_waitcnt lgkmcnt(0)
	v_mfma_f32_16x16x32_bf16 v[102:105], v[214:217], v[166:169], v[102:105]
	v_mfma_f32_16x16x32_bf16 v[98:101], v[214:217], v[174:177], v[98:101]
	s_setprio 1
	s_barrier
	v_readfirstlane_b32 s26, v146
	s_add_i32 s25, s24, 0x180
	s_mov_b32 m0, s26
	v_readfirstlane_b32 s26, v147
	ds_read_b128 v[218:221], v144
	ds_read_b128 v[222:225], v144 offset:1024
	ds_read_b128 v[226:229], v144 offset:2048
	ds_read_b128 v[230:233], v144 offset:3072
	buffer_load_dwordx4 v32, s[76:79], s25 offen lds
	s_mov_b32 m0, s26
	s_nop 0
	buffer_load_dwordx4 v131, s[76:79], s25 offen lds
	s_barrier
	s_waitcnt lgkmcnt(0)
	s_setprio 0
	s_waitcnt lgkmcnt(3)
	v_mfma_f32_16x16x32_bf16 v[94:97], v[186:189], v[218:221], v[94:97]
	s_waitcnt lgkmcnt(1)
	v_mfma_f32_16x16x32_bf16 v[90:93], v[186:189], v[226:229], v[90:93]
	v_mfma_f32_16x16x32_bf16 v[86:89], v[194:197], v[218:221], v[86:89]
	v_mfma_f32_16x16x32_bf16 v[82:85], v[194:197], v[226:229], v[82:85]
	v_mfma_f32_16x16x32_bf16 v[78:81], v[202:205], v[218:221], v[78:81]
	v_mfma_f32_16x16x32_bf16 v[74:77], v[202:205], v[226:229], v[74:77]
	v_mfma_f32_16x16x32_bf16 v[70:73], v[210:213], v[218:221], v[70:73]
	v_mfma_f32_16x16x32_bf16 v[66:69], v[210:213], v[226:229], v[66:69]
	v_mfma_f32_16x16x32_bf16 v[94:97], v[190:193], v[222:225], v[94:97]
	s_waitcnt lgkmcnt(0)
	v_mfma_f32_16x16x32_bf16 v[90:93], v[190:193], v[230:233], v[90:93]
	v_mfma_f32_16x16x32_bf16 v[86:89], v[198:201], v[222:225], v[86:89]
	v_mfma_f32_16x16x32_bf16 v[82:85], v[198:201], v[230:233], v[82:85]
	v_mfma_f32_16x16x32_bf16 v[78:81], v[206:209], v[222:225], v[78:81]
	v_mfma_f32_16x16x32_bf16 v[74:77], v[206:209], v[230:233], v[74:77]
	v_mfma_f32_16x16x32_bf16 v[70:73], v[214:217], v[222:225], v[70:73]
	v_mfma_f32_16x16x32_bf16 v[66:69], v[214:217], v[230:233], v[66:69]
	s_setprio 1
	v_readfirstlane_b32 s25, v148
	s_addk_i32 s23, 0x180
	s_mov_b32 m0, s25
	v_readfirstlane_b32 s25, v150
	s_barrier
	ds_read_b128 v[186:189], v143 offset:49152
	ds_read_b128 v[190:193], v143 offset:50176
	ds_read_b128 v[194:197], v142 offset:49152
	ds_read_b128 v[198:201], v142 offset:50176
	ds_read_b128 v[202:205], v141 offset:49152
	ds_read_b128 v[206:209], v141 offset:50176
	ds_read_b128 v[210:213], v140 offset:49152
	ds_read_b128 v[214:217], v140 offset:50176
	buffer_load_dwordx4 v32, s[4:7], s23 offen lds
	s_mov_b32 m0, s25
	s_nop 0
	buffer_load_dwordx4 v131, s[4:7], s23 offen lds
	s_barrier
; #define STAGE(P, BASE, br, kt) do { int _so = ((br) * K + (kt) * BK) * 2; \
;     __builtin_amdgcn_raw_ptr_buffer_load_lds(rs_##BASE, (__attribute__((address_space(3))) void*)((char*)(P) + tx * 16), 16, voff0, _so, 0, 0); \
;     __builtin_amdgcn_raw_ptr_buffer_load_lds(rs_##BASE, (__attribute__((address_space(3))) void*)((char*)(P) + tx * 16 + 8192), 16, voff1, _so, 0, 0); } while (0)
; #define LDA(dst, b, h) _Pragma("unroll") for (int m = 0; m < 4; ++m) _Pragma("unroll") for (int k = 0; k < 2; ++k) \
;     dst[m][k] = *reinterpret_cast<const bf16x8*>((char*)SA(b, h) + lds_byte(wr * 64 + m * 16 + fr, k * 32 + fq * 8))
; #define LDB(dst, b, h) _Pragma("unroll") for (int n = 0; n < 2; ++n) _Pragma("unroll") for (int k = 0; k < 2; ++k) \
;     dst[n][k] = *reinterpret_cast<const bf16x8*>((char*)SB(b, h) + lds_byte(wc * 32 + n * 16 + fr, k * 32 + fq * 8))
; #define MMA(ai, bj, At, Bt_) do { __builtin_amdgcn_s_setprio(1); \
;     _Pragma("unroll") for (int m = 0; m < 4; ++m) _Pragma("unroll") for (int n = 0; n < 2; ++n) _Pragma("unroll") for (int k = 0; k < 2; ++k) \
;       acc[ai][bj][m][n] = __builtin_amdgcn_mfma_f32_16x16x32_bf16(At[m][k], Bt_[n][k], acc[ai][bj][m][n], 0, 0, 0); \
;     __builtin_amdgcn_s_setprio(0); } while (0)
; #define WAIT_V(n) asm volatile("s_waitcnt vmcnt(" #n ")" ::: "memory")
; #define WAIT_L(n) asm volatile("s_waitcnt lgkmcnt(" #n ")" ::: "memory")
; #define BAR __builtin_amdgcn_s_barrier()
; #define SCHED __builtin_amdgcn_sched_barrier(0)
; template <class Epi> ...
;     ...
;   for (int t = 0; t < nt - 2; t += 2) {
;     LDB(B0, 0, 0); SCHED; LDA(At, 0, 0); STAGE(SA(1, 1), A, brow + HALF, t + 1);
;     WAIT_L(8); BAR; WAIT_L(0); MMA(0, 0, At, B0); BAR; SCHED;
;     LDB(B1, 0, 1); STAGE(SB(0, 0), Bt, bcol, t + 2);
;     ...
;     BAR; WAIT_L(0); MMA(1, 0, At, B0); BAR; SCHED;
;     STAGE(SB(1, 1), Bt, bcol + HALF, t + 3);
;     WAIT_V(6); BAR; MMA(1, 1, At, B1); BAR;
	s_waitcnt lgkmcnt(0)
	s_setprio 0
	s_waitcnt lgkmcnt(7)
	v_mfma_f32_16x16x32_bf16 v[62:65], v[186:189], v[156:159], v[62:65]
	v_mfma_f32_16x16x32_bf16 v[58:61], v[186:189], v[170:173], v[58:61]
	s_waitcnt lgkmcnt(5)
	v_mfma_f32_16x16x32_bf16 v[54:57], v[194:197], v[156:159], v[54:57]
	v_mfma_f32_16x16x32_bf16 v[50:53], v[194:197], v[170:173], v[50:53]
	s_waitcnt lgkmcnt(3)
	v_mfma_f32_16x16x32_bf16 v[46:49], v[202:205], v[156:159], v[46:49]
	v_mfma_f32_16x16x32_bf16 v[42:45], v[202:205], v[170:173], v[42:45]
	s_waitcnt lgkmcnt(1)
	v_mfma_f32_16x16x32_bf16 v[38:41], v[210:213], v[156:159], v[38:41]
	v_mfma_f32_16x16x32_bf16 v[34:37], v[210:213], v[170:173], v[34:37]
	v_mfma_f32_16x16x32_bf16 v[62:65], v[190:193], v[166:169], v[62:65]
	v_mfma_f32_16x16x32_bf16 v[58:61], v[190:193], v[174:177], v[58:61]
	v_mfma_f32_16x16x32_bf16 v[54:57], v[198:201], v[166:169], v[54:57]
	v_mfma_f32_16x16x32_bf16 v[50:53], v[198:201], v[174:177], v[50:53]
	v_mfma_f32_16x16x32_bf16 v[46:49], v[206:209], v[166:169], v[46:49]
	v_mfma_f32_16x16x32_bf16 v[42:45], v[206:209], v[174:177], v[42:45]
	s_waitcnt lgkmcnt(0)
	v_mfma_f32_16x16x32_bf16 v[38:41], v[214:217], v[166:169], v[38:41]
	v_mfma_f32_16x16x32_bf16 v[34:37], v[214:217], v[174:177], v[34:37]
	s_setprio 1
	s_barrier
	v_readfirstlane_b32 s23, v153
	s_add_i32 s24, s24, 0xb0180
	s_mov_b32 m0, s23
	v_readfirstlane_b32 s23, v154
	buffer_load_dwordx4 v32, s[76:79], s24 offen lds
	s_mov_b32 m0, s23
	s_nop 0
	buffer_load_dwordx4 v131, s[76:79], s24 offen lds
	s_waitcnt vmcnt(6)
	s_barrier
	s_setprio 0
	v_mfma_f32_16x16x32_bf16 v[28:31], v[186:189], v[218:221], v[28:31]
	v_mfma_f32_16x16x32_bf16 v[24:27], v[186:189], v[226:229], v[24:27]
	v_mfma_f32_16x16x32_bf16 v[20:23], v[194:197], v[218:221], v[20:23]
	v_mfma_f32_16x16x32_bf16 v[16:19], v[194:197], v[226:229], v[16:19]
	v_mfma_f32_16x16x32_bf16 v[12:15], v[202:205], v[218:221], v[12:15]
	v_mfma_f32_16x16x32_bf16 v[8:11], v[202:205], v[226:229], v[8:11]
	v_mfma_f32_16x16x32_bf16 v[4:7], v[210:213], v[218:221], v[4:7]
	v_mfma_f32_16x16x32_bf16 v[0:3], v[210:213], v[226:229], v[0:3]
	v_mfma_f32_16x16x32_bf16 v[28:31], v[190:193], v[222:225], v[28:31]
	v_mfma_f32_16x16x32_bf16 v[24:27], v[190:193], v[230:233], v[24:27]
	v_mfma_f32_16x16x32_bf16 v[20:23], v[198:201], v[222:225], v[20:23]
	v_mfma_f32_16x16x32_bf16 v[16:19], v[198:201], v[230:233], v[16:19]
	v_mfma_f32_16x16x32_bf16 v[12:15], v[206:209], v[222:225], v[12:15]
	v_mfma_f32_16x16x32_bf16 v[8:11], v[206:209], v[230:233], v[8:11]
	v_mfma_f32_16x16x32_bf16 v[4:7], v[214:217], v[222:225], v[4:7]
	v_mfma_f32_16x16x32_bf16 v[0:3], v[214:217], v[230:233], v[0:3]
	s_setprio 1
	s_add_i32 s14, s14, 2
	s_addk_i32 s15, 0x100
	s_cmp_lt_u32 s14, 40
	s_barrier
	s_cbranch_scc1 .LBB0_2336
	s_branch .Lpx8
.LBB0_2336:
	ds_read_b128 v[156:159], v155
	ds_read_b128 v[166:169], v155 offset:1024
	ds_read_b128 v[170:173], v155 offset:2048
	ds_read_b128 v[174:177], v155 offset:3072
	s_add_i32 s23, s21, s15
	v_readfirstlane_b32 s25, v152
	s_add_i32 s24, s23, 0xb0080
	s_mov_b32 m0, s25
	v_readfirstlane_b32 s25, v151
	ds_read_b128 v[186:189], v143
	ds_read_b128 v[190:193], v143 offset:1024
	ds_read_b128 v[194:197], v142
	ds_read_b128 v[198:201], v142 offset:1024
	ds_read_b128 v[202:205], v141
	ds_read_b128 v[206:209], v141 offset:1024
	ds_read_b128 v[210:213], v140
	ds_read_b128 v[214:217], v140 offset:1024
	buffer_load_dwordx4 v32, s[4:7], s24 offen lds
	s_mov_b32 m0, s25
	s_nop 0
	buffer_load_dwordx4 v131, s[4:7], s24 offen lds
	s_waitcnt lgkmcnt(8)
	s_barrier
	s_waitcnt lgkmcnt(0)
	s_setprio 0
	s_waitcnt lgkmcnt(7)
	v_mfma_f32_16x16x32_bf16 v[126:129], v[186:189], v[156:159], v[126:129]
	v_mfma_f32_16x16x32_bf16 v[122:125], v[186:189], v[170:173], v[122:125]
	s_waitcnt lgkmcnt(5)
	v_mfma_f32_16x16x32_bf16 v[118:121], v[194:197], v[156:159], v[118:121]
	v_mfma_f32_16x16x32_bf16 v[114:117], v[194:197], v[170:173], v[114:117]
	s_waitcnt lgkmcnt(3)
	v_mfma_f32_16x16x32_bf16 v[110:113], v[202:205], v[156:159], v[110:113]
	v_mfma_f32_16x16x32_bf16 v[106:109], v[202:205], v[170:173], v[106:109]
	s_waitcnt lgkmcnt(1)
	v_mfma_f32_16x16x32_bf16 v[102:105], v[210:213], v[156:159], v[102:105]
	v_mfma_f32_16x16x32_bf16 v[98:101], v[210:213], v[170:173], v[98:101]
	v_mfma_f32_16x16x32_bf16 v[126:129], v[190:193], v[166:169], v[126:129]
	v_mfma_f32_16x16x32_bf16 v[122:125], v[190:193], v[174:177], v[122:125]
	v_mfma_f32_16x16x32_bf16 v[118:121], v[198:201], v[166:169], v[118:121]
	v_mfma_f32_16x16x32_bf16 v[114:117], v[198:201], v[174:177], v[114:117]
	v_mfma_f32_16x16x32_bf16 v[110:113], v[206:209], v[166:169], v[110:113]
	v_mfma_f32_16x16x32_bf16 v[106:109], v[206:209], v[174:177], v[106:109]
	s_waitcnt lgkmcnt(0)
	v_mfma_f32_16x16x32_bf16 v[102:105], v[214:217], v[166:169], v[102:105]
	v_mfma_f32_16x16x32_bf16 v[98:101], v[214:217], v[174:177], v[98:101]
	s_setprio 1
	s_barrier
	s_add_i32 s24, s22, s15
	v_readfirstlane_b32 s26, v137
	s_add_i32 s25, s24, 0x100
	s_mov_b32 m0, s26
	v_readfirstlane_b32 s26, v139
	ds_read_b128 v[218:221], v149
	ds_read_b128 v[222:225], v149 offset:1024
	ds_read_b128 v[226:229], v149 offset:2048
	ds_read_b128 v[230:233], v149 offset:3072
	buffer_load_dwordx4 v32, s[76:79], s25 offen lds
	s_mov_b32 m0, s26
	s_nop 0
	buffer_load_dwordx4 v131, s[76:79], s25 offen lds
	s_barrier
; #define STAGE(P, BASE, br, kt) do { int _so = ((br) * K + (kt) * BK) * 2; \
;     __builtin_amdgcn_raw_ptr_buffer_load_lds(rs_##BASE, (__attribute__((address_space(3))) void*)((char*)(P) + tx * 16), 16, voff0, _so, 0, 0); \
;     __builtin_amdgcn_raw_ptr_buffer_load_lds(rs_##BASE, (__attribute__((address_space(3))) void*)((char*)(P) + tx * 16 + 8192), 16, voff1, _so, 0, 0); } while (0)
; #define LDA(dst, b, h) _Pragma("unroll") for (int m = 0; m < 4; ++m) _Pragma("unroll") for (int k = 0; k < 2; ++k) \
;     dst[m][k] = *reinterpret_cast<const bf16x8*>((char*)SA(b, h) + lds_byte(wr * 64 + m * 16 + fr, k * 32 + fq * 8))
; #define LDB(dst, b, h) _Pragma("unroll") for (int n = 0; n < 2; ++n) _Pragma("unroll") for (int k = 0; k < 2; ++k) \
;     dst[n][k] = *reinterpret_cast<const bf16x8*>((char*)SB(b, h) + lds_byte(wc * 32 + n * 16 + fr, k * 32 + fq * 8))
; #define MMA(ai, bj, At, Bt_) do { __builtin_amdgcn_s_setprio(1); \
;     _Pragma("unroll") for (int m = 0; m < 4; ++m) _Pragma("unroll") for (int n = 0; n < 2; ++n) _Pragma("unroll") for (int k = 0; k < 2; ++k) \
;       acc[ai][bj][m][n] = __builtin_amdgcn_mfma_f32_16x16x32_bf16(At[m][k], Bt_[n][k], acc[ai][bj][m][n], 0, 0, 0); \
;     __builtin_amdgcn_s_setprio(0); } while (0)
; #define WAIT_V(n) asm volatile("s_waitcnt vmcnt(" #n ")" ::: "memory")
; #define WAIT_L(n) asm volatile("s_waitcnt lgkmcnt(" #n ")" ::: "memory")
; #define BAR __builtin_amdgcn_s_barrier()
; #define SCHED __builtin_amdgcn_sched_barrier(0)
; template <class Epi> ...
;     ...
;     BAR; WAIT_L(0); MMA(0, 1, At, B1); BAR;
;     LDA(At, 0, 1); STAGE(SA(0, 0), A, brow, t + 2);
;     BAR; WAIT_L(0); MMA(1, 0, At, B0); BAR; SCHED;
;     STAGE(SB(0, 1), Bt, bcol + HALF, t + 2);
;     WAIT_V(6); BAR; MMA(1, 1, At, B1); BAR;
;     LDB(B0, 1, 0); SCHED; LDA(At, 1, 0); STAGE(SA(0, 1), A, brow + HALF, t + 2);
;     WAIT_L(8); BAR; WAIT_L(0); MMA(0, 0, At, B0); BAR; SCHED;
;     LDB(B1, 1, 1); STAGE(SB(1, 0), Bt, bcol, t + 3);
	s_waitcnt lgkmcnt(0)
	s_setprio 0
	s_waitcnt lgkmcnt(3)
	v_mfma_f32_16x16x32_bf16 v[94:97], v[186:189], v[218:221], v[94:97]
	s_waitcnt lgkmcnt(1)
	v_mfma_f32_16x16x32_bf16 v[90:93], v[186:189], v[226:229], v[90:93]
	v_mfma_f32_16x16x32_bf16 v[86:89], v[194:197], v[218:221], v[86:89]
	v_mfma_f32_16x16x32_bf16 v[82:85], v[194:197], v[226:229], v[82:85]
	v_mfma_f32_16x16x32_bf16 v[78:81], v[202:205], v[218:221], v[78:81]
	v_mfma_f32_16x16x32_bf16 v[74:77], v[202:205], v[226:229], v[74:77]
	v_mfma_f32_16x16x32_bf16 v[70:73], v[210:213], v[218:221], v[70:73]
	v_mfma_f32_16x16x32_bf16 v[66:69], v[210:213], v[226:229], v[66:69]
	v_mfma_f32_16x16x32_bf16 v[94:97], v[190:193], v[222:225], v[94:97]
	s_waitcnt lgkmcnt(0)
	v_mfma_f32_16x16x32_bf16 v[90:93], v[190:193], v[230:233], v[90:93]
	v_mfma_f32_16x16x32_bf16 v[86:89], v[198:201], v[222:225], v[86:89]
	v_mfma_f32_16x16x32_bf16 v[82:85], v[198:201], v[230:233], v[82:85]
	v_mfma_f32_16x16x32_bf16 v[78:81], v[206:209], v[222:225], v[78:81]
	v_mfma_f32_16x16x32_bf16 v[74:77], v[206:209], v[230:233], v[74:77]
	v_mfma_f32_16x16x32_bf16 v[70:73], v[214:217], v[222:225], v[70:73]
	v_mfma_f32_16x16x32_bf16 v[66:69], v[214:217], v[230:233], v[66:69]
	s_setprio 1
	v_readfirstlane_b32 s26, v136
	s_add_i32 s25, s23, 0x100
	s_mov_b32 m0, s26
	v_readfirstlane_b32 s26, v135
	s_barrier
	ds_read_b128 v[186:189], v143 offset:16384
	ds_read_b128 v[190:193], v143 offset:17408
	ds_read_b128 v[194:197], v142 offset:16384
	ds_read_b128 v[198:201], v142 offset:17408
	ds_read_b128 v[202:205], v141 offset:16384
	ds_read_b128 v[206:209], v141 offset:17408
	ds_read_b128 v[210:213], v140 offset:16384
	ds_read_b128 v[214:217], v140 offset:17408
	buffer_load_dwordx4 v32, s[4:7], s25 offen lds
	s_mov_b32 m0, s26
	s_nop 0
	buffer_load_dwordx4 v131, s[4:7], s25 offen lds
	s_barrier
	s_waitcnt lgkmcnt(0)
	s_setprio 0
	s_waitcnt lgkmcnt(7)
	v_mfma_f32_16x16x32_bf16 v[62:65], v[186:189], v[156:159], v[62:65]
	v_mfma_f32_16x16x32_bf16 v[58:61], v[186:189], v[170:173], v[58:61]
	s_waitcnt lgkmcnt(5)
	v_mfma_f32_16x16x32_bf16 v[54:57], v[194:197], v[156:159], v[54:57]
	v_mfma_f32_16x16x32_bf16 v[50:53], v[194:197], v[170:173], v[50:53]
	s_waitcnt lgkmcnt(3)
	v_mfma_f32_16x16x32_bf16 v[46:49], v[202:205], v[156:159], v[46:49]
	v_mfma_f32_16x16x32_bf16 v[42:45], v[202:205], v[170:173], v[42:45]
	s_waitcnt lgkmcnt(1)
	v_mfma_f32_16x16x32_bf16 v[38:41], v[210:213], v[156:159], v[38:41]
	v_mfma_f32_16x16x32_bf16 v[34:37], v[210:213], v[170:173], v[34:37]
	v_mfma_f32_16x16x32_bf16 v[62:65], v[190:193], v[166:169], v[62:65]
	v_mfma_f32_16x16x32_bf16 v[58:61], v[190:193], v[174:177], v[58:61]
	v_mfma_f32_16x16x32_bf16 v[54:57], v[198:201], v[166:169], v[54:57]
	v_mfma_f32_16x16x32_bf16 v[50:53], v[198:201], v[174:177], v[50:53]
	v_mfma_f32_16x16x32_bf16 v[46:49], v[206:209], v[166:169], v[46:49]
	v_mfma_f32_16x16x32_bf16 v[42:45], v[206:209], v[174:177], v[42:45]
	s_waitcnt lgkmcnt(0)
	v_mfma_f32_16x16x32_bf16 v[38:41], v[214:217], v[166:169], v[38:41]
	v_mfma_f32_16x16x32_bf16 v[34:37], v[214:217], v[174:177], v[34:37]
	s_setprio 1
	s_barrier
	v_readfirstlane_b32 s26, v134
	s_add_i32 s25, s24, 0xb0100
	s_mov_b32 m0, s26
	v_readfirstlane_b32 s26, v138
	buffer_load_dwordx4 v32, s[76:79], s25 offen lds
	s_mov_b32 m0, s26
	s_nop 0
	buffer_load_dwordx4 v131, s[76:79], s25 offen lds
	s_waitcnt vmcnt(6)
	s_barrier
	s_setprio 0
	v_mfma_f32_16x16x32_bf16 v[28:31], v[186:189], v[218:221], v[28:31]
	v_mfma_f32_16x16x32_bf16 v[24:27], v[186:189], v[226:229], v[24:27]
	v_mfma_f32_16x16x32_bf16 v[20:23], v[194:197], v[218:221], v[20:23]
	v_mfma_f32_16x16x32_bf16 v[16:19], v[194:197], v[226:229], v[16:19]
	v_mfma_f32_16x16x32_bf16 v[12:15], v[202:205], v[218:221], v[12:15]
	v_mfma_f32_16x16x32_bf16 v[8:11], v[202:205], v[226:229], v[8:11]
	v_mfma_f32_16x16x32_bf16 v[4:7], v[210:213], v[218:221], v[4:7]
	v_mfma_f32_16x16x32_bf16 v[0:3], v[210:213], v[226:229], v[0:3]
	v_mfma_f32_16x16x32_bf16 v[28:31], v[190:193], v[222:225], v[28:31]
	v_mfma_f32_16x16x32_bf16 v[24:27], v[190:193], v[230:233], v[24:27]
	v_mfma_f32_16x16x32_bf16 v[20:23], v[198:201], v[222:225], v[20:23]
	v_mfma_f32_16x16x32_bf16 v[16:19], v[198:201], v[230:233], v[16:19]
	v_mfma_f32_16x16x32_bf16 v[12:15], v[206:209], v[222:225], v[12:15]
	v_mfma_f32_16x16x32_bf16 v[8:11], v[206:209], v[230:233], v[8:11]
	v_mfma_f32_16x16x32_bf16 v[4:7], v[214:217], v[222:225], v[4:7]
	v_mfma_f32_16x16x32_bf16 v[0:3], v[214:217], v[230:233], v[0:3]
	s_setprio 1
	s_barrier
	ds_read_b128 v[156:159], v145
	ds_read_b128 v[166:169], v145 offset:1024
	ds_read_b128 v[170:173], v145 offset:2048
	ds_read_b128 v[174:177], v145 offset:3072
	v_readfirstlane_b32 s26, v133
	s_add_i32 s25, s23, 0xb0100
	s_mov_b32 m0, s26
	v_readfirstlane_b32 s26, v132
	ds_read_b128 v[186:189], v143 offset:32768
	ds_read_b128 v[190:193], v143 offset:33792
	ds_read_b128 v[194:197], v142 offset:32768
	ds_read_b128 v[198:201], v142 offset:33792
	ds_read_b128 v[202:205], v141 offset:32768
	ds_read_b128 v[206:209], v141 offset:33792
	ds_read_b128 v[210:213], v140 offset:32768
	ds_read_b128 v[214:217], v140 offset:33792
	buffer_load_dwordx4 v32, s[4:7], s25 offen lds
	s_mov_b32 m0, s26
	s_nop 0
	buffer_load_dwordx4 v131, s[4:7], s25 offen lds
	s_waitcnt lgkmcnt(8)
	s_barrier
; #define STAGE(P, BASE, br, kt) do { int _so = ((br) * K + (kt) * BK) * 2; \
;     __builtin_amdgcn_raw_ptr_buffer_load_lds(rs_##BASE, (__attribute__((address_space(3))) void*)((char*)(P) + tx * 16), 16, voff0, _so, 0, 0); \
;     __builtin_amdgcn_raw_ptr_buffer_load_lds(rs_##BASE, (__attribute__((address_space(3))) void*)((char*)(P) + tx * 16 + 8192), 16, voff1, _so, 0, 0); } while (0)
; #define LDA(dst, b, h) _Pragma("unroll") for (int m = 0; m < 4; ++m) _Pragma("unroll") for (int k = 0; k < 2; ++k) \
;     dst[m][k] = *reinterpret_cast<const bf16x8*>((char*)SA(b, h) + lds_byte(wr * 64 + m * 16 + fr, k * 32 + fq * 8))
; #define LDB(dst, b, h) _Pragma("unroll") for (int n = 0; n < 2; ++n) _Pragma("unroll") for (int k = 0; k < 2; ++k) \
;     dst[n][k] = *reinterpret_cast<const bf16x8*>((char*)SB(b, h) + lds_byte(wc * 32 + n * 16 + fr, k * 32 + fq * 8))
; #define MMA(ai, bj, At, Bt_) do { __builtin_amdgcn_s_setprio(1); \
;     _Pragma("unroll") for (int m = 0; m < 4; ++m) _Pragma("unroll") for (int n = 0; n < 2; ++n) _Pragma("unroll") for (int k = 0; k < 2; ++k) \
;       acc[ai][bj][m][n] = __builtin_amdgcn_mfma_f32_16x16x32_bf16(At[m][k], Bt_[n][k], acc[ai][bj][m][n], 0, 0, 0); \
;     __builtin_amdgcn_s_setprio(0); } while (0)
; #define WAIT_V(n) asm volatile("s_waitcnt vmcnt(" #n ")" ::: "memory")
; #define WAIT_L(n) asm volatile("s_waitcnt lgkmcnt(" #n ")" ::: "memory")
; #define BAR __builtin_amdgcn_s_barrier()
; #define SCHED __builtin_amdgcn_sched_barrier(0)
; template <class Epi> ...
;     ...
;     WAIT_L(8); BAR; WAIT_L(0); MMA(0, 0, At, B0); BAR; SCHED;
;     LDB(B1, 1, 1); STAGE(SB(1, 0), Bt, bcol, t + 3);
;     BAR; WAIT_L(0); MMA(0, 1, At, B1); BAR;
;     LDA(At, 1, 1); STAGE(SA(1, 0), A, brow, t + 3);
;     BAR; WAIT_L(0); MMA(1, 0, At, B0); BAR; SCHED;
;     STAGE(SB(1, 1), Bt, bcol + HALF, t + 3);
;     WAIT_V(6); BAR; MMA(1, 1, At, B1); BAR;
	s_waitcnt lgkmcnt(0)
	s_setprio 0
	s_waitcnt lgkmcnt(7)
	v_mfma_f32_16x16x32_bf16 v[126:129], v[186:189], v[156:159], v[126:129]
	v_mfma_f32_16x16x32_bf16 v[122:125], v[186:189], v[170:173], v[122:125]
	s_waitcnt lgkmcnt(5)
	v_mfma_f32_16x16x32_bf16 v[118:121], v[194:197], v[156:159], v[118:121]
	v_mfma_f32_16x16x32_bf16 v[114:117], v[194:197], v[170:173], v[114:117]
	s_waitcnt lgkmcnt(3)
	v_mfma_f32_16x16x32_bf16 v[110:113], v[202:205], v[156:159], v[110:113]
	v_mfma_f32_16x16x32_bf16 v[106:109], v[202:205], v[170:173], v[106:109]
	s_waitcnt lgkmcnt(1)
	v_mfma_f32_16x16x32_bf16 v[102:105], v[210:213], v[156:159], v[102:105]
	v_mfma_f32_16x16x32_bf16 v[98:101], v[210:213], v[170:173], v[98:101]
	v_mfma_f32_16x16x32_bf16 v[126:129], v[190:193], v[166:169], v[126:129]
	v_mfma_f32_16x16x32_bf16 v[122:125], v[190:193], v[174:177], v[122:125]
	v_mfma_f32_16x16x32_bf16 v[118:121], v[198:201], v[166:169], v[118:121]
	v_mfma_f32_16x16x32_bf16 v[114:117], v[198:201], v[174:177], v[114:117]
	v_mfma_f32_16x16x32_bf16 v[110:113], v[206:209], v[166:169], v[110:113]
	v_mfma_f32_16x16x32_bf16 v[106:109], v[206:209], v[174:177], v[106:109]
	s_waitcnt lgkmcnt(0)
	v_mfma_f32_16x16x32_bf16 v[102:105], v[214:217], v[166:169], v[102:105]
	v_mfma_f32_16x16x32_bf16 v[98:101], v[214:217], v[174:177], v[98:101]
	s_setprio 1
	s_barrier
	v_readfirstlane_b32 s26, v146
	s_add_i32 s25, s24, 0x180
	s_mov_b32 m0, s26
	v_readfirstlane_b32 s26, v147
	ds_read_b128 v[218:221], v144
	ds_read_b128 v[222:225], v144 offset:1024
	ds_read_b128 v[226:229], v144 offset:2048
	ds_read_b128 v[230:233], v144 offset:3072
	buffer_load_dwordx4 v32, s[76:79], s25 offen lds
	s_mov_b32 m0, s26
	s_nop 0
	buffer_load_dwordx4 v131, s[76:79], s25 offen lds
	s_barrier
	s_waitcnt lgkmcnt(0)
	s_setprio 0
	s_waitcnt lgkmcnt(3)
	v_mfma_f32_16x16x32_bf16 v[94:97], v[186:189], v[218:221], v[94:97]
	s_waitcnt lgkmcnt(1)
	v_mfma_f32_16x16x32_bf16 v[90:93], v[186:189], v[226:229], v[90:93]
	v_mfma_f32_16x16x32_bf16 v[86:89], v[194:197], v[218:221], v[86:89]
	v_mfma_f32_16x16x32_bf16 v[82:85], v[194:197], v[226:229], v[82:85]
	v_mfma_f32_16x16x32_bf16 v[78:81], v[202:205], v[218:221], v[78:81]
	v_mfma_f32_16x16x32_bf16 v[74:77], v[202:205], v[226:229], v[74:77]
	v_mfma_f32_16x16x32_bf16 v[70:73], v[210:213], v[218:221], v[70:73]
	v_mfma_f32_16x16x32_bf16 v[66:69], v[210:213], v[226:229], v[66:69]
	v_mfma_f32_16x16x32_bf16 v[94:97], v[190:193], v[222:225], v[94:97]
	s_waitcnt lgkmcnt(0)
	v_mfma_f32_16x16x32_bf16 v[90:93], v[190:193], v[230:233], v[90:93]
	v_mfma_f32_16x16x32_bf16 v[86:89], v[198:201], v[222:225], v[86:89]
	v_mfma_f32_16x16x32_bf16 v[82:85], v[198:201], v[230:233], v[82:85]
	v_mfma_f32_16x16x32_bf16 v[78:81], v[206:209], v[222:225], v[78:81]
	v_mfma_f32_16x16x32_bf16 v[74:77], v[206:209], v[230:233], v[74:77]
	v_mfma_f32_16x16x32_bf16 v[70:73], v[214:217], v[222:225], v[70:73]
	v_mfma_f32_16x16x32_bf16 v[66:69], v[214:217], v[230:233], v[66:69]
	s_setprio 1
	v_readfirstlane_b32 s25, v148
	s_addk_i32 s23, 0x180
	s_mov_b32 m0, s25
	v_readfirstlane_b32 s25, v150
	s_barrier
	ds_read_b128 v[186:189], v143 offset:49152
	ds_read_b128 v[190:193], v143 offset:50176
	ds_read_b128 v[194:197], v142 offset:49152
	ds_read_b128 v[198:201], v142 offset:50176
	ds_read_b128 v[202:205], v141 offset:49152
	ds_read_b128 v[206:209], v141 offset:50176
	ds_read_b128 v[210:213], v140 offset:49152
	ds_read_b128 v[214:217], v140 offset:50176
	buffer_load_dwordx4 v32, s[4:7], s23 offen lds
	s_mov_b32 m0, s25
	s_nop 0
	buffer_load_dwordx4 v131, s[4:7], s23 offen lds
	s_barrier
	s_waitcnt lgkmcnt(0)
	s_setprio 0
	s_waitcnt lgkmcnt(7)
	v_mfma_f32_16x16x32_bf16 v[62:65], v[186:189], v[156:159], v[62:65]
	v_mfma_f32_16x16x32_bf16 v[58:61], v[186:189], v[170:173], v[58:61]
	s_waitcnt lgkmcnt(5)
	v_mfma_f32_16x16x32_bf16 v[54:57], v[194:197], v[156:159], v[54:57]
	v_mfma_f32_16x16x32_bf16 v[50:53], v[194:197], v[170:173], v[50:53]
	s_waitcnt lgkmcnt(3)
	v_mfma_f32_16x16x32_bf16 v[46:49], v[202:205], v[156:159], v[46:49]
	v_mfma_f32_16x16x32_bf16 v[42:45], v[202:205], v[170:173], v[42:45]
	s_waitcnt lgkmcnt(1)
	v_mfma_f32_16x16x32_bf16 v[38:41], v[210:213], v[156:159], v[38:41]
	v_mfma_f32_16x16x32_bf16 v[34:37], v[210:213], v[170:173], v[34:37]
	v_mfma_f32_16x16x32_bf16 v[62:65], v[190:193], v[166:169], v[62:65]
	v_mfma_f32_16x16x32_bf16 v[58:61], v[190:193], v[174:177], v[58:61]
	v_mfma_f32_16x16x32_bf16 v[54:57], v[198:201], v[166:169], v[54:57]
	v_mfma_f32_16x16x32_bf16 v[50:53], v[198:201], v[174:177], v[50:53]
	v_mfma_f32_16x16x32_bf16 v[46:49], v[206:209], v[166:169], v[46:49]
	v_mfma_f32_16x16x32_bf16 v[42:45], v[206:209], v[174:177], v[42:45]
	s_waitcnt lgkmcnt(0)
	v_mfma_f32_16x16x32_bf16 v[38:41], v[214:217], v[166:169], v[38:41]
	v_mfma_f32_16x16x32_bf16 v[34:37], v[214:217], v[174:177], v[34:37]
	s_setprio 1
	s_barrier
	v_readfirstlane_b32 s23, v153
	s_add_i32 s24, s24, 0xb0180
	s_mov_b32 m0, s23
	v_readfirstlane_b32 s23, v154
	buffer_load_dwordx4 v32, s[76:79], s24 offen lds
	s_mov_b32 m0, s23
	s_nop 0
	buffer_load_dwordx4 v131, s[76:79], s24 offen lds
	s_waitcnt vmcnt(6)
	s_barrier
	s_setprio 0
	v_mfma_f32_16x16x32_bf16 v[28:31], v[186:189], v[218:221], v[28:31]
	v_mfma_f32_16x16x32_bf16 v[24:27], v[186:189], v[226:229], v[24:27]
	v_mfma_f32_16x16x32_bf16 v[20:23], v[194:197], v[218:221], v[20:23]
	v_mfma_f32_16x16x32_bf16 v[16:19], v[194:197], v[226:229], v[16:19]
	v_mfma_f32_16x16x32_bf16 v[12:15], v[202:205], v[218:221], v[12:15]
	v_mfma_f32_16x16x32_bf16 v[8:11], v[202:205], v[226:229], v[8:11]
	v_mfma_f32_16x16x32_bf16 v[4:7], v[210:213], v[218:221], v[4:7]
	v_mfma_f32_16x16x32_bf16 v[0:3], v[210:213], v[226:229], v[0:3]
	v_mfma_f32_16x16x32_bf16 v[28:31], v[190:193], v[222:225], v[28:31]
	v_mfma_f32_16x16x32_bf16 v[24:27], v[190:193], v[230:233], v[24:27]
	v_mfma_f32_16x16x32_bf16 v[20:23], v[198:201], v[222:225], v[20:23]
	v_mfma_f32_16x16x32_bf16 v[16:19], v[198:201], v[230:233], v[16:19]
	v_mfma_f32_16x16x32_bf16 v[12:15], v[206:209], v[222:225], v[12:15]
	v_mfma_f32_16x16x32_bf16 v[8:11], v[206:209], v[230:233], v[8:11]
	v_mfma_f32_16x16x32_bf16 v[4:7], v[214:217], v[222:225], v[4:7]
	v_mfma_f32_16x16x32_bf16 v[0:3], v[214:217], v[230:233], v[0:3]
	s_setprio 1
	s_add_i32 s14, s14, 2
	s_addk_i32 s15, 0x100
	s_cmp_lt_u32 s14, 40
	s_barrier
	s_cbranch_scc1 .LBB0_2336
; #define STAGE(P, BASE, br, kt) do { int _so = ((br) * K + (kt) * BK) * 2; \
;     __builtin_amdgcn_raw_ptr_buffer_load_lds(rs_##BASE, (__attribute__((address_space(3))) void*)((char*)(P) + tx * 16), 16, voff0, _so, 0, 0); \
;     __builtin_amdgcn_raw_ptr_buffer_load_lds(rs_##BASE, (__attribute__((address_space(3))) void*)((char*)(P) + tx * 16 + 8192), 16, voff1, _so, 0, 0); } while (0)
; #define LDA(dst, b, h) _Pragma("unroll") for (int m = 0; m < 4; ++m) _Pragma("unroll") for (int k = 0; k < 2; ++k) \
;     dst[m][k] = *reinterpret_cast<const bf16x8*>((char*)SA(b, h) + lds_byte(wr * 64 + m * 16 + fr, k * 32 + fq * 8))
; #define LDB(dst, b, h) _Pragma("unroll") for (int n = 0; n < 2; ++n) _Pragma("unroll") for (int k = 0; k < 2; ++k) \
;     dst[n][k] = *reinterpret_cast<const bf16x8*>((char*)SB(b, h) + lds_byte(wc * 32 + n * 16 + fr, k * 32 + fq * 8))
; #define MMA(ai, bj, At, Bt_) do { __builtin_amdgcn_s_setprio(1); \
;     _Pragma("unroll") for (int m = 0; m < 4; ++m) _Pragma("unroll") for (int n = 0; n < 2; ++n) _Pragma("unroll") for (int k = 0; k < 2; ++k) \
;       acc[ai][bj][m][n] = __builtin_amdgcn_mfma_f32_16x16x32_bf16(At[m][k], Bt_[n][k], acc[ai][bj][m][n], 0, 0, 0); \
;     __builtin_amdgcn_s_setprio(0); } while (0)
; #define WAIT_V(n) asm volatile("s_waitcnt vmcnt(" #n ")" ::: "memory")
; #define WAIT_L(n) asm volatile("s_waitcnt lgkmcnt(" #n ")" ::: "memory")
; #define BAR __builtin_amdgcn_s_barrier()
; template <class Epi> ...
;     ...
;   { LDB(B0, 0, 0); LDA(At, 0, 0); STAGE(SA(1, 1), A, brow + HALF, nt - 1);
;     BAR; WAIT_L(0); MMA(0, 0, At, B0); BAR;
;     LDB(B1, 0, 1); BAR; WAIT_L(0); MMA(0, 1, At, B1); BAR;
;     LDA(At, 0, 1); WAIT_V(4); BAR; WAIT_L(0); MMA(1, 0, At, B0); MMA(1, 1, At, B1); BAR; }
.Lpx8:
	v_readfirstlane_b32 s14, v152
	s_add_i32 s21, s21, 0xb1580
	s_mov_b32 s6, s78
	s_mov_b32 s7, s79
	s_mov_b32 m0, s14
	v_readfirstlane_b32 s14, v151
	ds_read_b128 v[156:159], v155
	ds_read_b128 v[166:169], v155 offset:1024
	ds_read_b128 v[170:173], v155 offset:2048
	ds_read_b128 v[174:177], v155 offset:3072
	ds_read_b128 v[186:189], v143
	ds_read_b128 v[190:193], v143 offset:1024
	ds_read_b128 v[194:197], v142
	ds_read_b128 v[198:201], v142 offset:1024
	ds_read_b128 v[202:205], v141
	ds_read_b128 v[206:209], v141 offset:1024
	ds_read_b128 v[210:213], v140
	ds_read_b128 v[214:217], v140 offset:1024
	buffer_load_dwordx4 v32, s[4:7], s21 offen lds
	s_mov_b32 m0, s14
	s_nop 0
	buffer_load_dwordx4 v131, s[4:7], s21 offen lds
	s_barrier
	s_waitcnt lgkmcnt(0)
	s_setprio 0
	s_waitcnt lgkmcnt(7)
	v_mfma_f32_16x16x32_bf16 v[126:129], v[186:189], v[156:159], v[126:129]
	v_mfma_f32_16x16x32_bf16 v[122:125], v[186:189], v[170:173], v[122:125]
	s_waitcnt lgkmcnt(5)
	v_mfma_f32_16x16x32_bf16 v[118:121], v[194:197], v[156:159], v[118:121]
	v_mfma_f32_16x16x32_bf16 v[114:117], v[194:197], v[170:173], v[114:117]
	s_waitcnt lgkmcnt(3)
	v_mfma_f32_16x16x32_bf16 v[110:113], v[202:205], v[156:159], v[110:113]
	v_mfma_f32_16x16x32_bf16 v[106:109], v[202:205], v[170:173], v[106:109]
	s_waitcnt lgkmcnt(1)
	v_mfma_f32_16x16x32_bf16 v[102:105], v[210:213], v[156:159], v[102:105]
	v_mfma_f32_16x16x32_bf16 v[98:101], v[210:213], v[170:173], v[98:101]
	v_mfma_f32_16x16x32_bf16 v[126:129], v[190:193], v[166:169], v[126:129]
	v_mfma_f32_16x16x32_bf16 v[122:125], v[190:193], v[174:177], v[122:125]
	v_mfma_f32_16x16x32_bf16 v[118:121], v[198:201], v[166:169], v[118:121]
	v_mfma_f32_16x16x32_bf16 v[114:117], v[198:201], v[174:177], v[114:117]
	v_mfma_f32_16x16x32_bf16 v[110:113], v[206:209], v[166:169], v[110:113]
	v_mfma_f32_16x16x32_bf16 v[106:109], v[206:209], v[174:177], v[106:109]
	s_waitcnt lgkmcnt(0)
	v_mfma_f32_16x16x32_bf16 v[102:105], v[214:217], v[166:169], v[102:105]
	v_mfma_f32_16x16x32_bf16 v[98:101], v[214:217], v[174:177], v[98:101]
	s_setprio 1
	s_barrier
	ds_read_b128 v[150:153], v149
	ds_read_b128 v[218:221], v149 offset:1024
	ds_read_b128 v[222:225], v149 offset:2048
	ds_read_b128 v[146:149], v149 offset:3072
	s_barrier
	s_waitcnt lgkmcnt(0)
	s_setprio 0
	s_waitcnt lgkmcnt(3)
	v_mfma_f32_16x16x32_bf16 v[78:81], v[202:205], v[150:153], v[78:81]
	s_waitcnt lgkmcnt(1)
	v_mfma_f32_16x16x32_bf16 v[74:77], v[202:205], v[222:225], v[74:77]
	v_mfma_f32_16x16x32_bf16 v[70:73], v[210:213], v[150:153], v[70:73]
	v_mfma_f32_16x16x32_bf16 v[66:69], v[210:213], v[222:225], v[66:69]
	v_mfma_f32_16x16x32_bf16 v[94:97], v[186:189], v[150:153], v[94:97]
	v_mfma_f32_16x16x32_bf16 v[90:93], v[186:189], v[222:225], v[90:93]
	v_mfma_f32_16x16x32_bf16 v[86:89], v[194:197], v[150:153], v[86:89]
	v_mfma_f32_16x16x32_bf16 v[82:85], v[194:197], v[222:225], v[82:85]
	v_mfma_f32_16x16x32_bf16 v[78:81], v[206:209], v[218:221], v[78:81]
	s_waitcnt lgkmcnt(0)
	v_mfma_f32_16x16x32_bf16 v[74:77], v[206:209], v[146:149], v[74:77]
	v_mfma_f32_16x16x32_bf16 v[70:73], v[214:217], v[218:221], v[70:73]
	v_mfma_f32_16x16x32_bf16 v[66:69], v[214:217], v[146:149], v[66:69]
	v_mfma_f32_16x16x32_bf16 v[226:229], v[190:193], v[218:221], v[94:97]
	v_mfma_f32_16x16x32_bf16 v[186:189], v[190:193], v[146:149], v[90:93]
	v_mfma_f32_16x16x32_bf16 v[190:193], v[198:201], v[218:221], v[86:89]
	v_mfma_f32_16x16x32_bf16 v[194:197], v[198:201], v[146:149], v[82:85]
	s_setprio 1
	s_barrier
	s_nop 0
	ds_read_b128 v[82:85], v143 offset:16384
	ds_read_b128 v[86:89], v143 offset:17408
	ds_read_b128 v[90:93], v142 offset:16384
	ds_read_b128 v[94:97], v142 offset:17408
	ds_read_b128 v[198:201], v141 offset:16384
	ds_read_b128 v[202:205], v141 offset:17408
	ds_read_b128 v[206:209], v140 offset:16384
	ds_read_b128 v[210:213], v140 offset:17408
	s_waitcnt vmcnt(4)
	s_barrier
	s_waitcnt lgkmcnt(0)
	s_setprio 0
	s_waitcnt lgkmcnt(3)
	v_mfma_f32_16x16x32_bf16 v[46:49], v[198:201], v[156:159], v[46:49]
	v_mfma_f32_16x16x32_bf16 v[42:45], v[198:201], v[170:173], v[42:45]
	s_waitcnt lgkmcnt(1)
	v_mfma_f32_16x16x32_bf16 v[38:41], v[206:209], v[156:159], v[38:41]
	v_mfma_f32_16x16x32_bf16 v[34:37], v[206:209], v[170:173], v[34:37]
	v_mfma_f32_16x16x32_bf16 v[62:65], v[82:85], v[156:159], v[62:65]
	v_mfma_f32_16x16x32_bf16 v[58:61], v[82:85], v[170:173], v[58:61]
	v_mfma_f32_16x16x32_bf16 v[54:57], v[90:93], v[156:159], v[54:57]
	v_mfma_f32_16x16x32_bf16 v[50:53], v[90:93], v[170:173], v[50:53]
	v_mfma_f32_16x16x32_bf16 v[46:49], v[202:205], v[166:169], v[46:49]
	v_mfma_f32_16x16x32_bf16 v[42:45], v[202:205], v[174:177], v[42:45]
	s_waitcnt lgkmcnt(0)
	v_mfma_f32_16x16x32_bf16 v[38:41], v[210:213], v[166:169], v[38:41]
	v_mfma_f32_16x16x32_bf16 v[34:37], v[210:213], v[174:177], v[34:37]
	v_mfma_f32_16x16x32_bf16 v[214:217], v[86:89], v[166:169], v[62:65]
	v_mfma_f32_16x16x32_bf16 v[230:233], v[86:89], v[174:177], v[58:61]
	v_mfma_f32_16x16x32_bf16 v[234:237], v[94:97], v[166:169], v[54:57]
	v_mfma_f32_16x16x32_bf16 v[238:241], v[94:97], v[174:177], v[50:53]
	s_setprio 1
	s_setprio 0
	v_mfma_f32_16x16x32_bf16 v[0:3], v[206:209], v[222:225], v[0:3]
	v_mfma_f32_16x16x32_bf16 v[28:31], v[82:85], v[150:153], v[28:31]
	v_mfma_f32_16x16x32_bf16 v[24:27], v[82:85], v[222:225], v[24:27]
	v_mfma_f32_16x16x32_bf16 v[20:23], v[90:93], v[150:153], v[20:23]
	v_mfma_f32_16x16x32_bf16 v[16:19], v[90:93], v[222:225], v[16:19]
	v_mfma_f32_16x16x32_bf16 v[12:15], v[198:201], v[150:153], v[12:15]
	v_mfma_f32_16x16x32_bf16 v[8:11], v[198:201], v[222:225], v[8:11]
	v_mfma_f32_16x16x32_bf16 v[4:7], v[206:209], v[150:153], v[4:7]
	v_mfma_f32_16x16x32_bf16 v[0:3], v[210:213], v[146:149], v[0:3]
	v_mfma_f32_16x16x32_bf16 v[154:157], v[86:89], v[218:221], v[28:31]
	v_mfma_f32_16x16x32_bf16 v[158:161], v[86:89], v[146:149], v[24:27]
	v_mfma_f32_16x16x32_bf16 v[166:169], v[94:97], v[218:221], v[20:23]
	v_mfma_f32_16x16x32_bf16 v[170:173], v[94:97], v[146:149], v[16:19]
	v_mfma_f32_16x16x32_bf16 v[174:177], v[202:205], v[218:221], v[12:15]
	v_mfma_f32_16x16x32_bf16 v[198:201], v[202:205], v[146:149], v[8:11]
	v_mfma_f32_16x16x32_bf16 v[150:153], v[210:213], v[218:221], v[4:7]
	s_setprio 1
	s_barrier
; #define LDA(dst, b, h) _Pragma("unroll") for (int m = 0; m < 4; ++m) _Pragma("unroll") for (int k = 0; k < 2; ++k) \
;     dst[m][k] = *reinterpret_cast<const bf16x8*>((char*)SA(b, h) + lds_byte(wr * 64 + m * 16 + fr, k * 32 + fq * 8))
; #define LDB(dst, b, h) _Pragma("unroll") for (int n = 0; n < 2; ++n) _Pragma("unroll") for (int k = 0; k < 2; ++k) \
;     dst[n][k] = *reinterpret_cast<const bf16x8*>((char*)SB(b, h) + lds_byte(wc * 32 + n * 16 + fr, k * 32 + fq * 8))
; #define MMA(ai, bj, At, Bt_) do { __builtin_amdgcn_s_setprio(1); \
;     _Pragma("unroll") for (int m = 0; m < 4; ++m) _Pragma("unroll") for (int n = 0; n < 2; ++n) _Pragma("unroll") for (int k = 0; k < 2; ++k) \
;       acc[ai][bj][m][n] = __builtin_amdgcn_mfma_f32_16x16x32_bf16(At[m][k], Bt_[n][k], acc[ai][bj][m][n], 0, 0, 0); \
;     __builtin_amdgcn_s_setprio(0); } while (0)
; #define WAIT_V(n) asm volatile("s_waitcnt vmcnt(" #n ")" ::: "memory")
; #define WAIT_L(n) asm volatile("s_waitcnt lgkmcnt(" #n ")" ::: "memory")
; #define BAR __builtin_amdgcn_s_barrier()
; template <class Epi> ...
;     ...
;   { LDB(B0, 1, 0); LDA(At, 1, 0); WAIT_V(2); BAR; WAIT_L(0); MMA(0, 0, At, B0); BAR;
;     LDB(B1, 1, 1); WAIT_V(0); BAR; WAIT_L(0); MMA(0, 1, At, B1); BAR;
;     LDA(At, 1, 1); BAR; WAIT_L(0); MMA(1, 0, At, B0); MMA(1, 1, At, B1); BAR; }
;   if (wr == 0) BAR;
	s_nop 0
	ds_read_b128 v[4:7], v145
	ds_read_b128 v[8:11], v145 offset:1024
	ds_read_b128 v[12:15], v145 offset:2048
	ds_read_b128 v[146:149], v145 offset:3072
	ds_read_b128 v[16:19], v143 offset:32768
	ds_read_b128 v[20:23], v143 offset:33792
	ds_read_b128 v[24:27], v142 offset:32768
	ds_read_b128 v[50:53], v142 offset:33792
	ds_read_b128 v[202:205], v141 offset:32768
	ds_read_b128 v[206:209], v141 offset:33792
	ds_read_b128 v[210:213], v140 offset:32768
	ds_read_b128 v[218:221], v140 offset:33792
	s_waitcnt vmcnt(2)
	s_barrier
	s_waitcnt lgkmcnt(0)
	s_setprio 0
	s_waitcnt lgkmcnt(7)
	v_mfma_f32_16x16x32_bf16 v[28:31], v[16:19], v[4:7], v[126:129]
	s_waitcnt lgkmcnt(6)
	v_mfma_f32_16x16x32_bf16 v[126:129], v[20:23], v[8:11], v[28:31]
	v_mfma_f32_16x16x32_bf16 v[28:31], v[16:19], v[12:15], v[122:125]
	v_mfma_f32_16x16x32_bf16 v[94:97], v[20:23], v[146:149], v[28:31]
	s_waitcnt lgkmcnt(5)
	v_mfma_f32_16x16x32_bf16 v[28:31], v[24:27], v[4:7], v[118:121]
	s_waitcnt lgkmcnt(4)
	v_mfma_f32_16x16x32_bf16 v[122:125], v[50:53], v[8:11], v[28:31]
	v_mfma_f32_16x16x32_bf16 v[28:31], v[24:27], v[12:15], v[114:117]
	v_mfma_f32_16x16x32_bf16 v[90:93], v[50:53], v[146:149], v[28:31]
	s_waitcnt lgkmcnt(3)
	v_mfma_f32_16x16x32_bf16 v[28:31], v[202:205], v[4:7], v[110:113]
	s_waitcnt lgkmcnt(2)
	v_mfma_f32_16x16x32_bf16 v[118:121], v[206:209], v[8:11], v[28:31]
	v_mfma_f32_16x16x32_bf16 v[28:31], v[202:205], v[12:15], v[106:109]
	v_mfma_f32_16x16x32_bf16 v[86:89], v[206:209], v[146:149], v[28:31]
	s_waitcnt lgkmcnt(1)
	v_mfma_f32_16x16x32_bf16 v[28:31], v[210:213], v[4:7], v[102:105]
	s_waitcnt lgkmcnt(0)
	v_mfma_f32_16x16x32_bf16 v[114:117], v[218:221], v[8:11], v[28:31]
	v_mfma_f32_16x16x32_bf16 v[28:31], v[210:213], v[12:15], v[98:101]
	v_mfma_f32_16x16x32_bf16 v[82:85], v[218:221], v[146:149], v[28:31]
	s_setprio 1
	s_barrier
	ds_read_b128 v[222:225], v144
	ds_read_b128 v[242:245], v144 offset:1024
	ds_read_b128 v[246:249], v144 offset:2048
	ds_read_b128 v[250:253], v144 offset:3072
	s_waitcnt vmcnt(0)
	s_barrier
	s_waitcnt lgkmcnt(0)
	s_setprio 0
	s_waitcnt lgkmcnt(3)
	v_mfma_f32_16x16x32_bf16 v[28:31], v[16:19], v[222:225], v[226:229]
	s_waitcnt lgkmcnt(1)
	v_mfma_f32_16x16x32_bf16 v[16:19], v[16:19], v[246:249], v[186:189]
	v_mfma_f32_16x16x32_bf16 v[62:65], v[20:23], v[242:245], v[28:31]
	s_waitcnt lgkmcnt(0)
	v_mfma_f32_16x16x32_bf16 v[28:31], v[20:23], v[250:253], v[16:19]
	v_mfma_f32_16x16x32_bf16 v[16:19], v[24:27], v[222:225], v[190:193]
	v_mfma_f32_16x16x32_bf16 v[58:61], v[50:53], v[242:245], v[16:19]
	v_mfma_f32_16x16x32_bf16 v[16:19], v[24:27], v[246:249], v[194:197]
	v_mfma_f32_16x16x32_bf16 v[24:27], v[50:53], v[250:253], v[16:19]
	v_mfma_f32_16x16x32_bf16 v[16:19], v[202:205], v[222:225], v[78:81]
	v_mfma_f32_16x16x32_bf16 v[54:57], v[206:209], v[242:245], v[16:19]
	v_mfma_f32_16x16x32_bf16 v[16:19], v[202:205], v[246:249], v[74:77]
	v_mfma_f32_16x16x32_bf16 v[20:23], v[206:209], v[250:253], v[16:19]
	v_mfma_f32_16x16x32_bf16 v[16:19], v[210:213], v[222:225], v[70:73]
	v_mfma_f32_16x16x32_bf16 v[50:53], v[218:221], v[242:245], v[16:19]
	v_mfma_f32_16x16x32_bf16 v[16:19], v[210:213], v[246:249], v[66:69]
	v_mfma_f32_16x16x32_bf16 v[16:19], v[218:221], v[250:253], v[16:19]
	s_setprio 1
	s_barrier
	ds_read_b128 v[186:189], v143 offset:49152
	ds_read_b128 v[190:193], v143 offset:50176
	ds_read_b128 v[194:197], v142 offset:49152
	ds_read_b128 v[142:145], v142 offset:50176
	ds_read_b128 v[202:205], v141 offset:49152
	ds_read_b128 v[206:209], v141 offset:50176
	ds_read_b128 v[210:213], v140 offset:49152
	ds_read_b128 v[218:221], v140 offset:50176
	s_barrier
	s_waitcnt lgkmcnt(0)
	s_setprio 0
	s_waitcnt lgkmcnt(7)
	v_mfma_f32_16x16x32_bf16 v[66:69], v[186:189], v[4:7], v[214:217]
	s_waitcnt lgkmcnt(6)
	v_mfma_f32_16x16x32_bf16 v[110:113], v[190:193], v[8:11], v[66:69]
	v_mfma_f32_16x16x32_bf16 v[66:69], v[186:189], v[12:15], v[230:233]
	v_mfma_f32_16x16x32_bf16 v[78:81], v[190:193], v[146:149], v[66:69]
	s_waitcnt lgkmcnt(5)
	v_mfma_f32_16x16x32_bf16 v[66:69], v[194:197], v[4:7], v[234:237]
	s_waitcnt lgkmcnt(3)
	v_mfma_f32_16x16x32_bf16 v[46:49], v[202:205], v[4:7], v[46:49]
	s_waitcnt lgkmcnt(1)
	v_mfma_f32_16x16x32_bf16 v[4:7], v[210:213], v[4:7], v[38:41]
	v_mfma_f32_16x16x32_bf16 v[106:109], v[142:145], v[8:11], v[66:69]
	v_mfma_f32_16x16x32_bf16 v[66:69], v[194:197], v[12:15], v[238:241]
	v_mfma_f32_16x16x32_bf16 v[42:45], v[202:205], v[12:15], v[42:45]
	s_waitcnt lgkmcnt(0)
	v_mfma_f32_16x16x32_bf16 v[98:101], v[218:221], v[8:11], v[4:7]
	v_mfma_f32_16x16x32_bf16 v[4:7], v[210:213], v[12:15], v[34:37]
	v_mfma_f32_16x16x32_bf16 v[74:77], v[142:145], v[146:149], v[66:69]
	v_mfma_f32_16x16x32_bf16 v[102:105], v[206:209], v[8:11], v[46:49]
	v_mfma_f32_16x16x32_bf16 v[70:73], v[206:209], v[146:149], v[42:45]
	v_mfma_f32_16x16x32_bf16 v[66:69], v[218:221], v[146:149], v[4:7]
	s_setprio 1
	s_setprio 0
	v_mfma_f32_16x16x32_bf16 v[4:7], v[186:189], v[222:225], v[154:157]
	v_mfma_f32_16x16x32_bf16 v[46:49], v[190:193], v[242:245], v[4:7]
	v_mfma_f32_16x16x32_bf16 v[4:7], v[186:189], v[246:249], v[158:161]
	v_mfma_f32_16x16x32_bf16 v[12:15], v[190:193], v[250:253], v[4:7]
	v_mfma_f32_16x16x32_bf16 v[4:7], v[194:197], v[222:225], v[166:169]
	v_mfma_f32_16x16x32_bf16 v[42:45], v[142:145], v[242:245], v[4:7]
	v_mfma_f32_16x16x32_bf16 v[4:7], v[194:197], v[246:249], v[170:173]
	v_mfma_f32_16x16x32_bf16 v[8:11], v[142:145], v[250:253], v[4:7]
	v_mfma_f32_16x16x32_bf16 v[4:7], v[202:205], v[222:225], v[174:177]
	v_mfma_f32_16x16x32_bf16 v[38:41], v[206:209], v[242:245], v[4:7]
	v_mfma_f32_16x16x32_bf16 v[4:7], v[202:205], v[246:249], v[198:201]
	v_mfma_f32_16x16x32_bf16 v[34:37], v[210:213], v[222:225], v[150:153]
	v_mfma_f32_16x16x32_bf16 v[0:3], v[210:213], v[246:249], v[0:3]
	v_mfma_f32_16x16x32_bf16 v[4:7], v[206:209], v[250:253], v[4:7]
	v_mfma_f32_16x16x32_bf16 v[34:37], v[218:221], v[242:245], v[34:37]
	v_mfma_f32_16x16x32_bf16 v[0:3], v[218:221], v[250:253], v[0:3]
	s_setprio 1
	v_cmp_gt_u32_e32 vcc, s59, v130
	s_barrier
	s_and_saveexec_b64 s[6:7], vcc
	s_cbranch_execz .LBB0_2339
	s_barrier
